# stack8 + loop-edge peel: first K-loop load segment copied in front of the loop with the pk zeroing interleaved behind its ds_reads (14 GEMM instances)
# speedup vs baseline: 1.0066x; 1.0017x over previous
; #define PG8_STAGE(bufoff, gbase, voff) do { _Pragma("unroll") for (int _i = 0; _i < 2; ++_i) \
;         __builtin_amdgcn_global_load_lds((const unsigned*)((const char*)(gbase) + (voff)[_i]), (PG8_LAS unsigned*)(lds + (bufoff) + ldsw + _i * 8192), 16, 0, 0); } while (0)
; #define PG8_LDA(dst, b, h) do { _Pragma("unroll") for (int m = 0; m < 4; ++m) _Pragma("unroll") for (int k = 0; k < 2; ++k) dst[m][k] = *(const PG8_LAS bf16x8*)(lds + PG8_SA(b, h) + aoff + m * 2048 + k * 1024); } while (0)
; #define PG8_LDB(dst, b, h) do { _Pragma("unroll") for (int n = 0; n < 2; ++n) _Pragma("unroll") for (int k = 0; k < 2; ++k) dst[n][k] = *(const PG8_LAS bf16x8*)(lds + PG8_SB(b, h) + boff + n * 2048 + k * 1024); } while (0)
; #define PG8_WAIT_V(n) asm volatile("s_waitcnt vmcnt(" #n ")" ::: "memory")
; #define PG8_WAIT_L(n) asm volatile("s_waitcnt lgkmcnt(" #n ")" ::: "memory")
; #define PG8_BAR __builtin_amdgcn_s_barrier()
; template <class Epi, class Sched, bool ALIGN_EPI = false, bool SP2 = false, bool ABLK = false, bool BBLK = false>
; __device__ __forceinline__ void gemm_phase(PG8_LAS unsigned char* lds, const Gemm g, const Sched& S, const Epi& E) {
;     ...
;         const bool has_next = S.next(ui + 1, nxt);
;         const char* nA = has_next ? (const char*)g.A + (size_t)nxt.pm * tstepA : cA; const char* nB = has_next ? (const char*)g.Bt + (size_t)nxt.pn * tstepB : cB;
;         for (int t = 0; t < nt; t += 2) {
;             const bool last = (t == nt - 2);
;             const char* a1 = cA + (size_t)(t + 1) * kstepA;
;             const char* a2 = last ? nA : cA + (size_t)(t + 2) * kstepA; const char* b2 = last ? nB : cB + (size_t)(t + 2) * kstepB;
;             const char* a3 = a2 + kstepA; const char* b3 = b2 + kstepB;
;             if (last && has_next) S.a_ready(nxt);
;             if constexpr (SP2) {
;             PG8_LDB(B0, 0, 0); PG8_LDB(B1, 0, 1); PG8_SCHED; PG8_LDA(At, 0, 0); PG8_STAGE(PG8_SA(1, 1), a1 + hstepA, voffA);
;             PG8_WAIT_V(8); PG8_WAIT_L(0); PG8_BAR; PG8_MMA(0, 0, At, B0); PG8_MMA(0, 1, At, B1); PG8_BAR; PG8_SCHED;
;     ...
;         for (int a = 0; a < 2; ++a)
; #pragma unroll
;             for (int b = 0; b < 2; ++b)
; #pragma unroll
;                 for (int m = 0; m < 4; ++m)
; #pragma unroll
;                     for (int n = 0; n < 2; ++n) acc[a][b][m][n] = (f32x4){0.f, 0.f, 0.f, 0.f};
.LBB0_215:
	s_ashr_i32 s15, s14, 31
	s_lshl_b64 s[18:19], s[14:15], 20
	s_add_u32 s18, s35, s18
	s_addc_u32 s19, s36, s19
	s_and_b64 s[20:21], s[4:5], exec
	s_cselect_b32 s15, s19, s23
	s_cselect_b32 s65, s18, s22
	s_ashr_i32 s13, s12, 31
	s_lshl_b64 s[20:21], s[12:13], 20
	s_add_u32 s20, s37, s20
	s_addc_u32 s21, s40, s21
	s_and_b64 s[26:27], s[4:5], exec
	s_cselect_b32 s13, s21, s25
	s_cselect_b32 s68, s20, s24
	s_add_u32 s22, s22, 0xc000
	s_addc_u32 s23, s23, 0
	s_add_u32 s72, s24, 0x10000
	v_mov_b32_e32 v2, 0
	s_addc_u32 s73, s25, 0
	s_mov_b32 s81, -2
	s_add_u32 s24, s22, 0x4000
	s_addc_u32 s25, s23, 0
	s_cmp_eq_u32 s81, 28
	s_cselect_b32 s28, s65, s24
	s_cselect_b32 s29, s15, s25
	s_cselect_b32 s26, s68, s72
	s_cselect_b32 s27, s13, s73
	s_add_u32 s24, s28, 0x8000
	s_addc_u32 s25, s29, 0
	s_add_i32 s75, 0, 0x10000
	v_add_u32_e32 v142, s75, v145
	s_add_i32 s80, 0, 0x14000
	ds_read_b128 v[148:151], v142
	v_pk_mov_b32 v[2:3], 0, 0
	v_pk_mov_b32 v[4:5], 0, 0
	v_pk_mov_b32 v[6:7], 0, 0
	v_pk_mov_b32 v[8:9], 0, 0
	ds_read_b128 v[152:155], v142 offset:1024
	v_pk_mov_b32 v[10:11], 0, 0
	v_pk_mov_b32 v[12:13], 0, 0
	v_pk_mov_b32 v[14:15], 0, 0
	v_pk_mov_b32 v[16:17], 0, 0
	ds_read_b128 v[156:159], v142 offset:2048
	v_pk_mov_b32 v[18:19], 0, 0
	v_pk_mov_b32 v[20:21], 0, 0
	v_pk_mov_b32 v[22:23], 0, 0
	v_pk_mov_b32 v[24:25], 0, 0
	ds_read_b128 v[160:163], v142 offset:3072
	v_pk_mov_b32 v[26:27], 0, 0
	v_pk_mov_b32 v[28:29], 0, 0
	v_pk_mov_b32 v[30:31], 0, 0
	v_pk_mov_b32 v[32:33], 0, 0
	v_add_u32_e32 v142, s80, v145
	ds_read_b128 v[164:167], v142
	v_pk_mov_b32 v[34:35], 0, 0
	v_pk_mov_b32 v[36:37], 0, 0
	v_pk_mov_b32 v[38:39], 0, 0
	v_pk_mov_b32 v[40:41], 0, 0
	ds_read_b128 v[168:171], v142 offset:1024
	v_pk_mov_b32 v[42:43], 0, 0
	v_pk_mov_b32 v[44:45], 0, 0
	v_pk_mov_b32 v[46:47], 0, 0
	v_pk_mov_b32 v[48:49], 0, 0
	ds_read_b128 v[172:175], v142 offset:2048
	v_pk_mov_b32 v[50:51], 0, 0
	v_pk_mov_b32 v[52:53], 0, 0
	v_pk_mov_b32 v[54:55], 0, 0
	v_pk_mov_b32 v[56:57], 0, 0
	ds_read_b128 v[176:179], v142 offset:3072
	v_pk_mov_b32 v[58:59], 0, 0
	v_pk_mov_b32 v[60:61], 0, 0
	v_pk_mov_b32 v[62:63], 0, 0
	v_pk_mov_b32 v[64:65], 0, 0
	v_lshl_add_u64 v[142:143], s[22:23], 0, v[138:139]
	s_add_i32 m0, s43, 0xc000
	ds_read_b128 v[180:183], v146
	v_pk_mov_b32 v[66:67], 0, 0
	v_pk_mov_b32 v[68:69], 0, 0
	v_pk_mov_b32 v[70:71], 0, 0
	v_pk_mov_b32 v[72:73], 0, 0
	ds_read_b128 v[196:199], v146 offset:1024
	v_pk_mov_b32 v[74:75], 0, 0
	v_pk_mov_b32 v[76:77], 0, 0
	v_pk_mov_b32 v[78:79], 0, 0
	v_pk_mov_b32 v[80:81], 0, 0
	ds_read_b128 v[200:203], v146 offset:2048
	v_pk_mov_b32 v[82:83], 0, 0
	v_pk_mov_b32 v[84:85], 0, 0
	v_pk_mov_b32 v[86:87], 0, 0
	v_pk_mov_b32 v[88:89], 0, 0
	ds_read_b128 v[204:207], v146 offset:3072
	v_pk_mov_b32 v[90:91], 0, 0
	v_pk_mov_b32 v[92:93], 0, 0
	v_pk_mov_b32 v[94:95], 0, 0
	v_pk_mov_b32 v[96:97], 0, 0
	ds_read_b128 v[208:211], v146 offset:4096
	v_pk_mov_b32 v[98:99], 0, 0
	v_pk_mov_b32 v[100:101], 0, 0
	v_pk_mov_b32 v[102:103], 0, 0
	v_pk_mov_b32 v[104:105], 0, 0
	ds_read_b128 v[212:215], v146 offset:5120
	v_pk_mov_b32 v[106:107], 0, 0
	v_pk_mov_b32 v[108:109], 0, 0
	v_pk_mov_b32 v[110:111], 0, 0
	v_pk_mov_b32 v[112:113], 0, 0
	ds_read_b128 v[216:219], v146 offset:6144
	v_pk_mov_b32 v[114:115], 0, 0
	v_pk_mov_b32 v[116:117], 0, 0
	v_pk_mov_b32 v[118:119], 0, 0
	v_pk_mov_b32 v[120:121], 0, 0
	ds_read_b128 v[220:223], v146 offset:7168
	v_pk_mov_b32 v[122:123], 0, 0
	v_pk_mov_b32 v[124:125], 0, 0
	v_pk_mov_b32 v[126:127], 0, 0
	v_pk_mov_b32 v[128:129], 0, 0
	global_load_lds_dwordx4 v[142:143], off
	v_lshl_add_u64 v[142:143], s[22:23], 0, v[140:141]
	s_add_i32 m0, s43, 0xe000
	s_nop 0
	global_load_lds_dwordx4 v[142:143], off
	s_waitcnt vmcnt(8)
	s_waitcnt lgkmcnt(0)
	s_barrier
	s_branch .Lpeel_216

; #define PG8_STAGE(bufoff, gbase, voff) do { _Pragma("unroll") for (int _i = 0; _i < 2; ++_i) \
;         __builtin_amdgcn_global_load_lds((const unsigned*)((const char*)(gbase) + (voff)[_i]), (PG8_LAS unsigned*)(lds + (bufoff) + ldsw + _i * 8192), 16, 0, 0); } while (0)
; #define PG8_LDA(dst, b, h) do { _Pragma("unroll") for (int m = 0; m < 4; ++m) _Pragma("unroll") for (int k = 0; k < 2; ++k) dst[m][k] = *(const PG8_LAS bf16x8*)(lds + PG8_SA(b, h) + aoff + m * 2048 + k * 1024); } while (0)
; #define PG8_LDB(dst, b, h) do { _Pragma("unroll") for (int n = 0; n < 2; ++n) _Pragma("unroll") for (int k = 0; k < 2; ++k) dst[n][k] = *(const PG8_LAS bf16x8*)(lds + PG8_SB(b, h) + boff + n * 2048 + k * 1024); } while (0)
; #define PG8_MMA(ai, bj, At, Bt) do { __builtin_amdgcn_s_setprio(1); _Pragma("unroll") for (int m = 0; m < 4; ++m) _Pragma("unroll") for (int n = 0; n < 2; ++n) _Pragma("unroll") for (int k = 0; k < 2; ++k) \
;         acc[ai][bj][m][n] = __builtin_amdgcn_mfma_f32_16x16x32_bf16(Bt[n][k], At[m][k], acc[ai][bj][m][n], 0, 0, 0); __builtin_amdgcn_s_setprio(0); } while (0)
; #define PG8_WAIT_V(n) asm volatile("s_waitcnt vmcnt(" #n ")" ::: "memory")
; #define PG8_WAIT_L(n) asm volatile("s_waitcnt lgkmcnt(" #n ")" ::: "memory")
; #define PG8_BAR __builtin_amdgcn_s_barrier()
; #define PG8_SCHED __builtin_amdgcn_sched_barrier(0)
; template <class Epi, class Sched, bool ALIGN_EPI = false, bool SP2 = false, bool ABLK = false, bool BBLK = false>
; __device__ __forceinline__ void gemm_phase(PG8_LAS unsigned char* lds, const Gemm g, const Sched& S, const Epi& E) {
;     ...
;             PG8_LDB(B0, 0, 0); PG8_LDB(B1, 0, 1); PG8_SCHED; PG8_LDA(At, 0, 0); PG8_STAGE(PG8_SA(1, 1), a1 + hstepA, voffA);
;             PG8_WAIT_V(8); PG8_WAIT_L(0); PG8_BAR; PG8_MMA(0, 0, At, B0); PG8_MMA(0, 1, At, B1); PG8_BAR; PG8_SCHED;
;             PG8_LDA(At, 0, 1); PG8_STAGE(PG8_SB(0, 0), b2, voffB); PG8_STAGE(PG8_SB(0, 1), b2 + hstepB, voffB); PG8_STAGE(PG8_SA(0, 0), a2, voffA);
;             PG8_WAIT_V(8); PG8_WAIT_L(0); PG8_BAR; PG8_MMA(1, 0, At, B0); PG8_MMA(1, 1, At, B1); PG8_BAR; PG8_SCHED;
.Lpeel_216:
	s_setprio 1
	s_waitcnt lgkmcnt(0)
	v_mfma_f32_16x16x32_bf16 v[126:129], v[148:151], v[180:183], v[126:129]
	v_mfma_f32_16x16x32_bf16 v[118:121], v[156:159], v[180:183], v[118:121]
	v_mfma_f32_16x16x32_bf16 v[110:113], v[148:151], v[200:203], v[110:113]
	v_mfma_f32_16x16x32_bf16 v[102:105], v[156:159], v[200:203], v[102:105]
	v_mfma_f32_16x16x32_bf16 v[94:97], v[148:151], v[208:211], v[94:97]
	v_mfma_f32_16x16x32_bf16 v[86:89], v[156:159], v[208:211], v[86:89]
	v_mfma_f32_16x16x32_bf16 v[78:81], v[148:151], v[216:219], v[78:81]
	v_mfma_f32_16x16x32_bf16 v[70:73], v[156:159], v[216:219], v[70:73]
	v_mfma_f32_16x16x32_bf16 v[126:129], v[152:155], v[196:199], v[126:129]
	v_mfma_f32_16x16x32_bf16 v[118:121], v[160:163], v[196:199], v[118:121]
	v_mfma_f32_16x16x32_bf16 v[110:113], v[152:155], v[204:207], v[110:113]
	v_mfma_f32_16x16x32_bf16 v[102:105], v[160:163], v[204:207], v[102:105]
	v_mfma_f32_16x16x32_bf16 v[94:97], v[152:155], v[212:215], v[94:97]
	v_mfma_f32_16x16x32_bf16 v[86:89], v[160:163], v[212:215], v[86:89]
	v_mfma_f32_16x16x32_bf16 v[78:81], v[152:155], v[220:223], v[78:81]
	v_mfma_f32_16x16x32_bf16 v[70:73], v[160:163], v[220:223], v[70:73]
	s_setprio 0
	s_setprio 1
	v_mfma_f32_16x16x32_bf16 v[122:125], v[164:167], v[180:183], v[122:125]
	v_mfma_f32_16x16x32_bf16 v[114:117], v[172:175], v[180:183], v[114:117]
	v_mfma_f32_16x16x32_bf16 v[106:109], v[164:167], v[200:203], v[106:109]
	v_mfma_f32_16x16x32_bf16 v[98:101], v[172:175], v[200:203], v[98:101]
	v_mfma_f32_16x16x32_bf16 v[90:93], v[164:167], v[208:211], v[90:93]
	v_mfma_f32_16x16x32_bf16 v[82:85], v[172:175], v[208:211], v[82:85]
	v_mfma_f32_16x16x32_bf16 v[74:77], v[164:167], v[216:219], v[74:77]
	v_mfma_f32_16x16x32_bf16 v[66:69], v[172:175], v[216:219], v[66:69]
	v_mfma_f32_16x16x32_bf16 v[122:125], v[168:171], v[196:199], v[122:125]
	v_mfma_f32_16x16x32_bf16 v[114:117], v[176:179], v[196:199], v[114:117]
	v_mfma_f32_16x16x32_bf16 v[106:109], v[168:171], v[204:207], v[106:109]
	v_mfma_f32_16x16x32_bf16 v[98:101], v[176:179], v[204:207], v[98:101]
	v_mfma_f32_16x16x32_bf16 v[90:93], v[168:171], v[212:215], v[90:93]
	v_mfma_f32_16x16x32_bf16 v[82:85], v[176:179], v[212:215], v[82:85]
	v_mfma_f32_16x16x32_bf16 v[74:77], v[168:171], v[220:223], v[74:77]
	v_mfma_f32_16x16x32_bf16 v[66:69], v[176:179], v[220:223], v[66:69]
	s_setprio 0
	s_barrier
	s_add_i32 s75, s75, s41
	v_lshl_add_u64 v[142:143], s[26:27], 0, v[134:135]
	s_mov_b32 m0, s75
	ds_read_b128 v[180:183], v146 offset:16384
	ds_read_b128 v[196:199], v146 offset:17408
	ds_read_b128 v[200:203], v146 offset:18432
	ds_read_b128 v[204:207], v146 offset:19456
	ds_read_b128 v[208:211], v146 offset:20480
	ds_read_b128 v[212:215], v146 offset:21504
	ds_read_b128 v[216:219], v146 offset:22528
	ds_read_b128 v[220:223], v146 offset:23552
	global_load_lds_dwordx4 v[142:143], off
	s_add_i32 m0, s75, 0x2000
	s_add_u32 s82, s26, 0x4000
	v_lshl_add_u64 v[142:143], s[26:27], 0, v[130:131]
	s_addc_u32 s83, s27, 0
	s_add_i32 s75, s80, s41
	global_load_lds_dwordx4 v[142:143], off
	v_lshl_add_u64 v[142:143], s[82:83], 0, v[134:135]
	s_mov_b32 m0, s75
	s_nop 0
	global_load_lds_dwordx4 v[142:143], off
	v_lshl_add_u64 v[142:143], s[82:83], 0, v[130:131]
	s_add_i32 m0, s75, 0x2000
	s_nop 0
	global_load_lds_dwordx4 v[142:143], off
	v_lshl_add_u64 v[142:143], s[28:29], 0, v[136:137]
	s_mov_b32 m0, s43
	s_nop 0
	global_load_lds_dwordx4 v[142:143], off
	v_lshl_add_u64 v[142:143], s[28:29], 0, v[132:133]
	s_mov_b32 m0, s44
	s_nop 0
	global_load_lds_dwordx4 v[142:143], off
	s_waitcnt vmcnt(8)
	s_waitcnt lgkmcnt(0)
	s_barrier
	s_setprio 1
	s_waitcnt lgkmcnt(0)
	v_mfma_f32_16x16x32_bf16 v[62:65], v[148:151], v[180:183], v[62:65]
	v_mfma_f32_16x16x32_bf16 v[54:57], v[156:159], v[180:183], v[54:57]
	v_mfma_f32_16x16x32_bf16 v[46:49], v[148:151], v[200:203], v[46:49]
	v_mfma_f32_16x16x32_bf16 v[38:41], v[156:159], v[200:203], v[38:41]
	v_mfma_f32_16x16x32_bf16 v[30:33], v[148:151], v[208:211], v[30:33]
	v_mfma_f32_16x16x32_bf16 v[22:25], v[156:159], v[208:211], v[22:25]
	v_mfma_f32_16x16x32_bf16 v[14:17], v[148:151], v[216:219], v[14:17]
	v_mfma_f32_16x16x32_bf16 v[6:9], v[156:159], v[216:219], v[6:9]
	v_mfma_f32_16x16x32_bf16 v[62:65], v[152:155], v[196:199], v[62:65]
	v_mfma_f32_16x16x32_bf16 v[54:57], v[160:163], v[196:199], v[54:57]
	v_mfma_f32_16x16x32_bf16 v[46:49], v[152:155], v[204:207], v[46:49]
	v_mfma_f32_16x16x32_bf16 v[38:41], v[160:163], v[204:207], v[38:41]
	v_mfma_f32_16x16x32_bf16 v[30:33], v[152:155], v[212:215], v[30:33]
	v_mfma_f32_16x16x32_bf16 v[22:25], v[160:163], v[212:215], v[22:25]
	v_mfma_f32_16x16x32_bf16 v[14:17], v[152:155], v[220:223], v[14:17]
	v_mfma_f32_16x16x32_bf16 v[6:9], v[160:163], v[220:223], v[6:9]
	s_setprio 0
	s_setprio 1
	v_mfma_f32_16x16x32_bf16 v[58:61], v[164:167], v[180:183], v[58:61]
	v_mfma_f32_16x16x32_bf16 v[50:53], v[172:175], v[180:183], v[50:53]
	v_mfma_f32_16x16x32_bf16 v[42:45], v[164:167], v[200:203], v[42:45]
	v_mfma_f32_16x16x32_bf16 v[34:37], v[172:175], v[200:203], v[34:37]
	v_mfma_f32_16x16x32_bf16 v[26:29], v[164:167], v[208:211], v[26:29]
	v_mfma_f32_16x16x32_bf16 v[18:21], v[172:175], v[208:211], v[18:21]
	v_mfma_f32_16x16x32_bf16 v[10:13], v[164:167], v[216:219], v[10:13]
	v_mfma_f32_16x16x32_bf16 v[2:5], v[172:175], v[216:219], v[2:5]
	v_mfma_f32_16x16x32_bf16 v[58:61], v[168:171], v[196:199], v[58:61]
	v_mfma_f32_16x16x32_bf16 v[50:53], v[176:179], v[196:199], v[50:53]
	v_mfma_f32_16x16x32_bf16 v[42:45], v[168:171], v[204:207], v[42:45]
	v_mfma_f32_16x16x32_bf16 v[34:37], v[176:179], v[204:207], v[34:37]
	v_mfma_f32_16x16x32_bf16 v[26:29], v[168:171], v[212:215], v[26:29]
	v_mfma_f32_16x16x32_bf16 v[18:21], v[176:179], v[212:215], v[18:21]
	v_mfma_f32_16x16x32_bf16 v[10:13], v[168:171], v[220:223], v[10:13]
	v_mfma_f32_16x16x32_bf16 v[2:5], v[176:179], v[220:223], v[2:5]
	s_setprio 0
	s_barrier
; #define PG8_STAGE(bufoff, gbase, voff) do { _Pragma("unroll") for (int _i = 0; _i < 2; ++_i) \
;         __builtin_amdgcn_global_load_lds((const unsigned*)((const char*)(gbase) + (voff)[_i]), (PG8_LAS unsigned*)(lds + (bufoff) + ldsw + _i * 8192), 16, 0, 0); } while (0)
; #define PG8_LDA(dst, b, h) do { _Pragma("unroll") for (int m = 0; m < 4; ++m) _Pragma("unroll") for (int k = 0; k < 2; ++k) dst[m][k] = *(const PG8_LAS bf16x8*)(lds + PG8_SA(b, h) + aoff + m * 2048 + k * 1024); } while (0)
; #define PG8_LDB(dst, b, h) do { _Pragma("unroll") for (int n = 0; n < 2; ++n) _Pragma("unroll") for (int k = 0; k < 2; ++k) dst[n][k] = *(const PG8_LAS bf16x8*)(lds + PG8_SB(b, h) + boff + n * 2048 + k * 1024); } while (0)
; #define PG8_MMA(ai, bj, At, Bt) do { __builtin_amdgcn_s_setprio(1); _Pragma("unroll") for (int m = 0; m < 4; ++m) _Pragma("unroll") for (int n = 0; n < 2; ++n) _Pragma("unroll") for (int k = 0; k < 2; ++k) \
;         acc[ai][bj][m][n] = __builtin_amdgcn_mfma_f32_16x16x32_bf16(Bt[n][k], At[m][k], acc[ai][bj][m][n], 0, 0, 0); __builtin_amdgcn_s_setprio(0); } while (0)
; #define PG8_WAIT_V(n) asm volatile("s_waitcnt vmcnt(" #n ")" ::: "memory")
; #define PG8_WAIT_L(n) asm volatile("s_waitcnt lgkmcnt(" #n ")" ::: "memory")
; #define PG8_BAR __builtin_amdgcn_s_barrier()
; #define PG8_SCHED __builtin_amdgcn_sched_barrier(0)
; template <class Epi, class Sched, bool ALIGN_EPI = false, bool SP2 = false, bool ABLK = false, bool BBLK = false>
; __device__ __forceinline__ void gemm_phase(PG8_LAS unsigned char* lds, const Gemm g, const Sched& S, const Epi& E) {
;     ...
;             PG8_LDB(B0, 1, 0); PG8_LDB(B1, 1, 1); PG8_SCHED; PG8_LDA(At, 1, 0); PG8_STAGE(PG8_SA(0, 1), a2 + hstepA, voffA);
;             PG8_WAIT_V(8); PG8_WAIT_L(0); PG8_BAR; PG8_MMA(0, 0, At, B0); PG8_MMA(0, 1, At, B1); PG8_BAR; PG8_SCHED;
	s_add_i32 s75, 0, 0x18000
	v_add_u32_e32 v142, s75, v145
	s_add_i32 s80, 0, 0x1c000
	ds_read_b128 v[148:151], v142
	ds_read_b128 v[152:155], v142 offset:1024
	ds_read_b128 v[156:159], v142 offset:2048
	ds_read_b128 v[160:163], v142 offset:3072
	v_add_u32_e32 v142, s80, v145
	ds_read_b128 v[164:167], v142
	ds_read_b128 v[168:171], v142 offset:1024
	ds_read_b128 v[172:175], v142 offset:2048
	ds_read_b128 v[176:179], v142 offset:3072
	s_add_u32 s28, s28, 0x4000
	s_addc_u32 s29, s29, 0
	s_mov_b32 m0, s45
	v_lshl_add_u64 v[142:143], s[28:29], 0, v[136:137]
	ds_read_b128 v[180:183], v146 offset:32768
	ds_read_b128 v[196:199], v146 offset:33792
	ds_read_b128 v[200:203], v146 offset:34816
	ds_read_b128 v[204:207], v146 offset:35840
	ds_read_b128 v[208:211], v146 offset:36864
	ds_read_b128 v[212:215], v146 offset:37888
	ds_read_b128 v[216:219], v146 offset:38912
	ds_read_b128 v[220:223], v146 offset:39936
	global_load_lds_dwordx4 v[142:143], off
	v_lshl_add_u64 v[142:143], s[28:29], 0, v[132:133]
	s_mov_b32 m0, s46
	s_nop 0
	global_load_lds_dwordx4 v[142:143], off
	s_waitcnt vmcnt(8)
	s_waitcnt lgkmcnt(0)
	s_barrier
	s_setprio 1
	s_waitcnt lgkmcnt(0)
	v_mfma_f32_16x16x32_bf16 v[126:129], v[148:151], v[180:183], v[126:129]
	v_mfma_f32_16x16x32_bf16 v[118:121], v[156:159], v[180:183], v[118:121]
	v_mfma_f32_16x16x32_bf16 v[110:113], v[148:151], v[200:203], v[110:113]
	v_mfma_f32_16x16x32_bf16 v[102:105], v[156:159], v[200:203], v[102:105]
	v_mfma_f32_16x16x32_bf16 v[94:97], v[148:151], v[208:211], v[94:97]
	v_mfma_f32_16x16x32_bf16 v[86:89], v[156:159], v[208:211], v[86:89]
	v_mfma_f32_16x16x32_bf16 v[78:81], v[148:151], v[216:219], v[78:81]
	v_mfma_f32_16x16x32_bf16 v[70:73], v[156:159], v[216:219], v[70:73]
	v_mfma_f32_16x16x32_bf16 v[126:129], v[152:155], v[196:199], v[126:129]
	v_mfma_f32_16x16x32_bf16 v[118:121], v[160:163], v[196:199], v[118:121]
	v_mfma_f32_16x16x32_bf16 v[110:113], v[152:155], v[204:207], v[110:113]
	v_mfma_f32_16x16x32_bf16 v[102:105], v[160:163], v[204:207], v[102:105]
	v_mfma_f32_16x16x32_bf16 v[94:97], v[152:155], v[212:215], v[94:97]
	v_mfma_f32_16x16x32_bf16 v[86:89], v[160:163], v[212:215], v[86:89]
	v_mfma_f32_16x16x32_bf16 v[78:81], v[152:155], v[220:223], v[78:81]
	v_mfma_f32_16x16x32_bf16 v[70:73], v[160:163], v[220:223], v[70:73]
	s_setprio 0
	s_setprio 1
	v_mfma_f32_16x16x32_bf16 v[122:125], v[164:167], v[180:183], v[122:125]
	v_mfma_f32_16x16x32_bf16 v[114:117], v[172:175], v[180:183], v[114:117]
	v_mfma_f32_16x16x32_bf16 v[106:109], v[164:167], v[200:203], v[106:109]
	v_mfma_f32_16x16x32_bf16 v[98:101], v[172:175], v[200:203], v[98:101]
	v_mfma_f32_16x16x32_bf16 v[90:93], v[164:167], v[208:211], v[90:93]
	v_mfma_f32_16x16x32_bf16 v[82:85], v[172:175], v[208:211], v[82:85]
	v_mfma_f32_16x16x32_bf16 v[74:77], v[164:167], v[216:219], v[74:77]
	v_mfma_f32_16x16x32_bf16 v[66:69], v[172:175], v[216:219], v[66:69]
	v_mfma_f32_16x16x32_bf16 v[122:125], v[168:171], v[196:199], v[122:125]
	v_mfma_f32_16x16x32_bf16 v[114:117], v[176:179], v[196:199], v[114:117]
	v_mfma_f32_16x16x32_bf16 v[106:109], v[168:171], v[204:207], v[106:109]
	v_mfma_f32_16x16x32_bf16 v[98:101], v[176:179], v[204:207], v[98:101]
	v_mfma_f32_16x16x32_bf16 v[90:93], v[168:171], v[212:215], v[90:93]
	v_mfma_f32_16x16x32_bf16 v[82:85], v[176:179], v[212:215], v[82:85]
	v_mfma_f32_16x16x32_bf16 v[74:77], v[168:171], v[220:223], v[74:77]
	v_mfma_f32_16x16x32_bf16 v[66:69], v[176:179], v[220:223], v[66:69]
	s_setprio 0
	s_barrier
; #define PG8_STAGE(bufoff, gbase, voff) do { _Pragma("unroll") for (int _i = 0; _i < 2; ++_i) \
;         __builtin_amdgcn_global_load_lds((const unsigned*)((const char*)(gbase) + (voff)[_i]), (PG8_LAS unsigned*)(lds + (bufoff) + ldsw + _i * 8192), 16, 0, 0); } while (0)
; #define PG8_LDA(dst, b, h) do { _Pragma("unroll") for (int m = 0; m < 4; ++m) _Pragma("unroll") for (int k = 0; k < 2; ++k) dst[m][k] = *(const PG8_LAS bf16x8*)(lds + PG8_SA(b, h) + aoff + m * 2048 + k * 1024); } while (0)
; #define PG8_MMA(ai, bj, At, Bt) do { __builtin_amdgcn_s_setprio(1); _Pragma("unroll") for (int m = 0; m < 4; ++m) _Pragma("unroll") for (int n = 0; n < 2; ++n) _Pragma("unroll") for (int k = 0; k < 2; ++k) \
;         acc[ai][bj][m][n] = __builtin_amdgcn_mfma_f32_16x16x32_bf16(Bt[n][k], At[m][k], acc[ai][bj][m][n], 0, 0, 0); __builtin_amdgcn_s_setprio(0); } while (0)
; #define PG8_WAIT_V(n) asm volatile("s_waitcnt vmcnt(" #n ")" ::: "memory")
; #define PG8_WAIT_L(n) asm volatile("s_waitcnt lgkmcnt(" #n ")" ::: "memory")
; #define PG8_BAR __builtin_amdgcn_s_barrier()
; #define PG8_SCHED __builtin_amdgcn_sched_barrier(0)
; template <class Epi, class Sched, bool ALIGN_EPI = false, bool SP2 = false, bool ABLK = false, bool BBLK = false>
; __device__ __forceinline__ void gemm_phase(PG8_LAS unsigned char* lds, const Gemm g, const Sched& S, const Epi& E) {
;     ...
;             PG8_LDA(At, 1, 1); PG8_STAGE(PG8_SB(1, 0), b3, voffB); PG8_STAGE(PG8_SB(1, 1), b3 + hstepB, voffB); PG8_STAGE(PG8_SA(1, 0), a3, voffA);
;             PG8_WAIT_V(8); PG8_WAIT_L(0); PG8_BAR; PG8_MMA(1, 0, At, B0); PG8_MMA(1, 1, At, B1); PG8_BAR; PG8_SCHED;
;     ...
;         if constexpr (ALIGN_EPI) { if (wr == 0) PG8_BAR; }
	s_add_u32 s28, s26, 0x8000
	s_addc_u32 s29, s27, 0
	s_add_i32 s75, s75, s41
	v_lshl_add_u64 v[142:143], s[28:29], 0, v[134:135]
	s_mov_b32 m0, s75
	ds_read_b128 v[180:183], v146 offset:49152
	ds_read_b128 v[196:199], v146 offset:50176
	ds_read_b128 v[200:203], v146 offset:51200
	ds_read_b128 v[204:207], v146 offset:52224
	ds_read_b128 v[208:211], v146 offset:53248
	ds_read_b128 v[212:215], v146 offset:54272
	ds_read_b128 v[216:219], v146 offset:55296
	ds_read_b128 v[220:223], v146 offset:56320
	global_load_lds_dwordx4 v[142:143], off
	s_add_i32 m0, s75, 0x2000
	s_add_u32 s26, s26, 0xc000
	v_lshl_add_u64 v[142:143], s[28:29], 0, v[130:131]
	s_addc_u32 s27, s27, 0
	s_add_i32 s28, s80, s41
	global_load_lds_dwordx4 v[142:143], off
	v_lshl_add_u64 v[142:143], s[26:27], 0, v[134:135]
	s_mov_b32 m0, s28
	s_nop 0
	global_load_lds_dwordx4 v[142:143], off
	v_lshl_add_u64 v[142:143], s[26:27], 0, v[130:131]
	s_add_i32 m0, s28, 0x2000
	s_nop 0
	global_load_lds_dwordx4 v[142:143], off
	v_lshl_add_u64 v[142:143], s[24:25], 0, v[136:137]
	s_mov_b32 m0, s51
	s_nop 0
	global_load_lds_dwordx4 v[142:143], off
	v_lshl_add_u64 v[142:143], s[24:25], 0, v[132:133]
	s_mov_b32 m0, s53
	s_nop 0
	global_load_lds_dwordx4 v[142:143], off
	s_waitcnt vmcnt(8)
	s_waitcnt lgkmcnt(0)
	s_barrier
	s_setprio 1
	s_waitcnt lgkmcnt(0)
	v_mfma_f32_16x16x32_bf16 v[62:65], v[148:151], v[180:183], v[62:65]
	v_mfma_f32_16x16x32_bf16 v[54:57], v[156:159], v[180:183], v[54:57]
	v_mfma_f32_16x16x32_bf16 v[46:49], v[148:151], v[200:203], v[46:49]
	v_mfma_f32_16x16x32_bf16 v[38:41], v[156:159], v[200:203], v[38:41]
	v_mfma_f32_16x16x32_bf16 v[30:33], v[148:151], v[208:211], v[30:33]
	v_mfma_f32_16x16x32_bf16 v[22:25], v[156:159], v[208:211], v[22:25]
	v_mfma_f32_16x16x32_bf16 v[14:17], v[148:151], v[216:219], v[14:17]
	v_mfma_f32_16x16x32_bf16 v[6:9], v[156:159], v[216:219], v[6:9]
	v_mfma_f32_16x16x32_bf16 v[62:65], v[152:155], v[196:199], v[62:65]
	v_mfma_f32_16x16x32_bf16 v[54:57], v[160:163], v[196:199], v[54:57]
	v_mfma_f32_16x16x32_bf16 v[46:49], v[152:155], v[204:207], v[46:49]
	v_mfma_f32_16x16x32_bf16 v[38:41], v[160:163], v[204:207], v[38:41]
	v_mfma_f32_16x16x32_bf16 v[30:33], v[152:155], v[212:215], v[30:33]
	v_mfma_f32_16x16x32_bf16 v[22:25], v[160:163], v[212:215], v[22:25]
	v_mfma_f32_16x16x32_bf16 v[14:17], v[152:155], v[220:223], v[14:17]
	v_mfma_f32_16x16x32_bf16 v[6:9], v[160:163], v[220:223], v[6:9]
	s_setprio 0
	s_setprio 1
	v_mfma_f32_16x16x32_bf16 v[58:61], v[164:167], v[180:183], v[58:61]
	v_mfma_f32_16x16x32_bf16 v[50:53], v[172:175], v[180:183], v[50:53]
	v_mfma_f32_16x16x32_bf16 v[42:45], v[164:167], v[200:203], v[42:45]
	v_mfma_f32_16x16x32_bf16 v[34:37], v[172:175], v[200:203], v[34:37]
	v_mfma_f32_16x16x32_bf16 v[26:29], v[164:167], v[208:211], v[26:29]
	v_mfma_f32_16x16x32_bf16 v[18:21], v[172:175], v[208:211], v[18:21]
	v_mfma_f32_16x16x32_bf16 v[10:13], v[164:167], v[216:219], v[10:13]
	v_mfma_f32_16x16x32_bf16 v[2:5], v[172:175], v[216:219], v[2:5]
	v_mfma_f32_16x16x32_bf16 v[58:61], v[168:171], v[196:199], v[58:61]
	v_mfma_f32_16x16x32_bf16 v[50:53], v[176:179], v[196:199], v[50:53]
	v_mfma_f32_16x16x32_bf16 v[42:45], v[168:171], v[204:207], v[42:45]
	v_mfma_f32_16x16x32_bf16 v[34:37], v[176:179], v[204:207], v[34:37]
	v_mfma_f32_16x16x32_bf16 v[26:29], v[168:171], v[212:215], v[26:29]
	v_mfma_f32_16x16x32_bf16 v[18:21], v[176:179], v[212:215], v[18:21]
	v_mfma_f32_16x16x32_bf16 v[10:13], v[168:171], v[220:223], v[10:13]
	v_mfma_f32_16x16x32_bf16 v[2:5], v[176:179], v[220:223], v[2:5]
	s_setprio 0
	s_barrier
	s_add_i32 s81, s81, 2
	s_add_u32 s22, s22, 0x10000
	s_addc_u32 s23, s23, 0
	s_add_u32 s72, s72, 0x10000
	s_addc_u32 s73, s73, 0
	s_cmp_gt_u32 s81, 29
	s_cbranch_scc0 .LBB0_216
	s_and_b64 vcc, exec, s[10:11]
	s_cbranch_vccz .LBB0_219
	s_barrier

; #define PG8_STAGE(bufoff, gbase, voff) do { _Pragma("unroll") for (int _i = 0; _i < 2; ++_i) \
;         __builtin_amdgcn_global_load_lds((const unsigned*)((const char*)(gbase) + (voff)[_i]), (PG8_LAS unsigned*)(lds + (bufoff) + ldsw + _i * 8192), 16, 0, 0); } while (0)
; #define PG8_LDA(dst, b, h) do { _Pragma("unroll") for (int m = 0; m < 4; ++m) _Pragma("unroll") for (int k = 0; k < 2; ++k) dst[m][k] = *(const PG8_LAS bf16x8*)(lds + PG8_SA(b, h) + aoff + m * 2048 + k * 1024); } while (0)
; #define PG8_LDB(dst, b, h) do { _Pragma("unroll") for (int n = 0; n < 2; ++n) _Pragma("unroll") for (int k = 0; k < 2; ++k) dst[n][k] = *(const PG8_LAS bf16x8*)(lds + PG8_SB(b, h) + boff + n * 2048 + k * 1024); } while (0)
; #define PG8_WAIT_V(n) asm volatile("s_waitcnt vmcnt(" #n ")" ::: "memory")
; #define PG8_WAIT_L(n) asm volatile("s_waitcnt lgkmcnt(" #n ")" ::: "memory")
; #define PG8_BAR __builtin_amdgcn_s_barrier()
; template <class Epi, class Sched, bool ALIGN_EPI = false, bool SP2 = false, bool ABLK = false, bool BBLK = false>
; __device__ __forceinline__ void gemm_phase(PG8_LAS unsigned char* lds, const Gemm g, const Sched& S, const Epi& E) {
;     ...
;         const bool has_next = S.next(ui + 1, nxt);
;         const char* nA = has_next ? (const char*)g.A + (size_t)nxt.pm * tstepA : cA; const char* nB = has_next ? (const char*)g.Bt + (size_t)nxt.pn * tstepB : cB;
;         for (int t = 0; t < nt; t += 2) {
;             const bool last = (t == nt - 2);
;             const char* a1 = cA + (size_t)(t + 1) * kstepA;
;             const char* a2 = last ? nA : cA + (size_t)(t + 2) * kstepA; const char* b2 = last ? nB : cB + (size_t)(t + 2) * kstepB;
;             const char* a3 = a2 + kstepA; const char* b3 = b2 + kstepB;
;             if (last && has_next) S.a_ready(nxt);
;             if constexpr (SP2) {
;             PG8_LDB(B0, 0, 0); PG8_LDB(B1, 0, 1); PG8_SCHED; PG8_LDA(At, 0, 0); PG8_STAGE(PG8_SA(1, 1), a1 + hstepA, voffA);
;             PG8_WAIT_V(8); PG8_WAIT_L(0); PG8_BAR; PG8_MMA(0, 0, At, B0); PG8_MMA(0, 1, At, B1); PG8_BAR; PG8_SCHED;
;     ...
;         for (int a = 0; a < 2; ++a)
; #pragma unroll
;             for (int b = 0; b < 2; ++b)
; #pragma unroll
;                 for (int m = 0; m < 4; ++m)
; #pragma unroll
;                     for (int n = 0; n < 2; ++n) acc[a][b][m][n] = (f32x4){0.f, 0.f, 0.f, 0.f};
.LBB0_304:
	s_add_u32 s0, s0, 0xc000
	s_addc_u32 s1, s1, 0
	s_add_u32 s29, s34, 0x10000
	v_mov_b32_e32 v2, 0
	s_addc_u32 s31, s35, 0
	s_mov_b32 s33, -2
	s_add_u32 s8, s0, 0x4000
	s_addc_u32 s9, s1, 0
	s_cmpk_eq_i32 s33, 0x54
	s_cselect_b32 s36, s24, s8
	s_cselect_b32 s37, s25, s9
	s_cselect_b32 s34, s26, s29
	s_cselect_b32 s35, s27, s31
	s_add_u32 s8, s36, 0x8000
	s_addc_u32 s9, s37, 0
	s_add_i32 s40, 0, 0x10000
	s_add_i32 s44, 0, 0x14000
	v_add_u32_e32 v142, s40, v206
	v_add_u32_e32 v158, s44, v206
	ds_read_b128 v[130:133], v142
	v_pk_mov_b32 v[2:3], 0, 0
	v_pk_mov_b32 v[4:5], 0, 0
	v_pk_mov_b32 v[6:7], 0, 0
	v_pk_mov_b32 v[8:9], 0, 0
	ds_read_b128 v[134:137], v142 offset:1024
	v_pk_mov_b32 v[10:11], 0, 0
	v_pk_mov_b32 v[12:13], 0, 0
	v_pk_mov_b32 v[14:15], 0, 0
	v_pk_mov_b32 v[16:17], 0, 0
	ds_read_b128 v[138:141], v142 offset:2048
	v_pk_mov_b32 v[18:19], 0, 0
	v_pk_mov_b32 v[20:21], 0, 0
	v_pk_mov_b32 v[22:23], 0, 0
	v_pk_mov_b32 v[24:25], 0, 0
	ds_read_b128 v[142:145], v142 offset:3072
	v_pk_mov_b32 v[26:27], 0, 0
	v_pk_mov_b32 v[28:29], 0, 0
	v_pk_mov_b32 v[30:31], 0, 0
	v_pk_mov_b32 v[32:33], 0, 0
	ds_read_b128 v[146:149], v158
	v_pk_mov_b32 v[34:35], 0, 0
	v_pk_mov_b32 v[36:37], 0, 0
	v_pk_mov_b32 v[38:39], 0, 0
	v_pk_mov_b32 v[40:41], 0, 0
	ds_read_b128 v[150:153], v158 offset:1024
	v_pk_mov_b32 v[42:43], 0, 0
	v_pk_mov_b32 v[44:45], 0, 0
	v_pk_mov_b32 v[46:47], 0, 0
	v_pk_mov_b32 v[48:49], 0, 0
	ds_read_b128 v[154:157], v158 offset:2048
	v_pk_mov_b32 v[50:51], 0, 0
	v_pk_mov_b32 v[52:53], 0, 0
	v_pk_mov_b32 v[54:55], 0, 0
	v_pk_mov_b32 v[56:57], 0, 0
	ds_read_b128 v[158:161], v158 offset:3072
	v_pk_mov_b32 v[58:59], 0, 0
	v_pk_mov_b32 v[60:61], 0, 0
	v_pk_mov_b32 v[62:63], 0, 0
	v_pk_mov_b32 v[64:65], 0, 0
	v_lshl_add_u64 v[202:203], s[0:1], 0, v[184:185]
	s_add_i32 m0, s3, 0xc000
	ds_read_b128 v[162:165], v207
	v_pk_mov_b32 v[66:67], 0, 0
	v_pk_mov_b32 v[68:69], 0, 0
	v_pk_mov_b32 v[70:71], 0, 0
	v_pk_mov_b32 v[72:73], 0, 0
	ds_read_b128 v[166:169], v207 offset:1024
	v_pk_mov_b32 v[74:75], 0, 0
	v_pk_mov_b32 v[76:77], 0, 0
	v_pk_mov_b32 v[78:79], 0, 0
	v_pk_mov_b32 v[80:81], 0, 0
	ds_read_b128 v[170:173], v207 offset:2048
	v_pk_mov_b32 v[82:83], 0, 0
	v_pk_mov_b32 v[84:85], 0, 0
	v_pk_mov_b32 v[86:87], 0, 0
	v_pk_mov_b32 v[88:89], 0, 0
	ds_read_b128 v[174:177], v207 offset:3072
	v_pk_mov_b32 v[90:91], 0, 0
	v_pk_mov_b32 v[92:93], 0, 0
	v_pk_mov_b32 v[94:95], 0, 0
	v_pk_mov_b32 v[96:97], 0, 0
	ds_read_b128 v[198:201], v207 offset:4096
	v_pk_mov_b32 v[98:99], 0, 0
	v_pk_mov_b32 v[100:101], 0, 0
	v_pk_mov_b32 v[102:103], 0, 0
	v_pk_mov_b32 v[104:105], 0, 0
	ds_read_b128 v[208:211], v207 offset:5120
	v_pk_mov_b32 v[106:107], 0, 0
	v_pk_mov_b32 v[108:109], 0, 0
	v_pk_mov_b32 v[110:111], 0, 0
	v_pk_mov_b32 v[112:113], 0, 0
	ds_read_b128 v[212:215], v207 offset:6144
	v_pk_mov_b32 v[114:115], 0, 0
	v_pk_mov_b32 v[116:117], 0, 0
	v_pk_mov_b32 v[118:119], 0, 0
	v_pk_mov_b32 v[120:121], 0, 0
	ds_read_b128 v[216:219], v207 offset:7168
	v_pk_mov_b32 v[122:123], 0, 0
	v_pk_mov_b32 v[124:125], 0, 0
	v_pk_mov_b32 v[126:127], 0, 0
	v_pk_mov_b32 v[128:129], 0, 0
	global_load_lds_dwordx4 v[202:203], off
	v_lshl_add_u64 v[202:203], s[0:1], 0, v[196:197]
	s_add_i32 m0, s3, 0xe000
	s_nop 0
	global_load_lds_dwordx4 v[202:203], off
	s_waitcnt vmcnt(8)
	s_waitcnt lgkmcnt(0)
	s_barrier
	s_branch .Lpeel_305

; #define PG8_STAGE(bufoff, gbase, voff) do { _Pragma("unroll") for (int _i = 0; _i < 2; ++_i) \
;         __builtin_amdgcn_global_load_lds((const unsigned*)((const char*)(gbase) + (voff)[_i]), (PG8_LAS unsigned*)(lds + (bufoff) + ldsw + _i * 8192), 16, 0, 0); } while (0)
; #define PG8_LDA(dst, b, h) do { _Pragma("unroll") for (int m = 0; m < 4; ++m) _Pragma("unroll") for (int k = 0; k < 2; ++k) dst[m][k] = *(const PG8_LAS bf16x8*)(lds + PG8_SA(b, h) + aoff + m * 2048 + k * 1024); } while (0)
; #define PG8_MMA(ai, bj, At, Bt) do { __builtin_amdgcn_s_setprio(1); _Pragma("unroll") for (int m = 0; m < 4; ++m) _Pragma("unroll") for (int n = 0; n < 2; ++n) _Pragma("unroll") for (int k = 0; k < 2; ++k) \
;         acc[ai][bj][m][n] = __builtin_amdgcn_mfma_f32_16x16x32_bf16(Bt[n][k], At[m][k], acc[ai][bj][m][n], 0, 0, 0); __builtin_amdgcn_s_setprio(0); } while (0)
; #define PG8_WAIT_V(n) asm volatile("s_waitcnt vmcnt(" #n ")" ::: "memory")
; #define PG8_WAIT_L(n) asm volatile("s_waitcnt lgkmcnt(" #n ")" ::: "memory")
; #define PG8_BAR __builtin_amdgcn_s_barrier()
; #define PG8_SCHED __builtin_amdgcn_sched_barrier(0)
; template <class Epi, class Sched, bool ALIGN_EPI = false, bool SP2 = false, bool ABLK = false, bool BBLK = false>
; __device__ __forceinline__ void gemm_phase(PG8_LAS unsigned char* lds, const Gemm g, const Sched& S, const Epi& E) {
;     ...
;             PG8_WAIT_V(8); PG8_WAIT_L(0); PG8_BAR; PG8_MMA(0, 0, At, B0); PG8_MMA(0, 1, At, B1); PG8_BAR; PG8_SCHED;
;             PG8_LDA(At, 0, 1); PG8_STAGE(PG8_SB(0, 0), b2, voffB); PG8_STAGE(PG8_SB(0, 1), b2 + hstepB, voffB); PG8_STAGE(PG8_SA(0, 0), a2, voffA);
;             PG8_WAIT_V(8); PG8_WAIT_L(0); PG8_BAR; PG8_MMA(1, 0, At, B0); PG8_MMA(1, 1, At, B1); PG8_BAR; PG8_SCHED;
.Lpeel_305:
	s_setprio 1
	s_waitcnt lgkmcnt(0)
	v_mfma_f32_16x16x32_bf16 v[30:33], v[130:133], v[162:165], v[30:33]
	v_mfma_f32_16x16x32_bf16 v[22:25], v[138:141], v[162:165], v[22:25]
	v_mfma_f32_16x16x32_bf16 v[10:13], v[130:133], v[170:173], v[10:13]
	v_mfma_f32_16x16x32_bf16 v[6:9], v[138:141], v[170:173], v[6:9]
	v_mfma_f32_16x16x32_bf16 v[50:53], v[130:133], v[198:201], v[50:53]
	v_mfma_f32_16x16x32_bf16 v[54:57], v[138:141], v[198:201], v[54:57]
	v_mfma_f32_16x16x32_bf16 v[74:77], v[130:133], v[212:215], v[74:77]
	v_mfma_f32_16x16x32_bf16 v[78:81], v[138:141], v[212:215], v[78:81]
	v_mfma_f32_16x16x32_bf16 v[30:33], v[134:137], v[166:169], v[30:33]
	v_mfma_f32_16x16x32_bf16 v[22:25], v[142:145], v[166:169], v[22:25]
	v_mfma_f32_16x16x32_bf16 v[10:13], v[134:137], v[174:177], v[10:13]
	v_mfma_f32_16x16x32_bf16 v[6:9], v[142:145], v[174:177], v[6:9]
	v_mfma_f32_16x16x32_bf16 v[50:53], v[134:137], v[208:211], v[50:53]
	v_mfma_f32_16x16x32_bf16 v[54:57], v[142:145], v[208:211], v[54:57]
	v_mfma_f32_16x16x32_bf16 v[74:77], v[134:137], v[216:219], v[74:77]
	v_mfma_f32_16x16x32_bf16 v[78:81], v[142:145], v[216:219], v[78:81]
	s_setprio 0
	s_setprio 1
	v_mfma_f32_16x16x32_bf16 v[26:29], v[146:149], v[162:165], v[26:29]
	v_mfma_f32_16x16x32_bf16 v[18:21], v[154:157], v[162:165], v[18:21]
	v_mfma_f32_16x16x32_bf16 v[42:45], v[146:149], v[170:173], v[42:45]
	v_mfma_f32_16x16x32_bf16 v[46:49], v[154:157], v[170:173], v[46:49]
	v_mfma_f32_16x16x32_bf16 v[66:69], v[146:149], v[198:201], v[66:69]
	v_mfma_f32_16x16x32_bf16 v[70:73], v[154:157], v[198:201], v[70:73]
	v_mfma_f32_16x16x32_bf16 v[82:85], v[146:149], v[212:215], v[82:85]
	v_mfma_f32_16x16x32_bf16 v[86:89], v[154:157], v[212:215], v[86:89]
	v_mfma_f32_16x16x32_bf16 v[26:29], v[150:153], v[166:169], v[26:29]
	v_mfma_f32_16x16x32_bf16 v[18:21], v[158:161], v[166:169], v[18:21]
	v_mfma_f32_16x16x32_bf16 v[42:45], v[150:153], v[174:177], v[42:45]
	v_mfma_f32_16x16x32_bf16 v[46:49], v[158:161], v[174:177], v[46:49]
	v_mfma_f32_16x16x32_bf16 v[66:69], v[150:153], v[208:211], v[66:69]
	v_mfma_f32_16x16x32_bf16 v[70:73], v[158:161], v[208:211], v[70:73]
	v_mfma_f32_16x16x32_bf16 v[82:85], v[150:153], v[216:219], v[82:85]
	v_mfma_f32_16x16x32_bf16 v[86:89], v[158:161], v[216:219], v[86:89]
	s_setprio 0
	s_barrier
	s_add_i32 s40, s40, s2
	v_lshl_add_u64 v[202:203], s[34:35], 0, v[186:187]
	s_mov_b32 m0, s40
	ds_read_b128 v[162:165], v207 offset:16384
	ds_read_b128 v[166:169], v207 offset:17408
	ds_read_b128 v[170:173], v207 offset:18432
	ds_read_b128 v[174:177], v207 offset:19456
	ds_read_b128 v[198:201], v207 offset:20480
	ds_read_b128 v[208:211], v207 offset:21504
	ds_read_b128 v[212:215], v207 offset:22528
	ds_read_b128 v[216:219], v207 offset:23552
	global_load_lds_dwordx4 v[202:203], off
	s_add_i32 m0, s40, 0x2000
	s_add_u32 s40, s34, 0x4000
	v_lshl_add_u64 v[202:203], s[34:35], 0, v[182:183]
	s_addc_u32 s41, s35, 0
	s_add_i32 s44, s44, s2
	global_load_lds_dwordx4 v[202:203], off
	v_lshl_add_u64 v[202:203], s[40:41], 0, v[186:187]
	s_mov_b32 m0, s44
	s_nop 0
	global_load_lds_dwordx4 v[202:203], off
	v_lshl_add_u64 v[202:203], s[40:41], 0, v[182:183]
	s_add_i32 m0, s44, 0x2000
	s_nop 0
	global_load_lds_dwordx4 v[202:203], off
	v_lshl_add_u64 v[202:203], s[36:37], 0, v[178:179]
	s_mov_b32 m0, s3
	s_nop 0
	global_load_lds_dwordx4 v[202:203], off
	v_lshl_add_u64 v[202:203], s[36:37], 0, v[180:181]
	s_mov_b32 m0, s42
	s_nop 0
	global_load_lds_dwordx4 v[202:203], off
	s_waitcnt vmcnt(8)
	s_waitcnt lgkmcnt(0)
	s_barrier
	s_setprio 1
	s_waitcnt lgkmcnt(0)
	v_mfma_f32_16x16x32_bf16 v[106:109], v[130:133], v[162:165], v[106:109]
	v_mfma_f32_16x16x32_bf16 v[110:113], v[138:141], v[162:165], v[110:113]
	v_mfma_f32_16x16x32_bf16 v[122:125], v[130:133], v[170:173], v[122:125]
	v_mfma_f32_16x16x32_bf16 v[126:129], v[138:141], v[170:173], v[126:129]
	v_mfma_f32_16x16x32_bf16 v[94:97], v[130:133], v[198:201], v[94:97]
	v_mfma_f32_16x16x32_bf16 v[90:93], v[138:141], v[198:201], v[90:93]
	v_mfma_f32_16x16x32_bf16 v[38:41], v[130:133], v[212:215], v[38:41]
	v_mfma_f32_16x16x32_bf16 v[34:37], v[138:141], v[212:215], v[34:37]
	v_mfma_f32_16x16x32_bf16 v[106:109], v[134:137], v[166:169], v[106:109]
	v_mfma_f32_16x16x32_bf16 v[110:113], v[142:145], v[166:169], v[110:113]
	v_mfma_f32_16x16x32_bf16 v[122:125], v[134:137], v[174:177], v[122:125]
	v_mfma_f32_16x16x32_bf16 v[126:129], v[142:145], v[174:177], v[126:129]
	v_mfma_f32_16x16x32_bf16 v[94:97], v[134:137], v[208:211], v[94:97]
	v_mfma_f32_16x16x32_bf16 v[90:93], v[142:145], v[208:211], v[90:93]
	v_mfma_f32_16x16x32_bf16 v[38:41], v[134:137], v[216:219], v[38:41]
	v_mfma_f32_16x16x32_bf16 v[34:37], v[142:145], v[216:219], v[34:37]
	s_setprio 0
	s_setprio 1
	v_mfma_f32_16x16x32_bf16 v[114:117], v[146:149], v[162:165], v[114:117]
	v_mfma_f32_16x16x32_bf16 v[118:121], v[154:157], v[162:165], v[118:121]
	v_mfma_f32_16x16x32_bf16 v[102:105], v[146:149], v[170:173], v[102:105]
	v_mfma_f32_16x16x32_bf16 v[98:101], v[154:157], v[170:173], v[98:101]
	v_mfma_f32_16x16x32_bf16 v[62:65], v[146:149], v[198:201], v[62:65]
	v_mfma_f32_16x16x32_bf16 v[58:61], v[154:157], v[198:201], v[58:61]
	v_mfma_f32_16x16x32_bf16 v[14:17], v[146:149], v[212:215], v[14:17]
	v_mfma_f32_16x16x32_bf16 v[2:5], v[154:157], v[212:215], v[2:5]
	v_mfma_f32_16x16x32_bf16 v[114:117], v[150:153], v[166:169], v[114:117]
	v_mfma_f32_16x16x32_bf16 v[118:121], v[158:161], v[166:169], v[118:121]
	v_mfma_f32_16x16x32_bf16 v[102:105], v[150:153], v[174:177], v[102:105]
	v_mfma_f32_16x16x32_bf16 v[98:101], v[158:161], v[174:177], v[98:101]
	v_mfma_f32_16x16x32_bf16 v[62:65], v[150:153], v[208:211], v[62:65]
	v_mfma_f32_16x16x32_bf16 v[58:61], v[158:161], v[208:211], v[58:61]
	v_mfma_f32_16x16x32_bf16 v[14:17], v[150:153], v[216:219], v[14:17]
	v_mfma_f32_16x16x32_bf16 v[2:5], v[158:161], v[216:219], v[2:5]
	s_setprio 0
	s_barrier
; #define PG8_STAGE(bufoff, gbase, voff) do { _Pragma("unroll") for (int _i = 0; _i < 2; ++_i) \
;         __builtin_amdgcn_global_load_lds((const unsigned*)((const char*)(gbase) + (voff)[_i]), (PG8_LAS unsigned*)(lds + (bufoff) + ldsw + _i * 8192), 16, 0, 0); } while (0)
; #define PG8_LDA(dst, b, h) do { _Pragma("unroll") for (int m = 0; m < 4; ++m) _Pragma("unroll") for (int k = 0; k < 2; ++k) dst[m][k] = *(const PG8_LAS bf16x8*)(lds + PG8_SA(b, h) + aoff + m * 2048 + k * 1024); } while (0)
; #define PG8_LDB(dst, b, h) do { _Pragma("unroll") for (int n = 0; n < 2; ++n) _Pragma("unroll") for (int k = 0; k < 2; ++k) dst[n][k] = *(const PG8_LAS bf16x8*)(lds + PG8_SB(b, h) + boff + n * 2048 + k * 1024); } while (0)
; #define PG8_MMA(ai, bj, At, Bt) do { __builtin_amdgcn_s_setprio(1); _Pragma("unroll") for (int m = 0; m < 4; ++m) _Pragma("unroll") for (int n = 0; n < 2; ++n) _Pragma("unroll") for (int k = 0; k < 2; ++k) \
;         acc[ai][bj][m][n] = __builtin_amdgcn_mfma_f32_16x16x32_bf16(Bt[n][k], At[m][k], acc[ai][bj][m][n], 0, 0, 0); __builtin_amdgcn_s_setprio(0); } while (0)
; #define PG8_WAIT_V(n) asm volatile("s_waitcnt vmcnt(" #n ")" ::: "memory")
; #define PG8_WAIT_L(n) asm volatile("s_waitcnt lgkmcnt(" #n ")" ::: "memory")
; #define PG8_BAR __builtin_amdgcn_s_barrier()
; #define PG8_SCHED __builtin_amdgcn_sched_barrier(0)
; template <class Epi, class Sched, bool ALIGN_EPI = false, bool SP2 = false, bool ABLK = false, bool BBLK = false>
; __device__ __forceinline__ void gemm_phase(PG8_LAS unsigned char* lds, const Gemm g, const Sched& S, const Epi& E) {
;     ...
;             PG8_LDB(B0, 1, 0); PG8_LDB(B1, 1, 1); PG8_SCHED; PG8_LDA(At, 1, 0); PG8_STAGE(PG8_SA(0, 1), a2 + hstepA, voffA);
;             PG8_WAIT_V(8); PG8_WAIT_L(0); PG8_BAR; PG8_MMA(0, 0, At, B0); PG8_MMA(0, 1, At, B1); PG8_BAR; PG8_SCHED;
	s_add_i32 s40, 0, 0x18000
	s_add_i32 s41, 0, 0x1c000
	v_add_u32_e32 v142, s40, v206
	v_add_u32_e32 v158, s41, v206
	ds_read_b128 v[130:133], v142
	ds_read_b128 v[134:137], v142 offset:1024
	ds_read_b128 v[138:141], v142 offset:2048
	ds_read_b128 v[142:145], v142 offset:3072
	ds_read_b128 v[146:149], v158
	ds_read_b128 v[150:153], v158 offset:1024
	ds_read_b128 v[154:157], v158 offset:2048
	ds_read_b128 v[158:161], v158 offset:3072
	s_add_u32 s36, s36, 0x4000
	s_addc_u32 s37, s37, 0
	s_mov_b32 m0, s43
	v_lshl_add_u64 v[202:203], s[36:37], 0, v[178:179]
	ds_read_b128 v[162:165], v207 offset:32768
	ds_read_b128 v[166:169], v207 offset:33792
	ds_read_b128 v[170:173], v207 offset:34816
	ds_read_b128 v[174:177], v207 offset:35840
	ds_read_b128 v[198:201], v207 offset:36864
	ds_read_b128 v[208:211], v207 offset:37888
	ds_read_b128 v[212:215], v207 offset:38912
	ds_read_b128 v[216:219], v207 offset:39936
	global_load_lds_dwordx4 v[202:203], off
	v_lshl_add_u64 v[202:203], s[36:37], 0, v[180:181]
	s_mov_b32 m0, s53
	s_nop 0
	global_load_lds_dwordx4 v[202:203], off
	s_waitcnt vmcnt(8)
	s_waitcnt lgkmcnt(0)
	s_barrier
	s_setprio 1
	s_waitcnt lgkmcnt(0)
	v_mfma_f32_16x16x32_bf16 v[30:33], v[130:133], v[162:165], v[30:33]
	v_mfma_f32_16x16x32_bf16 v[22:25], v[138:141], v[162:165], v[22:25]
	v_mfma_f32_16x16x32_bf16 v[10:13], v[130:133], v[170:173], v[10:13]
	v_mfma_f32_16x16x32_bf16 v[6:9], v[138:141], v[170:173], v[6:9]
	v_mfma_f32_16x16x32_bf16 v[50:53], v[130:133], v[198:201], v[50:53]
	v_mfma_f32_16x16x32_bf16 v[54:57], v[138:141], v[198:201], v[54:57]
	v_mfma_f32_16x16x32_bf16 v[74:77], v[130:133], v[212:215], v[74:77]
	v_mfma_f32_16x16x32_bf16 v[78:81], v[138:141], v[212:215], v[78:81]
	v_mfma_f32_16x16x32_bf16 v[30:33], v[134:137], v[166:169], v[30:33]
	v_mfma_f32_16x16x32_bf16 v[22:25], v[142:145], v[166:169], v[22:25]
	v_mfma_f32_16x16x32_bf16 v[10:13], v[134:137], v[174:177], v[10:13]
	v_mfma_f32_16x16x32_bf16 v[6:9], v[142:145], v[174:177], v[6:9]
	v_mfma_f32_16x16x32_bf16 v[50:53], v[134:137], v[208:211], v[50:53]
	v_mfma_f32_16x16x32_bf16 v[54:57], v[142:145], v[208:211], v[54:57]
	v_mfma_f32_16x16x32_bf16 v[74:77], v[134:137], v[216:219], v[74:77]
	v_mfma_f32_16x16x32_bf16 v[78:81], v[142:145], v[216:219], v[78:81]
	s_setprio 0
	s_setprio 1
	v_mfma_f32_16x16x32_bf16 v[26:29], v[146:149], v[162:165], v[26:29]
	v_mfma_f32_16x16x32_bf16 v[18:21], v[154:157], v[162:165], v[18:21]
	v_mfma_f32_16x16x32_bf16 v[42:45], v[146:149], v[170:173], v[42:45]
	v_mfma_f32_16x16x32_bf16 v[46:49], v[154:157], v[170:173], v[46:49]
	v_mfma_f32_16x16x32_bf16 v[66:69], v[146:149], v[198:201], v[66:69]
	v_mfma_f32_16x16x32_bf16 v[70:73], v[154:157], v[198:201], v[70:73]
	v_mfma_f32_16x16x32_bf16 v[82:85], v[146:149], v[212:215], v[82:85]
	v_mfma_f32_16x16x32_bf16 v[86:89], v[154:157], v[212:215], v[86:89]
	v_mfma_f32_16x16x32_bf16 v[26:29], v[150:153], v[166:169], v[26:29]
	v_mfma_f32_16x16x32_bf16 v[18:21], v[158:161], v[166:169], v[18:21]
	v_mfma_f32_16x16x32_bf16 v[42:45], v[150:153], v[174:177], v[42:45]
	v_mfma_f32_16x16x32_bf16 v[46:49], v[158:161], v[174:177], v[46:49]
	v_mfma_f32_16x16x32_bf16 v[66:69], v[150:153], v[208:211], v[66:69]
	v_mfma_f32_16x16x32_bf16 v[70:73], v[158:161], v[208:211], v[70:73]
	v_mfma_f32_16x16x32_bf16 v[82:85], v[150:153], v[216:219], v[82:85]
	v_mfma_f32_16x16x32_bf16 v[86:89], v[158:161], v[216:219], v[86:89]
	s_setprio 0
	s_barrier
; #define PG8_STAGE(bufoff, gbase, voff) do { _Pragma("unroll") for (int _i = 0; _i < 2; ++_i) \
;         __builtin_amdgcn_global_load_lds((const unsigned*)((const char*)(gbase) + (voff)[_i]), (PG8_LAS unsigned*)(lds + (bufoff) + ldsw + _i * 8192), 16, 0, 0); } while (0)
; #define PG8_LDA(dst, b, h) do { _Pragma("unroll") for (int m = 0; m < 4; ++m) _Pragma("unroll") for (int k = 0; k < 2; ++k) dst[m][k] = *(const PG8_LAS bf16x8*)(lds + PG8_SA(b, h) + aoff + m * 2048 + k * 1024); } while (0)
; #define PG8_MMA(ai, bj, At, Bt) do { __builtin_amdgcn_s_setprio(1); _Pragma("unroll") for (int m = 0; m < 4; ++m) _Pragma("unroll") for (int n = 0; n < 2; ++n) _Pragma("unroll") for (int k = 0; k < 2; ++k) \
;         acc[ai][bj][m][n] = __builtin_amdgcn_mfma_f32_16x16x32_bf16(Bt[n][k], At[m][k], acc[ai][bj][m][n], 0, 0, 0); __builtin_amdgcn_s_setprio(0); } while (0)
; #define PG8_WAIT_V(n) asm volatile("s_waitcnt vmcnt(" #n ")" ::: "memory")
; #define PG8_WAIT_L(n) asm volatile("s_waitcnt lgkmcnt(" #n ")" ::: "memory")
; #define PG8_BAR __builtin_amdgcn_s_barrier()
; #define PG8_SCHED __builtin_amdgcn_sched_barrier(0)
; template <class Epi, class Sched, bool ALIGN_EPI = false, bool SP2 = false, bool ABLK = false, bool BBLK = false>
; __device__ __forceinline__ void gemm_phase(PG8_LAS unsigned char* lds, const Gemm g, const Sched& S, const Epi& E) {
;     ...
;             PG8_LDA(At, 1, 1); PG8_STAGE(PG8_SB(1, 0), b3, voffB); PG8_STAGE(PG8_SB(1, 1), b3 + hstepB, voffB); PG8_STAGE(PG8_SA(1, 0), a3, voffA);
;             PG8_WAIT_V(8); PG8_WAIT_L(0); PG8_BAR; PG8_MMA(1, 0, At, B0); PG8_MMA(1, 1, At, B1); PG8_BAR; PG8_SCHED;
;     ...
;         if constexpr (ALIGN_EPI) { if (wr == 0) PG8_BAR; }
	s_add_u32 s36, s34, 0x8000
	s_addc_u32 s37, s35, 0
	s_add_i32 s40, s40, s2
	v_lshl_add_u64 v[202:203], s[36:37], 0, v[186:187]
	s_mov_b32 m0, s40
	ds_read_b128 v[162:165], v207 offset:49152
	ds_read_b128 v[166:169], v207 offset:50176
	ds_read_b128 v[170:173], v207 offset:51200
	ds_read_b128 v[174:177], v207 offset:52224
	ds_read_b128 v[198:201], v207 offset:53248
	ds_read_b128 v[208:211], v207 offset:54272
	ds_read_b128 v[212:215], v207 offset:55296
	ds_read_b128 v[216:219], v207 offset:56320
	global_load_lds_dwordx4 v[202:203], off
	s_add_i32 m0, s40, 0x2000
	s_add_u32 s34, s34, 0xc000
	v_lshl_add_u64 v[202:203], s[36:37], 0, v[182:183]
	s_addc_u32 s35, s35, 0
	s_add_i32 s36, s41, s2
	global_load_lds_dwordx4 v[202:203], off
	v_lshl_add_u64 v[202:203], s[34:35], 0, v[186:187]
	s_mov_b32 m0, s36
	s_nop 0
	global_load_lds_dwordx4 v[202:203], off
	v_lshl_add_u64 v[202:203], s[34:35], 0, v[182:183]
	s_add_i32 m0, s36, 0x2000
	s_nop 0
	global_load_lds_dwordx4 v[202:203], off
	v_lshl_add_u64 v[202:203], s[8:9], 0, v[178:179]
	s_mov_b32 m0, s92
	s_nop 0
	global_load_lds_dwordx4 v[202:203], off
	v_lshl_add_u64 v[202:203], s[8:9], 0, v[180:181]
	s_mov_b32 m0, s93
	s_nop 0
	global_load_lds_dwordx4 v[202:203], off
	s_waitcnt vmcnt(8)
	s_waitcnt lgkmcnt(0)
	s_barrier
	s_setprio 1
	s_waitcnt lgkmcnt(0)
	v_mfma_f32_16x16x32_bf16 v[106:109], v[130:133], v[162:165], v[106:109]
	v_mfma_f32_16x16x32_bf16 v[110:113], v[138:141], v[162:165], v[110:113]
	v_mfma_f32_16x16x32_bf16 v[122:125], v[130:133], v[170:173], v[122:125]
	v_mfma_f32_16x16x32_bf16 v[126:129], v[138:141], v[170:173], v[126:129]
	v_mfma_f32_16x16x32_bf16 v[94:97], v[130:133], v[198:201], v[94:97]
	v_mfma_f32_16x16x32_bf16 v[90:93], v[138:141], v[198:201], v[90:93]
	v_mfma_f32_16x16x32_bf16 v[38:41], v[130:133], v[212:215], v[38:41]
	v_mfma_f32_16x16x32_bf16 v[34:37], v[138:141], v[212:215], v[34:37]
	v_mfma_f32_16x16x32_bf16 v[106:109], v[134:137], v[166:169], v[106:109]
	v_mfma_f32_16x16x32_bf16 v[110:113], v[142:145], v[166:169], v[110:113]
	v_mfma_f32_16x16x32_bf16 v[122:125], v[134:137], v[174:177], v[122:125]
	v_mfma_f32_16x16x32_bf16 v[126:129], v[142:145], v[174:177], v[126:129]
	v_mfma_f32_16x16x32_bf16 v[94:97], v[134:137], v[208:211], v[94:97]
	v_mfma_f32_16x16x32_bf16 v[90:93], v[142:145], v[208:211], v[90:93]
	v_mfma_f32_16x16x32_bf16 v[38:41], v[134:137], v[216:219], v[38:41]
	v_mfma_f32_16x16x32_bf16 v[34:37], v[142:145], v[216:219], v[34:37]
	s_setprio 0
	s_setprio 1
	v_mfma_f32_16x16x32_bf16 v[114:117], v[146:149], v[162:165], v[114:117]
	v_mfma_f32_16x16x32_bf16 v[118:121], v[154:157], v[162:165], v[118:121]
	v_mfma_f32_16x16x32_bf16 v[102:105], v[146:149], v[170:173], v[102:105]
	v_mfma_f32_16x16x32_bf16 v[98:101], v[154:157], v[170:173], v[98:101]
	v_mfma_f32_16x16x32_bf16 v[62:65], v[146:149], v[198:201], v[62:65]
	v_mfma_f32_16x16x32_bf16 v[58:61], v[154:157], v[198:201], v[58:61]
	v_mfma_f32_16x16x32_bf16 v[14:17], v[146:149], v[212:215], v[14:17]
	v_mfma_f32_16x16x32_bf16 v[2:5], v[154:157], v[212:215], v[2:5]
	v_mfma_f32_16x16x32_bf16 v[114:117], v[150:153], v[166:169], v[114:117]
	v_mfma_f32_16x16x32_bf16 v[118:121], v[158:161], v[166:169], v[118:121]
	v_mfma_f32_16x16x32_bf16 v[102:105], v[150:153], v[174:177], v[102:105]
	v_mfma_f32_16x16x32_bf16 v[98:101], v[158:161], v[174:177], v[98:101]
	v_mfma_f32_16x16x32_bf16 v[62:65], v[150:153], v[208:211], v[62:65]
	v_mfma_f32_16x16x32_bf16 v[58:61], v[158:161], v[208:211], v[58:61]
	v_mfma_f32_16x16x32_bf16 v[14:17], v[150:153], v[216:219], v[14:17]
	v_mfma_f32_16x16x32_bf16 v[2:5], v[158:161], v[216:219], v[2:5]
	s_setprio 0
	s_barrier
	s_add_i32 s33, s33, 2
	s_add_u32 s0, s0, 0x10000
	s_addc_u32 s1, s1, 0
	s_add_u32 s29, s29, 0x10000
	s_addc_u32 s31, s31, 0
	s_cmpk_gt_u32 s33, 0x55
	s_cbranch_scc0 .LBB0_305
	s_and_b64 vcc, exec, s[18:19]
	s_cbranch_vccz .LBB0_308
	s_barrier

; #define PG8_STAGE(bufoff, gbase, voff) do { _Pragma("unroll") for (int _i = 0; _i < 2; ++_i) \
;         __builtin_amdgcn_global_load_lds((const unsigned*)((const char*)(gbase) + (voff)[_i]), (PG8_LAS unsigned*)(lds + (bufoff) + ldsw + _i * 8192), 16, 0, 0); } while (0)
; #define PG8_LDA(dst, b, h) do { _Pragma("unroll") for (int m = 0; m < 4; ++m) _Pragma("unroll") for (int k = 0; k < 2; ++k) dst[m][k] = *(const PG8_LAS bf16x8*)(lds + PG8_SA(b, h) + aoff + m * 2048 + k * 1024); } while (0)
; #define PG8_LDB(dst, b, h) do { _Pragma("unroll") for (int n = 0; n < 2; ++n) _Pragma("unroll") for (int k = 0; k < 2; ++k) dst[n][k] = *(const PG8_LAS bf16x8*)(lds + PG8_SB(b, h) + boff + n * 2048 + k * 1024); } while (0)
; #define PG8_WAIT_V(n) asm volatile("s_waitcnt vmcnt(" #n ")" ::: "memory")
; #define PG8_WAIT_L(n) asm volatile("s_waitcnt lgkmcnt(" #n ")" ::: "memory")
; #define PG8_BAR __builtin_amdgcn_s_barrier()
; template <class Epi, class Sched, bool ALIGN_EPI = false, bool SP2 = false, bool ABLK = false, bool BBLK = false>
; __device__ __forceinline__ void gemm_phase(PG8_LAS unsigned char* lds, const Gemm g, const Sched& S, const Epi& E) {
;     ...
;         const bool has_next = S.next(ui + 1, nxt);
;         const char* nA = has_next ? (const char*)g.A + (size_t)nxt.pm * tstepA : cA; const char* nB = has_next ? (const char*)g.Bt + (size_t)nxt.pn * tstepB : cB;
;         for (int t = 0; t < nt; t += 2) {
;             const bool last = (t == nt - 2);
;             const char* a1 = cA + (size_t)(t + 1) * kstepA;
;             const char* a2 = last ? nA : cA + (size_t)(t + 2) * kstepA; const char* b2 = last ? nB : cB + (size_t)(t + 2) * kstepB;
;             const char* a3 = a2 + kstepA; const char* b3 = b2 + kstepB;
;             if (last && has_next) S.a_ready(nxt);
;             if constexpr (SP2) {
;             PG8_LDB(B0, 0, 0); PG8_LDB(B1, 0, 1); PG8_SCHED; PG8_LDA(At, 0, 0); PG8_STAGE(PG8_SA(1, 1), a1 + hstepA, voffA);
;             PG8_WAIT_V(8); PG8_WAIT_L(0); PG8_BAR; PG8_MMA(0, 0, At, B0); PG8_MMA(0, 1, At, B1); PG8_BAR; PG8_SCHED;
;     ...
;         for (int a = 0; a < 2; ++a)
; #pragma unroll
;             for (int b = 0; b < 2; ++b)
; #pragma unroll
;                 for (int m = 0; m < 4; ++m)
; #pragma unroll
;                     for (int n = 0; n < 2; ++n) acc[a][b][m][n] = (f32x4){0.f, 0.f, 0.f, 0.f};
.LBB0_366:
	s_add_u32 s0, s0, 0xc000
	s_addc_u32 s1, s1, 0
	s_add_u32 s29, s34, 0x10000
	v_mov_b32_e32 v66, 0
	s_addc_u32 s31, s35, 0
	s_mov_b32 s33, -2
	s_add_u32 s8, s0, 0x4000
	s_addc_u32 s9, s1, 0
	s_cmpk_eq_i32 s33, 0x54
	s_cselect_b32 s36, s24, s8
	s_cselect_b32 s37, s25, s9
	s_cselect_b32 s34, s26, s29
	s_cselect_b32 s35, s27, s31
	s_add_u32 s8, s36, 0x8000
	s_addc_u32 s9, s37, 0
	s_add_i32 s40, 0, 0x10000
	s_add_i32 s44, 0, 0x14000
	v_add_u32_e32 v142, s40, v206
	v_add_u32_e32 v158, s44, v206
	ds_read_b128 v[26:29], v142
	v_pk_mov_b32 v[2:3], 0, 0
	v_pk_mov_b32 v[4:5], 0, 0
	v_pk_mov_b32 v[6:7], 0, 0
	v_pk_mov_b32 v[8:9], 0, 0
	ds_read_b128 v[30:33], v142 offset:1024
	v_pk_mov_b32 v[10:11], 0, 0
	v_pk_mov_b32 v[12:13], 0, 0
	v_pk_mov_b32 v[14:15], 0, 0
	v_pk_mov_b32 v[16:17], 0, 0
	ds_read_b128 v[138:141], v142 offset:2048
	v_pk_mov_b32 v[18:19], 0, 0
	v_pk_mov_b32 v[20:21], 0, 0
	v_pk_mov_b32 v[22:23], 0, 0
	v_pk_mov_b32 v[24:25], 0, 0
	ds_read_b128 v[142:145], v142 offset:3072
	v_pk_mov_b32 v[34:35], 0, 0
	v_pk_mov_b32 v[36:37], 0, 0
	v_pk_mov_b32 v[38:39], 0, 0
	v_pk_mov_b32 v[40:41], 0, 0
	ds_read_b128 v[146:149], v158
	v_pk_mov_b32 v[42:43], 0, 0
	v_pk_mov_b32 v[44:45], 0, 0
	v_pk_mov_b32 v[46:47], 0, 0
	v_pk_mov_b32 v[48:49], 0, 0
	ds_read_b128 v[150:153], v158 offset:1024
	v_pk_mov_b32 v[50:51], 0, 0
	v_pk_mov_b32 v[52:53], 0, 0
	v_pk_mov_b32 v[54:55], 0, 0
	v_pk_mov_b32 v[56:57], 0, 0
	ds_read_b128 v[154:157], v158 offset:2048
	v_pk_mov_b32 v[58:59], 0, 0
	v_pk_mov_b32 v[60:61], 0, 0
	v_pk_mov_b32 v[62:63], 0, 0
	v_pk_mov_b32 v[64:65], 0, 0
	ds_read_b128 v[158:161], v158 offset:3072
	v_pk_mov_b32 v[66:67], 0, 0
	v_pk_mov_b32 v[68:69], 0, 0
	v_pk_mov_b32 v[70:71], 0, 0
	v_pk_mov_b32 v[72:73], 0, 0
	v_lshl_add_u64 v[202:203], s[0:1], 0, v[184:185]
	s_add_i32 m0, s83, 0xc000
	ds_read_b128 v[162:165], v207
	v_pk_mov_b32 v[74:75], 0, 0
	v_pk_mov_b32 v[76:77], 0, 0
	v_pk_mov_b32 v[78:79], 0, 0
	v_pk_mov_b32 v[80:81], 0, 0
	ds_read_b128 v[166:169], v207 offset:1024
	v_pk_mov_b32 v[82:83], 0, 0
	v_pk_mov_b32 v[84:85], 0, 0
	v_pk_mov_b32 v[86:87], 0, 0
	v_pk_mov_b32 v[88:89], 0, 0
	ds_read_b128 v[170:173], v207 offset:2048
	v_pk_mov_b32 v[90:91], 0, 0
	v_pk_mov_b32 v[92:93], 0, 0
	v_pk_mov_b32 v[94:95], 0, 0
	v_pk_mov_b32 v[96:97], 0, 0
	ds_read_b128 v[174:177], v207 offset:3072
	v_pk_mov_b32 v[98:99], 0, 0
	v_pk_mov_b32 v[100:101], 0, 0
	v_pk_mov_b32 v[102:103], 0, 0
	v_pk_mov_b32 v[104:105], 0, 0
	ds_read_b128 v[198:201], v207 offset:4096
	v_pk_mov_b32 v[106:107], 0, 0
	v_pk_mov_b32 v[108:109], 0, 0
	v_pk_mov_b32 v[110:111], 0, 0
	v_pk_mov_b32 v[112:113], 0, 0
	ds_read_b128 v[208:211], v207 offset:5120
	v_pk_mov_b32 v[114:115], 0, 0
	v_pk_mov_b32 v[116:117], 0, 0
	v_pk_mov_b32 v[118:119], 0, 0
	v_pk_mov_b32 v[120:121], 0, 0
	ds_read_b128 v[212:215], v207 offset:6144
	v_pk_mov_b32 v[122:123], 0, 0
	v_pk_mov_b32 v[124:125], 0, 0
	v_pk_mov_b32 v[126:127], 0, 0
	v_pk_mov_b32 v[128:129], 0, 0
	ds_read_b128 v[216:219], v207 offset:7168
	v_pk_mov_b32 v[130:131], 0, 0
	v_pk_mov_b32 v[132:133], 0, 0
	v_pk_mov_b32 v[134:135], 0, 0
	v_pk_mov_b32 v[136:137], 0, 0
	global_load_lds_dwordx4 v[202:203], off
	v_lshl_add_u64 v[202:203], s[0:1], 0, v[196:197]
	s_add_i32 m0, s83, 0xe000
	s_nop 0
	global_load_lds_dwordx4 v[202:203], off
	s_waitcnt vmcnt(8)
	s_waitcnt lgkmcnt(0)
	s_barrier
	s_branch .Lpeel_367

; #define PG8_STAGE(bufoff, gbase, voff) do { _Pragma("unroll") for (int _i = 0; _i < 2; ++_i) \
;         __builtin_amdgcn_global_load_lds((const unsigned*)((const char*)(gbase) + (voff)[_i]), (PG8_LAS unsigned*)(lds + (bufoff) + ldsw + _i * 8192), 16, 0, 0); } while (0)
; #define PG8_LDA(dst, b, h) do { _Pragma("unroll") for (int m = 0; m < 4; ++m) _Pragma("unroll") for (int k = 0; k < 2; ++k) dst[m][k] = *(const PG8_LAS bf16x8*)(lds + PG8_SA(b, h) + aoff + m * 2048 + k * 1024); } while (0)
; #define PG8_MMA(ai, bj, At, Bt) do { __builtin_amdgcn_s_setprio(1); _Pragma("unroll") for (int m = 0; m < 4; ++m) _Pragma("unroll") for (int n = 0; n < 2; ++n) _Pragma("unroll") for (int k = 0; k < 2; ++k) \
;         acc[ai][bj][m][n] = __builtin_amdgcn_mfma_f32_16x16x32_bf16(Bt[n][k], At[m][k], acc[ai][bj][m][n], 0, 0, 0); __builtin_amdgcn_s_setprio(0); } while (0)
; #define PG8_WAIT_V(n) asm volatile("s_waitcnt vmcnt(" #n ")" ::: "memory")
; #define PG8_WAIT_L(n) asm volatile("s_waitcnt lgkmcnt(" #n ")" ::: "memory")
; #define PG8_BAR __builtin_amdgcn_s_barrier()
; #define PG8_SCHED __builtin_amdgcn_sched_barrier(0)
; template <class Epi, class Sched, bool ALIGN_EPI = false, bool SP2 = false, bool ABLK = false, bool BBLK = false>
; __device__ __forceinline__ void gemm_phase(PG8_LAS unsigned char* lds, const Gemm g, const Sched& S, const Epi& E) {
;     ...
;             PG8_WAIT_V(8); PG8_WAIT_L(0); PG8_BAR; PG8_MMA(0, 0, At, B0); PG8_MMA(0, 1, At, B1); PG8_BAR; PG8_SCHED;
;             PG8_LDA(At, 0, 1); PG8_STAGE(PG8_SB(0, 0), b2, voffB); PG8_STAGE(PG8_SB(0, 1), b2 + hstepB, voffB); PG8_STAGE(PG8_SA(0, 0), a2, voffA);
;             PG8_WAIT_V(8); PG8_WAIT_L(0); PG8_BAR; PG8_MMA(1, 0, At, B0); PG8_MMA(1, 1, At, B1); PG8_BAR; PG8_SCHED;
.Lpeel_367:
	s_setprio 1
	s_waitcnt lgkmcnt(0)
	v_mfma_f32_16x16x32_bf16 v[22:25], v[26:29], v[162:165], v[22:25]
	v_mfma_f32_16x16x32_bf16 v[18:21], v[138:141], v[162:165], v[18:21]
	v_mfma_f32_16x16x32_bf16 v[62:65], v[26:29], v[170:173], v[62:65]
	v_mfma_f32_16x16x32_bf16 v[58:61], v[138:141], v[170:173], v[58:61]
	v_mfma_f32_16x16x32_bf16 v[54:57], v[26:29], v[198:201], v[54:57]
	v_mfma_f32_16x16x32_bf16 v[50:53], v[138:141], v[198:201], v[50:53]
	v_mfma_f32_16x16x32_bf16 v[126:129], v[26:29], v[212:215], v[126:129]
	v_mfma_f32_16x16x32_bf16 v[122:125], v[138:141], v[212:215], v[122:125]
	v_mfma_f32_16x16x32_bf16 v[22:25], v[30:33], v[166:169], v[22:25]
	v_mfma_f32_16x16x32_bf16 v[18:21], v[142:145], v[166:169], v[18:21]
	v_mfma_f32_16x16x32_bf16 v[62:65], v[30:33], v[174:177], v[62:65]
	v_mfma_f32_16x16x32_bf16 v[58:61], v[142:145], v[174:177], v[58:61]
	v_mfma_f32_16x16x32_bf16 v[54:57], v[30:33], v[208:211], v[54:57]
	v_mfma_f32_16x16x32_bf16 v[50:53], v[142:145], v[208:211], v[50:53]
	v_mfma_f32_16x16x32_bf16 v[126:129], v[30:33], v[216:219], v[126:129]
	v_mfma_f32_16x16x32_bf16 v[122:125], v[142:145], v[216:219], v[122:125]
	s_setprio 0
	s_setprio 1
	v_mfma_f32_16x16x32_bf16 v[14:17], v[146:149], v[162:165], v[14:17]
	v_mfma_f32_16x16x32_bf16 v[10:13], v[154:157], v[162:165], v[10:13]
	v_mfma_f32_16x16x32_bf16 v[6:9], v[146:149], v[170:173], v[6:9]
	v_mfma_f32_16x16x32_bf16 v[2:5], v[154:157], v[170:173], v[2:5]
	v_mfma_f32_16x16x32_bf16 v[46:49], v[146:149], v[198:201], v[46:49]
	v_mfma_f32_16x16x32_bf16 v[42:45], v[154:157], v[198:201], v[42:45]
	v_mfma_f32_16x16x32_bf16 v[38:41], v[146:149], v[212:215], v[38:41]
	v_mfma_f32_16x16x32_bf16 v[34:37], v[154:157], v[212:215], v[34:37]
	v_mfma_f32_16x16x32_bf16 v[14:17], v[150:153], v[166:169], v[14:17]
	v_mfma_f32_16x16x32_bf16 v[10:13], v[158:161], v[166:169], v[10:13]
	v_mfma_f32_16x16x32_bf16 v[6:9], v[150:153], v[174:177], v[6:9]
	v_mfma_f32_16x16x32_bf16 v[2:5], v[158:161], v[174:177], v[2:5]
	v_mfma_f32_16x16x32_bf16 v[46:49], v[150:153], v[208:211], v[46:49]
	v_mfma_f32_16x16x32_bf16 v[42:45], v[158:161], v[208:211], v[42:45]
	v_mfma_f32_16x16x32_bf16 v[38:41], v[150:153], v[216:219], v[38:41]
	v_mfma_f32_16x16x32_bf16 v[34:37], v[158:161], v[216:219], v[34:37]
	s_setprio 0
	s_barrier
	s_add_i32 s40, s40, s81
	v_lshl_add_u64 v[202:203], s[34:35], 0, v[186:187]
	s_mov_b32 m0, s40
	ds_read_b128 v[162:165], v207 offset:16384
	ds_read_b128 v[166:169], v207 offset:17408
	ds_read_b128 v[170:173], v207 offset:18432
	ds_read_b128 v[174:177], v207 offset:19456
	ds_read_b128 v[198:201], v207 offset:20480
	ds_read_b128 v[208:211], v207 offset:21504
	ds_read_b128 v[212:215], v207 offset:22528
	ds_read_b128 v[216:219], v207 offset:23552
	global_load_lds_dwordx4 v[202:203], off
	s_add_i32 m0, s40, 0x2000
	s_add_u32 s40, s34, 0x4000
	v_lshl_add_u64 v[202:203], s[34:35], 0, v[182:183]
	s_addc_u32 s41, s35, 0
	s_add_i32 s44, s44, s81
	global_load_lds_dwordx4 v[202:203], off
	v_lshl_add_u64 v[202:203], s[40:41], 0, v[186:187]
	s_mov_b32 m0, s44
	s_nop 0
	global_load_lds_dwordx4 v[202:203], off
	v_lshl_add_u64 v[202:203], s[40:41], 0, v[182:183]
	s_add_i32 m0, s44, 0x2000
	s_nop 0
	global_load_lds_dwordx4 v[202:203], off
	v_lshl_add_u64 v[202:203], s[36:37], 0, v[178:179]
	s_mov_b32 m0, s83
	s_nop 0
	global_load_lds_dwordx4 v[202:203], off
	v_lshl_add_u64 v[202:203], s[36:37], 0, v[180:181]
	s_mov_b32 m0, s84
	s_nop 0
	global_load_lds_dwordx4 v[202:203], off
	s_waitcnt vmcnt(8)
	s_waitcnt lgkmcnt(0)
	s_barrier
	s_setprio 1
	s_waitcnt lgkmcnt(0)
	v_mfma_f32_16x16x32_bf16 v[118:121], v[26:29], v[162:165], v[118:121]
	v_mfma_f32_16x16x32_bf16 v[114:117], v[138:141], v[162:165], v[114:117]
	v_mfma_f32_16x16x32_bf16 v[134:137], v[26:29], v[170:173], v[134:137]
	v_mfma_f32_16x16x32_bf16 v[130:133], v[138:141], v[170:173], v[130:133]
	v_mfma_f32_16x16x32_bf16 v[110:113], v[26:29], v[198:201], v[110:113]
	v_mfma_f32_16x16x32_bf16 v[106:109], v[138:141], v[198:201], v[106:109]
	v_mfma_f32_16x16x32_bf16 v[26:29], v[26:29], v[212:215], v[102:105]
	v_mfma_f32_16x16x32_bf16 v[118:121], v[30:33], v[166:169], v[118:121]
	v_mfma_f32_16x16x32_bf16 v[114:117], v[142:145], v[166:169], v[114:117]
	v_mfma_f32_16x16x32_bf16 v[134:137], v[30:33], v[174:177], v[134:137]
	v_mfma_f32_16x16x32_bf16 v[130:133], v[142:145], v[174:177], v[130:133]
	v_mfma_f32_16x16x32_bf16 v[110:113], v[30:33], v[208:211], v[110:113]
	v_mfma_f32_16x16x32_bf16 v[106:109], v[142:145], v[208:211], v[106:109]
	v_mfma_f32_16x16x32_bf16 v[26:29], v[30:33], v[216:219], v[26:29]
	v_mfma_f32_16x16x32_bf16 v[30:33], v[138:141], v[212:215], v[98:101]
	v_mfma_f32_16x16x32_bf16 v[30:33], v[142:145], v[216:219], v[30:33]
	s_setprio 0
	s_setprio 1
	v_mfma_f32_16x16x32_bf16 v[94:97], v[146:149], v[162:165], v[94:97]
	v_mfma_f32_16x16x32_bf16 v[90:93], v[154:157], v[162:165], v[90:93]
	v_mfma_f32_16x16x32_bf16 v[74:77], v[146:149], v[170:173], v[74:77]
	v_mfma_f32_16x16x32_bf16 v[70:73], v[154:157], v[170:173], v[70:73]
	v_mfma_f32_16x16x32_bf16 v[86:89], v[146:149], v[198:201], v[86:89]
	v_mfma_f32_16x16x32_bf16 v[82:85], v[154:157], v[198:201], v[82:85]
	v_mfma_f32_16x16x32_bf16 v[78:81], v[146:149], v[212:215], v[78:81]
	v_mfma_f32_16x16x32_bf16 v[66:69], v[154:157], v[212:215], v[66:69]
	v_mfma_f32_16x16x32_bf16 v[94:97], v[150:153], v[166:169], v[94:97]
	v_mfma_f32_16x16x32_bf16 v[90:93], v[158:161], v[166:169], v[90:93]
	v_mfma_f32_16x16x32_bf16 v[74:77], v[150:153], v[174:177], v[74:77]
	v_mfma_f32_16x16x32_bf16 v[70:73], v[158:161], v[174:177], v[70:73]
	v_mfma_f32_16x16x32_bf16 v[86:89], v[150:153], v[208:211], v[86:89]
	v_mfma_f32_16x16x32_bf16 v[82:85], v[158:161], v[208:211], v[82:85]
	v_mfma_f32_16x16x32_bf16 v[78:81], v[150:153], v[216:219], v[78:81]
	v_mfma_f32_16x16x32_bf16 v[66:69], v[158:161], v[216:219], v[66:69]
	s_setprio 0
	s_barrier
; #define PG8_STAGE(bufoff, gbase, voff) do { _Pragma("unroll") for (int _i = 0; _i < 2; ++_i) \
;         __builtin_amdgcn_global_load_lds((const unsigned*)((const char*)(gbase) + (voff)[_i]), (PG8_LAS unsigned*)(lds + (bufoff) + ldsw + _i * 8192), 16, 0, 0); } while (0)
; #define PG8_LDA(dst, b, h) do { _Pragma("unroll") for (int m = 0; m < 4; ++m) _Pragma("unroll") for (int k = 0; k < 2; ++k) dst[m][k] = *(const PG8_LAS bf16x8*)(lds + PG8_SA(b, h) + aoff + m * 2048 + k * 1024); } while (0)
; #define PG8_LDB(dst, b, h) do { _Pragma("unroll") for (int n = 0; n < 2; ++n) _Pragma("unroll") for (int k = 0; k < 2; ++k) dst[n][k] = *(const PG8_LAS bf16x8*)(lds + PG8_SB(b, h) + boff + n * 2048 + k * 1024); } while (0)
; #define PG8_MMA(ai, bj, At, Bt) do { __builtin_amdgcn_s_setprio(1); _Pragma("unroll") for (int m = 0; m < 4; ++m) _Pragma("unroll") for (int n = 0; n < 2; ++n) _Pragma("unroll") for (int k = 0; k < 2; ++k) \
;         acc[ai][bj][m][n] = __builtin_amdgcn_mfma_f32_16x16x32_bf16(Bt[n][k], At[m][k], acc[ai][bj][m][n], 0, 0, 0); __builtin_amdgcn_s_setprio(0); } while (0)
; #define PG8_WAIT_V(n) asm volatile("s_waitcnt vmcnt(" #n ")" ::: "memory")
; #define PG8_WAIT_L(n) asm volatile("s_waitcnt lgkmcnt(" #n ")" ::: "memory")
; #define PG8_BAR __builtin_amdgcn_s_barrier()
; #define PG8_SCHED __builtin_amdgcn_sched_barrier(0)
; template <class Epi, class Sched, bool ALIGN_EPI = false, bool SP2 = false, bool ABLK = false, bool BBLK = false>
; __device__ __forceinline__ void gemm_phase(PG8_LAS unsigned char* lds, const Gemm g, const Sched& S, const Epi& E) {
;     ...
;             PG8_LDB(B0, 1, 0); PG8_LDB(B1, 1, 1); PG8_SCHED; PG8_LDA(At, 1, 0); PG8_STAGE(PG8_SA(0, 1), a2 + hstepA, voffA);
;             PG8_WAIT_V(8); PG8_WAIT_L(0); PG8_BAR; PG8_MMA(0, 0, At, B0); PG8_MMA(0, 1, At, B1); PG8_BAR; PG8_SCHED;
	s_add_i32 s40, 0, 0x18000
	s_add_i32 s41, 0, 0x1c000
	v_add_u32_e32 v142, s40, v206
	v_add_u32_e32 v158, s41, v206
	ds_read_b128 v[98:101], v142
	ds_read_b128 v[102:105], v142 offset:1024
	ds_read_b128 v[138:141], v142 offset:2048
	ds_read_b128 v[142:145], v142 offset:3072
	ds_read_b128 v[146:149], v158
	ds_read_b128 v[150:153], v158 offset:1024
	ds_read_b128 v[154:157], v158 offset:2048
	ds_read_b128 v[158:161], v158 offset:3072
	s_add_u32 s36, s36, 0x4000
	s_addc_u32 s37, s37, 0
	s_mov_b32 m0, s92
	v_lshl_add_u64 v[202:203], s[36:37], 0, v[178:179]
	ds_read_b128 v[162:165], v207 offset:32768
	ds_read_b128 v[166:169], v207 offset:33792
	ds_read_b128 v[170:173], v207 offset:34816
	ds_read_b128 v[174:177], v207 offset:35840
	ds_read_b128 v[198:201], v207 offset:36864
	ds_read_b128 v[208:211], v207 offset:37888
	ds_read_b128 v[212:215], v207 offset:38912
	ds_read_b128 v[216:219], v207 offset:39936
	global_load_lds_dwordx4 v[202:203], off
	v_lshl_add_u64 v[202:203], s[36:37], 0, v[180:181]
	s_mov_b32 m0, s93
	s_nop 0
	global_load_lds_dwordx4 v[202:203], off
	s_waitcnt vmcnt(8)
	s_waitcnt lgkmcnt(0)
	s_barrier
	s_setprio 1
	s_waitcnt lgkmcnt(0)
	v_mfma_f32_16x16x32_bf16 v[22:25], v[98:101], v[162:165], v[22:25]
	v_mfma_f32_16x16x32_bf16 v[18:21], v[138:141], v[162:165], v[18:21]
	v_mfma_f32_16x16x32_bf16 v[62:65], v[98:101], v[170:173], v[62:65]
	v_mfma_f32_16x16x32_bf16 v[58:61], v[138:141], v[170:173], v[58:61]
	v_mfma_f32_16x16x32_bf16 v[54:57], v[98:101], v[198:201], v[54:57]
	v_mfma_f32_16x16x32_bf16 v[50:53], v[138:141], v[198:201], v[50:53]
	v_mfma_f32_16x16x32_bf16 v[126:129], v[98:101], v[212:215], v[126:129]
	v_mfma_f32_16x16x32_bf16 v[122:125], v[138:141], v[212:215], v[122:125]
	v_mfma_f32_16x16x32_bf16 v[22:25], v[102:105], v[166:169], v[22:25]
	v_mfma_f32_16x16x32_bf16 v[18:21], v[142:145], v[166:169], v[18:21]
	v_mfma_f32_16x16x32_bf16 v[62:65], v[102:105], v[174:177], v[62:65]
	v_mfma_f32_16x16x32_bf16 v[58:61], v[142:145], v[174:177], v[58:61]
	v_mfma_f32_16x16x32_bf16 v[54:57], v[102:105], v[208:211], v[54:57]
	v_mfma_f32_16x16x32_bf16 v[50:53], v[142:145], v[208:211], v[50:53]
	v_mfma_f32_16x16x32_bf16 v[126:129], v[102:105], v[216:219], v[126:129]
	v_mfma_f32_16x16x32_bf16 v[122:125], v[142:145], v[216:219], v[122:125]
	s_setprio 0
	s_setprio 1
	v_mfma_f32_16x16x32_bf16 v[14:17], v[146:149], v[162:165], v[14:17]
	v_mfma_f32_16x16x32_bf16 v[10:13], v[154:157], v[162:165], v[10:13]
	v_mfma_f32_16x16x32_bf16 v[6:9], v[146:149], v[170:173], v[6:9]
	v_mfma_f32_16x16x32_bf16 v[2:5], v[154:157], v[170:173], v[2:5]
	v_mfma_f32_16x16x32_bf16 v[46:49], v[146:149], v[198:201], v[46:49]
	v_mfma_f32_16x16x32_bf16 v[42:45], v[154:157], v[198:201], v[42:45]
	v_mfma_f32_16x16x32_bf16 v[38:41], v[146:149], v[212:215], v[38:41]
	v_mfma_f32_16x16x32_bf16 v[34:37], v[154:157], v[212:215], v[34:37]
	v_mfma_f32_16x16x32_bf16 v[14:17], v[150:153], v[166:169], v[14:17]
	v_mfma_f32_16x16x32_bf16 v[10:13], v[158:161], v[166:169], v[10:13]
	v_mfma_f32_16x16x32_bf16 v[6:9], v[150:153], v[174:177], v[6:9]
	v_mfma_f32_16x16x32_bf16 v[2:5], v[158:161], v[174:177], v[2:5]
	v_mfma_f32_16x16x32_bf16 v[46:49], v[150:153], v[208:211], v[46:49]
	v_mfma_f32_16x16x32_bf16 v[42:45], v[158:161], v[208:211], v[42:45]
	v_mfma_f32_16x16x32_bf16 v[38:41], v[150:153], v[216:219], v[38:41]
	v_mfma_f32_16x16x32_bf16 v[34:37], v[158:161], v[216:219], v[34:37]
	s_setprio 0
	s_barrier
; #define PG8_STAGE(bufoff, gbase, voff) do { _Pragma("unroll") for (int _i = 0; _i < 2; ++_i) \
;         __builtin_amdgcn_global_load_lds((const unsigned*)((const char*)(gbase) + (voff)[_i]), (PG8_LAS unsigned*)(lds + (bufoff) + ldsw + _i * 8192), 16, 0, 0); } while (0)
; #define PG8_LDA(dst, b, h) do { _Pragma("unroll") for (int m = 0; m < 4; ++m) _Pragma("unroll") for (int k = 0; k < 2; ++k) dst[m][k] = *(const PG8_LAS bf16x8*)(lds + PG8_SA(b, h) + aoff + m * 2048 + k * 1024); } while (0)
; #define PG8_MMA(ai, bj, At, Bt) do { __builtin_amdgcn_s_setprio(1); _Pragma("unroll") for (int m = 0; m < 4; ++m) _Pragma("unroll") for (int n = 0; n < 2; ++n) _Pragma("unroll") for (int k = 0; k < 2; ++k) \
;         acc[ai][bj][m][n] = __builtin_amdgcn_mfma_f32_16x16x32_bf16(Bt[n][k], At[m][k], acc[ai][bj][m][n], 0, 0, 0); __builtin_amdgcn_s_setprio(0); } while (0)
; #define PG8_WAIT_V(n) asm volatile("s_waitcnt vmcnt(" #n ")" ::: "memory")
; #define PG8_WAIT_L(n) asm volatile("s_waitcnt lgkmcnt(" #n ")" ::: "memory")
; #define PG8_BAR __builtin_amdgcn_s_barrier()
; #define PG8_SCHED __builtin_amdgcn_sched_barrier(0)
; template <class Epi, class Sched, bool ALIGN_EPI = false, bool SP2 = false, bool ABLK = false, bool BBLK = false>
; __device__ __forceinline__ void gemm_phase(PG8_LAS unsigned char* lds, const Gemm g, const Sched& S, const Epi& E) {
;     ...
;             PG8_LDA(At, 1, 1); PG8_STAGE(PG8_SB(1, 0), b3, voffB); PG8_STAGE(PG8_SB(1, 1), b3 + hstepB, voffB); PG8_STAGE(PG8_SA(1, 0), a3, voffA);
;             PG8_WAIT_V(8); PG8_WAIT_L(0); PG8_BAR; PG8_MMA(1, 0, At, B0); PG8_MMA(1, 1, At, B1); PG8_BAR; PG8_SCHED;
;     ...
;         if constexpr (ALIGN_EPI) { if (wr == 0) PG8_BAR; }
	s_add_u32 s36, s34, 0x8000
	s_addc_u32 s37, s35, 0
	s_add_i32 s40, s40, s81
	v_lshl_add_u64 v[202:203], s[36:37], 0, v[186:187]
	s_mov_b32 m0, s40
	ds_read_b128 v[162:165], v207 offset:49152
	ds_read_b128 v[166:169], v207 offset:50176
	ds_read_b128 v[170:173], v207 offset:51200
	ds_read_b128 v[174:177], v207 offset:52224
	ds_read_b128 v[198:201], v207 offset:53248
	ds_read_b128 v[208:211], v207 offset:54272
	ds_read_b128 v[212:215], v207 offset:55296
	ds_read_b128 v[216:219], v207 offset:56320
	global_load_lds_dwordx4 v[202:203], off
	s_add_i32 m0, s40, 0x2000
	s_add_u32 s34, s34, 0xc000
	v_lshl_add_u64 v[202:203], s[36:37], 0, v[182:183]
	s_addc_u32 s35, s35, 0
	s_add_i32 s36, s41, s81
	global_load_lds_dwordx4 v[202:203], off
	v_lshl_add_u64 v[202:203], s[34:35], 0, v[186:187]
	s_mov_b32 m0, s36
	s_nop 0
	global_load_lds_dwordx4 v[202:203], off
	v_lshl_add_u64 v[202:203], s[34:35], 0, v[182:183]
	s_add_i32 m0, s36, 0x2000
	s_nop 0
	global_load_lds_dwordx4 v[202:203], off
	v_lshl_add_u64 v[202:203], s[8:9], 0, v[178:179]
	s_mov_b32 m0, s22
	s_nop 0
	global_load_lds_dwordx4 v[202:203], off
	v_lshl_add_u64 v[202:203], s[8:9], 0, v[180:181]
	s_mov_b32 m0, s23
	s_nop 0
	global_load_lds_dwordx4 v[202:203], off
	s_waitcnt vmcnt(8)
	s_waitcnt lgkmcnt(0)
	s_barrier
	s_setprio 1
	s_waitcnt lgkmcnt(0)
	v_mfma_f32_16x16x32_bf16 v[118:121], v[98:101], v[162:165], v[118:121]
	v_mfma_f32_16x16x32_bf16 v[134:137], v[98:101], v[170:173], v[134:137]
	v_mfma_f32_16x16x32_bf16 v[110:113], v[98:101], v[198:201], v[110:113]
	v_mfma_f32_16x16x32_bf16 v[26:29], v[98:101], v[212:215], v[26:29]
	v_mfma_f32_16x16x32_bf16 v[118:121], v[102:105], v[166:169], v[118:121]
	v_mfma_f32_16x16x32_bf16 v[114:117], v[138:141], v[162:165], v[114:117]
	v_mfma_f32_16x16x32_bf16 v[134:137], v[102:105], v[174:177], v[134:137]
	v_mfma_f32_16x16x32_bf16 v[130:133], v[138:141], v[170:173], v[130:133]
	v_mfma_f32_16x16x32_bf16 v[110:113], v[102:105], v[208:211], v[110:113]
	v_mfma_f32_16x16x32_bf16 v[106:109], v[138:141], v[198:201], v[106:109]
	v_mfma_f32_16x16x32_bf16 v[102:105], v[102:105], v[216:219], v[26:29]
	v_mfma_f32_16x16x32_bf16 v[26:29], v[138:141], v[212:215], v[30:33]
	v_mfma_f32_16x16x32_bf16 v[114:117], v[142:145], v[166:169], v[114:117]
	v_mfma_f32_16x16x32_bf16 v[130:133], v[142:145], v[174:177], v[130:133]
	v_mfma_f32_16x16x32_bf16 v[106:109], v[142:145], v[208:211], v[106:109]
	v_mfma_f32_16x16x32_bf16 v[98:101], v[142:145], v[216:219], v[26:29]
	s_setprio 0
	s_setprio 1
	v_mfma_f32_16x16x32_bf16 v[26:29], v[146:149], v[162:165], v[94:97]
	v_mfma_f32_16x16x32_bf16 v[94:97], v[150:153], v[166:169], v[26:29]
	v_mfma_f32_16x16x32_bf16 v[26:29], v[154:157], v[162:165], v[90:93]
	v_mfma_f32_16x16x32_bf16 v[90:93], v[158:161], v[166:169], v[26:29]
	v_mfma_f32_16x16x32_bf16 v[26:29], v[146:149], v[170:173], v[74:77]
	v_mfma_f32_16x16x32_bf16 v[74:77], v[150:153], v[174:177], v[26:29]
	v_mfma_f32_16x16x32_bf16 v[26:29], v[154:157], v[170:173], v[70:73]
	v_mfma_f32_16x16x32_bf16 v[70:73], v[158:161], v[174:177], v[26:29]
	v_mfma_f32_16x16x32_bf16 v[26:29], v[146:149], v[198:201], v[86:89]
	v_mfma_f32_16x16x32_bf16 v[86:89], v[150:153], v[208:211], v[26:29]
	v_mfma_f32_16x16x32_bf16 v[26:29], v[154:157], v[198:201], v[82:85]
	v_mfma_f32_16x16x32_bf16 v[82:85], v[158:161], v[208:211], v[26:29]
	v_mfma_f32_16x16x32_bf16 v[26:29], v[146:149], v[212:215], v[78:81]
	v_mfma_f32_16x16x32_bf16 v[78:81], v[150:153], v[216:219], v[26:29]
	v_mfma_f32_16x16x32_bf16 v[26:29], v[154:157], v[212:215], v[66:69]
	v_mfma_f32_16x16x32_bf16 v[66:69], v[158:161], v[216:219], v[26:29]
	s_setprio 0
	s_barrier
	s_add_i32 s33, s33, 2
	s_add_u32 s0, s0, 0x10000
	s_addc_u32 s1, s1, 0
	s_add_u32 s29, s29, 0x10000
	s_addc_u32 s31, s31, 0
	s_cmpk_gt_u32 s33, 0x55
	s_cbranch_scc0 .LBB0_367
	s_and_b64 vcc, exec, s[18:19]
	s_cbranch_vccz .LBB0_370
	s_barrier

; #define PG8_STAGE(bufoff, gbase, voff) do { _Pragma("unroll") for (int _i = 0; _i < 2; ++_i) \
;         __builtin_amdgcn_global_load_lds((const unsigned*)((const char*)(gbase) + (voff)[_i]), (PG8_LAS unsigned*)(lds + (bufoff) + ldsw + _i * 8192), 16, 0, 0); } while (0)
; #define PG8_LDA(dst, b, h) do { _Pragma("unroll") for (int m = 0; m < 4; ++m) _Pragma("unroll") for (int k = 0; k < 2; ++k) dst[m][k] = *(const PG8_LAS bf16x8*)(lds + PG8_SA(b, h) + aoff + m * 2048 + k * 1024); } while (0)
; #define PG8_LDB(dst, b, h) do { _Pragma("unroll") for (int n = 0; n < 2; ++n) _Pragma("unroll") for (int k = 0; k < 2; ++k) dst[n][k] = *(const PG8_LAS bf16x8*)(lds + PG8_SB(b, h) + boff + n * 2048 + k * 1024); } while (0)
; #define PG8_WAIT_V(n) asm volatile("s_waitcnt vmcnt(" #n ")" ::: "memory")
; #define PG8_WAIT_L(n) asm volatile("s_waitcnt lgkmcnt(" #n ")" ::: "memory")
; #define PG8_BAR __builtin_amdgcn_s_barrier()
; template <class Epi, class Sched, bool ALIGN_EPI = false, bool SP2 = false, bool ABLK = false, bool BBLK = false>
; __device__ __forceinline__ void gemm_phase(PG8_LAS unsigned char* lds, const Gemm g, const Sched& S, const Epi& E) {
;     ...
;         const bool has_next = S.next(ui + 1, nxt);
;         const char* nA = has_next ? (const char*)g.A + (size_t)nxt.pm * tstepA : cA; const char* nB = has_next ? (const char*)g.Bt + (size_t)nxt.pn * tstepB : cB;
;         for (int t = 0; t < nt; t += 2) {
;             const bool last = (t == nt - 2);
;             const char* a1 = cA + (size_t)(t + 1) * kstepA;
;             const char* a2 = last ? nA : cA + (size_t)(t + 2) * kstepA; const char* b2 = last ? nB : cB + (size_t)(t + 2) * kstepB;
;             const char* a3 = a2 + kstepA; const char* b3 = b2 + kstepB;
;             if (last && has_next) S.a_ready(nxt);
;             if constexpr (SP2) {
;             PG8_LDB(B0, 0, 0); PG8_LDB(B1, 0, 1); PG8_SCHED; PG8_LDA(At, 0, 0); PG8_STAGE(PG8_SA(1, 1), a1 + hstepA, voffA);
;             PG8_WAIT_V(8); PG8_WAIT_L(0); PG8_BAR; PG8_MMA(0, 0, At, B0); PG8_MMA(0, 1, At, B1); PG8_BAR; PG8_SCHED;
;     ...
;         for (int a = 0; a < 2; ++a)
; #pragma unroll
;             for (int b = 0; b < 2; ++b)
; #pragma unroll
;                 for (int m = 0; m < 4; ++m)
; #pragma unroll
;                     for (int n = 0; n < 2; ++n) acc[a][b][m][n] = (f32x4){0.f, 0.f, 0.f, 0.f};
.LBB0_593:
	s_ashr_i32 s21, s20, 31
	s_lshl_b64 s[24:25], s[20:21], 20
	s_add_u32 s24, s51, s24
	s_addc_u32 s25, s53, s25
	s_and_b64 s[26:27], s[6:7], exec
	s_cselect_b32 s9, s25, s1
	s_cselect_b32 s16, s24, s0
	s_ashr_i32 s23, s22, 31
	s_lshl_b64 s[26:27], s[22:23], 20
	s_add_u32 s26, s44, s26
	s_addc_u32 s27, s45, s27
	s_and_b64 s[34:35], s[6:7], exec
	s_cselect_b32 s21, s27, s31
	s_cselect_b32 s23, s26, s30
	s_add_u32 s0, s0, 0xc000
	s_addc_u32 s1, s1, 0
	s_add_u32 s29, s30, 0x10000
	v_mov_b32_e32 v2, 0
	s_addc_u32 s40, s31, 0
	s_mov_b32 s41, -2
	v_mov_b32_e32 v3, v2
	v_mov_b32_e32 v4, v2
	v_mov_b32_e32 v5, v2
	v_mov_b32_e32 v6, v2
	v_mov_b32_e32 v7, v2
	v_mov_b32_e32 v8, v2
	v_mov_b32_e32 v9, v2
	s_waitcnt vmcnt(0)
	s_add_u32 s30, s0, 0x4000
	s_addc_u32 s31, s1, 0
	s_cmp_eq_u32 s41, 28
	s_cselect_b32 s36, s16, s30
	s_cselect_b32 s37, s9, s31
	s_cselect_b32 s34, s23, s29
	s_cselect_b32 s35, s21, s40
	s_add_u32 s30, s36, 0x8000
	s_addc_u32 s31, s37, 0
	s_add_i32 s60, 0, 0x10000
	s_add_i32 s75, 0, 0x14000
	v_add_u32_e32 v142, s60, v169
	v_add_u32_e32 v171, s75, v169
	ds_read_b128 v[130:133], v142
	v_pk_mov_b32 v[10:11], 0, 0
	v_pk_mov_b32 v[12:13], 0, 0
	v_pk_mov_b32 v[14:15], 0, 0
	v_pk_mov_b32 v[16:17], 0, 0
	ds_read_b128 v[134:137], v142 offset:1024
	v_pk_mov_b32 v[18:19], 0, 0
	v_pk_mov_b32 v[20:21], 0, 0
	v_pk_mov_b32 v[22:23], 0, 0
	v_pk_mov_b32 v[24:25], 0, 0
	ds_read_b128 v[138:141], v142 offset:2048
	v_pk_mov_b32 v[26:27], 0, 0
	v_pk_mov_b32 v[28:29], 0, 0
	v_pk_mov_b32 v[30:31], 0, 0
	v_pk_mov_b32 v[32:33], 0, 0
	ds_read_b128 v[142:145], v142 offset:3072
	v_pk_mov_b32 v[34:35], 0, 0
	v_pk_mov_b32 v[36:37], 0, 0
	v_pk_mov_b32 v[38:39], 0, 0
	v_pk_mov_b32 v[40:41], 0, 0
	ds_read_b128 v[160:163], v171
	v_pk_mov_b32 v[42:43], 0, 0
	v_pk_mov_b32 v[44:45], 0, 0
	v_pk_mov_b32 v[46:47], 0, 0
	v_pk_mov_b32 v[48:49], 0, 0
	ds_read_b128 v[164:167], v171 offset:1024
	v_pk_mov_b32 v[50:51], 0, 0
	v_pk_mov_b32 v[52:53], 0, 0
	v_pk_mov_b32 v[54:55], 0, 0
	v_pk_mov_b32 v[56:57], 0, 0
	ds_read_b128 v[172:175], v171 offset:2048
	v_pk_mov_b32 v[58:59], 0, 0
	v_pk_mov_b32 v[60:61], 0, 0
	v_pk_mov_b32 v[62:63], 0, 0
	v_pk_mov_b32 v[64:65], 0, 0
	ds_read_b128 v[176:179], v171 offset:3072
	v_pk_mov_b32 v[66:67], 0, 0
	v_pk_mov_b32 v[68:69], 0, 0
	v_pk_mov_b32 v[70:71], 0, 0
	v_pk_mov_b32 v[72:73], 0, 0
	v_lshl_add_u64 v[184:185], s[0:1], 0, v[156:157]
	s_add_i32 m0, s83, 0xc000
	ds_read_b128 v[180:183], v170
	v_pk_mov_b32 v[74:75], 0, 0
	v_pk_mov_b32 v[76:77], 0, 0
	v_pk_mov_b32 v[78:79], 0, 0
	v_pk_mov_b32 v[80:81], 0, 0
	ds_read_b128 v[196:199], v170 offset:1024
	v_pk_mov_b32 v[82:83], 0, 0
	v_pk_mov_b32 v[84:85], 0, 0
	v_pk_mov_b32 v[86:87], 0, 0
	v_pk_mov_b32 v[88:89], 0, 0
	ds_read_b128 v[200:203], v170 offset:2048
	v_pk_mov_b32 v[90:91], 0, 0
	v_pk_mov_b32 v[92:93], 0, 0
	v_pk_mov_b32 v[94:95], 0, 0
	v_pk_mov_b32 v[96:97], 0, 0
	ds_read_b128 v[204:207], v170 offset:3072
	v_pk_mov_b32 v[98:99], 0, 0
	v_pk_mov_b32 v[100:101], 0, 0
	v_pk_mov_b32 v[102:103], 0, 0
	v_pk_mov_b32 v[104:105], 0, 0
	ds_read_b128 v[208:211], v170 offset:4096
	v_pk_mov_b32 v[106:107], 0, 0
	v_pk_mov_b32 v[108:109], 0, 0
	v_pk_mov_b32 v[110:111], 0, 0
	v_pk_mov_b32 v[112:113], 0, 0
	ds_read_b128 v[212:215], v170 offset:5120
	v_pk_mov_b32 v[114:115], 0, 0
	v_pk_mov_b32 v[116:117], 0, 0
	v_pk_mov_b32 v[118:119], 0, 0
	v_pk_mov_b32 v[120:121], 0, 0
	ds_read_b128 v[216:219], v170 offset:6144
	v_pk_mov_b32 v[122:123], 0, 0
	v_pk_mov_b32 v[124:125], 0, 0
	v_pk_mov_b32 v[126:127], 0, 0
	v_pk_mov_b32 v[128:129], 0, 0
	ds_read_b128 v[220:223], v170 offset:7168
	global_load_lds_dwordx4 v[184:185], off
	v_lshl_add_u64 v[184:185], s[0:1], 0, v[158:159]
	s_add_i32 m0, s83, 0xe000
	s_nop 0
	global_load_lds_dwordx4 v[184:185], off
	s_waitcnt vmcnt(8)
	s_waitcnt lgkmcnt(0)
	s_barrier
	s_branch .Lpeel_594

; #define PG8_STAGE(bufoff, gbase, voff) do { _Pragma("unroll") for (int _i = 0; _i < 2; ++_i) \
;         __builtin_amdgcn_global_load_lds((const unsigned*)((const char*)(gbase) + (voff)[_i]), (PG8_LAS unsigned*)(lds + (bufoff) + ldsw + _i * 8192), 16, 0, 0); } while (0)
; #define PG8_LDA(dst, b, h) do { _Pragma("unroll") for (int m = 0; m < 4; ++m) _Pragma("unroll") for (int k = 0; k < 2; ++k) dst[m][k] = *(const PG8_LAS bf16x8*)(lds + PG8_SA(b, h) + aoff + m * 2048 + k * 1024); } while (0)
; #define PG8_MMA(ai, bj, At, Bt) do { __builtin_amdgcn_s_setprio(1); _Pragma("unroll") for (int m = 0; m < 4; ++m) _Pragma("unroll") for (int n = 0; n < 2; ++n) _Pragma("unroll") for (int k = 0; k < 2; ++k) \
;         acc[ai][bj][m][n] = __builtin_amdgcn_mfma_f32_16x16x32_bf16(Bt[n][k], At[m][k], acc[ai][bj][m][n], 0, 0, 0); __builtin_amdgcn_s_setprio(0); } while (0)
; #define PG8_WAIT_V(n) asm volatile("s_waitcnt vmcnt(" #n ")" ::: "memory")
; #define PG8_WAIT_L(n) asm volatile("s_waitcnt lgkmcnt(" #n ")" ::: "memory")
; #define PG8_BAR __builtin_amdgcn_s_barrier()
; #define PG8_SCHED __builtin_amdgcn_sched_barrier(0)
; template <class Epi, class Sched, bool ALIGN_EPI = false, bool SP2 = false, bool ABLK = false, bool BBLK = false>
; __device__ __forceinline__ void gemm_phase(PG8_LAS unsigned char* lds, const Gemm g, const Sched& S, const Epi& E) {
;     ...
;             PG8_WAIT_V(8); PG8_WAIT_L(0); PG8_BAR; PG8_MMA(0, 0, At, B0); PG8_MMA(0, 1, At, B1); PG8_BAR; PG8_SCHED;
;             PG8_LDA(At, 0, 1); PG8_STAGE(PG8_SB(0, 0), b2, voffB); PG8_STAGE(PG8_SB(0, 1), b2 + hstepB, voffB); PG8_STAGE(PG8_SA(0, 0), a2, voffA);
;             PG8_WAIT_V(8); PG8_WAIT_L(0); PG8_BAR; PG8_MMA(1, 0, At, B0); PG8_MMA(1, 1, At, B1); PG8_BAR; PG8_SCHED;
.Lpeel_594:
	s_setprio 1
	s_waitcnt lgkmcnt(0)
	v_mfma_f32_16x16x32_bf16 v[126:129], v[130:133], v[180:183], v[126:129]
	v_mfma_f32_16x16x32_bf16 v[122:125], v[138:141], v[180:183], v[122:125]
	v_mfma_f32_16x16x32_bf16 v[110:113], v[130:133], v[200:203], v[110:113]
	v_mfma_f32_16x16x32_bf16 v[106:109], v[138:141], v[200:203], v[106:109]
	v_mfma_f32_16x16x32_bf16 v[94:97], v[130:133], v[208:211], v[94:97]
	v_mfma_f32_16x16x32_bf16 v[90:93], v[138:141], v[208:211], v[90:93]
	v_mfma_f32_16x16x32_bf16 v[78:81], v[130:133], v[216:219], v[78:81]
	v_mfma_f32_16x16x32_bf16 v[74:77], v[138:141], v[216:219], v[74:77]
	v_mfma_f32_16x16x32_bf16 v[126:129], v[134:137], v[196:199], v[126:129]
	v_mfma_f32_16x16x32_bf16 v[122:125], v[142:145], v[196:199], v[122:125]
	v_mfma_f32_16x16x32_bf16 v[110:113], v[134:137], v[204:207], v[110:113]
	v_mfma_f32_16x16x32_bf16 v[106:109], v[142:145], v[204:207], v[106:109]
	v_mfma_f32_16x16x32_bf16 v[94:97], v[134:137], v[212:215], v[94:97]
	v_mfma_f32_16x16x32_bf16 v[90:93], v[142:145], v[212:215], v[90:93]
	v_mfma_f32_16x16x32_bf16 v[78:81], v[134:137], v[220:223], v[78:81]
	v_mfma_f32_16x16x32_bf16 v[74:77], v[142:145], v[220:223], v[74:77]
	s_setprio 0
	s_setprio 1
	v_mfma_f32_16x16x32_bf16 v[118:121], v[160:163], v[180:183], v[118:121]
	v_mfma_f32_16x16x32_bf16 v[114:117], v[172:175], v[180:183], v[114:117]
	v_mfma_f32_16x16x32_bf16 v[102:105], v[160:163], v[200:203], v[102:105]
	v_mfma_f32_16x16x32_bf16 v[98:101], v[172:175], v[200:203], v[98:101]
	v_mfma_f32_16x16x32_bf16 v[86:89], v[160:163], v[208:211], v[86:89]
	v_mfma_f32_16x16x32_bf16 v[82:85], v[172:175], v[208:211], v[82:85]
	v_mfma_f32_16x16x32_bf16 v[70:73], v[160:163], v[216:219], v[70:73]
	v_mfma_f32_16x16x32_bf16 v[66:69], v[172:175], v[216:219], v[66:69]
	v_mfma_f32_16x16x32_bf16 v[118:121], v[164:167], v[196:199], v[118:121]
	v_mfma_f32_16x16x32_bf16 v[114:117], v[176:179], v[196:199], v[114:117]
	v_mfma_f32_16x16x32_bf16 v[102:105], v[164:167], v[204:207], v[102:105]
	v_mfma_f32_16x16x32_bf16 v[98:101], v[176:179], v[204:207], v[98:101]
	v_mfma_f32_16x16x32_bf16 v[86:89], v[164:167], v[212:215], v[86:89]
	v_mfma_f32_16x16x32_bf16 v[82:85], v[176:179], v[212:215], v[82:85]
	v_mfma_f32_16x16x32_bf16 v[70:73], v[164:167], v[220:223], v[70:73]
	v_mfma_f32_16x16x32_bf16 v[66:69], v[176:179], v[220:223], v[66:69]
	s_setprio 0
	s_barrier
	s_add_i32 s60, s60, s81
	v_lshl_add_u64 v[184:185], s[34:35], 0, v[148:149]
	s_mov_b32 m0, s60
	ds_read_b128 v[180:183], v170 offset:16384
	ds_read_b128 v[196:199], v170 offset:17408
	ds_read_b128 v[200:203], v170 offset:18432
	ds_read_b128 v[204:207], v170 offset:19456
	ds_read_b128 v[208:211], v170 offset:20480
	ds_read_b128 v[212:215], v170 offset:21504
	ds_read_b128 v[216:219], v170 offset:22528
	ds_read_b128 v[220:223], v170 offset:23552
	global_load_lds_dwordx4 v[184:185], off
	s_add_i32 m0, s60, 0x2000
	s_add_u32 s60, s34, 0x4000
	v_lshl_add_u64 v[184:185], s[34:35], 0, v[152:153]
	s_addc_u32 s61, s35, 0
	s_add_i32 s75, s75, s81
	global_load_lds_dwordx4 v[184:185], off
	v_lshl_add_u64 v[184:185], s[60:61], 0, v[148:149]
	s_mov_b32 m0, s75
	s_nop 0
	global_load_lds_dwordx4 v[184:185], off
	v_lshl_add_u64 v[184:185], s[60:61], 0, v[152:153]
	s_add_i32 m0, s75, 0x2000
	s_nop 0
	global_load_lds_dwordx4 v[184:185], off
	v_lshl_add_u64 v[184:185], s[36:37], 0, v[146:147]
	s_mov_b32 m0, s83
	s_nop 0
	global_load_lds_dwordx4 v[184:185], off
	v_lshl_add_u64 v[184:185], s[36:37], 0, v[150:151]
	s_mov_b32 m0, s84
	s_nop 0
	global_load_lds_dwordx4 v[184:185], off
	s_waitcnt vmcnt(8)
	s_waitcnt lgkmcnt(0)
	s_barrier
	s_setprio 1
	s_waitcnt lgkmcnt(0)
	v_mfma_f32_16x16x32_bf16 v[62:65], v[130:133], v[180:183], v[62:65]
	v_mfma_f32_16x16x32_bf16 v[58:61], v[138:141], v[180:183], v[58:61]
	v_mfma_f32_16x16x32_bf16 v[46:49], v[130:133], v[200:203], v[46:49]
	v_mfma_f32_16x16x32_bf16 v[42:45], v[138:141], v[200:203], v[42:45]
	v_mfma_f32_16x16x32_bf16 v[30:33], v[130:133], v[208:211], v[30:33]
	v_mfma_f32_16x16x32_bf16 v[26:29], v[138:141], v[208:211], v[26:29]
	v_mfma_f32_16x16x32_bf16 v[14:17], v[130:133], v[216:219], v[14:17]
	v_mfma_f32_16x16x32_bf16 v[10:13], v[138:141], v[216:219], v[10:13]
	v_mfma_f32_16x16x32_bf16 v[62:65], v[134:137], v[196:199], v[62:65]
	v_mfma_f32_16x16x32_bf16 v[58:61], v[142:145], v[196:199], v[58:61]
	v_mfma_f32_16x16x32_bf16 v[46:49], v[134:137], v[204:207], v[46:49]
	v_mfma_f32_16x16x32_bf16 v[42:45], v[142:145], v[204:207], v[42:45]
	v_mfma_f32_16x16x32_bf16 v[30:33], v[134:137], v[212:215], v[30:33]
	v_mfma_f32_16x16x32_bf16 v[26:29], v[142:145], v[212:215], v[26:29]
	v_mfma_f32_16x16x32_bf16 v[14:17], v[134:137], v[220:223], v[14:17]
	v_mfma_f32_16x16x32_bf16 v[10:13], v[142:145], v[220:223], v[10:13]
	s_setprio 0
	s_setprio 1
	v_mfma_f32_16x16x32_bf16 v[54:57], v[160:163], v[180:183], v[54:57]
	v_mfma_f32_16x16x32_bf16 v[50:53], v[172:175], v[180:183], v[50:53]
	v_mfma_f32_16x16x32_bf16 v[38:41], v[160:163], v[200:203], v[38:41]
	v_mfma_f32_16x16x32_bf16 v[34:37], v[172:175], v[200:203], v[34:37]
	v_mfma_f32_16x16x32_bf16 v[22:25], v[160:163], v[208:211], v[22:25]
	v_mfma_f32_16x16x32_bf16 v[18:21], v[172:175], v[208:211], v[18:21]
	v_mfma_f32_16x16x32_bf16 v[6:9], v[160:163], v[216:219], v[6:9]
	v_mfma_f32_16x16x32_bf16 v[2:5], v[172:175], v[216:219], v[2:5]
	v_mfma_f32_16x16x32_bf16 v[54:57], v[164:167], v[196:199], v[54:57]
	v_mfma_f32_16x16x32_bf16 v[50:53], v[176:179], v[196:199], v[50:53]
	v_mfma_f32_16x16x32_bf16 v[38:41], v[164:167], v[204:207], v[38:41]
	v_mfma_f32_16x16x32_bf16 v[34:37], v[176:179], v[204:207], v[34:37]
	v_mfma_f32_16x16x32_bf16 v[22:25], v[164:167], v[212:215], v[22:25]
	v_mfma_f32_16x16x32_bf16 v[18:21], v[176:179], v[212:215], v[18:21]
	v_mfma_f32_16x16x32_bf16 v[6:9], v[164:167], v[220:223], v[6:9]
	v_mfma_f32_16x16x32_bf16 v[2:5], v[176:179], v[220:223], v[2:5]
	s_setprio 0
	s_barrier
; #define PG8_STAGE(bufoff, gbase, voff) do { _Pragma("unroll") for (int _i = 0; _i < 2; ++_i) \
;         __builtin_amdgcn_global_load_lds((const unsigned*)((const char*)(gbase) + (voff)[_i]), (PG8_LAS unsigned*)(lds + (bufoff) + ldsw + _i * 8192), 16, 0, 0); } while (0)
; #define PG8_LDA(dst, b, h) do { _Pragma("unroll") for (int m = 0; m < 4; ++m) _Pragma("unroll") for (int k = 0; k < 2; ++k) dst[m][k] = *(const PG8_LAS bf16x8*)(lds + PG8_SA(b, h) + aoff + m * 2048 + k * 1024); } while (0)
; #define PG8_LDB(dst, b, h) do { _Pragma("unroll") for (int n = 0; n < 2; ++n) _Pragma("unroll") for (int k = 0; k < 2; ++k) dst[n][k] = *(const PG8_LAS bf16x8*)(lds + PG8_SB(b, h) + boff + n * 2048 + k * 1024); } while (0)
; #define PG8_MMA(ai, bj, At, Bt) do { __builtin_amdgcn_s_setprio(1); _Pragma("unroll") for (int m = 0; m < 4; ++m) _Pragma("unroll") for (int n = 0; n < 2; ++n) _Pragma("unroll") for (int k = 0; k < 2; ++k) \
;         acc[ai][bj][m][n] = __builtin_amdgcn_mfma_f32_16x16x32_bf16(Bt[n][k], At[m][k], acc[ai][bj][m][n], 0, 0, 0); __builtin_amdgcn_s_setprio(0); } while (0)
; #define PG8_WAIT_V(n) asm volatile("s_waitcnt vmcnt(" #n ")" ::: "memory")
; #define PG8_WAIT_L(n) asm volatile("s_waitcnt lgkmcnt(" #n ")" ::: "memory")
; #define PG8_BAR __builtin_amdgcn_s_barrier()
; #define PG8_SCHED __builtin_amdgcn_sched_barrier(0)
; template <class Epi, class Sched, bool ALIGN_EPI = false, bool SP2 = false, bool ABLK = false, bool BBLK = false>
; __device__ __forceinline__ void gemm_phase(PG8_LAS unsigned char* lds, const Gemm g, const Sched& S, const Epi& E) {
;     ...
;             PG8_LDB(B0, 1, 0); PG8_LDB(B1, 1, 1); PG8_SCHED; PG8_LDA(At, 1, 0); PG8_STAGE(PG8_SA(0, 1), a2 + hstepA, voffA);
;             PG8_WAIT_V(8); PG8_WAIT_L(0); PG8_BAR; PG8_MMA(0, 0, At, B0); PG8_MMA(0, 1, At, B1); PG8_BAR; PG8_SCHED;
	s_add_i32 s60, 0, 0x18000
	s_add_i32 s61, 0, 0x1c000
	v_add_u32_e32 v142, s60, v169
	v_add_u32_e32 v171, s61, v169
	ds_read_b128 v[130:133], v142
	ds_read_b128 v[134:137], v142 offset:1024
	ds_read_b128 v[138:141], v142 offset:2048
	ds_read_b128 v[142:145], v142 offset:3072
	ds_read_b128 v[160:163], v171
	ds_read_b128 v[164:167], v171 offset:1024
	ds_read_b128 v[172:175], v171 offset:2048
	ds_read_b128 v[176:179], v171 offset:3072
	s_add_u32 s36, s36, 0x4000
	s_addc_u32 s37, s37, 0
	s_mov_b32 m0, s86
	v_lshl_add_u64 v[184:185], s[36:37], 0, v[146:147]
	ds_read_b128 v[180:183], v170 offset:32768
	ds_read_b128 v[196:199], v170 offset:33792
	ds_read_b128 v[200:203], v170 offset:34816
	ds_read_b128 v[204:207], v170 offset:35840
	ds_read_b128 v[208:211], v170 offset:36864
	ds_read_b128 v[212:215], v170 offset:37888
	ds_read_b128 v[216:219], v170 offset:38912
	ds_read_b128 v[220:223], v170 offset:39936
	global_load_lds_dwordx4 v[184:185], off
	v_lshl_add_u64 v[184:185], s[36:37], 0, v[150:151]
	s_mov_b32 m0, s88
	s_nop 0
	global_load_lds_dwordx4 v[184:185], off
	s_waitcnt vmcnt(8)
	s_waitcnt lgkmcnt(0)
	s_barrier
	s_setprio 1
	s_waitcnt lgkmcnt(0)
	v_mfma_f32_16x16x32_bf16 v[126:129], v[130:133], v[180:183], v[126:129]
	v_mfma_f32_16x16x32_bf16 v[122:125], v[138:141], v[180:183], v[122:125]
	v_mfma_f32_16x16x32_bf16 v[110:113], v[130:133], v[200:203], v[110:113]
	v_mfma_f32_16x16x32_bf16 v[106:109], v[138:141], v[200:203], v[106:109]
	v_mfma_f32_16x16x32_bf16 v[94:97], v[130:133], v[208:211], v[94:97]
	v_mfma_f32_16x16x32_bf16 v[90:93], v[138:141], v[208:211], v[90:93]
	v_mfma_f32_16x16x32_bf16 v[78:81], v[130:133], v[216:219], v[78:81]
	v_mfma_f32_16x16x32_bf16 v[74:77], v[138:141], v[216:219], v[74:77]
	v_mfma_f32_16x16x32_bf16 v[126:129], v[134:137], v[196:199], v[126:129]
	v_mfma_f32_16x16x32_bf16 v[122:125], v[142:145], v[196:199], v[122:125]
	v_mfma_f32_16x16x32_bf16 v[110:113], v[134:137], v[204:207], v[110:113]
	v_mfma_f32_16x16x32_bf16 v[106:109], v[142:145], v[204:207], v[106:109]
	v_mfma_f32_16x16x32_bf16 v[94:97], v[134:137], v[212:215], v[94:97]
	v_mfma_f32_16x16x32_bf16 v[90:93], v[142:145], v[212:215], v[90:93]
	v_mfma_f32_16x16x32_bf16 v[78:81], v[134:137], v[220:223], v[78:81]
	v_mfma_f32_16x16x32_bf16 v[74:77], v[142:145], v[220:223], v[74:77]
	s_setprio 0
	s_setprio 1
	v_mfma_f32_16x16x32_bf16 v[118:121], v[160:163], v[180:183], v[118:121]
	v_mfma_f32_16x16x32_bf16 v[114:117], v[172:175], v[180:183], v[114:117]
	v_mfma_f32_16x16x32_bf16 v[102:105], v[160:163], v[200:203], v[102:105]
	v_mfma_f32_16x16x32_bf16 v[98:101], v[172:175], v[200:203], v[98:101]
	v_mfma_f32_16x16x32_bf16 v[86:89], v[160:163], v[208:211], v[86:89]
	v_mfma_f32_16x16x32_bf16 v[82:85], v[172:175], v[208:211], v[82:85]
	v_mfma_f32_16x16x32_bf16 v[70:73], v[160:163], v[216:219], v[70:73]
	v_mfma_f32_16x16x32_bf16 v[66:69], v[172:175], v[216:219], v[66:69]
	v_mfma_f32_16x16x32_bf16 v[118:121], v[164:167], v[196:199], v[118:121]
	v_mfma_f32_16x16x32_bf16 v[114:117], v[176:179], v[196:199], v[114:117]
	v_mfma_f32_16x16x32_bf16 v[102:105], v[164:167], v[204:207], v[102:105]
	v_mfma_f32_16x16x32_bf16 v[98:101], v[176:179], v[204:207], v[98:101]
	v_mfma_f32_16x16x32_bf16 v[86:89], v[164:167], v[212:215], v[86:89]
	v_mfma_f32_16x16x32_bf16 v[82:85], v[176:179], v[212:215], v[82:85]
	v_mfma_f32_16x16x32_bf16 v[70:73], v[164:167], v[220:223], v[70:73]
	v_mfma_f32_16x16x32_bf16 v[66:69], v[176:179], v[220:223], v[66:69]
	s_setprio 0
	s_barrier
; #define PG8_STAGE(bufoff, gbase, voff) do { _Pragma("unroll") for (int _i = 0; _i < 2; ++_i) \
;         __builtin_amdgcn_global_load_lds((const unsigned*)((const char*)(gbase) + (voff)[_i]), (PG8_LAS unsigned*)(lds + (bufoff) + ldsw + _i * 8192), 16, 0, 0); } while (0)
; #define PG8_LDA(dst, b, h) do { _Pragma("unroll") for (int m = 0; m < 4; ++m) _Pragma("unroll") for (int k = 0; k < 2; ++k) dst[m][k] = *(const PG8_LAS bf16x8*)(lds + PG8_SA(b, h) + aoff + m * 2048 + k * 1024); } while (0)
; #define PG8_MMA(ai, bj, At, Bt) do { __builtin_amdgcn_s_setprio(1); _Pragma("unroll") for (int m = 0; m < 4; ++m) _Pragma("unroll") for (int n = 0; n < 2; ++n) _Pragma("unroll") for (int k = 0; k < 2; ++k) \
;         acc[ai][bj][m][n] = __builtin_amdgcn_mfma_f32_16x16x32_bf16(Bt[n][k], At[m][k], acc[ai][bj][m][n], 0, 0, 0); __builtin_amdgcn_s_setprio(0); } while (0)
; #define PG8_WAIT_V(n) asm volatile("s_waitcnt vmcnt(" #n ")" ::: "memory")
; #define PG8_WAIT_L(n) asm volatile("s_waitcnt lgkmcnt(" #n ")" ::: "memory")
; #define PG8_BAR __builtin_amdgcn_s_barrier()
; #define PG8_SCHED __builtin_amdgcn_sched_barrier(0)
; template <class Epi, class Sched, bool ALIGN_EPI = false, bool SP2 = false, bool ABLK = false, bool BBLK = false>
; __device__ __forceinline__ void gemm_phase(PG8_LAS unsigned char* lds, const Gemm g, const Sched& S, const Epi& E) {
;     ...
;             PG8_LDA(At, 1, 1); PG8_STAGE(PG8_SB(1, 0), b3, voffB); PG8_STAGE(PG8_SB(1, 1), b3 + hstepB, voffB); PG8_STAGE(PG8_SA(1, 0), a3, voffA);
;             PG8_WAIT_V(8); PG8_WAIT_L(0); PG8_BAR; PG8_MMA(1, 0, At, B0); PG8_MMA(1, 1, At, B1); PG8_BAR; PG8_SCHED;
;     ...
;         if constexpr (ALIGN_EPI) { if (wr == 0) PG8_BAR; }
	s_add_u32 s36, s34, 0x8000
	s_addc_u32 s37, s35, 0
	s_add_i32 s60, s60, s81
	v_lshl_add_u64 v[184:185], s[36:37], 0, v[148:149]
	s_mov_b32 m0, s60
	ds_read_b128 v[180:183], v170 offset:49152
	ds_read_b128 v[196:199], v170 offset:50176
	ds_read_b128 v[200:203], v170 offset:51200
	ds_read_b128 v[204:207], v170 offset:52224
	ds_read_b128 v[208:211], v170 offset:53248
	ds_read_b128 v[212:215], v170 offset:54272
	ds_read_b128 v[216:219], v170 offset:55296
	ds_read_b128 v[220:223], v170 offset:56320
	global_load_lds_dwordx4 v[184:185], off
	s_add_i32 m0, s60, 0x2000
	s_add_u32 s34, s34, 0xc000
	v_lshl_add_u64 v[184:185], s[36:37], 0, v[152:153]
	s_addc_u32 s35, s35, 0
	s_add_i32 s36, s61, s81
	global_load_lds_dwordx4 v[184:185], off
	v_lshl_add_u64 v[184:185], s[34:35], 0, v[148:149]
	s_mov_b32 m0, s36
	s_nop 0
	global_load_lds_dwordx4 v[184:185], off
	v_lshl_add_u64 v[184:185], s[34:35], 0, v[152:153]
	s_add_i32 m0, s36, 0x2000
	s_nop 0
	global_load_lds_dwordx4 v[184:185], off
	v_lshl_add_u64 v[184:185], s[30:31], 0, v[146:147]
	s_mov_b32 m0, s90
	s_nop 0
	global_load_lds_dwordx4 v[184:185], off
	v_lshl_add_u64 v[184:185], s[30:31], 0, v[150:151]
	s_mov_b32 m0, s91
	s_nop 0
	global_load_lds_dwordx4 v[184:185], off
	s_waitcnt vmcnt(8)
	s_waitcnt lgkmcnt(0)
	s_barrier
	s_setprio 1
	s_waitcnt lgkmcnt(0)
	v_mfma_f32_16x16x32_bf16 v[62:65], v[130:133], v[180:183], v[62:65]
	v_mfma_f32_16x16x32_bf16 v[58:61], v[138:141], v[180:183], v[58:61]
	v_mfma_f32_16x16x32_bf16 v[46:49], v[130:133], v[200:203], v[46:49]
	v_mfma_f32_16x16x32_bf16 v[42:45], v[138:141], v[200:203], v[42:45]
	v_mfma_f32_16x16x32_bf16 v[30:33], v[130:133], v[208:211], v[30:33]
	v_mfma_f32_16x16x32_bf16 v[26:29], v[138:141], v[208:211], v[26:29]
	v_mfma_f32_16x16x32_bf16 v[14:17], v[130:133], v[216:219], v[14:17]
	v_mfma_f32_16x16x32_bf16 v[10:13], v[138:141], v[216:219], v[10:13]
	v_mfma_f32_16x16x32_bf16 v[62:65], v[134:137], v[196:199], v[62:65]
	v_mfma_f32_16x16x32_bf16 v[58:61], v[142:145], v[196:199], v[58:61]
	v_mfma_f32_16x16x32_bf16 v[46:49], v[134:137], v[204:207], v[46:49]
	v_mfma_f32_16x16x32_bf16 v[42:45], v[142:145], v[204:207], v[42:45]
	v_mfma_f32_16x16x32_bf16 v[30:33], v[134:137], v[212:215], v[30:33]
	v_mfma_f32_16x16x32_bf16 v[26:29], v[142:145], v[212:215], v[26:29]
	v_mfma_f32_16x16x32_bf16 v[14:17], v[134:137], v[220:223], v[14:17]
	v_mfma_f32_16x16x32_bf16 v[10:13], v[142:145], v[220:223], v[10:13]
	s_setprio 0
	s_setprio 1
	v_mfma_f32_16x16x32_bf16 v[54:57], v[160:163], v[180:183], v[54:57]
	v_mfma_f32_16x16x32_bf16 v[50:53], v[172:175], v[180:183], v[50:53]
	v_mfma_f32_16x16x32_bf16 v[38:41], v[160:163], v[200:203], v[38:41]
	v_mfma_f32_16x16x32_bf16 v[34:37], v[172:175], v[200:203], v[34:37]
	v_mfma_f32_16x16x32_bf16 v[22:25], v[160:163], v[208:211], v[22:25]
	v_mfma_f32_16x16x32_bf16 v[18:21], v[172:175], v[208:211], v[18:21]
	v_mfma_f32_16x16x32_bf16 v[6:9], v[160:163], v[216:219], v[6:9]
	v_mfma_f32_16x16x32_bf16 v[2:5], v[172:175], v[216:219], v[2:5]
	v_mfma_f32_16x16x32_bf16 v[54:57], v[164:167], v[196:199], v[54:57]
	v_mfma_f32_16x16x32_bf16 v[50:53], v[176:179], v[196:199], v[50:53]
	v_mfma_f32_16x16x32_bf16 v[38:41], v[164:167], v[204:207], v[38:41]
	v_mfma_f32_16x16x32_bf16 v[34:37], v[176:179], v[204:207], v[34:37]
	v_mfma_f32_16x16x32_bf16 v[22:25], v[164:167], v[212:215], v[22:25]
	v_mfma_f32_16x16x32_bf16 v[18:21], v[176:179], v[212:215], v[18:21]
	v_mfma_f32_16x16x32_bf16 v[6:9], v[164:167], v[220:223], v[6:9]
	v_mfma_f32_16x16x32_bf16 v[2:5], v[176:179], v[220:223], v[2:5]
	s_setprio 0
	s_barrier
	s_add_i32 s41, s41, 2
	s_add_u32 s0, s0, 0x10000
	s_addc_u32 s1, s1, 0
	s_add_u32 s29, s29, 0x10000
	s_addc_u32 s40, s40, 0
	s_cmp_gt_u32 s41, 29
	s_cbranch_scc0 .LBB0_594
	s_and_b64 vcc, exec, s[18:19]
	s_cbranch_vccz .LBB0_597
	s_barrier

; #define PG8_STAGE(bufoff, gbase, voff) do { _Pragma("unroll") for (int _i = 0; _i < 2; ++_i) \
;         __builtin_amdgcn_global_load_lds((const unsigned*)((const char*)(gbase) + (voff)[_i]), (PG8_LAS unsigned*)(lds + (bufoff) + ldsw + _i * 8192), 16, 0, 0); } while (0)
; #define PG8_LDA(dst, b, h) do { _Pragma("unroll") for (int m = 0; m < 4; ++m) _Pragma("unroll") for (int k = 0; k < 2; ++k) dst[m][k] = *(const PG8_LAS bf16x8*)(lds + PG8_SA(b, h) + aoff + m * 2048 + k * 1024); } while (0)
; #define PG8_LDB(dst, b, h) do { _Pragma("unroll") for (int n = 0; n < 2; ++n) _Pragma("unroll") for (int k = 0; k < 2; ++k) dst[n][k] = *(const PG8_LAS bf16x8*)(lds + PG8_SB(b, h) + boff + n * 2048 + k * 1024); } while (0)
; #define PG8_WAIT_V(n) asm volatile("s_waitcnt vmcnt(" #n ")" ::: "memory")
; #define PG8_WAIT_L(n) asm volatile("s_waitcnt lgkmcnt(" #n ")" ::: "memory")
; #define PG8_BAR __builtin_amdgcn_s_barrier()
; template <class Epi, class Sched, bool ALIGN_EPI = false, bool SP2 = false, bool ABLK = false, bool BBLK = false>
; __device__ __forceinline__ void gemm_phase(PG8_LAS unsigned char* lds, const Gemm g, const Sched& S, const Epi& E) {
;     ...
;         const bool has_next = S.next(ui + 1, nxt);
;         const char* nA = has_next ? (const char*)g.A + (size_t)nxt.pm * tstepA : cA; const char* nB = has_next ? (const char*)g.Bt + (size_t)nxt.pn * tstepB : cB;
;         for (int t = 0; t < nt; t += 2) {
;             const bool last = (t == nt - 2);
;             const char* a1 = cA + (size_t)(t + 1) * kstepA;
;             const char* a2 = last ? nA : cA + (size_t)(t + 2) * kstepA; const char* b2 = last ? nB : cB + (size_t)(t + 2) * kstepB;
;             const char* a3 = a2 + kstepA; const char* b3 = b2 + kstepB;
;             if (last && has_next) S.a_ready(nxt);
;             if constexpr (SP2) {
;             PG8_LDB(B0, 0, 0); PG8_LDB(B1, 0, 1); PG8_SCHED; PG8_LDA(At, 0, 0); PG8_STAGE(PG8_SA(1, 1), a1 + hstepA, voffA);
;             PG8_WAIT_V(8); PG8_WAIT_L(0); PG8_BAR; PG8_MMA(0, 0, At, B0); PG8_MMA(0, 1, At, B1); PG8_BAR; PG8_SCHED;
;     ...
;         for (int a = 0; a < 2; ++a)
; #pragma unroll
;             for (int b = 0; b < 2; ++b)
; #pragma unroll
;                 for (int m = 0; m < 4; ++m)
; #pragma unroll
;                     for (int n = 0; n < 2; ++n) acc[a][b][m][n] = (f32x4){0.f, 0.f, 0.f, 0.f};
.LBB0_657:
	s_ashr_i32 s13, s12, 31
	s_lshl_b64 s[14:15], s[12:13], 20
	s_add_u32 s14, s31, s14
	s_addc_u32 s15, s33, s15
	s_and_b64 s[18:19], s[6:7], exec
	s_cselect_b32 s13, s15, s23
	s_cselect_b32 s61, s14, s22
	s_ashr_i32 s1, s0, 31
	s_lshl_b64 s[18:19], s[0:1], 20
	s_add_u32 s18, s51, s18
	s_addc_u32 s19, s53, s19
	s_and_b64 s[26:27], s[6:7], exec
	s_cselect_b32 s1, s19, s25
	s_cselect_b32 s65, s18, s24
	s_add_u32 s22, s22, 0xc000
	s_addc_u32 s23, s23, 0
	s_add_u32 s68, s24, 0x10000
	v_mov_b32_e32 v2, 0
	s_addc_u32 s72, s25, 0
	s_mov_b32 s73, -2
	s_add_u32 s24, s22, 0x4000
	s_addc_u32 s25, s23, 0
	s_cmp_eq_u32 s73, 28
	s_cselect_b32 s28, s61, s24
	s_cselect_b32 s29, s13, s25
	s_cselect_b32 s26, s65, s68
	s_cselect_b32 s27, s1, s72
	s_add_u32 s24, s28, 0x8000
	s_addc_u32 s25, s29, 0
	s_add_i32 s75, 0, 0x10000
	s_add_i32 s82, 0, 0x14000
	v_add_u32_e32 v158, s75, v147
	v_add_u32_e32 v174, s82, v147
	ds_read_b128 v[142:145], v158
	v_pk_mov_b32 v[2:3], 0, 0
	v_pk_mov_b32 v[4:5], 0, 0
	v_pk_mov_b32 v[6:7], 0, 0
	v_pk_mov_b32 v[8:9], 0, 0
	ds_read_b128 v[150:153], v158 offset:1024
	v_pk_mov_b32 v[10:11], 0, 0
	v_pk_mov_b32 v[12:13], 0, 0
	v_pk_mov_b32 v[14:15], 0, 0
	v_pk_mov_b32 v[16:17], 0, 0
	ds_read_b128 v[154:157], v158 offset:2048
	v_pk_mov_b32 v[18:19], 0, 0
	v_pk_mov_b32 v[20:21], 0, 0
	v_pk_mov_b32 v[22:23], 0, 0
	v_pk_mov_b32 v[24:25], 0, 0
	ds_read_b128 v[158:161], v158 offset:3072
	v_pk_mov_b32 v[26:27], 0, 0
	v_pk_mov_b32 v[28:29], 0, 0
	v_pk_mov_b32 v[30:31], 0, 0
	v_pk_mov_b32 v[32:33], 0, 0
	ds_read_b128 v[162:165], v174
	v_pk_mov_b32 v[34:35], 0, 0
	v_pk_mov_b32 v[36:37], 0, 0
	v_pk_mov_b32 v[38:39], 0, 0
	v_pk_mov_b32 v[40:41], 0, 0
	ds_read_b128 v[166:169], v174 offset:1024
	v_pk_mov_b32 v[42:43], 0, 0
	v_pk_mov_b32 v[44:45], 0, 0
	v_pk_mov_b32 v[46:47], 0, 0
	v_pk_mov_b32 v[48:49], 0, 0
	ds_read_b128 v[170:173], v174 offset:2048
	v_pk_mov_b32 v[50:51], 0, 0
	v_pk_mov_b32 v[52:53], 0, 0
	v_pk_mov_b32 v[54:55], 0, 0
	v_pk_mov_b32 v[56:57], 0, 0
	ds_read_b128 v[174:177], v174 offset:3072
	v_pk_mov_b32 v[58:59], 0, 0
	v_pk_mov_b32 v[60:61], 0, 0
	v_pk_mov_b32 v[62:63], 0, 0
	v_pk_mov_b32 v[64:65], 0, 0
	v_lshl_add_u64 v[220:221], s[22:23], 0, v[138:139]
	s_add_i32 m0, s40, 0xc000
	ds_read_b128 v[178:181], v149
	v_pk_mov_b32 v[66:67], 0, 0
	v_pk_mov_b32 v[68:69], 0, 0
	v_pk_mov_b32 v[70:71], 0, 0
	v_pk_mov_b32 v[72:73], 0, 0
	ds_read_b128 v[182:185], v149 offset:1024
	v_pk_mov_b32 v[74:75], 0, 0
	v_pk_mov_b32 v[76:77], 0, 0
	v_pk_mov_b32 v[78:79], 0, 0
	v_pk_mov_b32 v[80:81], 0, 0
	ds_read_b128 v[196:199], v149 offset:2048
	v_pk_mov_b32 v[82:83], 0, 0
	v_pk_mov_b32 v[84:85], 0, 0
	v_pk_mov_b32 v[86:87], 0, 0
	v_pk_mov_b32 v[88:89], 0, 0
	ds_read_b128 v[200:203], v149 offset:3072
	v_pk_mov_b32 v[90:91], 0, 0
	v_pk_mov_b32 v[92:93], 0, 0
	v_pk_mov_b32 v[94:95], 0, 0
	v_pk_mov_b32 v[96:97], 0, 0
	ds_read_b128 v[204:207], v149 offset:4096
	v_pk_mov_b32 v[98:99], 0, 0
	v_pk_mov_b32 v[100:101], 0, 0
	v_pk_mov_b32 v[102:103], 0, 0
	v_pk_mov_b32 v[104:105], 0, 0
	ds_read_b128 v[208:211], v149 offset:5120
	v_pk_mov_b32 v[106:107], 0, 0
	v_pk_mov_b32 v[108:109], 0, 0
	v_pk_mov_b32 v[110:111], 0, 0
	v_pk_mov_b32 v[112:113], 0, 0
	ds_read_b128 v[212:215], v149 offset:6144
	v_pk_mov_b32 v[114:115], 0, 0
	v_pk_mov_b32 v[116:117], 0, 0
	v_pk_mov_b32 v[118:119], 0, 0
	v_pk_mov_b32 v[120:121], 0, 0
	ds_read_b128 v[216:219], v149 offset:7168
	v_pk_mov_b32 v[122:123], 0, 0
	v_pk_mov_b32 v[124:125], 0, 0
	v_pk_mov_b32 v[126:127], 0, 0
	v_pk_mov_b32 v[128:129], 0, 0
	global_load_lds_dwordx4 v[220:221], off
	v_lshl_add_u64 v[220:221], s[22:23], 0, v[140:141]
	s_add_i32 m0, s40, 0xe000
	s_nop 0
	global_load_lds_dwordx4 v[220:221], off
	s_waitcnt vmcnt(8)
	s_waitcnt lgkmcnt(0)
	s_barrier
	s_branch .Lpeel_658

; #define PG8_STAGE(bufoff, gbase, voff) do { _Pragma("unroll") for (int _i = 0; _i < 2; ++_i) \
;         __builtin_amdgcn_global_load_lds((const unsigned*)((const char*)(gbase) + (voff)[_i]), (PG8_LAS unsigned*)(lds + (bufoff) + ldsw + _i * 8192), 16, 0, 0); } while (0)
; #define PG8_LDA(dst, b, h) do { _Pragma("unroll") for (int m = 0; m < 4; ++m) _Pragma("unroll") for (int k = 0; k < 2; ++k) dst[m][k] = *(const PG8_LAS bf16x8*)(lds + PG8_SA(b, h) + aoff + m * 2048 + k * 1024); } while (0)
; #define PG8_MMA(ai, bj, At, Bt) do { __builtin_amdgcn_s_setprio(1); _Pragma("unroll") for (int m = 0; m < 4; ++m) _Pragma("unroll") for (int n = 0; n < 2; ++n) _Pragma("unroll") for (int k = 0; k < 2; ++k) \
;         acc[ai][bj][m][n] = __builtin_amdgcn_mfma_f32_16x16x32_bf16(Bt[n][k], At[m][k], acc[ai][bj][m][n], 0, 0, 0); __builtin_amdgcn_s_setprio(0); } while (0)
; #define PG8_WAIT_V(n) asm volatile("s_waitcnt vmcnt(" #n ")" ::: "memory")
; #define PG8_WAIT_L(n) asm volatile("s_waitcnt lgkmcnt(" #n ")" ::: "memory")
; #define PG8_BAR __builtin_amdgcn_s_barrier()
; #define PG8_SCHED __builtin_amdgcn_sched_barrier(0)
; template <class Epi, class Sched, bool ALIGN_EPI = false, bool SP2 = false, bool ABLK = false, bool BBLK = false>
; __device__ __forceinline__ void gemm_phase(PG8_LAS unsigned char* lds, const Gemm g, const Sched& S, const Epi& E) {
;     ...
;             PG8_WAIT_V(8); PG8_WAIT_L(0); PG8_BAR; PG8_MMA(0, 0, At, B0); PG8_MMA(0, 1, At, B1); PG8_BAR; PG8_SCHED;
;             PG8_LDA(At, 0, 1); PG8_STAGE(PG8_SB(0, 0), b2, voffB); PG8_STAGE(PG8_SB(0, 1), b2 + hstepB, voffB); PG8_STAGE(PG8_SA(0, 0), a2, voffA);
;             PG8_WAIT_V(8); PG8_WAIT_L(0); PG8_BAR; PG8_MMA(1, 0, At, B0); PG8_MMA(1, 1, At, B1); PG8_BAR; PG8_SCHED;
.Lpeel_658:
	s_setprio 1
	s_waitcnt lgkmcnt(0)
	v_mfma_f32_16x16x32_bf16 v[126:129], v[142:145], v[178:181], v[126:129]
	v_mfma_f32_16x16x32_bf16 v[122:125], v[154:157], v[178:181], v[122:125]
	v_mfma_f32_16x16x32_bf16 v[114:117], v[142:145], v[196:199], v[114:117]
	v_mfma_f32_16x16x32_bf16 v[106:109], v[154:157], v[196:199], v[106:109]
	v_mfma_f32_16x16x32_bf16 v[102:105], v[142:145], v[204:207], v[102:105]
	v_mfma_f32_16x16x32_bf16 v[94:97], v[154:157], v[204:207], v[94:97]
	v_mfma_f32_16x16x32_bf16 v[86:89], v[142:145], v[212:215], v[86:89]
	v_mfma_f32_16x16x32_bf16 v[78:81], v[154:157], v[212:215], v[78:81]
	v_mfma_f32_16x16x32_bf16 v[126:129], v[150:153], v[182:185], v[126:129]
	v_mfma_f32_16x16x32_bf16 v[122:125], v[158:161], v[182:185], v[122:125]
	v_mfma_f32_16x16x32_bf16 v[114:117], v[150:153], v[200:203], v[114:117]
	v_mfma_f32_16x16x32_bf16 v[106:109], v[158:161], v[200:203], v[106:109]
	v_mfma_f32_16x16x32_bf16 v[102:105], v[150:153], v[208:211], v[102:105]
	v_mfma_f32_16x16x32_bf16 v[94:97], v[158:161], v[208:211], v[94:97]
	v_mfma_f32_16x16x32_bf16 v[86:89], v[150:153], v[216:219], v[86:89]
	v_mfma_f32_16x16x32_bf16 v[78:81], v[158:161], v[216:219], v[78:81]
	s_setprio 0
	s_setprio 1
	v_mfma_f32_16x16x32_bf16 v[118:121], v[162:165], v[178:181], v[118:121]
	v_mfma_f32_16x16x32_bf16 v[110:113], v[170:173], v[178:181], v[110:113]
	v_mfma_f32_16x16x32_bf16 v[98:101], v[162:165], v[196:199], v[98:101]
	v_mfma_f32_16x16x32_bf16 v[90:93], v[170:173], v[196:199], v[90:93]
	v_mfma_f32_16x16x32_bf16 v[82:85], v[162:165], v[204:207], v[82:85]
	v_mfma_f32_16x16x32_bf16 v[74:77], v[170:173], v[204:207], v[74:77]
	v_mfma_f32_16x16x32_bf16 v[70:73], v[162:165], v[212:215], v[70:73]
	v_mfma_f32_16x16x32_bf16 v[66:69], v[170:173], v[212:215], v[66:69]
	v_mfma_f32_16x16x32_bf16 v[118:121], v[166:169], v[182:185], v[118:121]
	v_mfma_f32_16x16x32_bf16 v[110:113], v[174:177], v[182:185], v[110:113]
	v_mfma_f32_16x16x32_bf16 v[98:101], v[166:169], v[200:203], v[98:101]
	v_mfma_f32_16x16x32_bf16 v[90:93], v[174:177], v[200:203], v[90:93]
	v_mfma_f32_16x16x32_bf16 v[82:85], v[166:169], v[208:211], v[82:85]
	v_mfma_f32_16x16x32_bf16 v[74:77], v[174:177], v[208:211], v[74:77]
	v_mfma_f32_16x16x32_bf16 v[70:73], v[166:169], v[216:219], v[70:73]
	v_mfma_f32_16x16x32_bf16 v[66:69], v[174:177], v[216:219], v[66:69]
	s_setprio 0
	s_barrier
	s_add_i32 s75, s75, s37
	v_lshl_add_u64 v[220:221], s[26:27], 0, v[134:135]
	s_mov_b32 m0, s75
	ds_read_b128 v[178:181], v149 offset:16384
	ds_read_b128 v[182:185], v149 offset:17408
	ds_read_b128 v[196:199], v149 offset:18432
	ds_read_b128 v[200:203], v149 offset:19456
	ds_read_b128 v[204:207], v149 offset:20480
	ds_read_b128 v[208:211], v149 offset:21504
	ds_read_b128 v[212:215], v149 offset:22528
	ds_read_b128 v[216:219], v149 offset:23552
	global_load_lds_dwordx4 v[220:221], off
	s_add_i32 m0, s75, 0x2000
	s_add_u32 s80, s26, 0x4000
	v_lshl_add_u64 v[220:221], s[26:27], 0, v[130:131]
	s_addc_u32 s81, s27, 0
	s_add_i32 s75, s82, s37
	global_load_lds_dwordx4 v[220:221], off
	v_lshl_add_u64 v[220:221], s[80:81], 0, v[134:135]
	s_mov_b32 m0, s75
	s_nop 0
	global_load_lds_dwordx4 v[220:221], off
	v_lshl_add_u64 v[220:221], s[80:81], 0, v[130:131]
	s_add_i32 m0, s75, 0x2000
	s_nop 0
	global_load_lds_dwordx4 v[220:221], off
	v_lshl_add_u64 v[220:221], s[28:29], 0, v[136:137]
	s_mov_b32 m0, s40
	s_nop 0
	global_load_lds_dwordx4 v[220:221], off
	v_lshl_add_u64 v[220:221], s[28:29], 0, v[132:133]
	s_mov_b32 m0, s41
	s_nop 0
	global_load_lds_dwordx4 v[220:221], off
	s_waitcnt vmcnt(8)
	s_waitcnt lgkmcnt(0)
	s_barrier
	s_setprio 1
	s_waitcnt lgkmcnt(0)
	v_mfma_f32_16x16x32_bf16 v[62:65], v[142:145], v[178:181], v[62:65]
	v_mfma_f32_16x16x32_bf16 v[58:61], v[154:157], v[178:181], v[58:61]
	v_mfma_f32_16x16x32_bf16 v[50:53], v[142:145], v[196:199], v[50:53]
	v_mfma_f32_16x16x32_bf16 v[42:45], v[154:157], v[196:199], v[42:45]
	v_mfma_f32_16x16x32_bf16 v[38:41], v[142:145], v[204:207], v[38:41]
	v_mfma_f32_16x16x32_bf16 v[30:33], v[154:157], v[204:207], v[30:33]
	v_mfma_f32_16x16x32_bf16 v[22:25], v[142:145], v[212:215], v[22:25]
	v_mfma_f32_16x16x32_bf16 v[14:17], v[154:157], v[212:215], v[14:17]
	v_mfma_f32_16x16x32_bf16 v[62:65], v[150:153], v[182:185], v[62:65]
	v_mfma_f32_16x16x32_bf16 v[58:61], v[158:161], v[182:185], v[58:61]
	v_mfma_f32_16x16x32_bf16 v[50:53], v[150:153], v[200:203], v[50:53]
	v_mfma_f32_16x16x32_bf16 v[42:45], v[158:161], v[200:203], v[42:45]
	v_mfma_f32_16x16x32_bf16 v[38:41], v[150:153], v[208:211], v[38:41]
	v_mfma_f32_16x16x32_bf16 v[30:33], v[158:161], v[208:211], v[30:33]
	v_mfma_f32_16x16x32_bf16 v[22:25], v[150:153], v[216:219], v[22:25]
	v_mfma_f32_16x16x32_bf16 v[14:17], v[158:161], v[216:219], v[14:17]
	s_setprio 0
	s_setprio 1
	v_mfma_f32_16x16x32_bf16 v[54:57], v[162:165], v[178:181], v[54:57]
	v_mfma_f32_16x16x32_bf16 v[46:49], v[170:173], v[178:181], v[46:49]
	v_mfma_f32_16x16x32_bf16 v[34:37], v[162:165], v[196:199], v[34:37]
	v_mfma_f32_16x16x32_bf16 v[26:29], v[170:173], v[196:199], v[26:29]
	v_mfma_f32_16x16x32_bf16 v[18:21], v[162:165], v[204:207], v[18:21]
	v_mfma_f32_16x16x32_bf16 v[10:13], v[170:173], v[204:207], v[10:13]
	v_mfma_f32_16x16x32_bf16 v[6:9], v[162:165], v[212:215], v[6:9]
	v_mfma_f32_16x16x32_bf16 v[2:5], v[170:173], v[212:215], v[2:5]
	v_mfma_f32_16x16x32_bf16 v[54:57], v[166:169], v[182:185], v[54:57]
	v_mfma_f32_16x16x32_bf16 v[46:49], v[174:177], v[182:185], v[46:49]
	v_mfma_f32_16x16x32_bf16 v[34:37], v[166:169], v[200:203], v[34:37]
	v_mfma_f32_16x16x32_bf16 v[26:29], v[174:177], v[200:203], v[26:29]
	v_mfma_f32_16x16x32_bf16 v[18:21], v[166:169], v[208:211], v[18:21]
	v_mfma_f32_16x16x32_bf16 v[10:13], v[174:177], v[208:211], v[10:13]
	v_mfma_f32_16x16x32_bf16 v[6:9], v[166:169], v[216:219], v[6:9]
	v_mfma_f32_16x16x32_bf16 v[2:5], v[174:177], v[216:219], v[2:5]
	s_setprio 0
	s_barrier
; #define PG8_STAGE(bufoff, gbase, voff) do { _Pragma("unroll") for (int _i = 0; _i < 2; ++_i) \
;         __builtin_amdgcn_global_load_lds((const unsigned*)((const char*)(gbase) + (voff)[_i]), (PG8_LAS unsigned*)(lds + (bufoff) + ldsw + _i * 8192), 16, 0, 0); } while (0)
; #define PG8_LDA(dst, b, h) do { _Pragma("unroll") for (int m = 0; m < 4; ++m) _Pragma("unroll") for (int k = 0; k < 2; ++k) dst[m][k] = *(const PG8_LAS bf16x8*)(lds + PG8_SA(b, h) + aoff + m * 2048 + k * 1024); } while (0)
; #define PG8_LDB(dst, b, h) do { _Pragma("unroll") for (int n = 0; n < 2; ++n) _Pragma("unroll") for (int k = 0; k < 2; ++k) dst[n][k] = *(const PG8_LAS bf16x8*)(lds + PG8_SB(b, h) + boff + n * 2048 + k * 1024); } while (0)
; #define PG8_MMA(ai, bj, At, Bt) do { __builtin_amdgcn_s_setprio(1); _Pragma("unroll") for (int m = 0; m < 4; ++m) _Pragma("unroll") for (int n = 0; n < 2; ++n) _Pragma("unroll") for (int k = 0; k < 2; ++k) \
;         acc[ai][bj][m][n] = __builtin_amdgcn_mfma_f32_16x16x32_bf16(Bt[n][k], At[m][k], acc[ai][bj][m][n], 0, 0, 0); __builtin_amdgcn_s_setprio(0); } while (0)
; #define PG8_WAIT_V(n) asm volatile("s_waitcnt vmcnt(" #n ")" ::: "memory")
; #define PG8_WAIT_L(n) asm volatile("s_waitcnt lgkmcnt(" #n ")" ::: "memory")
; #define PG8_BAR __builtin_amdgcn_s_barrier()
; #define PG8_SCHED __builtin_amdgcn_sched_barrier(0)
; template <class Epi, class Sched, bool ALIGN_EPI = false, bool SP2 = false, bool ABLK = false, bool BBLK = false>
; __device__ __forceinline__ void gemm_phase(PG8_LAS unsigned char* lds, const Gemm g, const Sched& S, const Epi& E) {
;     ...
;             PG8_LDB(B0, 1, 0); PG8_LDB(B1, 1, 1); PG8_SCHED; PG8_LDA(At, 1, 0); PG8_STAGE(PG8_SA(0, 1), a2 + hstepA, voffA);
;             PG8_WAIT_V(8); PG8_WAIT_L(0); PG8_BAR; PG8_MMA(0, 0, At, B0); PG8_MMA(0, 1, At, B1); PG8_BAR; PG8_SCHED;
	s_add_i32 s75, 0, 0x18000
	s_add_i32 s80, 0, 0x1c000
	v_add_u32_e32 v158, s75, v147
	v_add_u32_e32 v174, s80, v147
	ds_read_b128 v[142:145], v158
	ds_read_b128 v[150:153], v158 offset:1024
	ds_read_b128 v[154:157], v158 offset:2048
	ds_read_b128 v[158:161], v158 offset:3072
	ds_read_b128 v[162:165], v174
	ds_read_b128 v[166:169], v174 offset:1024
	ds_read_b128 v[170:173], v174 offset:2048
	ds_read_b128 v[174:177], v174 offset:3072
	s_add_u32 s28, s28, 0x4000
	s_addc_u32 s29, s29, 0
	s_mov_b32 m0, s44
	v_lshl_add_u64 v[220:221], s[28:29], 0, v[136:137]
	ds_read_b128 v[178:181], v149 offset:32768
	ds_read_b128 v[182:185], v149 offset:33792
	ds_read_b128 v[196:199], v149 offset:34816
	ds_read_b128 v[200:203], v149 offset:35840
	ds_read_b128 v[204:207], v149 offset:36864
	ds_read_b128 v[208:211], v149 offset:37888
	ds_read_b128 v[212:215], v149 offset:38912
	ds_read_b128 v[216:219], v149 offset:39936
	global_load_lds_dwordx4 v[220:221], off
	v_lshl_add_u64 v[220:221], s[28:29], 0, v[132:133]
	s_mov_b32 m0, s45
	s_nop 0
	global_load_lds_dwordx4 v[220:221], off
	s_waitcnt vmcnt(8)
	s_waitcnt lgkmcnt(0)
	s_barrier
	s_setprio 1
	s_waitcnt lgkmcnt(0)
	v_mfma_f32_16x16x32_bf16 v[126:129], v[142:145], v[178:181], v[126:129]
	v_mfma_f32_16x16x32_bf16 v[122:125], v[154:157], v[178:181], v[122:125]
	v_mfma_f32_16x16x32_bf16 v[114:117], v[142:145], v[196:199], v[114:117]
	v_mfma_f32_16x16x32_bf16 v[106:109], v[154:157], v[196:199], v[106:109]
	v_mfma_f32_16x16x32_bf16 v[102:105], v[142:145], v[204:207], v[102:105]
	v_mfma_f32_16x16x32_bf16 v[94:97], v[154:157], v[204:207], v[94:97]
	v_mfma_f32_16x16x32_bf16 v[86:89], v[142:145], v[212:215], v[86:89]
	v_mfma_f32_16x16x32_bf16 v[78:81], v[154:157], v[212:215], v[78:81]
	v_mfma_f32_16x16x32_bf16 v[126:129], v[150:153], v[182:185], v[126:129]
	v_mfma_f32_16x16x32_bf16 v[122:125], v[158:161], v[182:185], v[122:125]
	v_mfma_f32_16x16x32_bf16 v[114:117], v[150:153], v[200:203], v[114:117]
	v_mfma_f32_16x16x32_bf16 v[106:109], v[158:161], v[200:203], v[106:109]
	v_mfma_f32_16x16x32_bf16 v[102:105], v[150:153], v[208:211], v[102:105]
	v_mfma_f32_16x16x32_bf16 v[94:97], v[158:161], v[208:211], v[94:97]
	v_mfma_f32_16x16x32_bf16 v[86:89], v[150:153], v[216:219], v[86:89]
	v_mfma_f32_16x16x32_bf16 v[78:81], v[158:161], v[216:219], v[78:81]
	s_setprio 0
	s_setprio 1
	v_mfma_f32_16x16x32_bf16 v[118:121], v[162:165], v[178:181], v[118:121]
	v_mfma_f32_16x16x32_bf16 v[110:113], v[170:173], v[178:181], v[110:113]
	v_mfma_f32_16x16x32_bf16 v[98:101], v[162:165], v[196:199], v[98:101]
	v_mfma_f32_16x16x32_bf16 v[90:93], v[170:173], v[196:199], v[90:93]
	v_mfma_f32_16x16x32_bf16 v[82:85], v[162:165], v[204:207], v[82:85]
	v_mfma_f32_16x16x32_bf16 v[74:77], v[170:173], v[204:207], v[74:77]
	v_mfma_f32_16x16x32_bf16 v[70:73], v[162:165], v[212:215], v[70:73]
	v_mfma_f32_16x16x32_bf16 v[66:69], v[170:173], v[212:215], v[66:69]
	v_mfma_f32_16x16x32_bf16 v[118:121], v[166:169], v[182:185], v[118:121]
	v_mfma_f32_16x16x32_bf16 v[110:113], v[174:177], v[182:185], v[110:113]
	v_mfma_f32_16x16x32_bf16 v[98:101], v[166:169], v[200:203], v[98:101]
	v_mfma_f32_16x16x32_bf16 v[90:93], v[174:177], v[200:203], v[90:93]
	v_mfma_f32_16x16x32_bf16 v[82:85], v[166:169], v[208:211], v[82:85]
	v_mfma_f32_16x16x32_bf16 v[74:77], v[174:177], v[208:211], v[74:77]
	v_mfma_f32_16x16x32_bf16 v[70:73], v[166:169], v[216:219], v[70:73]
	v_mfma_f32_16x16x32_bf16 v[66:69], v[174:177], v[216:219], v[66:69]
	s_setprio 0
	s_barrier
; #define PG8_STAGE(bufoff, gbase, voff) do { _Pragma("unroll") for (int _i = 0; _i < 2; ++_i) \
;         __builtin_amdgcn_global_load_lds((const unsigned*)((const char*)(gbase) + (voff)[_i]), (PG8_LAS unsigned*)(lds + (bufoff) + ldsw + _i * 8192), 16, 0, 0); } while (0)
; #define PG8_LDA(dst, b, h) do { _Pragma("unroll") for (int m = 0; m < 4; ++m) _Pragma("unroll") for (int k = 0; k < 2; ++k) dst[m][k] = *(const PG8_LAS bf16x8*)(lds + PG8_SA(b, h) + aoff + m * 2048 + k * 1024); } while (0)
; #define PG8_MMA(ai, bj, At, Bt) do { __builtin_amdgcn_s_setprio(1); _Pragma("unroll") for (int m = 0; m < 4; ++m) _Pragma("unroll") for (int n = 0; n < 2; ++n) _Pragma("unroll") for (int k = 0; k < 2; ++k) \
;         acc[ai][bj][m][n] = __builtin_amdgcn_mfma_f32_16x16x32_bf16(Bt[n][k], At[m][k], acc[ai][bj][m][n], 0, 0, 0); __builtin_amdgcn_s_setprio(0); } while (0)
; #define PG8_WAIT_V(n) asm volatile("s_waitcnt vmcnt(" #n ")" ::: "memory")
; #define PG8_WAIT_L(n) asm volatile("s_waitcnt lgkmcnt(" #n ")" ::: "memory")
; #define PG8_BAR __builtin_amdgcn_s_barrier()
; #define PG8_SCHED __builtin_amdgcn_sched_barrier(0)
; template <class Epi, class Sched, bool ALIGN_EPI = false, bool SP2 = false, bool ABLK = false, bool BBLK = false>
; __device__ __forceinline__ void gemm_phase(PG8_LAS unsigned char* lds, const Gemm g, const Sched& S, const Epi& E) {
;     ...
;             PG8_LDA(At, 1, 1); PG8_STAGE(PG8_SB(1, 0), b3, voffB); PG8_STAGE(PG8_SB(1, 1), b3 + hstepB, voffB); PG8_STAGE(PG8_SA(1, 0), a3, voffA);
;             PG8_WAIT_V(8); PG8_WAIT_L(0); PG8_BAR; PG8_MMA(1, 0, At, B0); PG8_MMA(1, 1, At, B1); PG8_BAR; PG8_SCHED;
;     ...
;         if constexpr (ALIGN_EPI) { if (wr == 0) PG8_BAR; }
	s_add_u32 s28, s26, 0x8000
	s_addc_u32 s29, s27, 0
	s_add_i32 s75, s75, s37
	v_lshl_add_u64 v[220:221], s[28:29], 0, v[134:135]
	s_mov_b32 m0, s75
	ds_read_b128 v[178:181], v149 offset:49152
	ds_read_b128 v[182:185], v149 offset:50176
	ds_read_b128 v[196:199], v149 offset:51200
	ds_read_b128 v[200:203], v149 offset:52224
	ds_read_b128 v[204:207], v149 offset:53248
	ds_read_b128 v[208:211], v149 offset:54272
	ds_read_b128 v[212:215], v149 offset:55296
	ds_read_b128 v[216:219], v149 offset:56320
	global_load_lds_dwordx4 v[220:221], off
	s_add_i32 m0, s75, 0x2000
	s_add_u32 s26, s26, 0xc000
	v_lshl_add_u64 v[220:221], s[28:29], 0, v[130:131]
	s_addc_u32 s27, s27, 0
	s_add_i32 s28, s80, s37
	global_load_lds_dwordx4 v[220:221], off
	v_lshl_add_u64 v[220:221], s[26:27], 0, v[134:135]
	s_mov_b32 m0, s28
	s_nop 0
	global_load_lds_dwordx4 v[220:221], off
	v_lshl_add_u64 v[220:221], s[26:27], 0, v[130:131]
	s_add_i32 m0, s28, 0x2000
	s_nop 0
	global_load_lds_dwordx4 v[220:221], off
	v_lshl_add_u64 v[220:221], s[24:25], 0, v[136:137]
	s_mov_b32 m0, s46
	s_nop 0
	global_load_lds_dwordx4 v[220:221], off
	v_lshl_add_u64 v[220:221], s[24:25], 0, v[132:133]
	s_mov_b32 m0, s47
	s_nop 0
	global_load_lds_dwordx4 v[220:221], off
	s_waitcnt vmcnt(8)
	s_waitcnt lgkmcnt(0)
	s_barrier
	s_setprio 1
	s_waitcnt lgkmcnt(0)
	v_mfma_f32_16x16x32_bf16 v[62:65], v[142:145], v[178:181], v[62:65]
	v_mfma_f32_16x16x32_bf16 v[58:61], v[154:157], v[178:181], v[58:61]
	v_mfma_f32_16x16x32_bf16 v[50:53], v[142:145], v[196:199], v[50:53]
	v_mfma_f32_16x16x32_bf16 v[42:45], v[154:157], v[196:199], v[42:45]
	v_mfma_f32_16x16x32_bf16 v[38:41], v[142:145], v[204:207], v[38:41]
	v_mfma_f32_16x16x32_bf16 v[30:33], v[154:157], v[204:207], v[30:33]
	v_mfma_f32_16x16x32_bf16 v[22:25], v[142:145], v[212:215], v[22:25]
	v_mfma_f32_16x16x32_bf16 v[14:17], v[154:157], v[212:215], v[14:17]
	v_mfma_f32_16x16x32_bf16 v[62:65], v[150:153], v[182:185], v[62:65]
	v_mfma_f32_16x16x32_bf16 v[58:61], v[158:161], v[182:185], v[58:61]
	v_mfma_f32_16x16x32_bf16 v[50:53], v[150:153], v[200:203], v[50:53]
	v_mfma_f32_16x16x32_bf16 v[42:45], v[158:161], v[200:203], v[42:45]
	v_mfma_f32_16x16x32_bf16 v[38:41], v[150:153], v[208:211], v[38:41]
	v_mfma_f32_16x16x32_bf16 v[30:33], v[158:161], v[208:211], v[30:33]
	v_mfma_f32_16x16x32_bf16 v[22:25], v[150:153], v[216:219], v[22:25]
	v_mfma_f32_16x16x32_bf16 v[14:17], v[158:161], v[216:219], v[14:17]
	s_setprio 0
	s_setprio 1
	v_mfma_f32_16x16x32_bf16 v[54:57], v[162:165], v[178:181], v[54:57]
	v_mfma_f32_16x16x32_bf16 v[46:49], v[170:173], v[178:181], v[46:49]
	v_mfma_f32_16x16x32_bf16 v[34:37], v[162:165], v[196:199], v[34:37]
	v_mfma_f32_16x16x32_bf16 v[26:29], v[170:173], v[196:199], v[26:29]
	v_mfma_f32_16x16x32_bf16 v[18:21], v[162:165], v[204:207], v[18:21]
	v_mfma_f32_16x16x32_bf16 v[10:13], v[170:173], v[204:207], v[10:13]
	v_mfma_f32_16x16x32_bf16 v[6:9], v[162:165], v[212:215], v[6:9]
	v_mfma_f32_16x16x32_bf16 v[2:5], v[170:173], v[212:215], v[2:5]
	v_mfma_f32_16x16x32_bf16 v[54:57], v[166:169], v[182:185], v[54:57]
	v_mfma_f32_16x16x32_bf16 v[46:49], v[174:177], v[182:185], v[46:49]
	v_mfma_f32_16x16x32_bf16 v[34:37], v[166:169], v[200:203], v[34:37]
	v_mfma_f32_16x16x32_bf16 v[26:29], v[174:177], v[200:203], v[26:29]
	v_mfma_f32_16x16x32_bf16 v[18:21], v[166:169], v[208:211], v[18:21]
	v_mfma_f32_16x16x32_bf16 v[10:13], v[174:177], v[208:211], v[10:13]
	v_mfma_f32_16x16x32_bf16 v[6:9], v[166:169], v[216:219], v[6:9]
	v_mfma_f32_16x16x32_bf16 v[2:5], v[174:177], v[216:219], v[2:5]
	s_setprio 0
	s_barrier
	s_add_i32 s73, s73, 2
	s_add_u32 s22, s22, 0x10000
	s_addc_u32 s23, s23, 0
	s_add_u32 s68, s68, 0x10000
	s_addc_u32 s72, s72, 0
	s_cmp_gt_u32 s73, 29
	s_cbranch_scc0 .LBB0_658
	s_and_b64 vcc, exec, s[8:9]
	s_cbranch_vccz .LBB0_661
	s_barrier

; #define PG8_STAGE(bufoff, gbase, voff) do { _Pragma("unroll") for (int _i = 0; _i < 2; ++_i) \
;         __builtin_amdgcn_global_load_lds((const unsigned*)((const char*)(gbase) + (voff)[_i]), (PG8_LAS unsigned*)(lds + (bufoff) + ldsw + _i * 8192), 16, 0, 0); } while (0)
; #define PG8_LDA(dst, b, h) do { _Pragma("unroll") for (int m = 0; m < 4; ++m) _Pragma("unroll") for (int k = 0; k < 2; ++k) dst[m][k] = *(const PG8_LAS bf16x8*)(lds + PG8_SA(b, h) + aoff + m * 2048 + k * 1024); } while (0)
; #define PG8_LDB(dst, b, h) do { _Pragma("unroll") for (int n = 0; n < 2; ++n) _Pragma("unroll") for (int k = 0; k < 2; ++k) dst[n][k] = *(const PG8_LAS bf16x8*)(lds + PG8_SB(b, h) + boff + n * 2048 + k * 1024); } while (0)
; #define PG8_WAIT_V(n) asm volatile("s_waitcnt vmcnt(" #n ")" ::: "memory")
; #define PG8_WAIT_L(n) asm volatile("s_waitcnt lgkmcnt(" #n ")" ::: "memory")
; #define PG8_BAR __builtin_amdgcn_s_barrier()
; template <class Epi, class Sched, bool ALIGN_EPI = false, bool SP2 = false, bool ABLK = false, bool BBLK = false>
; __device__ __forceinline__ void gemm_phase(PG8_LAS unsigned char* lds, const Gemm g, const Sched& S, const Epi& E) {
;     ...
;         const bool has_next = S.next(ui + 1, nxt);
;         const char* nA = has_next ? (const char*)g.A + (size_t)nxt.pm * tstepA : cA; const char* nB = has_next ? (const char*)g.Bt + (size_t)nxt.pn * tstepB : cB;
;         for (int t = 0; t < nt; t += 2) {
;             const bool last = (t == nt - 2);
;             const char* a1 = cA + (size_t)(t + 1) * kstepA;
;             const char* a2 = last ? nA : cA + (size_t)(t + 2) * kstepA; const char* b2 = last ? nB : cB + (size_t)(t + 2) * kstepB;
;             const char* a3 = a2 + kstepA; const char* b3 = b2 + kstepB;
;             if (last && has_next) S.a_ready(nxt);
;             if constexpr (SP2) {
;             PG8_LDB(B0, 0, 0); PG8_LDB(B1, 0, 1); PG8_SCHED; PG8_LDA(At, 0, 0); PG8_STAGE(PG8_SA(1, 1), a1 + hstepA, voffA);
;             PG8_WAIT_V(8); PG8_WAIT_L(0); PG8_BAR; PG8_MMA(0, 0, At, B0); PG8_MMA(0, 1, At, B1); PG8_BAR; PG8_SCHED;
;     ...
;         for (int a = 0; a < 2; ++a)
; #pragma unroll
;             for (int b = 0; b < 2; ++b)
; #pragma unroll
;                 for (int m = 0; m < 4; ++m)
; #pragma unroll
;                     for (int n = 0; n < 2; ++n) acc[a][b][m][n] = (f32x4){0.f, 0.f, 0.f, 0.f};
.LBB0_765:
	s_ashr_i32 s15, s14, 31
	s_lshl_b64 s[18:19], s[14:15], 20
	s_add_u32 s18, s33, s18
	s_addc_u32 s19, s34, s19
	s_and_b64 s[20:21], s[6:7], exec
	s_cselect_b32 s1, s19, s25
	s_cselect_b32 s11, s18, s24
	s_ashr_i32 s13, s12, 31
	s_lshl_b64 s[20:21], s[12:13], 20
	s_add_u32 s20, s35, s20
	s_addc_u32 s21, s36, s21
	s_and_b64 s[28:29], s[6:7], exec
	s_cselect_b32 s13, s21, s27
	s_cselect_b32 s15, s20, s26
	s_add_u32 s24, s24, 0x80080
	s_addc_u32 s25, s25, 0
	s_add_u32 s23, s26, 0x100
	v_mov_b32_e32 v2, 0
	s_addc_u32 s65, s27, 0
	s_mov_b32 s68, -2
	s_add_u32 s26, s24, 0xfff80080
	s_addc_u32 s27, s25, -1
	s_add_i32 s72, 0, 0x10000
	s_cmp_eq_u32 s68, 28
	s_cselect_b32 s29, s1, s27
	s_cselect_b32 s28, s11, s26
	v_add_u32_e32 v142, s72, v145
	s_cselect_b32 s27, s13, s65
	s_cselect_b32 s26, s15, s23
	s_add_i32 s75, 0, 0x14000
	ds_read_b128 v[148:151], v142
	v_pk_mov_b32 v[2:3], 0, 0
	v_pk_mov_b32 v[4:5], 0, 0
	v_pk_mov_b32 v[6:7], 0, 0
	v_pk_mov_b32 v[8:9], 0, 0
	ds_read_b128 v[152:155], v142 offset:1024
	v_pk_mov_b32 v[10:11], 0, 0
	v_pk_mov_b32 v[12:13], 0, 0
	v_pk_mov_b32 v[14:15], 0, 0
	v_pk_mov_b32 v[16:17], 0, 0
	ds_read_b128 v[156:159], v142 offset:2048
	v_pk_mov_b32 v[18:19], 0, 0
	v_pk_mov_b32 v[20:21], 0, 0
	v_pk_mov_b32 v[22:23], 0, 0
	v_pk_mov_b32 v[24:25], 0, 0
	ds_read_b128 v[160:163], v142 offset:3072
	v_pk_mov_b32 v[26:27], 0, 0
	v_pk_mov_b32 v[28:29], 0, 0
	v_pk_mov_b32 v[30:31], 0, 0
	v_pk_mov_b32 v[32:33], 0, 0
	v_add_u32_e32 v142, s75, v145
	ds_read_b128 v[164:167], v142
	v_pk_mov_b32 v[34:35], 0, 0
	v_pk_mov_b32 v[36:37], 0, 0
	v_pk_mov_b32 v[38:39], 0, 0
	v_pk_mov_b32 v[40:41], 0, 0
	ds_read_b128 v[168:171], v142 offset:1024
	v_pk_mov_b32 v[42:43], 0, 0
	v_pk_mov_b32 v[44:45], 0, 0
	v_pk_mov_b32 v[46:47], 0, 0
	v_pk_mov_b32 v[48:49], 0, 0
	ds_read_b128 v[172:175], v142 offset:2048
	v_pk_mov_b32 v[50:51], 0, 0
	v_pk_mov_b32 v[52:53], 0, 0
	v_pk_mov_b32 v[54:55], 0, 0
	v_pk_mov_b32 v[56:57], 0, 0
	ds_read_b128 v[176:179], v142 offset:3072
	v_pk_mov_b32 v[58:59], 0, 0
	v_pk_mov_b32 v[60:61], 0, 0
	v_pk_mov_b32 v[62:63], 0, 0
	v_pk_mov_b32 v[64:65], 0, 0
	v_lshl_add_u64 v[142:143], s[24:25], 0, v[138:139]
	s_add_i32 m0, s45, 0xc000
	ds_read_b128 v[180:183], v146
	v_pk_mov_b32 v[66:67], 0, 0
	v_pk_mov_b32 v[68:69], 0, 0
	v_pk_mov_b32 v[70:71], 0, 0
	v_pk_mov_b32 v[72:73], 0, 0
	ds_read_b128 v[196:199], v146 offset:1024
	v_pk_mov_b32 v[74:75], 0, 0
	v_pk_mov_b32 v[76:77], 0, 0
	v_pk_mov_b32 v[78:79], 0, 0
	v_pk_mov_b32 v[80:81], 0, 0
	ds_read_b128 v[200:203], v146 offset:2048
	v_pk_mov_b32 v[82:83], 0, 0
	v_pk_mov_b32 v[84:85], 0, 0
	v_pk_mov_b32 v[86:87], 0, 0
	v_pk_mov_b32 v[88:89], 0, 0
	ds_read_b128 v[204:207], v146 offset:3072
	v_pk_mov_b32 v[90:91], 0, 0
	v_pk_mov_b32 v[92:93], 0, 0
	v_pk_mov_b32 v[94:95], 0, 0
	v_pk_mov_b32 v[96:97], 0, 0
	ds_read_b128 v[208:211], v146 offset:4096
	v_pk_mov_b32 v[98:99], 0, 0
	v_pk_mov_b32 v[100:101], 0, 0
	v_pk_mov_b32 v[102:103], 0, 0
	v_pk_mov_b32 v[104:105], 0, 0
	ds_read_b128 v[212:215], v146 offset:5120
	v_pk_mov_b32 v[106:107], 0, 0
	v_pk_mov_b32 v[108:109], 0, 0
	v_pk_mov_b32 v[110:111], 0, 0
	v_pk_mov_b32 v[112:113], 0, 0
	ds_read_b128 v[216:219], v146 offset:6144
	v_pk_mov_b32 v[114:115], 0, 0
	v_pk_mov_b32 v[116:117], 0, 0
	v_pk_mov_b32 v[118:119], 0, 0
	v_pk_mov_b32 v[120:121], 0, 0
	ds_read_b128 v[220:223], v146 offset:7168
	v_pk_mov_b32 v[122:123], 0, 0
	v_pk_mov_b32 v[124:125], 0, 0
	v_pk_mov_b32 v[126:127], 0, 0
	v_pk_mov_b32 v[128:129], 0, 0
	global_load_lds_dwordx4 v[142:143], off
	v_lshl_add_u64 v[142:143], s[24:25], 0, v[140:141]
	s_add_i32 m0, s45, 0xe000
	s_nop 0
	global_load_lds_dwordx4 v[142:143], off
	s_waitcnt vmcnt(8)
	s_waitcnt lgkmcnt(0)
	s_barrier
	s_branch .Lpeel_766

; #define PG8_STAGE(bufoff, gbase, voff) do { _Pragma("unroll") for (int _i = 0; _i < 2; ++_i) \
;         __builtin_amdgcn_global_load_lds((const unsigned*)((const char*)(gbase) + (voff)[_i]), (PG8_LAS unsigned*)(lds + (bufoff) + ldsw + _i * 8192), 16, 0, 0); } while (0)
; #define PG8_LDA(dst, b, h) do { _Pragma("unroll") for (int m = 0; m < 4; ++m) _Pragma("unroll") for (int k = 0; k < 2; ++k) dst[m][k] = *(const PG8_LAS bf16x8*)(lds + PG8_SA(b, h) + aoff + m * 2048 + k * 1024); } while (0)
; #define PG8_MMA(ai, bj, At, Bt) do { __builtin_amdgcn_s_setprio(1); _Pragma("unroll") for (int m = 0; m < 4; ++m) _Pragma("unroll") for (int n = 0; n < 2; ++n) _Pragma("unroll") for (int k = 0; k < 2; ++k) \
;         acc[ai][bj][m][n] = __builtin_amdgcn_mfma_f32_16x16x32_bf16(Bt[n][k], At[m][k], acc[ai][bj][m][n], 0, 0, 0); __builtin_amdgcn_s_setprio(0); } while (0)
; #define PG8_WAIT_V(n) asm volatile("s_waitcnt vmcnt(" #n ")" ::: "memory")
; #define PG8_WAIT_L(n) asm volatile("s_waitcnt lgkmcnt(" #n ")" ::: "memory")
; #define PG8_BAR __builtin_amdgcn_s_barrier()
; #define PG8_SCHED __builtin_amdgcn_sched_barrier(0)
; template <class Epi, class Sched, bool ALIGN_EPI = false, bool SP2 = false, bool ABLK = false, bool BBLK = false>
; __device__ __forceinline__ void gemm_phase(PG8_LAS unsigned char* lds, const Gemm g, const Sched& S, const Epi& E) {
;     ...
;             PG8_WAIT_V(8); PG8_WAIT_L(0); PG8_BAR; PG8_MMA(0, 0, At, B0); PG8_MMA(0, 1, At, B1); PG8_BAR; PG8_SCHED;
;             PG8_LDA(At, 0, 1); PG8_STAGE(PG8_SB(0, 0), b2, voffB); PG8_STAGE(PG8_SB(0, 1), b2 + hstepB, voffB); PG8_STAGE(PG8_SA(0, 0), a2, voffA);
;             PG8_WAIT_V(8); PG8_WAIT_L(0); PG8_BAR; PG8_MMA(1, 0, At, B0); PG8_MMA(1, 1, At, B1); PG8_BAR; PG8_SCHED;
.Lpeel_766:
	s_setprio 1
	s_waitcnt lgkmcnt(0)
	v_mfma_f32_16x16x32_bf16 v[126:129], v[148:151], v[180:183], v[126:129]
	v_mfma_f32_16x16x32_bf16 v[122:125], v[156:159], v[180:183], v[122:125]
	v_mfma_f32_16x16x32_bf16 v[114:117], v[148:151], v[200:203], v[114:117]
	v_mfma_f32_16x16x32_bf16 v[106:109], v[156:159], v[200:203], v[106:109]
	v_mfma_f32_16x16x32_bf16 v[98:101], v[148:151], v[208:211], v[98:101]
	v_mfma_f32_16x16x32_bf16 v[90:93], v[156:159], v[208:211], v[90:93]
	v_mfma_f32_16x16x32_bf16 v[82:85], v[148:151], v[216:219], v[82:85]
	v_mfma_f32_16x16x32_bf16 v[74:77], v[156:159], v[216:219], v[74:77]
	v_mfma_f32_16x16x32_bf16 v[126:129], v[152:155], v[196:199], v[126:129]
	v_mfma_f32_16x16x32_bf16 v[122:125], v[160:163], v[196:199], v[122:125]
	v_mfma_f32_16x16x32_bf16 v[114:117], v[152:155], v[204:207], v[114:117]
	v_mfma_f32_16x16x32_bf16 v[106:109], v[160:163], v[204:207], v[106:109]
	v_mfma_f32_16x16x32_bf16 v[98:101], v[152:155], v[212:215], v[98:101]
	v_mfma_f32_16x16x32_bf16 v[90:93], v[160:163], v[212:215], v[90:93]
	v_mfma_f32_16x16x32_bf16 v[82:85], v[152:155], v[220:223], v[82:85]
	v_mfma_f32_16x16x32_bf16 v[74:77], v[160:163], v[220:223], v[74:77]
	s_setprio 0
	s_setprio 1
	v_mfma_f32_16x16x32_bf16 v[118:121], v[164:167], v[180:183], v[118:121]
	v_mfma_f32_16x16x32_bf16 v[110:113], v[172:175], v[180:183], v[110:113]
	v_mfma_f32_16x16x32_bf16 v[102:105], v[164:167], v[200:203], v[102:105]
	v_mfma_f32_16x16x32_bf16 v[94:97], v[172:175], v[200:203], v[94:97]
	v_mfma_f32_16x16x32_bf16 v[86:89], v[164:167], v[208:211], v[86:89]
	v_mfma_f32_16x16x32_bf16 v[78:81], v[172:175], v[208:211], v[78:81]
	v_mfma_f32_16x16x32_bf16 v[70:73], v[164:167], v[216:219], v[70:73]
	v_mfma_f32_16x16x32_bf16 v[66:69], v[172:175], v[216:219], v[66:69]
	v_mfma_f32_16x16x32_bf16 v[118:121], v[168:171], v[196:199], v[118:121]
	v_mfma_f32_16x16x32_bf16 v[110:113], v[176:179], v[196:199], v[110:113]
	v_mfma_f32_16x16x32_bf16 v[102:105], v[168:171], v[204:207], v[102:105]
	v_mfma_f32_16x16x32_bf16 v[94:97], v[176:179], v[204:207], v[94:97]
	v_mfma_f32_16x16x32_bf16 v[86:89], v[168:171], v[212:215], v[86:89]
	v_mfma_f32_16x16x32_bf16 v[78:81], v[176:179], v[212:215], v[78:81]
	v_mfma_f32_16x16x32_bf16 v[70:73], v[168:171], v[220:223], v[70:73]
	v_mfma_f32_16x16x32_bf16 v[66:69], v[176:179], v[220:223], v[66:69]
	s_setprio 0
	s_barrier
	s_add_i32 s72, s72, s37
	v_lshl_add_u64 v[142:143], s[26:27], 0, v[134:135]
	s_mov_b32 m0, s72
	ds_read_b128 v[180:183], v146 offset:16384
	ds_read_b128 v[196:199], v146 offset:17408
	ds_read_b128 v[200:203], v146 offset:18432
	ds_read_b128 v[204:207], v146 offset:19456
	ds_read_b128 v[208:211], v146 offset:20480
	ds_read_b128 v[212:215], v146 offset:21504
	ds_read_b128 v[216:219], v146 offset:22528
	ds_read_b128 v[220:223], v146 offset:23552
	global_load_lds_dwordx4 v[142:143], off
	s_add_i32 m0, s72, 0x2000
	s_add_u32 s72, s26, 0x80000
	v_lshl_add_u64 v[184:185], s[26:27], 0, v[130:131]
	s_addc_u32 s73, s27, 0
	s_add_i32 s75, s75, s37
	global_load_lds_dwordx4 v[184:185], off
	v_lshl_add_u64 v[224:225], s[72:73], 0, v[134:135]
	s_mov_b32 m0, s75
	v_lshl_add_u64 v[226:227], s[28:29], 0, v[132:133]
	global_load_lds_dwordx4 v[224:225], off
	v_lshl_add_u64 v[224:225], s[72:73], 0, v[130:131]
	s_add_i32 m0, s75, 0x2000
	s_nop 0
	global_load_lds_dwordx4 v[224:225], off
	v_lshl_add_u64 v[224:225], s[28:29], 0, v[136:137]
	s_mov_b32 m0, s45
	s_nop 0
	global_load_lds_dwordx4 v[224:225], off
	s_mov_b32 m0, s46
	s_nop 0
	global_load_lds_dwordx4 v[226:227], off
	s_waitcnt vmcnt(8)
	s_waitcnt lgkmcnt(0)
	s_barrier
	s_setprio 1
	s_waitcnt lgkmcnt(0)
	v_mfma_f32_16x16x32_bf16 v[62:65], v[148:151], v[180:183], v[62:65]
	v_mfma_f32_16x16x32_bf16 v[58:61], v[156:159], v[180:183], v[58:61]
	v_mfma_f32_16x16x32_bf16 v[50:53], v[148:151], v[200:203], v[50:53]
	v_mfma_f32_16x16x32_bf16 v[42:45], v[156:159], v[200:203], v[42:45]
	v_mfma_f32_16x16x32_bf16 v[34:37], v[148:151], v[208:211], v[34:37]
	v_mfma_f32_16x16x32_bf16 v[26:29], v[156:159], v[208:211], v[26:29]
	v_mfma_f32_16x16x32_bf16 v[18:21], v[148:151], v[216:219], v[18:21]
	v_mfma_f32_16x16x32_bf16 v[10:13], v[156:159], v[216:219], v[10:13]
	v_mfma_f32_16x16x32_bf16 v[62:65], v[152:155], v[196:199], v[62:65]
	v_mfma_f32_16x16x32_bf16 v[58:61], v[160:163], v[196:199], v[58:61]
	v_mfma_f32_16x16x32_bf16 v[50:53], v[152:155], v[204:207], v[50:53]
	v_mfma_f32_16x16x32_bf16 v[42:45], v[160:163], v[204:207], v[42:45]
	v_mfma_f32_16x16x32_bf16 v[34:37], v[152:155], v[212:215], v[34:37]
	v_mfma_f32_16x16x32_bf16 v[26:29], v[160:163], v[212:215], v[26:29]
	v_mfma_f32_16x16x32_bf16 v[18:21], v[152:155], v[220:223], v[18:21]
	v_mfma_f32_16x16x32_bf16 v[10:13], v[160:163], v[220:223], v[10:13]
	s_setprio 0
	s_setprio 1
	v_mfma_f32_16x16x32_bf16 v[54:57], v[164:167], v[180:183], v[54:57]
	v_mfma_f32_16x16x32_bf16 v[46:49], v[172:175], v[180:183], v[46:49]
	v_mfma_f32_16x16x32_bf16 v[38:41], v[164:167], v[200:203], v[38:41]
	v_mfma_f32_16x16x32_bf16 v[30:33], v[172:175], v[200:203], v[30:33]
	v_mfma_f32_16x16x32_bf16 v[22:25], v[164:167], v[208:211], v[22:25]
	v_mfma_f32_16x16x32_bf16 v[14:17], v[172:175], v[208:211], v[14:17]
	v_mfma_f32_16x16x32_bf16 v[6:9], v[164:167], v[216:219], v[6:9]
	v_mfma_f32_16x16x32_bf16 v[2:5], v[172:175], v[216:219], v[2:5]
	v_mfma_f32_16x16x32_bf16 v[54:57], v[168:171], v[196:199], v[54:57]
	v_mfma_f32_16x16x32_bf16 v[46:49], v[176:179], v[196:199], v[46:49]
	v_mfma_f32_16x16x32_bf16 v[38:41], v[168:171], v[204:207], v[38:41]
	v_mfma_f32_16x16x32_bf16 v[30:33], v[176:179], v[204:207], v[30:33]
	v_mfma_f32_16x16x32_bf16 v[22:25], v[168:171], v[212:215], v[22:25]
	v_mfma_f32_16x16x32_bf16 v[14:17], v[176:179], v[212:215], v[14:17]
	v_mfma_f32_16x16x32_bf16 v[6:9], v[168:171], v[220:223], v[6:9]
	v_mfma_f32_16x16x32_bf16 v[2:5], v[176:179], v[220:223], v[2:5]
	s_setprio 0
	s_barrier
; #define PG8_STAGE(bufoff, gbase, voff) do { _Pragma("unroll") for (int _i = 0; _i < 2; ++_i) \
;         __builtin_amdgcn_global_load_lds((const unsigned*)((const char*)(gbase) + (voff)[_i]), (PG8_LAS unsigned*)(lds + (bufoff) + ldsw + _i * 8192), 16, 0, 0); } while (0)
; #define PG8_LDA(dst, b, h) do { _Pragma("unroll") for (int m = 0; m < 4; ++m) _Pragma("unroll") for (int k = 0; k < 2; ++k) dst[m][k] = *(const PG8_LAS bf16x8*)(lds + PG8_SA(b, h) + aoff + m * 2048 + k * 1024); } while (0)
; #define PG8_LDB(dst, b, h) do { _Pragma("unroll") for (int n = 0; n < 2; ++n) _Pragma("unroll") for (int k = 0; k < 2; ++k) dst[n][k] = *(const PG8_LAS bf16x8*)(lds + PG8_SB(b, h) + boff + n * 2048 + k * 1024); } while (0)
; #define PG8_MMA(ai, bj, At, Bt) do { __builtin_amdgcn_s_setprio(1); _Pragma("unroll") for (int m = 0; m < 4; ++m) _Pragma("unroll") for (int n = 0; n < 2; ++n) _Pragma("unroll") for (int k = 0; k < 2; ++k) \
;         acc[ai][bj][m][n] = __builtin_amdgcn_mfma_f32_16x16x32_bf16(Bt[n][k], At[m][k], acc[ai][bj][m][n], 0, 0, 0); __builtin_amdgcn_s_setprio(0); } while (0)
; #define PG8_WAIT_V(n) asm volatile("s_waitcnt vmcnt(" #n ")" ::: "memory")
; #define PG8_WAIT_L(n) asm volatile("s_waitcnt lgkmcnt(" #n ")" ::: "memory")
; #define PG8_BAR __builtin_amdgcn_s_barrier()
; #define PG8_SCHED __builtin_amdgcn_sched_barrier(0)
; template <class Epi, class Sched, bool ALIGN_EPI = false, bool SP2 = false, bool ABLK = false, bool BBLK = false>
; __device__ __forceinline__ void gemm_phase(PG8_LAS unsigned char* lds, const Gemm g, const Sched& S, const Epi& E) {
;     ...
;             PG8_LDB(B0, 1, 0); PG8_LDB(B1, 1, 1); PG8_SCHED; PG8_LDA(At, 1, 0); PG8_STAGE(PG8_SA(0, 1), a2 + hstepA, voffA);
;             PG8_WAIT_V(8); PG8_WAIT_L(0); PG8_BAR; PG8_MMA(0, 0, At, B0); PG8_MMA(0, 1, At, B1); PG8_BAR; PG8_SCHED;
	s_add_i32 s72, 0, 0x18000
	v_add_u32_e32 v147, s72, v145
	s_add_i32 s73, 0, 0x1c000
	ds_read_b128 v[148:151], v147
	ds_read_b128 v[152:155], v147 offset:1024
	ds_read_b128 v[156:159], v147 offset:2048
	ds_read_b128 v[160:163], v147 offset:3072
	v_add_u32_e32 v147, s73, v145
	ds_read_b128 v[164:167], v147
	ds_read_b128 v[168:171], v147 offset:1024
	ds_read_b128 v[172:175], v147 offset:2048
	ds_read_b128 v[176:179], v147 offset:3072
	s_add_u32 s28, s28, 0x80000
	s_addc_u32 s29, s29, 0
	s_mov_b32 m0, s47
	v_lshl_add_u64 v[228:229], s[28:29], 0, v[136:137]
	ds_read_b128 v[180:183], v146 offset:32768
	ds_read_b128 v[196:199], v146 offset:33792
	ds_read_b128 v[200:203], v146 offset:34816
	ds_read_b128 v[204:207], v146 offset:35840
	ds_read_b128 v[208:211], v146 offset:36864
	ds_read_b128 v[212:215], v146 offset:37888
	ds_read_b128 v[216:219], v146 offset:38912
	ds_read_b128 v[220:223], v146 offset:39936
	global_load_lds_dwordx4 v[228:229], off
	v_lshl_add_u64 v[228:229], s[28:29], 0, v[132:133]
	s_mov_b32 m0, s50
	s_nop 0
	global_load_lds_dwordx4 v[228:229], off
	s_waitcnt vmcnt(8)
	s_waitcnt lgkmcnt(0)
	s_barrier
	s_setprio 1
	s_waitcnt lgkmcnt(0)
	v_mfma_f32_16x16x32_bf16 v[126:129], v[148:151], v[180:183], v[126:129]
	v_mfma_f32_16x16x32_bf16 v[122:125], v[156:159], v[180:183], v[122:125]
	v_mfma_f32_16x16x32_bf16 v[114:117], v[148:151], v[200:203], v[114:117]
	v_mfma_f32_16x16x32_bf16 v[106:109], v[156:159], v[200:203], v[106:109]
	v_mfma_f32_16x16x32_bf16 v[98:101], v[148:151], v[208:211], v[98:101]
	v_mfma_f32_16x16x32_bf16 v[90:93], v[156:159], v[208:211], v[90:93]
	v_mfma_f32_16x16x32_bf16 v[82:85], v[148:151], v[216:219], v[82:85]
	v_mfma_f32_16x16x32_bf16 v[74:77], v[156:159], v[216:219], v[74:77]
	v_mfma_f32_16x16x32_bf16 v[126:129], v[152:155], v[196:199], v[126:129]
	v_mfma_f32_16x16x32_bf16 v[122:125], v[160:163], v[196:199], v[122:125]
	v_mfma_f32_16x16x32_bf16 v[114:117], v[152:155], v[204:207], v[114:117]
	v_mfma_f32_16x16x32_bf16 v[106:109], v[160:163], v[204:207], v[106:109]
	v_mfma_f32_16x16x32_bf16 v[98:101], v[152:155], v[212:215], v[98:101]
	v_mfma_f32_16x16x32_bf16 v[90:93], v[160:163], v[212:215], v[90:93]
	v_mfma_f32_16x16x32_bf16 v[82:85], v[152:155], v[220:223], v[82:85]
	v_mfma_f32_16x16x32_bf16 v[74:77], v[160:163], v[220:223], v[74:77]
	s_setprio 0
	s_setprio 1
	v_mfma_f32_16x16x32_bf16 v[118:121], v[164:167], v[180:183], v[118:121]
	v_mfma_f32_16x16x32_bf16 v[110:113], v[172:175], v[180:183], v[110:113]
	v_mfma_f32_16x16x32_bf16 v[102:105], v[164:167], v[200:203], v[102:105]
	v_mfma_f32_16x16x32_bf16 v[94:97], v[172:175], v[200:203], v[94:97]
	v_mfma_f32_16x16x32_bf16 v[86:89], v[164:167], v[208:211], v[86:89]
	v_mfma_f32_16x16x32_bf16 v[78:81], v[172:175], v[208:211], v[78:81]
	v_mfma_f32_16x16x32_bf16 v[70:73], v[164:167], v[216:219], v[70:73]
	v_mfma_f32_16x16x32_bf16 v[66:69], v[172:175], v[216:219], v[66:69]
	v_mfma_f32_16x16x32_bf16 v[118:121], v[168:171], v[196:199], v[118:121]
	v_mfma_f32_16x16x32_bf16 v[110:113], v[176:179], v[196:199], v[110:113]
	v_mfma_f32_16x16x32_bf16 v[102:105], v[168:171], v[204:207], v[102:105]
	v_mfma_f32_16x16x32_bf16 v[94:97], v[176:179], v[204:207], v[94:97]
	v_mfma_f32_16x16x32_bf16 v[86:89], v[168:171], v[212:215], v[86:89]
	v_mfma_f32_16x16x32_bf16 v[78:81], v[176:179], v[212:215], v[78:81]
	v_mfma_f32_16x16x32_bf16 v[70:73], v[168:171], v[220:223], v[70:73]
	v_mfma_f32_16x16x32_bf16 v[66:69], v[176:179], v[220:223], v[66:69]
	s_setprio 0
	s_barrier
; #define PG8_STAGE(bufoff, gbase, voff) do { _Pragma("unroll") for (int _i = 0; _i < 2; ++_i) \
;         __builtin_amdgcn_global_load_lds((const unsigned*)((const char*)(gbase) + (voff)[_i]), (PG8_LAS unsigned*)(lds + (bufoff) + ldsw + _i * 8192), 16, 0, 0); } while (0)
; #define PG8_LDA(dst, b, h) do { _Pragma("unroll") for (int m = 0; m < 4; ++m) _Pragma("unroll") for (int k = 0; k < 2; ++k) dst[m][k] = *(const PG8_LAS bf16x8*)(lds + PG8_SA(b, h) + aoff + m * 2048 + k * 1024); } while (0)
; #define PG8_MMA(ai, bj, At, Bt) do { __builtin_amdgcn_s_setprio(1); _Pragma("unroll") for (int m = 0; m < 4; ++m) _Pragma("unroll") for (int n = 0; n < 2; ++n) _Pragma("unroll") for (int k = 0; k < 2; ++k) \
;         acc[ai][bj][m][n] = __builtin_amdgcn_mfma_f32_16x16x32_bf16(Bt[n][k], At[m][k], acc[ai][bj][m][n], 0, 0, 0); __builtin_amdgcn_s_setprio(0); } while (0)
; #define PG8_WAIT_V(n) asm volatile("s_waitcnt vmcnt(" #n ")" ::: "memory")
; #define PG8_WAIT_L(n) asm volatile("s_waitcnt lgkmcnt(" #n ")" ::: "memory")
; #define PG8_BAR __builtin_amdgcn_s_barrier()
; #define PG8_SCHED __builtin_amdgcn_sched_barrier(0)
; template <class Epi, class Sched, bool ALIGN_EPI = false, bool SP2 = false, bool ABLK = false, bool BBLK = false>
; __device__ __forceinline__ void gemm_phase(PG8_LAS unsigned char* lds, const Gemm g, const Sched& S, const Epi& E) {
;     ...
;             PG8_LDA(At, 1, 1); PG8_STAGE(PG8_SB(1, 0), b3, voffB); PG8_STAGE(PG8_SB(1, 1), b3 + hstepB, voffB); PG8_STAGE(PG8_SA(1, 0), a3, voffA);
;             PG8_WAIT_V(8); PG8_WAIT_L(0); PG8_BAR; PG8_MMA(1, 0, At, B0); PG8_MMA(1, 1, At, B1); PG8_BAR; PG8_SCHED;
;     ...
;         if constexpr (ALIGN_EPI) { if (wr == 0) PG8_BAR; }
	s_add_i32 s28, s72, s37
	v_lshl_add_u64 v[142:143], v[142:143], 0, s[62:63]
	s_mov_b32 m0, s28
	ds_read_b128 v[180:183], v146 offset:49152
	ds_read_b128 v[196:199], v146 offset:50176
	ds_read_b128 v[200:203], v146 offset:51200
	ds_read_b128 v[204:207], v146 offset:52224
	ds_read_b128 v[208:211], v146 offset:53248
	ds_read_b128 v[212:215], v146 offset:54272
	ds_read_b128 v[216:219], v146 offset:55296
	ds_read_b128 v[220:223], v146 offset:56320
	global_load_lds_dwordx4 v[142:143], off
	s_add_i32 m0, s28, 0x2000
	s_add_u32 s26, s26, 0x80080
	v_lshl_add_u64 v[142:143], v[184:185], 0, s[62:63]
	s_addc_u32 s27, s27, 0
	s_add_i32 s28, s73, s37
	global_load_lds_dwordx4 v[142:143], off
	v_lshl_add_u64 v[142:143], s[26:27], 0, v[134:135]
	s_mov_b32 m0, s28
	s_nop 0
	global_load_lds_dwordx4 v[142:143], off
	v_lshl_add_u64 v[142:143], s[26:27], 0, v[130:131]
	s_add_i32 m0, s28, 0x2000
	s_nop 0
	global_load_lds_dwordx4 v[142:143], off
	v_lshl_add_u64 v[142:143], v[224:225], 0, s[62:63]
	s_mov_b32 m0, s53
	s_nop 0
	global_load_lds_dwordx4 v[142:143], off
	v_lshl_add_u64 v[142:143], v[226:227], 0, s[62:63]
	s_mov_b32 m0, s56
	s_nop 0
	global_load_lds_dwordx4 v[142:143], off
	s_waitcnt vmcnt(8)
	s_waitcnt lgkmcnt(0)
	s_barrier
	s_setprio 1
	s_waitcnt lgkmcnt(0)
	v_mfma_f32_16x16x32_bf16 v[62:65], v[148:151], v[180:183], v[62:65]
	v_mfma_f32_16x16x32_bf16 v[58:61], v[156:159], v[180:183], v[58:61]
	v_mfma_f32_16x16x32_bf16 v[50:53], v[148:151], v[200:203], v[50:53]
	v_mfma_f32_16x16x32_bf16 v[42:45], v[156:159], v[200:203], v[42:45]
	v_mfma_f32_16x16x32_bf16 v[34:37], v[148:151], v[208:211], v[34:37]
	v_mfma_f32_16x16x32_bf16 v[26:29], v[156:159], v[208:211], v[26:29]
	v_mfma_f32_16x16x32_bf16 v[18:21], v[148:151], v[216:219], v[18:21]
	v_mfma_f32_16x16x32_bf16 v[10:13], v[156:159], v[216:219], v[10:13]
	v_mfma_f32_16x16x32_bf16 v[62:65], v[152:155], v[196:199], v[62:65]
	v_mfma_f32_16x16x32_bf16 v[58:61], v[160:163], v[196:199], v[58:61]
	v_mfma_f32_16x16x32_bf16 v[50:53], v[152:155], v[204:207], v[50:53]
	v_mfma_f32_16x16x32_bf16 v[42:45], v[160:163], v[204:207], v[42:45]
	v_mfma_f32_16x16x32_bf16 v[34:37], v[152:155], v[212:215], v[34:37]
	v_mfma_f32_16x16x32_bf16 v[26:29], v[160:163], v[212:215], v[26:29]
	v_mfma_f32_16x16x32_bf16 v[18:21], v[152:155], v[220:223], v[18:21]
	v_mfma_f32_16x16x32_bf16 v[10:13], v[160:163], v[220:223], v[10:13]
	s_setprio 0
	s_setprio 1
	v_mfma_f32_16x16x32_bf16 v[54:57], v[164:167], v[180:183], v[54:57]
	v_mfma_f32_16x16x32_bf16 v[46:49], v[172:175], v[180:183], v[46:49]
	v_mfma_f32_16x16x32_bf16 v[38:41], v[164:167], v[200:203], v[38:41]
	v_mfma_f32_16x16x32_bf16 v[30:33], v[172:175], v[200:203], v[30:33]
	v_mfma_f32_16x16x32_bf16 v[22:25], v[164:167], v[208:211], v[22:25]
	v_mfma_f32_16x16x32_bf16 v[14:17], v[172:175], v[208:211], v[14:17]
	v_mfma_f32_16x16x32_bf16 v[6:9], v[164:167], v[216:219], v[6:9]
	v_mfma_f32_16x16x32_bf16 v[2:5], v[172:175], v[216:219], v[2:5]
	v_mfma_f32_16x16x32_bf16 v[54:57], v[168:171], v[196:199], v[54:57]
	v_mfma_f32_16x16x32_bf16 v[46:49], v[176:179], v[196:199], v[46:49]
	v_mfma_f32_16x16x32_bf16 v[38:41], v[168:171], v[204:207], v[38:41]
	v_mfma_f32_16x16x32_bf16 v[30:33], v[176:179], v[204:207], v[30:33]
	v_mfma_f32_16x16x32_bf16 v[22:25], v[168:171], v[212:215], v[22:25]
	v_mfma_f32_16x16x32_bf16 v[14:17], v[176:179], v[212:215], v[14:17]
	v_mfma_f32_16x16x32_bf16 v[6:9], v[168:171], v[220:223], v[6:9]
	v_mfma_f32_16x16x32_bf16 v[2:5], v[176:179], v[220:223], v[2:5]
	s_setprio 0
	s_barrier
	s_add_i32 s68, s68, 2
	s_add_u32 s24, s24, 0x100
	s_addc_u32 s25, s25, 0
	s_add_u32 s23, s23, 0x100
	s_addc_u32 s65, s65, 0
	s_cmp_gt_u32 s68, 29
	s_cbranch_scc0 .LBB0_766
	s_and_b64 vcc, exec, s[8:9]
	s_cbranch_vccz .LBB0_769
	s_barrier

; #define PG8_STAGE(bufoff, gbase, voff) do { _Pragma("unroll") for (int _i = 0; _i < 2; ++_i) \
;         __builtin_amdgcn_global_load_lds((const unsigned*)((const char*)(gbase) + (voff)[_i]), (PG8_LAS unsigned*)(lds + (bufoff) + ldsw + _i * 8192), 16, 0, 0); } while (0)
; #define PG8_LDA(dst, b, h) do { _Pragma("unroll") for (int m = 0; m < 4; ++m) _Pragma("unroll") for (int k = 0; k < 2; ++k) dst[m][k] = *(const PG8_LAS bf16x8*)(lds + PG8_SA(b, h) + aoff + m * 2048 + k * 1024); } while (0)
; #define PG8_LDB(dst, b, h) do { _Pragma("unroll") for (int n = 0; n < 2; ++n) _Pragma("unroll") for (int k = 0; k < 2; ++k) dst[n][k] = *(const PG8_LAS bf16x8*)(lds + PG8_SB(b, h) + boff + n * 2048 + k * 1024); } while (0)
; #define PG8_WAIT_V(n) asm volatile("s_waitcnt vmcnt(" #n ")" ::: "memory")
; #define PG8_WAIT_L(n) asm volatile("s_waitcnt lgkmcnt(" #n ")" ::: "memory")
; #define PG8_BAR __builtin_amdgcn_s_barrier()
; template <class Epi, class Sched, bool ALIGN_EPI = false, bool SP2 = false, bool ABLK = false, bool BBLK = false>
; __device__ __forceinline__ void gemm_phase(PG8_LAS unsigned char* lds, const Gemm g, const Sched& S, const Epi& E) {
;     ...
;         const bool has_next = S.next(ui + 1, nxt);
;         const char* nA = has_next ? (const char*)g.A + (size_t)nxt.pm * tstepA : cA; const char* nB = has_next ? (const char*)g.Bt + (size_t)nxt.pn * tstepB : cB;
;         for (int t = 0; t < nt; t += 2) {
;             const bool last = (t == nt - 2);
;             const char* a1 = cA + (size_t)(t + 1) * kstepA;
;             const char* a2 = last ? nA : cA + (size_t)(t + 2) * kstepA; const char* b2 = last ? nB : cB + (size_t)(t + 2) * kstepB;
;             const char* a3 = a2 + kstepA; const char* b3 = b2 + kstepB;
;             if (last && has_next) S.a_ready(nxt);
;             if constexpr (SP2) {
;             PG8_LDB(B0, 0, 0); PG8_LDB(B1, 0, 1); PG8_SCHED; PG8_LDA(At, 0, 0); PG8_STAGE(PG8_SA(1, 1), a1 + hstepA, voffA);
;             PG8_WAIT_V(8); PG8_WAIT_L(0); PG8_BAR; PG8_MMA(0, 0, At, B0); PG8_MMA(0, 1, At, B1); PG8_BAR; PG8_SCHED;
;     ...
;         for (int a = 0; a < 2; ++a)
; #pragma unroll
;             for (int b = 0; b < 2; ++b)
; #pragma unroll
;                 for (int m = 0; m < 4; ++m)
; #pragma unroll
;                     for (int n = 0; n < 2; ++n) acc[a][b][m][n] = (f32x4){0.f, 0.f, 0.f, 0.f};
.LBB0_789:
	s_ashr_i32 s15, s14, 31
	s_lshl_b64 s[18:19], s[14:15], 20
	s_add_u32 s18, s36, s18
	s_addc_u32 s19, s37, s19
	s_and_b64 s[20:21], s[6:7], exec
	s_cselect_b32 s1, s19, s25
	s_cselect_b32 s11, s18, s24
	s_ashr_i32 s13, s12, 31
	s_lshl_b64 s[20:21], s[12:13], 20
	s_add_u32 s20, s44, s20
	s_addc_u32 s21, s45, s21
	s_and_b64 s[28:29], s[6:7], exec
	s_cselect_b32 s13, s21, s27
	s_cselect_b32 s15, s20, s26
	s_add_u32 s24, s24, 0x80080
	s_addc_u32 s25, s25, 0
	s_add_u32 s23, s26, 0x100
	v_mov_b32_e32 v2, 0
	s_addc_u32 s73, s27, 0
	s_mov_b32 s81, -2
	s_add_u32 s26, s24, 0xfff80080
	s_addc_u32 s27, s25, -1
	s_add_i32 s51, 0, 0x10000
	s_cmp_eq_u32 s81, 28
	s_cselect_b32 s29, s1, s27
	s_cselect_b32 s28, s11, s26
	v_add_u32_e32 v142, s51, v145
	s_cselect_b32 s27, s13, s73
	s_cselect_b32 s26, s15, s23
	s_add_i32 s75, 0, 0x14000
	ds_read_b128 v[148:151], v142
	v_pk_mov_b32 v[2:3], 0, 0
	v_pk_mov_b32 v[4:5], 0, 0
	v_pk_mov_b32 v[6:7], 0, 0
	v_pk_mov_b32 v[8:9], 0, 0
	ds_read_b128 v[152:155], v142 offset:1024
	v_pk_mov_b32 v[10:11], 0, 0
	v_pk_mov_b32 v[12:13], 0, 0
	v_pk_mov_b32 v[14:15], 0, 0
	v_pk_mov_b32 v[16:17], 0, 0
	ds_read_b128 v[156:159], v142 offset:2048
	v_pk_mov_b32 v[18:19], 0, 0
	v_pk_mov_b32 v[20:21], 0, 0
	v_pk_mov_b32 v[22:23], 0, 0
	v_pk_mov_b32 v[24:25], 0, 0
	ds_read_b128 v[160:163], v142 offset:3072
	v_pk_mov_b32 v[26:27], 0, 0
	v_pk_mov_b32 v[28:29], 0, 0
	v_pk_mov_b32 v[30:31], 0, 0
	v_pk_mov_b32 v[32:33], 0, 0
	v_add_u32_e32 v142, s75, v145
	ds_read_b128 v[164:167], v142
	v_pk_mov_b32 v[34:35], 0, 0
	v_pk_mov_b32 v[36:37], 0, 0
	v_pk_mov_b32 v[38:39], 0, 0
	v_pk_mov_b32 v[40:41], 0, 0
	ds_read_b128 v[168:171], v142 offset:1024
	v_pk_mov_b32 v[42:43], 0, 0
	v_pk_mov_b32 v[44:45], 0, 0
	v_pk_mov_b32 v[46:47], 0, 0
	v_pk_mov_b32 v[48:49], 0, 0
	ds_read_b128 v[172:175], v142 offset:2048
	v_pk_mov_b32 v[50:51], 0, 0
	v_pk_mov_b32 v[52:53], 0, 0
	v_pk_mov_b32 v[54:55], 0, 0
	v_pk_mov_b32 v[56:57], 0, 0
	ds_read_b128 v[176:179], v142 offset:3072
	v_pk_mov_b32 v[58:59], 0, 0
	v_pk_mov_b32 v[60:61], 0, 0
	v_pk_mov_b32 v[62:63], 0, 0
	v_pk_mov_b32 v[64:65], 0, 0
	v_lshl_add_u64 v[142:143], s[24:25], 0, v[138:139]
	s_add_i32 m0, s46, 0xc000
	ds_read_b128 v[180:183], v146
	v_pk_mov_b32 v[66:67], 0, 0
	v_pk_mov_b32 v[68:69], 0, 0
	v_pk_mov_b32 v[70:71], 0, 0
	v_pk_mov_b32 v[72:73], 0, 0
	ds_read_b128 v[196:199], v146 offset:1024
	v_pk_mov_b32 v[74:75], 0, 0
	v_pk_mov_b32 v[76:77], 0, 0
	v_pk_mov_b32 v[78:79], 0, 0
	v_pk_mov_b32 v[80:81], 0, 0
	ds_read_b128 v[200:203], v146 offset:2048
	v_pk_mov_b32 v[82:83], 0, 0
	v_pk_mov_b32 v[84:85], 0, 0
	v_pk_mov_b32 v[86:87], 0, 0
	v_pk_mov_b32 v[88:89], 0, 0
	ds_read_b128 v[204:207], v146 offset:3072
	v_pk_mov_b32 v[90:91], 0, 0
	v_pk_mov_b32 v[92:93], 0, 0
	v_pk_mov_b32 v[94:95], 0, 0
	v_pk_mov_b32 v[96:97], 0, 0
	ds_read_b128 v[208:211], v146 offset:4096
	v_pk_mov_b32 v[98:99], 0, 0
	v_pk_mov_b32 v[100:101], 0, 0
	v_pk_mov_b32 v[102:103], 0, 0
	v_pk_mov_b32 v[104:105], 0, 0
	ds_read_b128 v[212:215], v146 offset:5120
	v_pk_mov_b32 v[106:107], 0, 0
	v_pk_mov_b32 v[108:109], 0, 0
	v_pk_mov_b32 v[110:111], 0, 0
	v_pk_mov_b32 v[112:113], 0, 0
	ds_read_b128 v[216:219], v146 offset:6144
	v_pk_mov_b32 v[114:115], 0, 0
	v_pk_mov_b32 v[116:117], 0, 0
	v_pk_mov_b32 v[118:119], 0, 0
	v_pk_mov_b32 v[120:121], 0, 0
	ds_read_b128 v[220:223], v146 offset:7168
	v_pk_mov_b32 v[122:123], 0, 0
	v_pk_mov_b32 v[124:125], 0, 0
	v_pk_mov_b32 v[126:127], 0, 0
	v_pk_mov_b32 v[128:129], 0, 0
	global_load_lds_dwordx4 v[142:143], off
	v_lshl_add_u64 v[142:143], s[24:25], 0, v[140:141]
	s_add_i32 m0, s46, 0xe000
	s_nop 0
	global_load_lds_dwordx4 v[142:143], off
	s_waitcnt vmcnt(8)
	s_waitcnt lgkmcnt(0)
	s_barrier
	s_branch .Lpeel_790

; #define PG8_STAGE(bufoff, gbase, voff) do { _Pragma("unroll") for (int _i = 0; _i < 2; ++_i) \
;         __builtin_amdgcn_global_load_lds((const unsigned*)((const char*)(gbase) + (voff)[_i]), (PG8_LAS unsigned*)(lds + (bufoff) + ldsw + _i * 8192), 16, 0, 0); } while (0)
; #define PG8_LDA(dst, b, h) do { _Pragma("unroll") for (int m = 0; m < 4; ++m) _Pragma("unroll") for (int k = 0; k < 2; ++k) dst[m][k] = *(const PG8_LAS bf16x8*)(lds + PG8_SA(b, h) + aoff + m * 2048 + k * 1024); } while (0)
; #define PG8_MMA(ai, bj, At, Bt) do { __builtin_amdgcn_s_setprio(1); _Pragma("unroll") for (int m = 0; m < 4; ++m) _Pragma("unroll") for (int n = 0; n < 2; ++n) _Pragma("unroll") for (int k = 0; k < 2; ++k) \
;         acc[ai][bj][m][n] = __builtin_amdgcn_mfma_f32_16x16x32_bf16(Bt[n][k], At[m][k], acc[ai][bj][m][n], 0, 0, 0); __builtin_amdgcn_s_setprio(0); } while (0)
; #define PG8_WAIT_V(n) asm volatile("s_waitcnt vmcnt(" #n ")" ::: "memory")
; #define PG8_WAIT_L(n) asm volatile("s_waitcnt lgkmcnt(" #n ")" ::: "memory")
; #define PG8_BAR __builtin_amdgcn_s_barrier()
; #define PG8_SCHED __builtin_amdgcn_sched_barrier(0)
; template <class Epi, class Sched, bool ALIGN_EPI = false, bool SP2 = false, bool ABLK = false, bool BBLK = false>
; __device__ __forceinline__ void gemm_phase(PG8_LAS unsigned char* lds, const Gemm g, const Sched& S, const Epi& E) {
;     ...
;             PG8_WAIT_V(8); PG8_WAIT_L(0); PG8_BAR; PG8_MMA(0, 0, At, B0); PG8_MMA(0, 1, At, B1); PG8_BAR; PG8_SCHED;
;             PG8_LDA(At, 0, 1); PG8_STAGE(PG8_SB(0, 0), b2, voffB); PG8_STAGE(PG8_SB(0, 1), b2 + hstepB, voffB); PG8_STAGE(PG8_SA(0, 0), a2, voffA);
;             PG8_WAIT_V(8); PG8_WAIT_L(0); PG8_BAR; PG8_MMA(1, 0, At, B0); PG8_MMA(1, 1, At, B1); PG8_BAR; PG8_SCHED;
.Lpeel_790:
	s_setprio 1
	s_waitcnt lgkmcnt(0)
	v_mfma_f32_16x16x32_bf16 v[126:129], v[148:151], v[180:183], v[126:129]
	v_mfma_f32_16x16x32_bf16 v[122:125], v[156:159], v[180:183], v[122:125]
	v_mfma_f32_16x16x32_bf16 v[114:117], v[148:151], v[200:203], v[114:117]
	v_mfma_f32_16x16x32_bf16 v[106:109], v[156:159], v[200:203], v[106:109]
	v_mfma_f32_16x16x32_bf16 v[98:101], v[148:151], v[208:211], v[98:101]
	v_mfma_f32_16x16x32_bf16 v[90:93], v[156:159], v[208:211], v[90:93]
	v_mfma_f32_16x16x32_bf16 v[82:85], v[148:151], v[216:219], v[82:85]
	v_mfma_f32_16x16x32_bf16 v[74:77], v[156:159], v[216:219], v[74:77]
	v_mfma_f32_16x16x32_bf16 v[126:129], v[152:155], v[196:199], v[126:129]
	v_mfma_f32_16x16x32_bf16 v[122:125], v[160:163], v[196:199], v[122:125]
	v_mfma_f32_16x16x32_bf16 v[114:117], v[152:155], v[204:207], v[114:117]
	v_mfma_f32_16x16x32_bf16 v[106:109], v[160:163], v[204:207], v[106:109]
	v_mfma_f32_16x16x32_bf16 v[98:101], v[152:155], v[212:215], v[98:101]
	v_mfma_f32_16x16x32_bf16 v[90:93], v[160:163], v[212:215], v[90:93]
	v_mfma_f32_16x16x32_bf16 v[82:85], v[152:155], v[220:223], v[82:85]
	v_mfma_f32_16x16x32_bf16 v[74:77], v[160:163], v[220:223], v[74:77]
	s_setprio 0
	s_setprio 1
	v_mfma_f32_16x16x32_bf16 v[118:121], v[164:167], v[180:183], v[118:121]
	v_mfma_f32_16x16x32_bf16 v[110:113], v[172:175], v[180:183], v[110:113]
	v_mfma_f32_16x16x32_bf16 v[102:105], v[164:167], v[200:203], v[102:105]
	v_mfma_f32_16x16x32_bf16 v[94:97], v[172:175], v[200:203], v[94:97]
	v_mfma_f32_16x16x32_bf16 v[86:89], v[164:167], v[208:211], v[86:89]
	v_mfma_f32_16x16x32_bf16 v[78:81], v[172:175], v[208:211], v[78:81]
	v_mfma_f32_16x16x32_bf16 v[70:73], v[164:167], v[216:219], v[70:73]
	v_mfma_f32_16x16x32_bf16 v[66:69], v[172:175], v[216:219], v[66:69]
	v_mfma_f32_16x16x32_bf16 v[118:121], v[168:171], v[196:199], v[118:121]
	v_mfma_f32_16x16x32_bf16 v[110:113], v[176:179], v[196:199], v[110:113]
	v_mfma_f32_16x16x32_bf16 v[102:105], v[168:171], v[204:207], v[102:105]
	v_mfma_f32_16x16x32_bf16 v[94:97], v[176:179], v[204:207], v[94:97]
	v_mfma_f32_16x16x32_bf16 v[86:89], v[168:171], v[212:215], v[86:89]
	v_mfma_f32_16x16x32_bf16 v[78:81], v[176:179], v[212:215], v[78:81]
	v_mfma_f32_16x16x32_bf16 v[70:73], v[168:171], v[220:223], v[70:73]
	v_mfma_f32_16x16x32_bf16 v[66:69], v[176:179], v[220:223], v[66:69]
	s_setprio 0
	s_barrier
	s_add_i32 s51, s51, s35
	v_lshl_add_u64 v[142:143], s[26:27], 0, v[132:133]
	s_mov_b32 m0, s51
	ds_read_b128 v[180:183], v146 offset:16384
	ds_read_b128 v[196:199], v146 offset:17408
	ds_read_b128 v[200:203], v146 offset:18432
	ds_read_b128 v[204:207], v146 offset:19456
	ds_read_b128 v[208:211], v146 offset:20480
	ds_read_b128 v[212:215], v146 offset:21504
	ds_read_b128 v[216:219], v146 offset:22528
	ds_read_b128 v[220:223], v146 offset:23552
	global_load_lds_dwordx4 v[142:143], off
	s_add_i32 m0, s51, 0x2000
	s_add_u32 s82, s26, 0x80000
	v_lshl_add_u64 v[184:185], s[26:27], 0, v[136:137]
	s_addc_u32 s83, s27, 0
	s_add_i32 s51, s75, s35
	global_load_lds_dwordx4 v[184:185], off
	v_lshl_add_u64 v[224:225], s[82:83], 0, v[132:133]
	s_mov_b32 m0, s51
	v_lshl_add_u64 v[226:227], s[28:29], 0, v[134:135]
	global_load_lds_dwordx4 v[224:225], off
	v_lshl_add_u64 v[224:225], s[82:83], 0, v[136:137]
	s_add_i32 m0, s51, 0x2000
	s_nop 0
	global_load_lds_dwordx4 v[224:225], off
	v_lshl_add_u64 v[224:225], s[28:29], 0, v[130:131]
	s_mov_b32 m0, s46
	s_nop 0
	global_load_lds_dwordx4 v[224:225], off
	s_mov_b32 m0, s47
	s_nop 0
	global_load_lds_dwordx4 v[226:227], off
	s_waitcnt vmcnt(8)
	s_waitcnt lgkmcnt(0)
	s_barrier
	s_setprio 1
	s_waitcnt lgkmcnt(0)
	v_mfma_f32_16x16x32_bf16 v[62:65], v[148:151], v[180:183], v[62:65]
	v_mfma_f32_16x16x32_bf16 v[58:61], v[156:159], v[180:183], v[58:61]
	v_mfma_f32_16x16x32_bf16 v[50:53], v[148:151], v[200:203], v[50:53]
	v_mfma_f32_16x16x32_bf16 v[42:45], v[156:159], v[200:203], v[42:45]
	v_mfma_f32_16x16x32_bf16 v[34:37], v[148:151], v[208:211], v[34:37]
	v_mfma_f32_16x16x32_bf16 v[26:29], v[156:159], v[208:211], v[26:29]
	v_mfma_f32_16x16x32_bf16 v[18:21], v[148:151], v[216:219], v[18:21]
	v_mfma_f32_16x16x32_bf16 v[10:13], v[156:159], v[216:219], v[10:13]
	v_mfma_f32_16x16x32_bf16 v[62:65], v[152:155], v[196:199], v[62:65]
	v_mfma_f32_16x16x32_bf16 v[58:61], v[160:163], v[196:199], v[58:61]
	v_mfma_f32_16x16x32_bf16 v[50:53], v[152:155], v[204:207], v[50:53]
	v_mfma_f32_16x16x32_bf16 v[42:45], v[160:163], v[204:207], v[42:45]
	v_mfma_f32_16x16x32_bf16 v[34:37], v[152:155], v[212:215], v[34:37]
	v_mfma_f32_16x16x32_bf16 v[26:29], v[160:163], v[212:215], v[26:29]
	v_mfma_f32_16x16x32_bf16 v[18:21], v[152:155], v[220:223], v[18:21]
	v_mfma_f32_16x16x32_bf16 v[10:13], v[160:163], v[220:223], v[10:13]
	s_setprio 0
	s_setprio 1
	v_mfma_f32_16x16x32_bf16 v[54:57], v[164:167], v[180:183], v[54:57]
	v_mfma_f32_16x16x32_bf16 v[46:49], v[172:175], v[180:183], v[46:49]
	v_mfma_f32_16x16x32_bf16 v[38:41], v[164:167], v[200:203], v[38:41]
	v_mfma_f32_16x16x32_bf16 v[30:33], v[172:175], v[200:203], v[30:33]
	v_mfma_f32_16x16x32_bf16 v[22:25], v[164:167], v[208:211], v[22:25]
	v_mfma_f32_16x16x32_bf16 v[14:17], v[172:175], v[208:211], v[14:17]
	v_mfma_f32_16x16x32_bf16 v[6:9], v[164:167], v[216:219], v[6:9]
	v_mfma_f32_16x16x32_bf16 v[2:5], v[172:175], v[216:219], v[2:5]
	v_mfma_f32_16x16x32_bf16 v[54:57], v[168:171], v[196:199], v[54:57]
	v_mfma_f32_16x16x32_bf16 v[46:49], v[176:179], v[196:199], v[46:49]
	v_mfma_f32_16x16x32_bf16 v[38:41], v[168:171], v[204:207], v[38:41]
	v_mfma_f32_16x16x32_bf16 v[30:33], v[176:179], v[204:207], v[30:33]
	v_mfma_f32_16x16x32_bf16 v[22:25], v[168:171], v[212:215], v[22:25]
	v_mfma_f32_16x16x32_bf16 v[14:17], v[176:179], v[212:215], v[14:17]
	v_mfma_f32_16x16x32_bf16 v[6:9], v[168:171], v[220:223], v[6:9]
	v_mfma_f32_16x16x32_bf16 v[2:5], v[176:179], v[220:223], v[2:5]
	s_setprio 0
	s_barrier
; #define PG8_STAGE(bufoff, gbase, voff) do { _Pragma("unroll") for (int _i = 0; _i < 2; ++_i) \
;         __builtin_amdgcn_global_load_lds((const unsigned*)((const char*)(gbase) + (voff)[_i]), (PG8_LAS unsigned*)(lds + (bufoff) + ldsw + _i * 8192), 16, 0, 0); } while (0)
; #define PG8_LDA(dst, b, h) do { _Pragma("unroll") for (int m = 0; m < 4; ++m) _Pragma("unroll") for (int k = 0; k < 2; ++k) dst[m][k] = *(const PG8_LAS bf16x8*)(lds + PG8_SA(b, h) + aoff + m * 2048 + k * 1024); } while (0)
; #define PG8_LDB(dst, b, h) do { _Pragma("unroll") for (int n = 0; n < 2; ++n) _Pragma("unroll") for (int k = 0; k < 2; ++k) dst[n][k] = *(const PG8_LAS bf16x8*)(lds + PG8_SB(b, h) + boff + n * 2048 + k * 1024); } while (0)
; #define PG8_MMA(ai, bj, At, Bt) do { __builtin_amdgcn_s_setprio(1); _Pragma("unroll") for (int m = 0; m < 4; ++m) _Pragma("unroll") for (int n = 0; n < 2; ++n) _Pragma("unroll") for (int k = 0; k < 2; ++k) \
;         acc[ai][bj][m][n] = __builtin_amdgcn_mfma_f32_16x16x32_bf16(Bt[n][k], At[m][k], acc[ai][bj][m][n], 0, 0, 0); __builtin_amdgcn_s_setprio(0); } while (0)
; #define PG8_WAIT_V(n) asm volatile("s_waitcnt vmcnt(" #n ")" ::: "memory")
; #define PG8_WAIT_L(n) asm volatile("s_waitcnt lgkmcnt(" #n ")" ::: "memory")
; #define PG8_BAR __builtin_amdgcn_s_barrier()
; #define PG8_SCHED __builtin_amdgcn_sched_barrier(0)
; template <class Epi, class Sched, bool ALIGN_EPI = false, bool SP2 = false, bool ABLK = false, bool BBLK = false>
; __device__ __forceinline__ void gemm_phase(PG8_LAS unsigned char* lds, const Gemm g, const Sched& S, const Epi& E) {
;     ...
;             PG8_LDB(B0, 1, 0); PG8_LDB(B1, 1, 1); PG8_SCHED; PG8_LDA(At, 1, 0); PG8_STAGE(PG8_SA(0, 1), a2 + hstepA, voffA);
;             PG8_WAIT_V(8); PG8_WAIT_L(0); PG8_BAR; PG8_MMA(0, 0, At, B0); PG8_MMA(0, 1, At, B1); PG8_BAR; PG8_SCHED;
	s_add_i32 s51, 0, 0x18000
	v_add_u32_e32 v147, s51, v145
	s_add_i32 s75, 0, 0x1c000
	ds_read_b128 v[148:151], v147
	ds_read_b128 v[152:155], v147 offset:1024
	ds_read_b128 v[156:159], v147 offset:2048
	ds_read_b128 v[160:163], v147 offset:3072
	v_add_u32_e32 v147, s75, v145
	ds_read_b128 v[164:167], v147
	ds_read_b128 v[168:171], v147 offset:1024
	ds_read_b128 v[172:175], v147 offset:2048
	ds_read_b128 v[176:179], v147 offset:3072
	s_add_u32 s28, s28, 0x80000
	s_addc_u32 s29, s29, 0
	s_mov_b32 m0, s53
	v_lshl_add_u64 v[228:229], s[28:29], 0, v[130:131]
	ds_read_b128 v[180:183], v146 offset:32768
	ds_read_b128 v[196:199], v146 offset:33792
	ds_read_b128 v[200:203], v146 offset:34816
	ds_read_b128 v[204:207], v146 offset:35840
	ds_read_b128 v[208:211], v146 offset:36864
	ds_read_b128 v[212:215], v146 offset:37888
	ds_read_b128 v[216:219], v146 offset:38912
	ds_read_b128 v[220:223], v146 offset:39936
	global_load_lds_dwordx4 v[228:229], off
	v_lshl_add_u64 v[228:229], s[28:29], 0, v[134:135]
	s_mov_b32 m0, s56
	s_nop 0
	global_load_lds_dwordx4 v[228:229], off
	s_waitcnt vmcnt(8)
	s_waitcnt lgkmcnt(0)
	s_barrier
	s_setprio 1
	s_waitcnt lgkmcnt(0)
	v_mfma_f32_16x16x32_bf16 v[126:129], v[148:151], v[180:183], v[126:129]
	v_mfma_f32_16x16x32_bf16 v[122:125], v[156:159], v[180:183], v[122:125]
	v_mfma_f32_16x16x32_bf16 v[114:117], v[148:151], v[200:203], v[114:117]
	v_mfma_f32_16x16x32_bf16 v[106:109], v[156:159], v[200:203], v[106:109]
	v_mfma_f32_16x16x32_bf16 v[98:101], v[148:151], v[208:211], v[98:101]
	v_mfma_f32_16x16x32_bf16 v[90:93], v[156:159], v[208:211], v[90:93]
	v_mfma_f32_16x16x32_bf16 v[82:85], v[148:151], v[216:219], v[82:85]
	v_mfma_f32_16x16x32_bf16 v[74:77], v[156:159], v[216:219], v[74:77]
	v_mfma_f32_16x16x32_bf16 v[126:129], v[152:155], v[196:199], v[126:129]
	v_mfma_f32_16x16x32_bf16 v[122:125], v[160:163], v[196:199], v[122:125]
	v_mfma_f32_16x16x32_bf16 v[114:117], v[152:155], v[204:207], v[114:117]
	v_mfma_f32_16x16x32_bf16 v[106:109], v[160:163], v[204:207], v[106:109]
	v_mfma_f32_16x16x32_bf16 v[98:101], v[152:155], v[212:215], v[98:101]
	v_mfma_f32_16x16x32_bf16 v[90:93], v[160:163], v[212:215], v[90:93]
	v_mfma_f32_16x16x32_bf16 v[82:85], v[152:155], v[220:223], v[82:85]
	v_mfma_f32_16x16x32_bf16 v[74:77], v[160:163], v[220:223], v[74:77]
	s_setprio 0
	s_setprio 1
	v_mfma_f32_16x16x32_bf16 v[118:121], v[164:167], v[180:183], v[118:121]
	v_mfma_f32_16x16x32_bf16 v[110:113], v[172:175], v[180:183], v[110:113]
	v_mfma_f32_16x16x32_bf16 v[102:105], v[164:167], v[200:203], v[102:105]
	v_mfma_f32_16x16x32_bf16 v[94:97], v[172:175], v[200:203], v[94:97]
	v_mfma_f32_16x16x32_bf16 v[86:89], v[164:167], v[208:211], v[86:89]
	v_mfma_f32_16x16x32_bf16 v[78:81], v[172:175], v[208:211], v[78:81]
	v_mfma_f32_16x16x32_bf16 v[70:73], v[164:167], v[216:219], v[70:73]
	v_mfma_f32_16x16x32_bf16 v[66:69], v[172:175], v[216:219], v[66:69]
	v_mfma_f32_16x16x32_bf16 v[118:121], v[168:171], v[196:199], v[118:121]
	v_mfma_f32_16x16x32_bf16 v[110:113], v[176:179], v[196:199], v[110:113]
	v_mfma_f32_16x16x32_bf16 v[102:105], v[168:171], v[204:207], v[102:105]
	v_mfma_f32_16x16x32_bf16 v[94:97], v[176:179], v[204:207], v[94:97]
	v_mfma_f32_16x16x32_bf16 v[86:89], v[168:171], v[212:215], v[86:89]
	v_mfma_f32_16x16x32_bf16 v[78:81], v[176:179], v[212:215], v[78:81]
	v_mfma_f32_16x16x32_bf16 v[70:73], v[168:171], v[220:223], v[70:73]
	v_mfma_f32_16x16x32_bf16 v[66:69], v[176:179], v[220:223], v[66:69]
	s_setprio 0
	s_barrier
; #define PG8_STAGE(bufoff, gbase, voff) do { _Pragma("unroll") for (int _i = 0; _i < 2; ++_i) \
;         __builtin_amdgcn_global_load_lds((const unsigned*)((const char*)(gbase) + (voff)[_i]), (PG8_LAS unsigned*)(lds + (bufoff) + ldsw + _i * 8192), 16, 0, 0); } while (0)
; #define PG8_LDA(dst, b, h) do { _Pragma("unroll") for (int m = 0; m < 4; ++m) _Pragma("unroll") for (int k = 0; k < 2; ++k) dst[m][k] = *(const PG8_LAS bf16x8*)(lds + PG8_SA(b, h) + aoff + m * 2048 + k * 1024); } while (0)
; #define PG8_MMA(ai, bj, At, Bt) do { __builtin_amdgcn_s_setprio(1); _Pragma("unroll") for (int m = 0; m < 4; ++m) _Pragma("unroll") for (int n = 0; n < 2; ++n) _Pragma("unroll") for (int k = 0; k < 2; ++k) \
;         acc[ai][bj][m][n] = __builtin_amdgcn_mfma_f32_16x16x32_bf16(Bt[n][k], At[m][k], acc[ai][bj][m][n], 0, 0, 0); __builtin_amdgcn_s_setprio(0); } while (0)
; #define PG8_WAIT_V(n) asm volatile("s_waitcnt vmcnt(" #n ")" ::: "memory")
; #define PG8_WAIT_L(n) asm volatile("s_waitcnt lgkmcnt(" #n ")" ::: "memory")
; #define PG8_BAR __builtin_amdgcn_s_barrier()
; #define PG8_SCHED __builtin_amdgcn_sched_barrier(0)
; template <class Epi, class Sched, bool ALIGN_EPI = false, bool SP2 = false, bool ABLK = false, bool BBLK = false>
; __device__ __forceinline__ void gemm_phase(PG8_LAS unsigned char* lds, const Gemm g, const Sched& S, const Epi& E) {
;     ...
;             PG8_LDA(At, 1, 1); PG8_STAGE(PG8_SB(1, 0), b3, voffB); PG8_STAGE(PG8_SB(1, 1), b3 + hstepB, voffB); PG8_STAGE(PG8_SA(1, 0), a3, voffA);
;             PG8_WAIT_V(8); PG8_WAIT_L(0); PG8_BAR; PG8_MMA(1, 0, At, B0); PG8_MMA(1, 1, At, B1); PG8_BAR; PG8_SCHED;
;     ...
;         if constexpr (ALIGN_EPI) { if (wr == 0) PG8_BAR; }
	s_add_i32 s28, s51, s35
	v_lshl_add_u64 v[142:143], v[142:143], 0, s[62:63]
	s_mov_b32 m0, s28
	ds_read_b128 v[180:183], v146 offset:49152
	ds_read_b128 v[196:199], v146 offset:50176
	ds_read_b128 v[200:203], v146 offset:51200
	ds_read_b128 v[204:207], v146 offset:52224
	ds_read_b128 v[208:211], v146 offset:53248
	ds_read_b128 v[212:215], v146 offset:54272
	ds_read_b128 v[216:219], v146 offset:55296
	ds_read_b128 v[220:223], v146 offset:56320
	global_load_lds_dwordx4 v[142:143], off
	s_add_i32 m0, s28, 0x2000
	s_add_u32 s26, s26, 0x80080
	v_lshl_add_u64 v[142:143], v[184:185], 0, s[62:63]
	s_addc_u32 s27, s27, 0
	s_add_i32 s28, s75, s35
	global_load_lds_dwordx4 v[142:143], off
	v_lshl_add_u64 v[142:143], s[26:27], 0, v[132:133]
	s_mov_b32 m0, s28
	s_nop 0
	global_load_lds_dwordx4 v[142:143], off
	v_lshl_add_u64 v[142:143], s[26:27], 0, v[136:137]
	s_add_i32 m0, s28, 0x2000
	s_nop 0
	global_load_lds_dwordx4 v[142:143], off
	v_lshl_add_u64 v[142:143], v[224:225], 0, s[62:63]
	s_mov_b32 m0, s61
	s_nop 0
	global_load_lds_dwordx4 v[142:143], off
	v_lshl_add_u64 v[142:143], v[226:227], 0, s[62:63]
	s_mov_b32 m0, s65
	s_nop 0
	global_load_lds_dwordx4 v[142:143], off
	s_waitcnt vmcnt(8)
	s_waitcnt lgkmcnt(0)
	s_barrier
	s_setprio 1
	s_waitcnt lgkmcnt(0)
	v_mfma_f32_16x16x32_bf16 v[62:65], v[148:151], v[180:183], v[62:65]
	v_mfma_f32_16x16x32_bf16 v[58:61], v[156:159], v[180:183], v[58:61]
	v_mfma_f32_16x16x32_bf16 v[50:53], v[148:151], v[200:203], v[50:53]
	v_mfma_f32_16x16x32_bf16 v[42:45], v[156:159], v[200:203], v[42:45]
	v_mfma_f32_16x16x32_bf16 v[34:37], v[148:151], v[208:211], v[34:37]
	v_mfma_f32_16x16x32_bf16 v[26:29], v[156:159], v[208:211], v[26:29]
	v_mfma_f32_16x16x32_bf16 v[18:21], v[148:151], v[216:219], v[18:21]
	v_mfma_f32_16x16x32_bf16 v[10:13], v[156:159], v[216:219], v[10:13]
	v_mfma_f32_16x16x32_bf16 v[62:65], v[152:155], v[196:199], v[62:65]
	v_mfma_f32_16x16x32_bf16 v[58:61], v[160:163], v[196:199], v[58:61]
	v_mfma_f32_16x16x32_bf16 v[50:53], v[152:155], v[204:207], v[50:53]
	v_mfma_f32_16x16x32_bf16 v[42:45], v[160:163], v[204:207], v[42:45]
	v_mfma_f32_16x16x32_bf16 v[34:37], v[152:155], v[212:215], v[34:37]
	v_mfma_f32_16x16x32_bf16 v[26:29], v[160:163], v[212:215], v[26:29]
	v_mfma_f32_16x16x32_bf16 v[18:21], v[152:155], v[220:223], v[18:21]
	v_mfma_f32_16x16x32_bf16 v[10:13], v[160:163], v[220:223], v[10:13]
	s_setprio 0
	s_setprio 1
	v_mfma_f32_16x16x32_bf16 v[54:57], v[164:167], v[180:183], v[54:57]
	v_mfma_f32_16x16x32_bf16 v[46:49], v[172:175], v[180:183], v[46:49]
	v_mfma_f32_16x16x32_bf16 v[38:41], v[164:167], v[200:203], v[38:41]
	v_mfma_f32_16x16x32_bf16 v[30:33], v[172:175], v[200:203], v[30:33]
	v_mfma_f32_16x16x32_bf16 v[22:25], v[164:167], v[208:211], v[22:25]
	v_mfma_f32_16x16x32_bf16 v[14:17], v[172:175], v[208:211], v[14:17]
	v_mfma_f32_16x16x32_bf16 v[6:9], v[164:167], v[216:219], v[6:9]
	v_mfma_f32_16x16x32_bf16 v[2:5], v[172:175], v[216:219], v[2:5]
	v_mfma_f32_16x16x32_bf16 v[54:57], v[168:171], v[196:199], v[54:57]
	v_mfma_f32_16x16x32_bf16 v[46:49], v[176:179], v[196:199], v[46:49]
	v_mfma_f32_16x16x32_bf16 v[38:41], v[168:171], v[204:207], v[38:41]
	v_mfma_f32_16x16x32_bf16 v[30:33], v[176:179], v[204:207], v[30:33]
	v_mfma_f32_16x16x32_bf16 v[22:25], v[168:171], v[212:215], v[22:25]
	v_mfma_f32_16x16x32_bf16 v[14:17], v[176:179], v[212:215], v[14:17]
	v_mfma_f32_16x16x32_bf16 v[6:9], v[168:171], v[220:223], v[6:9]
	v_mfma_f32_16x16x32_bf16 v[2:5], v[176:179], v[220:223], v[2:5]
	s_setprio 0
	s_barrier
	s_add_i32 s81, s81, 2
	s_add_u32 s24, s24, 0x100
	s_addc_u32 s25, s25, 0
	s_add_u32 s23, s23, 0x100
	s_addc_u32 s73, s73, 0
	s_cmp_gt_u32 s81, 29
	s_cbranch_scc0 .LBB0_790
	s_and_b64 vcc, exec, s[8:9]
	s_cbranch_vccz .LBB0_793
	s_barrier

; #define PG8_STAGE(bufoff, gbase, voff) do { _Pragma("unroll") for (int _i = 0; _i < 2; ++_i) \
;         __builtin_amdgcn_global_load_lds((const unsigned*)((const char*)(gbase) + (voff)[_i]), (PG8_LAS unsigned*)(lds + (bufoff) + ldsw + _i * 8192), 16, 0, 0); } while (0)
; #define PG8_LDA(dst, b, h) do { _Pragma("unroll") for (int m = 0; m < 4; ++m) _Pragma("unroll") for (int k = 0; k < 2; ++k) dst[m][k] = *(const PG8_LAS bf16x8*)(lds + PG8_SA(b, h) + aoff + m * 2048 + k * 1024); } while (0)
; #define PG8_LDB(dst, b, h) do { _Pragma("unroll") for (int n = 0; n < 2; ++n) _Pragma("unroll") for (int k = 0; k < 2; ++k) dst[n][k] = *(const PG8_LAS bf16x8*)(lds + PG8_SB(b, h) + boff + n * 2048 + k * 1024); } while (0)
; #define PG8_WAIT_V(n) asm volatile("s_waitcnt vmcnt(" #n ")" ::: "memory")
; #define PG8_WAIT_L(n) asm volatile("s_waitcnt lgkmcnt(" #n ")" ::: "memory")
; #define PG8_BAR __builtin_amdgcn_s_barrier()
; template <class Epi, class Sched, bool ALIGN_EPI = false, bool SP2 = false, bool ABLK = false, bool BBLK = false>
; __device__ __forceinline__ void gemm_phase(PG8_LAS unsigned char* lds, const Gemm g, const Sched& S, const Epi& E) {
;     ...
;         const bool has_next = S.next(ui + 1, nxt);
;         const char* nA = has_next ? (const char*)g.A + (size_t)nxt.pm * tstepA : cA; const char* nB = has_next ? (const char*)g.Bt + (size_t)nxt.pn * tstepB : cB;
;         for (int t = 0; t < nt; t += 2) {
;             const bool last = (t == nt - 2);
;             const char* a1 = cA + (size_t)(t + 1) * kstepA;
;             const char* a2 = last ? nA : cA + (size_t)(t + 2) * kstepA; const char* b2 = last ? nB : cB + (size_t)(t + 2) * kstepB;
;             const char* a3 = a2 + kstepA; const char* b3 = b2 + kstepB;
;             if (last && has_next) S.a_ready(nxt);
;             if constexpr (SP2) {
;             PG8_LDB(B0, 0, 0); PG8_LDB(B1, 0, 1); PG8_SCHED; PG8_LDA(At, 0, 0); PG8_STAGE(PG8_SA(1, 1), a1 + hstepA, voffA);
;             PG8_WAIT_V(8); PG8_WAIT_L(0); PG8_BAR; PG8_MMA(0, 0, At, B0); PG8_MMA(0, 1, At, B1); PG8_BAR; PG8_SCHED;
;     ...
;         for (int a = 0; a < 2; ++a)
; #pragma unroll
;             for (int b = 0; b < 2; ++b)
; #pragma unroll
;                 for (int m = 0; m < 4; ++m)
; #pragma unroll
;                     for (int n = 0; n < 2; ++n) acc[a][b][m][n] = (f32x4){0.f, 0.f, 0.f, 0.f};
.LBB0_1116:
	s_ashr_i32 s23, s22, 31
	s_lshl_b64 s[24:25], s[22:23], 18
	s_add_u32 s24, s33, s24
	s_addc_u32 s25, s44, s25
	s_and_b64 s[26:27], s[6:7], exec
	s_cselect_b32 s23, s25, s35
	s_cselect_b32 s31, s24, s34
	s_ashr_i32 s21, s20, 31
	s_lshl_b64 s[26:27], s[20:21], 18
	s_add_u32 s26, s45, s26
	s_addc_u32 s27, s46, s27
	s_and_b64 s[36:37], s[6:7], exec
	s_cselect_b32 s21, s27, s1
	s_cselect_b32 s91, s26, s0
	s_add_u32 s92, s0, 0x10000
	s_addc_u32 s93, s1, 0
	s_add_u32 s0, s34, 0x20080
	v_mov_b32_e32 v2, 0
	s_addc_u32 s1, s35, 0
	s_mov_b32 s94, -2
	s_add_u32 s34, s0, 0xfffe0080
	s_addc_u32 s35, s1, -1
	s_add_i32 s52, 0, 0x10000
	s_cmp_eq_u32 s94, 4
	s_cselect_b32 s37, s23, s35
	s_cselect_b32 s36, s31, s34
	s_cselect_b32 s35, s21, s93
	s_cselect_b32 s34, s91, s92
	s_add_i32 s75, 0, 0x14000
	v_add_u32_e32 v142, s52, v163
	v_add_u32_e32 v160, s75, v163
	ds_read_b128 v[130:133], v142
	v_pk_mov_b32 v[2:3], 0, 0
	v_pk_mov_b32 v[4:5], 0, 0
	v_pk_mov_b32 v[6:7], 0, 0
	v_pk_mov_b32 v[8:9], 0, 0
	ds_read_b128 v[134:137], v142 offset:1024
	v_pk_mov_b32 v[10:11], 0, 0
	v_pk_mov_b32 v[12:13], 0, 0
	v_pk_mov_b32 v[14:15], 0, 0
	v_pk_mov_b32 v[16:17], 0, 0
	ds_read_b128 v[138:141], v142 offset:2048
	v_pk_mov_b32 v[18:19], 0, 0
	v_pk_mov_b32 v[20:21], 0, 0
	v_pk_mov_b32 v[22:23], 0, 0
	v_pk_mov_b32 v[24:25], 0, 0
	ds_read_b128 v[142:145], v142 offset:3072
	v_pk_mov_b32 v[26:27], 0, 0
	v_pk_mov_b32 v[28:29], 0, 0
	v_pk_mov_b32 v[30:31], 0, 0
	v_pk_mov_b32 v[32:33], 0, 0
	ds_read_b128 v[146:149], v160
	v_pk_mov_b32 v[34:35], 0, 0
	v_pk_mov_b32 v[36:37], 0, 0
	v_pk_mov_b32 v[38:39], 0, 0
	v_pk_mov_b32 v[40:41], 0, 0
	ds_read_b128 v[166:169], v160 offset:1024
	v_pk_mov_b32 v[42:43], 0, 0
	v_pk_mov_b32 v[44:45], 0, 0
	v_pk_mov_b32 v[46:47], 0, 0
	v_pk_mov_b32 v[48:49], 0, 0
	ds_read_b128 v[170:173], v160 offset:2048
	v_pk_mov_b32 v[50:51], 0, 0
	v_pk_mov_b32 v[52:53], 0, 0
	v_pk_mov_b32 v[54:55], 0, 0
	v_pk_mov_b32 v[56:57], 0, 0
	ds_read_b128 v[174:177], v160 offset:3072
	v_pk_mov_b32 v[58:59], 0, 0
	v_pk_mov_b32 v[60:61], 0, 0
	v_pk_mov_b32 v[62:63], 0, 0
	v_pk_mov_b32 v[64:65], 0, 0
	v_lshl_add_u64 v[160:161], s[0:1], 0, v[156:157]
	s_add_i32 m0, s29, 0xc000
	ds_read_b128 v[178:181], v165
	v_pk_mov_b32 v[66:67], 0, 0
	v_pk_mov_b32 v[68:69], 0, 0
	v_pk_mov_b32 v[70:71], 0, 0
	v_pk_mov_b32 v[72:73], 0, 0
	ds_read_b128 v[182:185], v165 offset:1024
	v_pk_mov_b32 v[74:75], 0, 0
	v_pk_mov_b32 v[76:77], 0, 0
	v_pk_mov_b32 v[78:79], 0, 0
	v_pk_mov_b32 v[80:81], 0, 0
	ds_read_b128 v[196:199], v165 offset:2048
	v_pk_mov_b32 v[82:83], 0, 0
	v_pk_mov_b32 v[84:85], 0, 0
	v_pk_mov_b32 v[86:87], 0, 0
	v_pk_mov_b32 v[88:89], 0, 0
	ds_read_b128 v[200:203], v165 offset:3072
	v_pk_mov_b32 v[90:91], 0, 0
	v_pk_mov_b32 v[92:93], 0, 0
	v_pk_mov_b32 v[94:95], 0, 0
	v_pk_mov_b32 v[96:97], 0, 0
	ds_read_b128 v[204:207], v165 offset:4096
	v_pk_mov_b32 v[98:99], 0, 0
	v_pk_mov_b32 v[100:101], 0, 0
	v_pk_mov_b32 v[102:103], 0, 0
	v_pk_mov_b32 v[104:105], 0, 0
	ds_read_b128 v[208:211], v165 offset:5120
	v_pk_mov_b32 v[106:107], 0, 0
	v_pk_mov_b32 v[108:109], 0, 0
	v_pk_mov_b32 v[110:111], 0, 0
	v_pk_mov_b32 v[112:113], 0, 0
	ds_read_b128 v[212:215], v165 offset:6144
	v_pk_mov_b32 v[114:115], 0, 0
	v_pk_mov_b32 v[116:117], 0, 0
	v_pk_mov_b32 v[118:119], 0, 0
	v_pk_mov_b32 v[120:121], 0, 0
	ds_read_b128 v[216:219], v165 offset:7168
	v_pk_mov_b32 v[122:123], 0, 0
	v_pk_mov_b32 v[124:125], 0, 0
	v_pk_mov_b32 v[126:127], 0, 0
	v_pk_mov_b32 v[128:129], 0, 0
	global_load_lds_dwordx4 v[160:161], off
	v_lshl_add_u64 v[160:161], s[0:1], 0, v[158:159]
	s_add_i32 m0, s29, 0xe000
	s_nop 0
	global_load_lds_dwordx4 v[160:161], off
	s_waitcnt vmcnt(8)
	s_waitcnt lgkmcnt(0)
	s_barrier
	s_branch .Lpeel_1117

; #define PG8_STAGE(bufoff, gbase, voff) do { _Pragma("unroll") for (int _i = 0; _i < 2; ++_i) \
;         __builtin_amdgcn_global_load_lds((const unsigned*)((const char*)(gbase) + (voff)[_i]), (PG8_LAS unsigned*)(lds + (bufoff) + ldsw + _i * 8192), 16, 0, 0); } while (0)
; #define PG8_LDA(dst, b, h) do { _Pragma("unroll") for (int m = 0; m < 4; ++m) _Pragma("unroll") for (int k = 0; k < 2; ++k) dst[m][k] = *(const PG8_LAS bf16x8*)(lds + PG8_SA(b, h) + aoff + m * 2048 + k * 1024); } while (0)
; #define PG8_MMA(ai, bj, At, Bt) do { __builtin_amdgcn_s_setprio(1); _Pragma("unroll") for (int m = 0; m < 4; ++m) _Pragma("unroll") for (int n = 0; n < 2; ++n) _Pragma("unroll") for (int k = 0; k < 2; ++k) \
;         acc[ai][bj][m][n] = __builtin_amdgcn_mfma_f32_16x16x32_bf16(Bt[n][k], At[m][k], acc[ai][bj][m][n], 0, 0, 0); __builtin_amdgcn_s_setprio(0); } while (0)
; #define PG8_WAIT_V(n) asm volatile("s_waitcnt vmcnt(" #n ")" ::: "memory")
; #define PG8_WAIT_L(n) asm volatile("s_waitcnt lgkmcnt(" #n ")" ::: "memory")
; #define PG8_BAR __builtin_amdgcn_s_barrier()
; #define PG8_SCHED __builtin_amdgcn_sched_barrier(0)
; template <class Epi, class Sched, bool ALIGN_EPI = false, bool SP2 = false, bool ABLK = false, bool BBLK = false>
; __device__ __forceinline__ void gemm_phase(PG8_LAS unsigned char* lds, const Gemm g, const Sched& S, const Epi& E) {
;     ...
;             PG8_WAIT_V(8); PG8_WAIT_L(0); PG8_BAR; PG8_MMA(0, 0, At, B0); PG8_MMA(0, 1, At, B1); PG8_BAR; PG8_SCHED;
;             PG8_LDA(At, 0, 1); PG8_STAGE(PG8_SB(0, 0), b2, voffB); PG8_STAGE(PG8_SB(0, 1), b2 + hstepB, voffB); PG8_STAGE(PG8_SA(0, 0), a2, voffA);
;             PG8_WAIT_V(8); PG8_WAIT_L(0); PG8_BAR; PG8_MMA(1, 0, At, B0); PG8_MMA(1, 1, At, B1); PG8_BAR; PG8_SCHED;
.Lpeel_1117:
	s_setprio 1
	s_waitcnt lgkmcnt(0)
	v_mfma_f32_16x16x32_bf16 v[126:129], v[130:133], v[178:181], v[126:129]
	v_mfma_f32_16x16x32_bf16 v[122:125], v[138:141], v[178:181], v[122:125]
	v_mfma_f32_16x16x32_bf16 v[118:121], v[130:133], v[196:199], v[118:121]
	v_mfma_f32_16x16x32_bf16 v[114:117], v[138:141], v[196:199], v[114:117]
	v_mfma_f32_16x16x32_bf16 v[94:97], v[130:133], v[204:207], v[94:97]
	v_mfma_f32_16x16x32_bf16 v[90:93], v[138:141], v[204:207], v[90:93]
	v_mfma_f32_16x16x32_bf16 v[78:81], v[130:133], v[212:215], v[78:81]
	v_mfma_f32_16x16x32_bf16 v[74:77], v[138:141], v[212:215], v[74:77]
	v_mfma_f32_16x16x32_bf16 v[126:129], v[134:137], v[182:185], v[126:129]
	v_mfma_f32_16x16x32_bf16 v[122:125], v[142:145], v[182:185], v[122:125]
	v_mfma_f32_16x16x32_bf16 v[118:121], v[134:137], v[200:203], v[118:121]
	v_mfma_f32_16x16x32_bf16 v[114:117], v[142:145], v[200:203], v[114:117]
	v_mfma_f32_16x16x32_bf16 v[94:97], v[134:137], v[208:211], v[94:97]
	v_mfma_f32_16x16x32_bf16 v[90:93], v[142:145], v[208:211], v[90:93]
	v_mfma_f32_16x16x32_bf16 v[78:81], v[134:137], v[216:219], v[78:81]
	v_mfma_f32_16x16x32_bf16 v[74:77], v[142:145], v[216:219], v[74:77]
	s_setprio 0
	s_setprio 1
	v_mfma_f32_16x16x32_bf16 v[110:113], v[146:149], v[178:181], v[110:113]
	v_mfma_f32_16x16x32_bf16 v[106:109], v[170:173], v[178:181], v[106:109]
	v_mfma_f32_16x16x32_bf16 v[102:105], v[146:149], v[196:199], v[102:105]
	v_mfma_f32_16x16x32_bf16 v[98:101], v[170:173], v[196:199], v[98:101]
	v_mfma_f32_16x16x32_bf16 v[86:89], v[146:149], v[204:207], v[86:89]
	v_mfma_f32_16x16x32_bf16 v[82:85], v[170:173], v[204:207], v[82:85]
	v_mfma_f32_16x16x32_bf16 v[70:73], v[146:149], v[212:215], v[70:73]
	v_mfma_f32_16x16x32_bf16 v[66:69], v[170:173], v[212:215], v[66:69]
	v_mfma_f32_16x16x32_bf16 v[110:113], v[166:169], v[182:185], v[110:113]
	v_mfma_f32_16x16x32_bf16 v[106:109], v[174:177], v[182:185], v[106:109]
	v_mfma_f32_16x16x32_bf16 v[102:105], v[166:169], v[200:203], v[102:105]
	v_mfma_f32_16x16x32_bf16 v[98:101], v[174:177], v[200:203], v[98:101]
	v_mfma_f32_16x16x32_bf16 v[86:89], v[166:169], v[208:211], v[86:89]
	v_mfma_f32_16x16x32_bf16 v[82:85], v[174:177], v[208:211], v[82:85]
	v_mfma_f32_16x16x32_bf16 v[70:73], v[166:169], v[216:219], v[70:73]
	v_mfma_f32_16x16x32_bf16 v[66:69], v[174:177], v[216:219], v[66:69]
	s_setprio 0
	s_barrier
	s_add_i32 s52, s52, s47
	v_lshl_add_u64 v[160:161], s[34:35], 0, v[150:151]
	s_mov_b32 m0, s52
	ds_read_b128 v[178:181], v165 offset:16384
	ds_read_b128 v[182:185], v165 offset:17408
	ds_read_b128 v[196:199], v165 offset:18432
	ds_read_b128 v[200:203], v165 offset:19456
	ds_read_b128 v[204:207], v165 offset:20480
	ds_read_b128 v[208:211], v165 offset:21504
	ds_read_b128 v[212:215], v165 offset:22528
	ds_read_b128 v[216:219], v165 offset:23552
	global_load_lds_dwordx4 v[160:161], off
	s_add_i32 m0, s52, 0x2000
	s_add_u32 s96, s34, 0x4000
	v_lshl_add_u64 v[160:161], s[34:35], 0, v[154:155]
	s_addc_u32 s97, s35, 0
	s_add_i32 s52, s75, s47
	global_load_lds_dwordx4 v[160:161], off
	v_lshl_add_u64 v[160:161], s[96:97], 0, v[150:151]
	s_mov_b32 m0, s52
	v_lshl_add_u64 v[188:189], s[36:37], 0, v[152:153]
	global_load_lds_dwordx4 v[160:161], off
	v_lshl_add_u64 v[160:161], s[96:97], 0, v[154:155]
	s_add_i32 m0, s52, 0x2000
	s_nop 0
	global_load_lds_dwordx4 v[160:161], off
	v_lshl_add_u64 v[160:161], s[36:37], 0, v[186:187]
	s_mov_b32 m0, s29
	s_nop 0
	global_load_lds_dwordx4 v[160:161], off
	s_mov_b32 m0, s65
	s_nop 0
	global_load_lds_dwordx4 v[188:189], off
	s_waitcnt vmcnt(8)
	s_waitcnt lgkmcnt(0)
	s_barrier
	s_setprio 1
	s_waitcnt lgkmcnt(0)
	v_mfma_f32_16x16x32_bf16 v[62:65], v[130:133], v[178:181], v[62:65]
	v_mfma_f32_16x16x32_bf16 v[58:61], v[138:141], v[178:181], v[58:61]
	v_mfma_f32_16x16x32_bf16 v[46:49], v[130:133], v[196:199], v[46:49]
	v_mfma_f32_16x16x32_bf16 v[42:45], v[138:141], v[196:199], v[42:45]
	v_mfma_f32_16x16x32_bf16 v[30:33], v[130:133], v[204:207], v[30:33]
	v_mfma_f32_16x16x32_bf16 v[26:29], v[138:141], v[204:207], v[26:29]
	v_mfma_f32_16x16x32_bf16 v[14:17], v[130:133], v[212:215], v[14:17]
	v_mfma_f32_16x16x32_bf16 v[10:13], v[138:141], v[212:215], v[10:13]
	v_mfma_f32_16x16x32_bf16 v[62:65], v[134:137], v[182:185], v[62:65]
	v_mfma_f32_16x16x32_bf16 v[58:61], v[142:145], v[182:185], v[58:61]
	v_mfma_f32_16x16x32_bf16 v[46:49], v[134:137], v[200:203], v[46:49]
	v_mfma_f32_16x16x32_bf16 v[42:45], v[142:145], v[200:203], v[42:45]
	v_mfma_f32_16x16x32_bf16 v[30:33], v[134:137], v[208:211], v[30:33]
	v_mfma_f32_16x16x32_bf16 v[26:29], v[142:145], v[208:211], v[26:29]
	v_mfma_f32_16x16x32_bf16 v[14:17], v[134:137], v[216:219], v[14:17]
	v_mfma_f32_16x16x32_bf16 v[10:13], v[142:145], v[216:219], v[10:13]
	s_setprio 0
	s_setprio 1
	v_mfma_f32_16x16x32_bf16 v[54:57], v[146:149], v[178:181], v[54:57]
	v_mfma_f32_16x16x32_bf16 v[50:53], v[170:173], v[178:181], v[50:53]
	v_mfma_f32_16x16x32_bf16 v[38:41], v[146:149], v[196:199], v[38:41]
	v_mfma_f32_16x16x32_bf16 v[34:37], v[170:173], v[196:199], v[34:37]
	v_mfma_f32_16x16x32_bf16 v[22:25], v[146:149], v[204:207], v[22:25]
	v_mfma_f32_16x16x32_bf16 v[18:21], v[170:173], v[204:207], v[18:21]
	v_mfma_f32_16x16x32_bf16 v[6:9], v[146:149], v[212:215], v[6:9]
	v_mfma_f32_16x16x32_bf16 v[2:5], v[170:173], v[212:215], v[2:5]
	v_mfma_f32_16x16x32_bf16 v[54:57], v[166:169], v[182:185], v[54:57]
	v_mfma_f32_16x16x32_bf16 v[50:53], v[174:177], v[182:185], v[50:53]
	v_mfma_f32_16x16x32_bf16 v[38:41], v[166:169], v[200:203], v[38:41]
	v_mfma_f32_16x16x32_bf16 v[34:37], v[174:177], v[200:203], v[34:37]
	v_mfma_f32_16x16x32_bf16 v[22:25], v[166:169], v[208:211], v[22:25]
	v_mfma_f32_16x16x32_bf16 v[18:21], v[174:177], v[208:211], v[18:21]
	v_mfma_f32_16x16x32_bf16 v[6:9], v[166:169], v[216:219], v[6:9]
	v_mfma_f32_16x16x32_bf16 v[2:5], v[174:177], v[216:219], v[2:5]
	s_setprio 0
	s_barrier
; #define PG8_STAGE(bufoff, gbase, voff) do { _Pragma("unroll") for (int _i = 0; _i < 2; ++_i) \
;         __builtin_amdgcn_global_load_lds((const unsigned*)((const char*)(gbase) + (voff)[_i]), (PG8_LAS unsigned*)(lds + (bufoff) + ldsw + _i * 8192), 16, 0, 0); } while (0)
; #define PG8_LDA(dst, b, h) do { _Pragma("unroll") for (int m = 0; m < 4; ++m) _Pragma("unroll") for (int k = 0; k < 2; ++k) dst[m][k] = *(const PG8_LAS bf16x8*)(lds + PG8_SA(b, h) + aoff + m * 2048 + k * 1024); } while (0)
; #define PG8_LDB(dst, b, h) do { _Pragma("unroll") for (int n = 0; n < 2; ++n) _Pragma("unroll") for (int k = 0; k < 2; ++k) dst[n][k] = *(const PG8_LAS bf16x8*)(lds + PG8_SB(b, h) + boff + n * 2048 + k * 1024); } while (0)
; #define PG8_MMA(ai, bj, At, Bt) do { __builtin_amdgcn_s_setprio(1); _Pragma("unroll") for (int m = 0; m < 4; ++m) _Pragma("unroll") for (int n = 0; n < 2; ++n) _Pragma("unroll") for (int k = 0; k < 2; ++k) \
;         acc[ai][bj][m][n] = __builtin_amdgcn_mfma_f32_16x16x32_bf16(Bt[n][k], At[m][k], acc[ai][bj][m][n], 0, 0, 0); __builtin_amdgcn_s_setprio(0); } while (0)
; #define PG8_WAIT_V(n) asm volatile("s_waitcnt vmcnt(" #n ")" ::: "memory")
; #define PG8_WAIT_L(n) asm volatile("s_waitcnt lgkmcnt(" #n ")" ::: "memory")
; #define PG8_BAR __builtin_amdgcn_s_barrier()
; #define PG8_SCHED __builtin_amdgcn_sched_barrier(0)
; template <class Epi, class Sched, bool ALIGN_EPI = false, bool SP2 = false, bool ABLK = false, bool BBLK = false>
; __device__ __forceinline__ void gemm_phase(PG8_LAS unsigned char* lds, const Gemm g, const Sched& S, const Epi& E) {
;     ...
;             PG8_LDB(B0, 1, 0); PG8_LDB(B1, 1, 1); PG8_SCHED; PG8_LDA(At, 1, 0); PG8_STAGE(PG8_SA(0, 1), a2 + hstepA, voffA);
;             PG8_WAIT_V(8); PG8_WAIT_L(0); PG8_BAR; PG8_MMA(0, 0, At, B0); PG8_MMA(0, 1, At, B1); PG8_BAR; PG8_SCHED;
	s_add_i32 s52, 0, 0x18000
	s_add_i32 s75, 0, 0x1c000
	v_add_u32_e32 v142, s52, v163
	v_add_u32_e32 v174, s75, v163
	ds_read_b128 v[130:133], v142
	ds_read_b128 v[134:137], v142 offset:1024
	ds_read_b128 v[138:141], v142 offset:2048
	ds_read_b128 v[142:145], v142 offset:3072
	ds_read_b128 v[146:149], v174
	ds_read_b128 v[166:169], v174 offset:1024
	ds_read_b128 v[170:173], v174 offset:2048
	ds_read_b128 v[174:177], v174 offset:3072
	s_add_u32 s36, s36, 0x20000
	s_addc_u32 s37, s37, 0
	s_mov_b32 m0, s68
	v_lshl_add_u64 v[190:191], s[36:37], 0, v[186:187]
	ds_read_b128 v[178:181], v165 offset:32768
	ds_read_b128 v[182:185], v165 offset:33792
	ds_read_b128 v[196:199], v165 offset:34816
	ds_read_b128 v[200:203], v165 offset:35840
	ds_read_b128 v[204:207], v165 offset:36864
	ds_read_b128 v[208:211], v165 offset:37888
	ds_read_b128 v[212:215], v165 offset:38912
	ds_read_b128 v[216:219], v165 offset:39936
	global_load_lds_dwordx4 v[190:191], off
	v_lshl_add_u64 v[190:191], s[36:37], 0, v[152:153]
	s_mov_b32 m0, s72
	s_nop 0
	global_load_lds_dwordx4 v[190:191], off
	s_waitcnt vmcnt(8)
	s_waitcnt lgkmcnt(0)
	s_barrier
	s_setprio 1
	s_waitcnt lgkmcnt(0)
	v_mfma_f32_16x16x32_bf16 v[126:129], v[130:133], v[178:181], v[126:129]
	v_mfma_f32_16x16x32_bf16 v[122:125], v[138:141], v[178:181], v[122:125]
	v_mfma_f32_16x16x32_bf16 v[118:121], v[130:133], v[196:199], v[118:121]
	v_mfma_f32_16x16x32_bf16 v[114:117], v[138:141], v[196:199], v[114:117]
	v_mfma_f32_16x16x32_bf16 v[94:97], v[130:133], v[204:207], v[94:97]
	v_mfma_f32_16x16x32_bf16 v[90:93], v[138:141], v[204:207], v[90:93]
	v_mfma_f32_16x16x32_bf16 v[78:81], v[130:133], v[212:215], v[78:81]
	v_mfma_f32_16x16x32_bf16 v[74:77], v[138:141], v[212:215], v[74:77]
	v_mfma_f32_16x16x32_bf16 v[126:129], v[134:137], v[182:185], v[126:129]
	v_mfma_f32_16x16x32_bf16 v[122:125], v[142:145], v[182:185], v[122:125]
	v_mfma_f32_16x16x32_bf16 v[118:121], v[134:137], v[200:203], v[118:121]
	v_mfma_f32_16x16x32_bf16 v[114:117], v[142:145], v[200:203], v[114:117]
	v_mfma_f32_16x16x32_bf16 v[94:97], v[134:137], v[208:211], v[94:97]
	v_mfma_f32_16x16x32_bf16 v[90:93], v[142:145], v[208:211], v[90:93]
	v_mfma_f32_16x16x32_bf16 v[78:81], v[134:137], v[216:219], v[78:81]
	v_mfma_f32_16x16x32_bf16 v[74:77], v[142:145], v[216:219], v[74:77]
	s_setprio 0
	s_setprio 1
	v_mfma_f32_16x16x32_bf16 v[110:113], v[146:149], v[178:181], v[110:113]
	v_mfma_f32_16x16x32_bf16 v[106:109], v[170:173], v[178:181], v[106:109]
	v_mfma_f32_16x16x32_bf16 v[102:105], v[146:149], v[196:199], v[102:105]
	v_mfma_f32_16x16x32_bf16 v[98:101], v[170:173], v[196:199], v[98:101]
	v_mfma_f32_16x16x32_bf16 v[86:89], v[146:149], v[204:207], v[86:89]
	v_mfma_f32_16x16x32_bf16 v[82:85], v[170:173], v[204:207], v[82:85]
	v_mfma_f32_16x16x32_bf16 v[70:73], v[146:149], v[212:215], v[70:73]
	v_mfma_f32_16x16x32_bf16 v[66:69], v[170:173], v[212:215], v[66:69]
	v_mfma_f32_16x16x32_bf16 v[110:113], v[166:169], v[182:185], v[110:113]
	v_mfma_f32_16x16x32_bf16 v[106:109], v[174:177], v[182:185], v[106:109]
	v_mfma_f32_16x16x32_bf16 v[102:105], v[166:169], v[200:203], v[102:105]
	v_mfma_f32_16x16x32_bf16 v[98:101], v[174:177], v[200:203], v[98:101]
	v_mfma_f32_16x16x32_bf16 v[86:89], v[166:169], v[208:211], v[86:89]
	v_mfma_f32_16x16x32_bf16 v[82:85], v[174:177], v[208:211], v[82:85]
	v_mfma_f32_16x16x32_bf16 v[70:73], v[166:169], v[216:219], v[70:73]
	v_mfma_f32_16x16x32_bf16 v[66:69], v[174:177], v[216:219], v[66:69]
	s_setprio 0
	s_barrier
; #define PG8_STAGE(bufoff, gbase, voff) do { _Pragma("unroll") for (int _i = 0; _i < 2; ++_i) \
;         __builtin_amdgcn_global_load_lds((const unsigned*)((const char*)(gbase) + (voff)[_i]), (PG8_LAS unsigned*)(lds + (bufoff) + ldsw + _i * 8192), 16, 0, 0); } while (0)
; #define PG8_LDA(dst, b, h) do { _Pragma("unroll") for (int m = 0; m < 4; ++m) _Pragma("unroll") for (int k = 0; k < 2; ++k) dst[m][k] = *(const PG8_LAS bf16x8*)(lds + PG8_SA(b, h) + aoff + m * 2048 + k * 1024); } while (0)
; #define PG8_LDB(dst, b, h) do { _Pragma("unroll") for (int n = 0; n < 2; ++n) _Pragma("unroll") for (int k = 0; k < 2; ++k) dst[n][k] = *(const PG8_LAS bf16x8*)(lds + PG8_SB(b, h) + boff + n * 2048 + k * 1024); } while (0)
; #define PG8_WAIT_V(n) asm volatile("s_waitcnt vmcnt(" #n ")" ::: "memory")
; #define PG8_WAIT_L(n) asm volatile("s_waitcnt lgkmcnt(" #n ")" ::: "memory")
; template <class Epi, class Sched, bool ALIGN_EPI = false, bool SP2 = false, bool ABLK = false, bool BBLK = false>
; __device__ __forceinline__ void gemm_phase(PG8_LAS unsigned char* lds, const Gemm g, const Sched& S, const Epi& E) {
;     ...
;             const char* a3 = a2 + kstepA; const char* b3 = b2 + kstepB;
;             if (last && has_next) S.a_ready(nxt);
;             if constexpr (SP2) {
;             PG8_LDB(B0, 0, 0); PG8_LDB(B1, 0, 1); PG8_SCHED; PG8_LDA(At, 0, 0); PG8_STAGE(PG8_SA(1, 1), a1 + hstepA, voffA);
;             PG8_WAIT_V(8); PG8_WAIT_L(0); PG8_BAR; PG8_MMA(0, 0, At, B0); PG8_MMA(0, 1, At, B1); PG8_BAR; PG8_SCHED;
;             PG8_LDA(At, 0, 1); PG8_STAGE(PG8_SB(0, 0), b2, voffB); PG8_STAGE(PG8_SB(0, 1), b2 + hstepB, voffB); PG8_STAGE(PG8_SA(0, 0), a2, voffA);
;             PG8_WAIT_V(8); PG8_WAIT_L(0); PG8_BAR; PG8_MMA(1, 0, At, B0); PG8_MMA(1, 1, At, B1); PG8_BAR; PG8_SCHED;
;             PG8_LDB(B0, 1, 0); PG8_LDB(B1, 1, 1); PG8_SCHED; PG8_LDA(At, 1, 0); PG8_STAGE(PG8_SA(0, 1), a2 + hstepA, voffA);
;             PG8_WAIT_V(8); PG8_WAIT_L(0); PG8_BAR; PG8_MMA(0, 0, At, B0); PG8_MMA(0, 1, At, B1); PG8_BAR; PG8_SCHED;
;             PG8_LDA(At, 1, 1); PG8_STAGE(PG8_SB(1, 0), b3, voffB); PG8_STAGE(PG8_SB(1, 1), b3 + hstepB, voffB); PG8_STAGE(PG8_SA(1, 0), a3, voffA);
;             PG8_WAIT_V(8); PG8_WAIT_L(0); PG8_BAR; PG8_MMA(1, 0, At, B0); PG8_MMA(1, 1, At, B1); PG8_BAR; PG8_SCHED;
;     ...
;         if constexpr (ALIGN_EPI) { if (wr == 0) PG8_BAR; }
	s_add_u32 s36, s34, 0x8000
	s_addc_u32 s37, s35, 0
	s_add_i32 s52, s52, s47
	v_lshl_add_u64 v[190:191], s[36:37], 0, v[150:151]
	s_mov_b32 m0, s52
	ds_read_b128 v[178:181], v165 offset:49152
	ds_read_b128 v[182:185], v165 offset:50176
	ds_read_b128 v[196:199], v165 offset:51200
	ds_read_b128 v[200:203], v165 offset:52224
	ds_read_b128 v[204:207], v165 offset:53248
	ds_read_b128 v[208:211], v165 offset:54272
	ds_read_b128 v[212:215], v165 offset:55296
	ds_read_b128 v[216:219], v165 offset:56320
	global_load_lds_dwordx4 v[190:191], off
	s_add_i32 m0, s52, 0x2000
	s_add_u32 s34, s34, 0xc000
	v_lshl_add_u64 v[190:191], s[36:37], 0, v[154:155]
	s_addc_u32 s35, s35, 0
	s_add_i32 s36, s75, s47
	global_load_lds_dwordx4 v[190:191], off
	v_lshl_add_u64 v[190:191], s[34:35], 0, v[150:151]
	s_mov_b32 m0, s36
	v_lshl_add_u64 v[160:161], v[160:161], 0, s[62:63]
	global_load_lds_dwordx4 v[190:191], off
	v_lshl_add_u64 v[190:191], s[34:35], 0, v[154:155]
	s_add_i32 m0, s36, 0x2000
	s_nop 0
	global_load_lds_dwordx4 v[190:191], off
	s_mov_b32 m0, s86
	s_nop 0
	global_load_lds_dwordx4 v[160:161], off
	v_lshl_add_u64 v[160:161], v[188:189], 0, s[62:63]
	s_mov_b32 m0, s88
	s_nop 0
	global_load_lds_dwordx4 v[160:161], off
	s_waitcnt vmcnt(8)
	s_waitcnt lgkmcnt(0)
	s_barrier
	s_setprio 1
	s_waitcnt lgkmcnt(0)
	v_mfma_f32_16x16x32_bf16 v[62:65], v[130:133], v[178:181], v[62:65]
	v_mfma_f32_16x16x32_bf16 v[58:61], v[138:141], v[178:181], v[58:61]
	v_mfma_f32_16x16x32_bf16 v[46:49], v[130:133], v[196:199], v[46:49]
	v_mfma_f32_16x16x32_bf16 v[42:45], v[138:141], v[196:199], v[42:45]
	v_mfma_f32_16x16x32_bf16 v[30:33], v[130:133], v[204:207], v[30:33]
	v_mfma_f32_16x16x32_bf16 v[26:29], v[138:141], v[204:207], v[26:29]
	v_mfma_f32_16x16x32_bf16 v[14:17], v[130:133], v[212:215], v[14:17]
	v_mfma_f32_16x16x32_bf16 v[10:13], v[138:141], v[212:215], v[10:13]
	v_mfma_f32_16x16x32_bf16 v[62:65], v[134:137], v[182:185], v[62:65]
	v_mfma_f32_16x16x32_bf16 v[58:61], v[142:145], v[182:185], v[58:61]
	v_mfma_f32_16x16x32_bf16 v[46:49], v[134:137], v[200:203], v[46:49]
	v_mfma_f32_16x16x32_bf16 v[42:45], v[142:145], v[200:203], v[42:45]
	v_mfma_f32_16x16x32_bf16 v[30:33], v[134:137], v[208:211], v[30:33]
	v_mfma_f32_16x16x32_bf16 v[26:29], v[142:145], v[208:211], v[26:29]
	v_mfma_f32_16x16x32_bf16 v[14:17], v[134:137], v[216:219], v[14:17]
	v_mfma_f32_16x16x32_bf16 v[10:13], v[142:145], v[216:219], v[10:13]
	s_setprio 0
	s_setprio 1
	v_mfma_f32_16x16x32_bf16 v[54:57], v[146:149], v[178:181], v[54:57]
	v_mfma_f32_16x16x32_bf16 v[50:53], v[170:173], v[178:181], v[50:53]
	v_mfma_f32_16x16x32_bf16 v[38:41], v[146:149], v[196:199], v[38:41]
	v_mfma_f32_16x16x32_bf16 v[34:37], v[170:173], v[196:199], v[34:37]
	v_mfma_f32_16x16x32_bf16 v[22:25], v[146:149], v[204:207], v[22:25]
	v_mfma_f32_16x16x32_bf16 v[18:21], v[170:173], v[204:207], v[18:21]
	v_mfma_f32_16x16x32_bf16 v[6:9], v[146:149], v[212:215], v[6:9]
	v_mfma_f32_16x16x32_bf16 v[2:5], v[170:173], v[212:215], v[2:5]
	v_mfma_f32_16x16x32_bf16 v[54:57], v[166:169], v[182:185], v[54:57]
	v_mfma_f32_16x16x32_bf16 v[50:53], v[174:177], v[182:185], v[50:53]
	v_mfma_f32_16x16x32_bf16 v[38:41], v[166:169], v[200:203], v[38:41]
	v_mfma_f32_16x16x32_bf16 v[34:37], v[174:177], v[200:203], v[34:37]
	v_mfma_f32_16x16x32_bf16 v[22:25], v[166:169], v[208:211], v[22:25]
	v_mfma_f32_16x16x32_bf16 v[18:21], v[174:177], v[208:211], v[18:21]
	v_mfma_f32_16x16x32_bf16 v[6:9], v[166:169], v[216:219], v[6:9]
	v_mfma_f32_16x16x32_bf16 v[2:5], v[174:177], v[216:219], v[2:5]
	s_setprio 0
	s_barrier
	s_add_i32 s94, s94, 2
	s_add_u32 s92, s92, 0x10000
	s_addc_u32 s93, s93, 0
	s_add_u32 s0, s0, 0x100
	s_addc_u32 s1, s1, 0
	s_cmp_gt_u32 s94, 5
	s_cbranch_scc0 .LBB0_1117
	s_and_b64 vcc, exec, s[18:19]
	s_cbranch_vccz .LBB0_1120
	s_barrier

; #define PG8_STAGE(bufoff, gbase, voff) do { _Pragma("unroll") for (int _i = 0; _i < 2; ++_i) \
;         __builtin_amdgcn_global_load_lds((const unsigned*)((const char*)(gbase) + (voff)[_i]), (PG8_LAS unsigned*)(lds + (bufoff) + ldsw + _i * 8192), 16, 0, 0); } while (0)
; #define PG8_LDA(dst, b, h) do { _Pragma("unroll") for (int m = 0; m < 4; ++m) _Pragma("unroll") for (int k = 0; k < 2; ++k) dst[m][k] = *(const PG8_LAS bf16x8*)(lds + PG8_SA(b, h) + aoff + m * 2048 + k * 1024); } while (0)
; #define PG8_LDB(dst, b, h) do { _Pragma("unroll") for (int n = 0; n < 2; ++n) _Pragma("unroll") for (int k = 0; k < 2; ++k) dst[n][k] = *(const PG8_LAS bf16x8*)(lds + PG8_SB(b, h) + boff + n * 2048 + k * 1024); } while (0)
; #define PG8_BAR __builtin_amdgcn_s_barrier()
; #define PG8_SCHED __builtin_amdgcn_sched_barrier(0)
; template <class Epi, class Sched, bool ALIGN_EPI = false, bool SP2 = false, bool ABLK = false, bool BBLK = false>
; __device__ __forceinline__ void gemm_phase(PG8_LAS unsigned char* lds, const Gemm g, const Sched& S, const Epi& E) {
;     ...
;         const bool has_next = S.next(ui + 1, nxt);
;         const char* nA = has_next ? (const char*)g.A + (size_t)nxt.pm * tstepA : cA; const char* nB = has_next ? (const char*)g.Bt + (size_t)nxt.pn * tstepB : cB;
;         for (int t = 0; t < nt; t += 2) {
;             const bool last = (t == nt - 2);
;             const char* a1 = cA + (size_t)(t + 1) * kstepA;
;             const char* a2 = last ? nA : cA + (size_t)(t + 2) * kstepA; const char* b2 = last ? nB : cB + (size_t)(t + 2) * kstepB;
;             const char* a3 = a2 + kstepA; const char* b3 = b2 + kstepB;
;             if (last && has_next) S.a_ready(nxt);
;             if constexpr (SP2) {
;             PG8_LDB(B0, 0, 0); PG8_LDB(B1, 0, 1); PG8_SCHED; PG8_LDA(At, 0, 0); PG8_STAGE(PG8_SA(1, 1), a1 + hstepA, voffA);
;     ...
; #pragma unroll
;         for (int a = 0; a < 2; ++a)
; #pragma unroll
;             for (int b = 0; b < 2; ++b)
; #pragma unroll
;                 for (int m = 0; m < 4; ++m)
; #pragma unroll
;                     for (int n = 0; n < 2; ++n) acc[a][b][m][n] = (f32x4){0.f, 0.f, 0.f, 0.f};
;         cur = nxt; cA = nA; cB = nB; ++ui;
;         if constexpr (ALIGN_EPI) { if (wr == 1) PG8_BAR; }
.LBB0_1139:
	s_ashr_i32 s23, s22, 31
	s_lshl_b64 s[24:25], s[22:23], 19
	s_add_u32 s24, s46, s24
	s_addc_u32 s25, s47, s25
	s_and_b64 s[26:27], s[6:7], exec
	s_cselect_b32 s23, s25, s35
	s_cselect_b32 s31, s24, s34
	s_ashr_i32 s21, s20, 31
	s_lshl_b64 s[26:27], s[20:21], 19
	s_add_u32 s26, s33, s26
	s_addc_u32 s27, s44, s27
	s_and_b64 s[36:37], s[6:7], exec
	s_cselect_b32 s21, s27, s1
	s_cselect_b32 s91, s26, s0
	s_add_u32 s92, s0, 0x10000
	s_addc_u32 s93, s1, 0
	s_add_u32 s0, s34, 0x40080
	v_mov_b32_e32 v2, 0
	s_addc_u32 s1, s35, 0
	s_mov_b32 s94, -2
	s_add_u32 s34, s0, 0xfffc0080
	s_addc_u32 s35, s1, -1
	s_add_i32 s52, 0, 0x10000
	s_cmp_eq_u32 s94, 12
	s_cselect_b32 s37, s23, s35
	s_cselect_b32 s36, s31, s34
	s_cselect_b32 s35, s21, s93
	s_cselect_b32 s34, s91, s92
	s_add_i32 s75, 0, 0x14000
	v_add_u32_e32 v142, s52, v223
	v_add_u32_e32 v158, s75, v223
	ds_read_b128 v[130:133], v142
	v_pk_mov_b32 v[2:3], 0, 0
	v_pk_mov_b32 v[4:5], 0, 0
	v_pk_mov_b32 v[6:7], 0, 0
	v_pk_mov_b32 v[8:9], 0, 0
	ds_read_b128 v[134:137], v142 offset:1024
	v_pk_mov_b32 v[10:11], 0, 0
	v_pk_mov_b32 v[12:13], 0, 0
	v_pk_mov_b32 v[14:15], 0, 0
	v_pk_mov_b32 v[16:17], 0, 0
	ds_read_b128 v[138:141], v142 offset:2048
	v_pk_mov_b32 v[18:19], 0, 0
	v_pk_mov_b32 v[20:21], 0, 0
	v_pk_mov_b32 v[22:23], 0, 0
	v_pk_mov_b32 v[24:25], 0, 0
	ds_read_b128 v[142:145], v142 offset:3072
	v_pk_mov_b32 v[26:27], 0, 0
	v_pk_mov_b32 v[28:29], 0, 0
	v_pk_mov_b32 v[30:31], 0, 0
	v_pk_mov_b32 v[32:33], 0, 0
	ds_read_b128 v[146:149], v158
	v_pk_mov_b32 v[34:35], 0, 0
	v_pk_mov_b32 v[36:37], 0, 0
	v_pk_mov_b32 v[38:39], 0, 0
	v_pk_mov_b32 v[40:41], 0, 0
	ds_read_b128 v[150:153], v158 offset:1024
	v_pk_mov_b32 v[42:43], 0, 0
	v_pk_mov_b32 v[44:45], 0, 0
	v_pk_mov_b32 v[46:47], 0, 0
	v_pk_mov_b32 v[48:49], 0, 0
	ds_read_b128 v[154:157], v158 offset:2048
	v_pk_mov_b32 v[50:51], 0, 0
	v_pk_mov_b32 v[52:53], 0, 0
	v_pk_mov_b32 v[54:55], 0, 0
	v_pk_mov_b32 v[56:57], 0, 0
	ds_read_b128 v[158:161], v158 offset:3072
	v_pk_mov_b32 v[58:59], 0, 0
	v_pk_mov_b32 v[60:61], 0, 0
	v_pk_mov_b32 v[62:63], 0, 0
	v_pk_mov_b32 v[64:65], 0, 0
	v_lshl_add_u64 v[188:189], s[0:1], 0, v[202:203]
	s_add_i32 m0, s29, 0xc000
	ds_read_b128 v[162:165], v225
	v_pk_mov_b32 v[66:67], 0, 0
	v_pk_mov_b32 v[68:69], 0, 0
	v_pk_mov_b32 v[70:71], 0, 0
	v_pk_mov_b32 v[72:73], 0, 0
	ds_read_b128 v[166:169], v225 offset:1024
	v_pk_mov_b32 v[74:75], 0, 0
	v_pk_mov_b32 v[76:77], 0, 0
	v_pk_mov_b32 v[78:79], 0, 0
	v_pk_mov_b32 v[80:81], 0, 0
	ds_read_b128 v[170:173], v225 offset:2048
	v_pk_mov_b32 v[82:83], 0, 0
	v_pk_mov_b32 v[84:85], 0, 0
	v_pk_mov_b32 v[86:87], 0, 0
	v_pk_mov_b32 v[88:89], 0, 0
	ds_read_b128 v[174:177], v225 offset:3072
	v_pk_mov_b32 v[90:91], 0, 0
	v_pk_mov_b32 v[92:93], 0, 0
	v_pk_mov_b32 v[94:95], 0, 0
	v_pk_mov_b32 v[96:97], 0, 0
	ds_read_b128 v[178:181], v225 offset:4096
	v_pk_mov_b32 v[98:99], 0, 0
	v_pk_mov_b32 v[100:101], 0, 0
	v_pk_mov_b32 v[102:103], 0, 0
	v_pk_mov_b32 v[104:105], 0, 0
	ds_read_b128 v[182:185], v225 offset:5120
	v_pk_mov_b32 v[106:107], 0, 0
	v_pk_mov_b32 v[108:109], 0, 0
	v_pk_mov_b32 v[110:111], 0, 0
	v_pk_mov_b32 v[112:113], 0, 0
	ds_read_b128 v[206:209], v225 offset:6144
	v_pk_mov_b32 v[114:115], 0, 0
	v_pk_mov_b32 v[116:117], 0, 0
	v_pk_mov_b32 v[118:119], 0, 0
	v_pk_mov_b32 v[120:121], 0, 0
	ds_read_b128 v[210:213], v225 offset:7168
	v_pk_mov_b32 v[122:123], 0, 0
	v_pk_mov_b32 v[124:125], 0, 0
	v_pk_mov_b32 v[126:127], 0, 0
	v_pk_mov_b32 v[128:129], 0, 0
	global_load_lds_dwordx4 v[188:189], off
	v_lshl_add_u64 v[188:189], s[0:1], 0, v[204:205]
	s_add_i32 m0, s29, 0xe000
	s_nop 0
	global_load_lds_dwordx4 v[188:189], off
	s_waitcnt vmcnt(8)
	s_waitcnt lgkmcnt(0)
	s_barrier
	s_branch .Lpeel_1140

; #define PG8_STAGE(bufoff, gbase, voff) do { _Pragma("unroll") for (int _i = 0; _i < 2; ++_i) \
;         __builtin_amdgcn_global_load_lds((const unsigned*)((const char*)(gbase) + (voff)[_i]), (PG8_LAS unsigned*)(lds + (bufoff) + ldsw + _i * 8192), 16, 0, 0); } while (0)
; #define PG8_LDA(dst, b, h) do { _Pragma("unroll") for (int m = 0; m < 4; ++m) _Pragma("unroll") for (int k = 0; k < 2; ++k) dst[m][k] = *(const PG8_LAS bf16x8*)(lds + PG8_SA(b, h) + aoff + m * 2048 + k * 1024); } while (0)
; #define PG8_MMA(ai, bj, At, Bt) do { __builtin_amdgcn_s_setprio(1); _Pragma("unroll") for (int m = 0; m < 4; ++m) _Pragma("unroll") for (int n = 0; n < 2; ++n) _Pragma("unroll") for (int k = 0; k < 2; ++k) \
;         acc[ai][bj][m][n] = __builtin_amdgcn_mfma_f32_16x16x32_bf16(Bt[n][k], At[m][k], acc[ai][bj][m][n], 0, 0, 0); __builtin_amdgcn_s_setprio(0); } while (0)
; #define PG8_WAIT_V(n) asm volatile("s_waitcnt vmcnt(" #n ")" ::: "memory")
; #define PG8_WAIT_L(n) asm volatile("s_waitcnt lgkmcnt(" #n ")" ::: "memory")
; #define PG8_BAR __builtin_amdgcn_s_barrier()
; #define PG8_SCHED __builtin_amdgcn_sched_barrier(0)
; template <class Epi, class Sched, bool ALIGN_EPI = false, bool SP2 = false, bool ABLK = false, bool BBLK = false>
; __device__ __forceinline__ void gemm_phase(PG8_LAS unsigned char* lds, const Gemm g, const Sched& S, const Epi& E) {
;     ...
;             PG8_WAIT_V(8); PG8_WAIT_L(0); PG8_BAR; PG8_MMA(0, 0, At, B0); PG8_MMA(0, 1, At, B1); PG8_BAR; PG8_SCHED;
;             PG8_LDA(At, 0, 1); PG8_STAGE(PG8_SB(0, 0), b2, voffB); PG8_STAGE(PG8_SB(0, 1), b2 + hstepB, voffB); PG8_STAGE(PG8_SA(0, 0), a2, voffA);
;             PG8_WAIT_V(8); PG8_WAIT_L(0); PG8_BAR; PG8_MMA(1, 0, At, B0); PG8_MMA(1, 1, At, B1); PG8_BAR; PG8_SCHED;
.Lpeel_1140:
	s_setprio 1
	s_waitcnt lgkmcnt(0)
	v_mfma_f32_16x16x32_bf16 v[126:129], v[130:133], v[162:165], v[126:129]
	v_mfma_f32_16x16x32_bf16 v[122:125], v[138:141], v[162:165], v[122:125]
	v_mfma_f32_16x16x32_bf16 v[110:113], v[130:133], v[170:173], v[110:113]
	v_mfma_f32_16x16x32_bf16 v[106:109], v[138:141], v[170:173], v[106:109]
	v_mfma_f32_16x16x32_bf16 v[94:97], v[130:133], v[178:181], v[94:97]
	v_mfma_f32_16x16x32_bf16 v[90:93], v[138:141], v[178:181], v[90:93]
	v_mfma_f32_16x16x32_bf16 v[78:81], v[130:133], v[206:209], v[78:81]
	v_mfma_f32_16x16x32_bf16 v[74:77], v[138:141], v[206:209], v[74:77]
	v_mfma_f32_16x16x32_bf16 v[126:129], v[134:137], v[166:169], v[126:129]
	v_mfma_f32_16x16x32_bf16 v[122:125], v[142:145], v[166:169], v[122:125]
	v_mfma_f32_16x16x32_bf16 v[110:113], v[134:137], v[174:177], v[110:113]
	v_mfma_f32_16x16x32_bf16 v[106:109], v[142:145], v[174:177], v[106:109]
	v_mfma_f32_16x16x32_bf16 v[94:97], v[134:137], v[182:185], v[94:97]
	v_mfma_f32_16x16x32_bf16 v[90:93], v[142:145], v[182:185], v[90:93]
	v_mfma_f32_16x16x32_bf16 v[78:81], v[134:137], v[210:213], v[78:81]
	v_mfma_f32_16x16x32_bf16 v[74:77], v[142:145], v[210:213], v[74:77]
	s_setprio 0
	s_setprio 1
	v_mfma_f32_16x16x32_bf16 v[118:121], v[146:149], v[162:165], v[118:121]
	v_mfma_f32_16x16x32_bf16 v[114:117], v[154:157], v[162:165], v[114:117]
	v_mfma_f32_16x16x32_bf16 v[102:105], v[146:149], v[170:173], v[102:105]
	v_mfma_f32_16x16x32_bf16 v[98:101], v[154:157], v[170:173], v[98:101]
	v_mfma_f32_16x16x32_bf16 v[86:89], v[146:149], v[178:181], v[86:89]
	v_mfma_f32_16x16x32_bf16 v[82:85], v[154:157], v[178:181], v[82:85]
	v_mfma_f32_16x16x32_bf16 v[70:73], v[146:149], v[206:209], v[70:73]
	v_mfma_f32_16x16x32_bf16 v[66:69], v[154:157], v[206:209], v[66:69]
	v_mfma_f32_16x16x32_bf16 v[118:121], v[150:153], v[166:169], v[118:121]
	v_mfma_f32_16x16x32_bf16 v[114:117], v[158:161], v[166:169], v[114:117]
	v_mfma_f32_16x16x32_bf16 v[102:105], v[150:153], v[174:177], v[102:105]
	v_mfma_f32_16x16x32_bf16 v[98:101], v[158:161], v[174:177], v[98:101]
	v_mfma_f32_16x16x32_bf16 v[86:89], v[150:153], v[182:185], v[86:89]
	v_mfma_f32_16x16x32_bf16 v[82:85], v[158:161], v[182:185], v[82:85]
	v_mfma_f32_16x16x32_bf16 v[70:73], v[150:153], v[210:213], v[70:73]
	v_mfma_f32_16x16x32_bf16 v[66:69], v[158:161], v[210:213], v[66:69]
	s_setprio 0
	s_barrier
	s_add_i32 s52, s52, s45
	v_lshl_add_u64 v[188:189], s[34:35], 0, v[196:197]
	s_mov_b32 m0, s52
	ds_read_b128 v[162:165], v225 offset:16384
	ds_read_b128 v[166:169], v225 offset:17408
	ds_read_b128 v[170:173], v225 offset:18432
	ds_read_b128 v[174:177], v225 offset:19456
	ds_read_b128 v[178:181], v225 offset:20480
	ds_read_b128 v[182:185], v225 offset:21504
	ds_read_b128 v[206:209], v225 offset:22528
	ds_read_b128 v[210:213], v225 offset:23552
	global_load_lds_dwordx4 v[188:189], off
	s_add_i32 m0, s52, 0x2000
	s_add_u32 s96, s34, 0x4000
	v_lshl_add_u64 v[188:189], s[34:35], 0, v[200:201]
	s_addc_u32 s97, s35, 0
	s_add_i32 s52, s75, s45
	global_load_lds_dwordx4 v[188:189], off
	v_lshl_add_u64 v[188:189], s[96:97], 0, v[196:197]
	s_mov_b32 m0, s52
	v_lshl_add_u64 v[190:191], s[36:37], 0, v[198:199]
	global_load_lds_dwordx4 v[188:189], off
	v_lshl_add_u64 v[188:189], s[96:97], 0, v[200:201]
	s_add_i32 m0, s52, 0x2000
	s_nop 0
	global_load_lds_dwordx4 v[188:189], off
	v_lshl_add_u64 v[188:189], s[36:37], 0, v[186:187]
	s_mov_b32 m0, s29
	s_nop 0
	global_load_lds_dwordx4 v[188:189], off
	s_mov_b32 m0, s65
	s_nop 0
	global_load_lds_dwordx4 v[190:191], off
	s_waitcnt vmcnt(8)
	s_waitcnt lgkmcnt(0)
	s_barrier
	s_setprio 1
	s_waitcnt lgkmcnt(0)
	v_mfma_f32_16x16x32_bf16 v[62:65], v[130:133], v[162:165], v[62:65]
	v_mfma_f32_16x16x32_bf16 v[58:61], v[138:141], v[162:165], v[58:61]
	v_mfma_f32_16x16x32_bf16 v[46:49], v[130:133], v[170:173], v[46:49]
	v_mfma_f32_16x16x32_bf16 v[42:45], v[138:141], v[170:173], v[42:45]
	v_mfma_f32_16x16x32_bf16 v[30:33], v[130:133], v[178:181], v[30:33]
	v_mfma_f32_16x16x32_bf16 v[26:29], v[138:141], v[178:181], v[26:29]
	v_mfma_f32_16x16x32_bf16 v[14:17], v[130:133], v[206:209], v[14:17]
	v_mfma_f32_16x16x32_bf16 v[10:13], v[138:141], v[206:209], v[10:13]
	v_mfma_f32_16x16x32_bf16 v[62:65], v[134:137], v[166:169], v[62:65]
	v_mfma_f32_16x16x32_bf16 v[58:61], v[142:145], v[166:169], v[58:61]
	v_mfma_f32_16x16x32_bf16 v[46:49], v[134:137], v[174:177], v[46:49]
	v_mfma_f32_16x16x32_bf16 v[42:45], v[142:145], v[174:177], v[42:45]
	v_mfma_f32_16x16x32_bf16 v[30:33], v[134:137], v[182:185], v[30:33]
	v_mfma_f32_16x16x32_bf16 v[26:29], v[142:145], v[182:185], v[26:29]
	v_mfma_f32_16x16x32_bf16 v[14:17], v[134:137], v[210:213], v[14:17]
	v_mfma_f32_16x16x32_bf16 v[10:13], v[142:145], v[210:213], v[10:13]
	s_setprio 0
	s_setprio 1
	v_mfma_f32_16x16x32_bf16 v[54:57], v[146:149], v[162:165], v[54:57]
	v_mfma_f32_16x16x32_bf16 v[50:53], v[154:157], v[162:165], v[50:53]
	v_mfma_f32_16x16x32_bf16 v[38:41], v[146:149], v[170:173], v[38:41]
	v_mfma_f32_16x16x32_bf16 v[34:37], v[154:157], v[170:173], v[34:37]
	v_mfma_f32_16x16x32_bf16 v[22:25], v[146:149], v[178:181], v[22:25]
	v_mfma_f32_16x16x32_bf16 v[18:21], v[154:157], v[178:181], v[18:21]
	v_mfma_f32_16x16x32_bf16 v[6:9], v[146:149], v[206:209], v[6:9]
	v_mfma_f32_16x16x32_bf16 v[2:5], v[154:157], v[206:209], v[2:5]
	v_mfma_f32_16x16x32_bf16 v[54:57], v[150:153], v[166:169], v[54:57]
	v_mfma_f32_16x16x32_bf16 v[50:53], v[158:161], v[166:169], v[50:53]
	v_mfma_f32_16x16x32_bf16 v[38:41], v[150:153], v[174:177], v[38:41]
	v_mfma_f32_16x16x32_bf16 v[34:37], v[158:161], v[174:177], v[34:37]
	v_mfma_f32_16x16x32_bf16 v[22:25], v[150:153], v[182:185], v[22:25]
	v_mfma_f32_16x16x32_bf16 v[18:21], v[158:161], v[182:185], v[18:21]
	v_mfma_f32_16x16x32_bf16 v[6:9], v[150:153], v[210:213], v[6:9]
	v_mfma_f32_16x16x32_bf16 v[2:5], v[158:161], v[210:213], v[2:5]
	s_setprio 0
	s_barrier
; #define PG8_STAGE(bufoff, gbase, voff) do { _Pragma("unroll") for (int _i = 0; _i < 2; ++_i) \
;         __builtin_amdgcn_global_load_lds((const unsigned*)((const char*)(gbase) + (voff)[_i]), (PG8_LAS unsigned*)(lds + (bufoff) + ldsw + _i * 8192), 16, 0, 0); } while (0)
; #define PG8_LDA(dst, b, h) do { _Pragma("unroll") for (int m = 0; m < 4; ++m) _Pragma("unroll") for (int k = 0; k < 2; ++k) dst[m][k] = *(const PG8_LAS bf16x8*)(lds + PG8_SA(b, h) + aoff + m * 2048 + k * 1024); } while (0)
; #define PG8_LDB(dst, b, h) do { _Pragma("unroll") for (int n = 0; n < 2; ++n) _Pragma("unroll") for (int k = 0; k < 2; ++k) dst[n][k] = *(const PG8_LAS bf16x8*)(lds + PG8_SB(b, h) + boff + n * 2048 + k * 1024); } while (0)
; #define PG8_MMA(ai, bj, At, Bt) do { __builtin_amdgcn_s_setprio(1); _Pragma("unroll") for (int m = 0; m < 4; ++m) _Pragma("unroll") for (int n = 0; n < 2; ++n) _Pragma("unroll") for (int k = 0; k < 2; ++k) \
;         acc[ai][bj][m][n] = __builtin_amdgcn_mfma_f32_16x16x32_bf16(Bt[n][k], At[m][k], acc[ai][bj][m][n], 0, 0, 0); __builtin_amdgcn_s_setprio(0); } while (0)
; #define PG8_WAIT_V(n) asm volatile("s_waitcnt vmcnt(" #n ")" ::: "memory")
; #define PG8_WAIT_L(n) asm volatile("s_waitcnt lgkmcnt(" #n ")" ::: "memory")
; #define PG8_BAR __builtin_amdgcn_s_barrier()
; #define PG8_SCHED __builtin_amdgcn_sched_barrier(0)
; template <class Epi, class Sched, bool ALIGN_EPI = false, bool SP2 = false, bool ABLK = false, bool BBLK = false>
; __device__ __forceinline__ void gemm_phase(PG8_LAS unsigned char* lds, const Gemm g, const Sched& S, const Epi& E) {
;     ...
;             PG8_LDB(B0, 1, 0); PG8_LDB(B1, 1, 1); PG8_SCHED; PG8_LDA(At, 1, 0); PG8_STAGE(PG8_SA(0, 1), a2 + hstepA, voffA);
;             PG8_WAIT_V(8); PG8_WAIT_L(0); PG8_BAR; PG8_MMA(0, 0, At, B0); PG8_MMA(0, 1, At, B1); PG8_BAR; PG8_SCHED;
	s_add_i32 s52, 0, 0x18000
	s_add_i32 s75, 0, 0x1c000
	v_add_u32_e32 v142, s52, v223
	v_add_u32_e32 v158, s75, v223
	ds_read_b128 v[130:133], v142
	ds_read_b128 v[134:137], v142 offset:1024
	ds_read_b128 v[138:141], v142 offset:2048
	ds_read_b128 v[142:145], v142 offset:3072
	ds_read_b128 v[146:149], v158
	ds_read_b128 v[150:153], v158 offset:1024
	ds_read_b128 v[154:157], v158 offset:2048
	ds_read_b128 v[158:161], v158 offset:3072
	s_add_u32 s36, s36, 0x40000
	s_addc_u32 s37, s37, 0
	s_mov_b32 m0, s68
	v_lshl_add_u64 v[192:193], s[36:37], 0, v[186:187]
	ds_read_b128 v[162:165], v225 offset:32768
	ds_read_b128 v[166:169], v225 offset:33792
	ds_read_b128 v[170:173], v225 offset:34816
	ds_read_b128 v[174:177], v225 offset:35840
	ds_read_b128 v[178:181], v225 offset:36864
	ds_read_b128 v[182:185], v225 offset:37888
	ds_read_b128 v[206:209], v225 offset:38912
	ds_read_b128 v[210:213], v225 offset:39936
	global_load_lds_dwordx4 v[192:193], off
	v_lshl_add_u64 v[192:193], s[36:37], 0, v[198:199]
	s_mov_b32 m0, s72
	s_nop 0
	global_load_lds_dwordx4 v[192:193], off
	s_waitcnt vmcnt(8)
	s_waitcnt lgkmcnt(0)
	s_barrier
	s_setprio 1
	s_waitcnt lgkmcnt(0)
	v_mfma_f32_16x16x32_bf16 v[126:129], v[130:133], v[162:165], v[126:129]
	v_mfma_f32_16x16x32_bf16 v[122:125], v[138:141], v[162:165], v[122:125]
	v_mfma_f32_16x16x32_bf16 v[110:113], v[130:133], v[170:173], v[110:113]
	v_mfma_f32_16x16x32_bf16 v[106:109], v[138:141], v[170:173], v[106:109]
	v_mfma_f32_16x16x32_bf16 v[94:97], v[130:133], v[178:181], v[94:97]
	v_mfma_f32_16x16x32_bf16 v[90:93], v[138:141], v[178:181], v[90:93]
	v_mfma_f32_16x16x32_bf16 v[78:81], v[130:133], v[206:209], v[78:81]
	v_mfma_f32_16x16x32_bf16 v[74:77], v[138:141], v[206:209], v[74:77]
	v_mfma_f32_16x16x32_bf16 v[126:129], v[134:137], v[166:169], v[126:129]
	v_mfma_f32_16x16x32_bf16 v[122:125], v[142:145], v[166:169], v[122:125]
	v_mfma_f32_16x16x32_bf16 v[110:113], v[134:137], v[174:177], v[110:113]
	v_mfma_f32_16x16x32_bf16 v[106:109], v[142:145], v[174:177], v[106:109]
	v_mfma_f32_16x16x32_bf16 v[94:97], v[134:137], v[182:185], v[94:97]
	v_mfma_f32_16x16x32_bf16 v[90:93], v[142:145], v[182:185], v[90:93]
	v_mfma_f32_16x16x32_bf16 v[78:81], v[134:137], v[210:213], v[78:81]
	v_mfma_f32_16x16x32_bf16 v[74:77], v[142:145], v[210:213], v[74:77]
	s_setprio 0
	s_setprio 1
	v_mfma_f32_16x16x32_bf16 v[118:121], v[146:149], v[162:165], v[118:121]
	v_mfma_f32_16x16x32_bf16 v[114:117], v[154:157], v[162:165], v[114:117]
	v_mfma_f32_16x16x32_bf16 v[102:105], v[146:149], v[170:173], v[102:105]
	v_mfma_f32_16x16x32_bf16 v[98:101], v[154:157], v[170:173], v[98:101]
	v_mfma_f32_16x16x32_bf16 v[86:89], v[146:149], v[178:181], v[86:89]
	v_mfma_f32_16x16x32_bf16 v[82:85], v[154:157], v[178:181], v[82:85]
	v_mfma_f32_16x16x32_bf16 v[70:73], v[146:149], v[206:209], v[70:73]
	v_mfma_f32_16x16x32_bf16 v[66:69], v[154:157], v[206:209], v[66:69]
	v_mfma_f32_16x16x32_bf16 v[118:121], v[150:153], v[166:169], v[118:121]
	v_mfma_f32_16x16x32_bf16 v[114:117], v[158:161], v[166:169], v[114:117]
	v_mfma_f32_16x16x32_bf16 v[102:105], v[150:153], v[174:177], v[102:105]
	v_mfma_f32_16x16x32_bf16 v[98:101], v[158:161], v[174:177], v[98:101]
	v_mfma_f32_16x16x32_bf16 v[86:89], v[150:153], v[182:185], v[86:89]
	v_mfma_f32_16x16x32_bf16 v[82:85], v[158:161], v[182:185], v[82:85]
	v_mfma_f32_16x16x32_bf16 v[70:73], v[150:153], v[210:213], v[70:73]
	v_mfma_f32_16x16x32_bf16 v[66:69], v[158:161], v[210:213], v[66:69]
	s_setprio 0
	s_barrier
; #define PG8_STAGE(bufoff, gbase, voff) do { _Pragma("unroll") for (int _i = 0; _i < 2; ++_i) \
;         __builtin_amdgcn_global_load_lds((const unsigned*)((const char*)(gbase) + (voff)[_i]), (PG8_LAS unsigned*)(lds + (bufoff) + ldsw + _i * 8192), 16, 0, 0); } while (0)
; #define PG8_LDA(dst, b, h) do { _Pragma("unroll") for (int m = 0; m < 4; ++m) _Pragma("unroll") for (int k = 0; k < 2; ++k) dst[m][k] = *(const PG8_LAS bf16x8*)(lds + PG8_SA(b, h) + aoff + m * 2048 + k * 1024); } while (0)
; #define PG8_MMA(ai, bj, At, Bt) do { __builtin_amdgcn_s_setprio(1); _Pragma("unroll") for (int m = 0; m < 4; ++m) _Pragma("unroll") for (int n = 0; n < 2; ++n) _Pragma("unroll") for (int k = 0; k < 2; ++k) \
;         acc[ai][bj][m][n] = __builtin_amdgcn_mfma_f32_16x16x32_bf16(Bt[n][k], At[m][k], acc[ai][bj][m][n], 0, 0, 0); __builtin_amdgcn_s_setprio(0); } while (0)
; #define PG8_WAIT_V(n) asm volatile("s_waitcnt vmcnt(" #n ")" ::: "memory")
; #define PG8_WAIT_L(n) asm volatile("s_waitcnt lgkmcnt(" #n ")" ::: "memory")
; #define PG8_BAR __builtin_amdgcn_s_barrier()
; #define PG8_SCHED __builtin_amdgcn_sched_barrier(0)
; template <class Epi, class Sched, bool ALIGN_EPI = false, bool SP2 = false, bool ABLK = false, bool BBLK = false>
; __device__ __forceinline__ void gemm_phase(PG8_LAS unsigned char* lds, const Gemm g, const Sched& S, const Epi& E) {
;     ...
;             PG8_LDA(At, 1, 1); PG8_STAGE(PG8_SB(1, 0), b3, voffB); PG8_STAGE(PG8_SB(1, 1), b3 + hstepB, voffB); PG8_STAGE(PG8_SA(1, 0), a3, voffA);
;             PG8_WAIT_V(8); PG8_WAIT_L(0); PG8_BAR; PG8_MMA(1, 0, At, B0); PG8_MMA(1, 1, At, B1); PG8_BAR; PG8_SCHED;
;     ...
;         if constexpr (ALIGN_EPI) { if (wr == 0) PG8_BAR; }
	s_add_u32 s36, s34, 0x8000
	s_addc_u32 s37, s35, 0
	s_add_i32 s52, s52, s45
	v_lshl_add_u64 v[192:193], s[36:37], 0, v[196:197]
	s_mov_b32 m0, s52
	ds_read_b128 v[162:165], v225 offset:49152
	ds_read_b128 v[166:169], v225 offset:50176
	ds_read_b128 v[170:173], v225 offset:51200
	ds_read_b128 v[174:177], v225 offset:52224
	ds_read_b128 v[178:181], v225 offset:53248
	ds_read_b128 v[182:185], v225 offset:54272
	ds_read_b128 v[206:209], v225 offset:55296
	ds_read_b128 v[210:213], v225 offset:56320
	global_load_lds_dwordx4 v[192:193], off
	s_add_i32 m0, s52, 0x2000
	s_add_u32 s34, s34, 0xc000
	v_lshl_add_u64 v[192:193], s[36:37], 0, v[200:201]
	s_addc_u32 s35, s35, 0
	s_add_i32 s36, s75, s45
	global_load_lds_dwordx4 v[192:193], off
	v_lshl_add_u64 v[192:193], s[34:35], 0, v[196:197]
	s_mov_b32 m0, s36
	v_lshl_add_u64 v[188:189], v[188:189], 0, s[62:63]
	global_load_lds_dwordx4 v[192:193], off
	v_lshl_add_u64 v[192:193], s[34:35], 0, v[200:201]
	s_add_i32 m0, s36, 0x2000
	s_nop 0
	global_load_lds_dwordx4 v[192:193], off
	s_mov_b32 m0, s86
	s_nop 0
	global_load_lds_dwordx4 v[188:189], off
	v_lshl_add_u64 v[188:189], v[190:191], 0, s[62:63]
	s_mov_b32 m0, s88
	s_nop 0
	global_load_lds_dwordx4 v[188:189], off
	s_waitcnt vmcnt(8)
	s_waitcnt lgkmcnt(0)
	s_barrier
	s_setprio 1
	s_waitcnt lgkmcnt(0)
	v_mfma_f32_16x16x32_bf16 v[62:65], v[130:133], v[162:165], v[62:65]
	v_mfma_f32_16x16x32_bf16 v[58:61], v[138:141], v[162:165], v[58:61]
	v_mfma_f32_16x16x32_bf16 v[46:49], v[130:133], v[170:173], v[46:49]
	v_mfma_f32_16x16x32_bf16 v[42:45], v[138:141], v[170:173], v[42:45]
	v_mfma_f32_16x16x32_bf16 v[30:33], v[130:133], v[178:181], v[30:33]
	v_mfma_f32_16x16x32_bf16 v[26:29], v[138:141], v[178:181], v[26:29]
	v_mfma_f32_16x16x32_bf16 v[14:17], v[130:133], v[206:209], v[14:17]
	v_mfma_f32_16x16x32_bf16 v[10:13], v[138:141], v[206:209], v[10:13]
	v_mfma_f32_16x16x32_bf16 v[62:65], v[134:137], v[166:169], v[62:65]
	v_mfma_f32_16x16x32_bf16 v[58:61], v[142:145], v[166:169], v[58:61]
	v_mfma_f32_16x16x32_bf16 v[46:49], v[134:137], v[174:177], v[46:49]
	v_mfma_f32_16x16x32_bf16 v[42:45], v[142:145], v[174:177], v[42:45]
	v_mfma_f32_16x16x32_bf16 v[30:33], v[134:137], v[182:185], v[30:33]
	v_mfma_f32_16x16x32_bf16 v[26:29], v[142:145], v[182:185], v[26:29]
	v_mfma_f32_16x16x32_bf16 v[14:17], v[134:137], v[210:213], v[14:17]
	v_mfma_f32_16x16x32_bf16 v[10:13], v[142:145], v[210:213], v[10:13]
	s_setprio 0
	s_setprio 1
	v_mfma_f32_16x16x32_bf16 v[54:57], v[146:149], v[162:165], v[54:57]
	v_mfma_f32_16x16x32_bf16 v[50:53], v[154:157], v[162:165], v[50:53]
	v_mfma_f32_16x16x32_bf16 v[38:41], v[146:149], v[170:173], v[38:41]
	v_mfma_f32_16x16x32_bf16 v[34:37], v[154:157], v[170:173], v[34:37]
	v_mfma_f32_16x16x32_bf16 v[22:25], v[146:149], v[178:181], v[22:25]
	v_mfma_f32_16x16x32_bf16 v[18:21], v[154:157], v[178:181], v[18:21]
	v_mfma_f32_16x16x32_bf16 v[6:9], v[146:149], v[206:209], v[6:9]
	v_mfma_f32_16x16x32_bf16 v[2:5], v[154:157], v[206:209], v[2:5]
	v_mfma_f32_16x16x32_bf16 v[54:57], v[150:153], v[166:169], v[54:57]
	v_mfma_f32_16x16x32_bf16 v[50:53], v[158:161], v[166:169], v[50:53]
	v_mfma_f32_16x16x32_bf16 v[38:41], v[150:153], v[174:177], v[38:41]
	v_mfma_f32_16x16x32_bf16 v[34:37], v[158:161], v[174:177], v[34:37]
	v_mfma_f32_16x16x32_bf16 v[22:25], v[150:153], v[182:185], v[22:25]
	v_mfma_f32_16x16x32_bf16 v[18:21], v[158:161], v[182:185], v[18:21]
	v_mfma_f32_16x16x32_bf16 v[6:9], v[150:153], v[210:213], v[6:9]
	v_mfma_f32_16x16x32_bf16 v[2:5], v[158:161], v[210:213], v[2:5]
	s_setprio 0
	s_barrier
	s_add_i32 s94, s94, 2
	s_add_u32 s92, s92, 0x10000
	s_addc_u32 s93, s93, 0
	s_add_u32 s0, s0, 0x100
	s_addc_u32 s1, s1, 0
	s_cmp_gt_u32 s94, 13
	s_cbranch_scc0 .LBB0_1140
	s_and_b64 vcc, exec, s[14:15]
	s_cbranch_vccz .LBB0_1143
	s_barrier

; #define PG8_STAGE(bufoff, gbase, voff) do { _Pragma("unroll") for (int _i = 0; _i < 2; ++_i) \
;         __builtin_amdgcn_global_load_lds((const unsigned*)((const char*)(gbase) + (voff)[_i]), (PG8_LAS unsigned*)(lds + (bufoff) + ldsw + _i * 8192), 16, 0, 0); } while (0)
; #define PG8_LDA(dst, b, h) do { _Pragma("unroll") for (int m = 0; m < 4; ++m) _Pragma("unroll") for (int k = 0; k < 2; ++k) dst[m][k] = *(const PG8_LAS bf16x8*)(lds + PG8_SA(b, h) + aoff + m * 2048 + k * 1024); } while (0)
; #define PG8_LDB(dst, b, h) do { _Pragma("unroll") for (int n = 0; n < 2; ++n) _Pragma("unroll") for (int k = 0; k < 2; ++k) dst[n][k] = *(const PG8_LAS bf16x8*)(lds + PG8_SB(b, h) + boff + n * 2048 + k * 1024); } while (0)
; #define PG8_BAR __builtin_amdgcn_s_barrier()
; #define PG8_SCHED __builtin_amdgcn_sched_barrier(0)
; template <class Epi, class Sched, bool ALIGN_EPI = false, bool SP2 = false, bool ABLK = false, bool BBLK = false>
; __device__ __forceinline__ void gemm_phase(PG8_LAS unsigned char* lds, const Gemm g, const Sched& S, const Epi& E) {
;     ...
;         const bool has_next = S.next(ui + 1, nxt);
;         const char* nA = has_next ? (const char*)g.A + (size_t)nxt.pm * tstepA : cA; const char* nB = has_next ? (const char*)g.Bt + (size_t)nxt.pn * tstepB : cB;
;         for (int t = 0; t < nt; t += 2) {
;             const bool last = (t == nt - 2);
;             const char* a1 = cA + (size_t)(t + 1) * kstepA;
;             const char* a2 = last ? nA : cA + (size_t)(t + 2) * kstepA; const char* b2 = last ? nB : cB + (size_t)(t + 2) * kstepB;
;             const char* a3 = a2 + kstepA; const char* b3 = b2 + kstepB;
;             if (last && has_next) S.a_ready(nxt);
;             if constexpr (SP2) {
;             PG8_LDB(B0, 0, 0); PG8_LDB(B1, 0, 1); PG8_SCHED; PG8_LDA(At, 0, 0); PG8_STAGE(PG8_SA(1, 1), a1 + hstepA, voffA);
;     ...
; #pragma unroll
;         for (int a = 0; a < 2; ++a)
; #pragma unroll
;             for (int b = 0; b < 2; ++b)
; #pragma unroll
;                 for (int m = 0; m < 4; ++m)
; #pragma unroll
;                     for (int n = 0; n < 2; ++n) acc[a][b][m][n] = (f32x4){0.f, 0.f, 0.f, 0.f};
;         cur = nxt; cA = nA; cB = nB; ++ui;
;         if constexpr (ALIGN_EPI) { if (wr == 1) PG8_BAR; }
.LBB0_1162:
	s_ashr_i32 s21, s20, 31
	s_lshl_b64 s[22:23], s[20:21], 18
	s_add_u32 s22, s33, s22
	s_addc_u32 s23, s36, s23
	s_and_b64 s[24:25], s[6:7], exec
	s_cselect_b32 s21, s23, s31
	s_cselect_b32 s29, s22, s30
	s_ashr_i32 s19, s18, 31
	s_lshl_b64 s[24:25], s[18:19], 18
	s_add_u32 s24, s37, s24
	s_addc_u32 s25, s44, s25
	s_and_b64 s[34:35], s[6:7], exec
	s_cselect_b32 s19, s25, s1
	s_cselect_b32 s61, s24, s0
	s_add_u32 s83, s0, 0x10000
	s_addc_u32 s84, s1, 0
	s_add_u32 s0, s30, 0x20080
	v_mov_b32_e32 v2, 0
	s_addc_u32 s1, s31, 0
	s_mov_b32 s86, -2
	s_add_u32 s30, s0, 0xfffe0080
	s_addc_u32 s31, s1, -1
	s_add_i32 s52, 0, 0x10000
	s_cmp_eq_u32 s86, 4
	s_cselect_b32 s35, s21, s31
	s_cselect_b32 s34, s29, s30
	s_cselect_b32 s31, s19, s84
	s_cselect_b32 s30, s61, s83
	s_add_i32 s75, 0, 0x14000
	v_add_u32_e32 v142, s52, v223
	v_add_u32_e32 v158, s75, v223
	ds_read_b128 v[130:133], v142
	v_pk_mov_b32 v[2:3], 0, 0
	v_pk_mov_b32 v[4:5], 0, 0
	v_pk_mov_b32 v[6:7], 0, 0
	v_pk_mov_b32 v[8:9], 0, 0
	ds_read_b128 v[134:137], v142 offset:1024
	v_pk_mov_b32 v[10:11], 0, 0
	v_pk_mov_b32 v[12:13], 0, 0
	v_pk_mov_b32 v[14:15], 0, 0
	v_pk_mov_b32 v[16:17], 0, 0
	ds_read_b128 v[138:141], v142 offset:2048
	v_pk_mov_b32 v[18:19], 0, 0
	v_pk_mov_b32 v[20:21], 0, 0
	v_pk_mov_b32 v[22:23], 0, 0
	v_pk_mov_b32 v[24:25], 0, 0
	ds_read_b128 v[142:145], v142 offset:3072
	v_pk_mov_b32 v[26:27], 0, 0
	v_pk_mov_b32 v[28:29], 0, 0
	v_pk_mov_b32 v[30:31], 0, 0
	v_pk_mov_b32 v[32:33], 0, 0
	ds_read_b128 v[146:149], v158
	v_pk_mov_b32 v[34:35], 0, 0
	v_pk_mov_b32 v[36:37], 0, 0
	v_pk_mov_b32 v[38:39], 0, 0
	v_pk_mov_b32 v[40:41], 0, 0
	ds_read_b128 v[150:153], v158 offset:1024
	v_pk_mov_b32 v[42:43], 0, 0
	v_pk_mov_b32 v[44:45], 0, 0
	v_pk_mov_b32 v[46:47], 0, 0
	v_pk_mov_b32 v[48:49], 0, 0
	ds_read_b128 v[154:157], v158 offset:2048
	v_pk_mov_b32 v[50:51], 0, 0
	v_pk_mov_b32 v[52:53], 0, 0
	v_pk_mov_b32 v[54:55], 0, 0
	v_pk_mov_b32 v[56:57], 0, 0
	ds_read_b128 v[158:161], v158 offset:3072
	v_pk_mov_b32 v[58:59], 0, 0
	v_pk_mov_b32 v[60:61], 0, 0
	v_pk_mov_b32 v[62:63], 0, 0
	v_pk_mov_b32 v[64:65], 0, 0
	v_lshl_add_u64 v[188:189], s[0:1], 0, v[202:203]
	s_add_i32 m0, s27, 0xc000
	ds_read_b128 v[162:165], v225
	v_pk_mov_b32 v[66:67], 0, 0
	v_pk_mov_b32 v[68:69], 0, 0
	v_pk_mov_b32 v[70:71], 0, 0
	v_pk_mov_b32 v[72:73], 0, 0
	ds_read_b128 v[166:169], v225 offset:1024
	v_pk_mov_b32 v[74:75], 0, 0
	v_pk_mov_b32 v[76:77], 0, 0
	v_pk_mov_b32 v[78:79], 0, 0
	v_pk_mov_b32 v[80:81], 0, 0
	ds_read_b128 v[170:173], v225 offset:2048
	v_pk_mov_b32 v[82:83], 0, 0
	v_pk_mov_b32 v[84:85], 0, 0
	v_pk_mov_b32 v[86:87], 0, 0
	v_pk_mov_b32 v[88:89], 0, 0
	ds_read_b128 v[174:177], v225 offset:3072
	v_pk_mov_b32 v[90:91], 0, 0
	v_pk_mov_b32 v[92:93], 0, 0
	v_pk_mov_b32 v[94:95], 0, 0
	v_pk_mov_b32 v[96:97], 0, 0
	ds_read_b128 v[178:181], v225 offset:4096
	v_pk_mov_b32 v[98:99], 0, 0
	v_pk_mov_b32 v[100:101], 0, 0
	v_pk_mov_b32 v[102:103], 0, 0
	v_pk_mov_b32 v[104:105], 0, 0
	ds_read_b128 v[182:185], v225 offset:5120
	v_pk_mov_b32 v[106:107], 0, 0
	v_pk_mov_b32 v[108:109], 0, 0
	v_pk_mov_b32 v[110:111], 0, 0
	v_pk_mov_b32 v[112:113], 0, 0
	ds_read_b128 v[206:209], v225 offset:6144
	v_pk_mov_b32 v[114:115], 0, 0
	v_pk_mov_b32 v[116:117], 0, 0
	v_pk_mov_b32 v[118:119], 0, 0
	v_pk_mov_b32 v[120:121], 0, 0
	ds_read_b128 v[210:213], v225 offset:7168
	v_pk_mov_b32 v[122:123], 0, 0
	v_pk_mov_b32 v[124:125], 0, 0
	v_pk_mov_b32 v[126:127], 0, 0
	v_pk_mov_b32 v[128:129], 0, 0
	global_load_lds_dwordx4 v[188:189], off
	v_lshl_add_u64 v[188:189], s[0:1], 0, v[204:205]
	s_add_i32 m0, s27, 0xe000
	s_nop 0
	global_load_lds_dwordx4 v[188:189], off
	s_waitcnt vmcnt(8)
	s_waitcnt lgkmcnt(0)
	s_barrier
	s_branch .Lpeel_1163

; #define PG8_STAGE(bufoff, gbase, voff) do { _Pragma("unroll") for (int _i = 0; _i < 2; ++_i) \
;         __builtin_amdgcn_global_load_lds((const unsigned*)((const char*)(gbase) + (voff)[_i]), (PG8_LAS unsigned*)(lds + (bufoff) + ldsw + _i * 8192), 16, 0, 0); } while (0)
; #define PG8_LDA(dst, b, h) do { _Pragma("unroll") for (int m = 0; m < 4; ++m) _Pragma("unroll") for (int k = 0; k < 2; ++k) dst[m][k] = *(const PG8_LAS bf16x8*)(lds + PG8_SA(b, h) + aoff + m * 2048 + k * 1024); } while (0)
; #define PG8_MMA(ai, bj, At, Bt) do { __builtin_amdgcn_s_setprio(1); _Pragma("unroll") for (int m = 0; m < 4; ++m) _Pragma("unroll") for (int n = 0; n < 2; ++n) _Pragma("unroll") for (int k = 0; k < 2; ++k) \
;         acc[ai][bj][m][n] = __builtin_amdgcn_mfma_f32_16x16x32_bf16(Bt[n][k], At[m][k], acc[ai][bj][m][n], 0, 0, 0); __builtin_amdgcn_s_setprio(0); } while (0)
; #define PG8_WAIT_V(n) asm volatile("s_waitcnt vmcnt(" #n ")" ::: "memory")
; #define PG8_WAIT_L(n) asm volatile("s_waitcnt lgkmcnt(" #n ")" ::: "memory")
; #define PG8_BAR __builtin_amdgcn_s_barrier()
; #define PG8_SCHED __builtin_amdgcn_sched_barrier(0)
; template <class Epi, class Sched, bool ALIGN_EPI = false, bool SP2 = false, bool ABLK = false, bool BBLK = false>
; __device__ __forceinline__ void gemm_phase(PG8_LAS unsigned char* lds, const Gemm g, const Sched& S, const Epi& E) {
;     ...
;             PG8_WAIT_V(8); PG8_WAIT_L(0); PG8_BAR; PG8_MMA(0, 0, At, B0); PG8_MMA(0, 1, At, B1); PG8_BAR; PG8_SCHED;
;             PG8_LDA(At, 0, 1); PG8_STAGE(PG8_SB(0, 0), b2, voffB); PG8_STAGE(PG8_SB(0, 1), b2 + hstepB, voffB); PG8_STAGE(PG8_SA(0, 0), a2, voffA);
;             PG8_WAIT_V(8); PG8_WAIT_L(0); PG8_BAR; PG8_MMA(1, 0, At, B0); PG8_MMA(1, 1, At, B1); PG8_BAR; PG8_SCHED;
.Lpeel_1163:
	s_setprio 1
	s_waitcnt lgkmcnt(0)
	v_mfma_f32_16x16x32_bf16 v[126:129], v[130:133], v[162:165], v[126:129]
	v_mfma_f32_16x16x32_bf16 v[122:125], v[138:141], v[162:165], v[122:125]
	v_mfma_f32_16x16x32_bf16 v[110:113], v[130:133], v[170:173], v[110:113]
	v_mfma_f32_16x16x32_bf16 v[106:109], v[138:141], v[170:173], v[106:109]
	v_mfma_f32_16x16x32_bf16 v[94:97], v[130:133], v[178:181], v[94:97]
	v_mfma_f32_16x16x32_bf16 v[90:93], v[138:141], v[178:181], v[90:93]
	v_mfma_f32_16x16x32_bf16 v[78:81], v[130:133], v[206:209], v[78:81]
	v_mfma_f32_16x16x32_bf16 v[74:77], v[138:141], v[206:209], v[74:77]
	v_mfma_f32_16x16x32_bf16 v[126:129], v[134:137], v[166:169], v[126:129]
	v_mfma_f32_16x16x32_bf16 v[122:125], v[142:145], v[166:169], v[122:125]
	v_mfma_f32_16x16x32_bf16 v[110:113], v[134:137], v[174:177], v[110:113]
	v_mfma_f32_16x16x32_bf16 v[106:109], v[142:145], v[174:177], v[106:109]
	v_mfma_f32_16x16x32_bf16 v[94:97], v[134:137], v[182:185], v[94:97]
	v_mfma_f32_16x16x32_bf16 v[90:93], v[142:145], v[182:185], v[90:93]
	v_mfma_f32_16x16x32_bf16 v[78:81], v[134:137], v[210:213], v[78:81]
	v_mfma_f32_16x16x32_bf16 v[74:77], v[142:145], v[210:213], v[74:77]
	s_setprio 0
	s_setprio 1
	v_mfma_f32_16x16x32_bf16 v[118:121], v[146:149], v[162:165], v[118:121]
	v_mfma_f32_16x16x32_bf16 v[114:117], v[154:157], v[162:165], v[114:117]
	v_mfma_f32_16x16x32_bf16 v[102:105], v[146:149], v[170:173], v[102:105]
	v_mfma_f32_16x16x32_bf16 v[98:101], v[154:157], v[170:173], v[98:101]
	v_mfma_f32_16x16x32_bf16 v[86:89], v[146:149], v[178:181], v[86:89]
	v_mfma_f32_16x16x32_bf16 v[82:85], v[154:157], v[178:181], v[82:85]
	v_mfma_f32_16x16x32_bf16 v[70:73], v[146:149], v[206:209], v[70:73]
	v_mfma_f32_16x16x32_bf16 v[66:69], v[154:157], v[206:209], v[66:69]
	v_mfma_f32_16x16x32_bf16 v[118:121], v[150:153], v[166:169], v[118:121]
	v_mfma_f32_16x16x32_bf16 v[114:117], v[158:161], v[166:169], v[114:117]
	v_mfma_f32_16x16x32_bf16 v[102:105], v[150:153], v[174:177], v[102:105]
	v_mfma_f32_16x16x32_bf16 v[98:101], v[158:161], v[174:177], v[98:101]
	v_mfma_f32_16x16x32_bf16 v[86:89], v[150:153], v[182:185], v[86:89]
	v_mfma_f32_16x16x32_bf16 v[82:85], v[158:161], v[182:185], v[82:85]
	v_mfma_f32_16x16x32_bf16 v[70:73], v[150:153], v[210:213], v[70:73]
	v_mfma_f32_16x16x32_bf16 v[66:69], v[158:161], v[210:213], v[66:69]
	s_setprio 0
	s_barrier
	s_add_i32 s52, s52, s45
	v_lshl_add_u64 v[188:189], s[30:31], 0, v[196:197]
	s_mov_b32 m0, s52
	ds_read_b128 v[162:165], v225 offset:16384
	ds_read_b128 v[166:169], v225 offset:17408
	ds_read_b128 v[170:173], v225 offset:18432
	ds_read_b128 v[174:177], v225 offset:19456
	ds_read_b128 v[178:181], v225 offset:20480
	ds_read_b128 v[182:185], v225 offset:21504
	ds_read_b128 v[206:209], v225 offset:22528
	ds_read_b128 v[210:213], v225 offset:23552
	global_load_lds_dwordx4 v[188:189], off
	s_add_i32 m0, s52, 0x2000
	s_add_u32 s88, s30, 0x4000
	v_lshl_add_u64 v[188:189], s[30:31], 0, v[200:201]
	s_addc_u32 s89, s31, 0
	s_add_i32 s52, s75, s45
	global_load_lds_dwordx4 v[188:189], off
	v_lshl_add_u64 v[188:189], s[88:89], 0, v[196:197]
	s_mov_b32 m0, s52
	v_lshl_add_u64 v[190:191], s[34:35], 0, v[198:199]
	global_load_lds_dwordx4 v[188:189], off
	v_lshl_add_u64 v[188:189], s[88:89], 0, v[200:201]
	s_add_i32 m0, s52, 0x2000
	s_nop 0
	global_load_lds_dwordx4 v[188:189], off
	v_lshl_add_u64 v[188:189], s[34:35], 0, v[186:187]
	s_mov_b32 m0, s27
	s_nop 0
	global_load_lds_dwordx4 v[188:189], off
	s_mov_b32 m0, s46
	s_nop 0
	global_load_lds_dwordx4 v[190:191], off
	s_waitcnt vmcnt(8)
	s_waitcnt lgkmcnt(0)
	s_barrier
	s_setprio 1
	s_waitcnt lgkmcnt(0)
	v_mfma_f32_16x16x32_bf16 v[62:65], v[130:133], v[162:165], v[62:65]
	v_mfma_f32_16x16x32_bf16 v[58:61], v[138:141], v[162:165], v[58:61]
	v_mfma_f32_16x16x32_bf16 v[46:49], v[130:133], v[170:173], v[46:49]
	v_mfma_f32_16x16x32_bf16 v[42:45], v[138:141], v[170:173], v[42:45]
	v_mfma_f32_16x16x32_bf16 v[30:33], v[130:133], v[178:181], v[30:33]
	v_mfma_f32_16x16x32_bf16 v[26:29], v[138:141], v[178:181], v[26:29]
	v_mfma_f32_16x16x32_bf16 v[14:17], v[130:133], v[206:209], v[14:17]
	v_mfma_f32_16x16x32_bf16 v[10:13], v[138:141], v[206:209], v[10:13]
	v_mfma_f32_16x16x32_bf16 v[62:65], v[134:137], v[166:169], v[62:65]
	v_mfma_f32_16x16x32_bf16 v[58:61], v[142:145], v[166:169], v[58:61]
	v_mfma_f32_16x16x32_bf16 v[46:49], v[134:137], v[174:177], v[46:49]
	v_mfma_f32_16x16x32_bf16 v[42:45], v[142:145], v[174:177], v[42:45]
	v_mfma_f32_16x16x32_bf16 v[30:33], v[134:137], v[182:185], v[30:33]
	v_mfma_f32_16x16x32_bf16 v[26:29], v[142:145], v[182:185], v[26:29]
	v_mfma_f32_16x16x32_bf16 v[14:17], v[134:137], v[210:213], v[14:17]
	v_mfma_f32_16x16x32_bf16 v[10:13], v[142:145], v[210:213], v[10:13]
	s_setprio 0
	s_setprio 1
	v_mfma_f32_16x16x32_bf16 v[54:57], v[146:149], v[162:165], v[54:57]
	v_mfma_f32_16x16x32_bf16 v[50:53], v[154:157], v[162:165], v[50:53]
	v_mfma_f32_16x16x32_bf16 v[38:41], v[146:149], v[170:173], v[38:41]
	v_mfma_f32_16x16x32_bf16 v[34:37], v[154:157], v[170:173], v[34:37]
	v_mfma_f32_16x16x32_bf16 v[22:25], v[146:149], v[178:181], v[22:25]
	v_mfma_f32_16x16x32_bf16 v[18:21], v[154:157], v[178:181], v[18:21]
	v_mfma_f32_16x16x32_bf16 v[6:9], v[146:149], v[206:209], v[6:9]
	v_mfma_f32_16x16x32_bf16 v[2:5], v[154:157], v[206:209], v[2:5]
	v_mfma_f32_16x16x32_bf16 v[54:57], v[150:153], v[166:169], v[54:57]
	v_mfma_f32_16x16x32_bf16 v[50:53], v[158:161], v[166:169], v[50:53]
	v_mfma_f32_16x16x32_bf16 v[38:41], v[150:153], v[174:177], v[38:41]
	v_mfma_f32_16x16x32_bf16 v[34:37], v[158:161], v[174:177], v[34:37]
	v_mfma_f32_16x16x32_bf16 v[22:25], v[150:153], v[182:185], v[22:25]
	v_mfma_f32_16x16x32_bf16 v[18:21], v[158:161], v[182:185], v[18:21]
	v_mfma_f32_16x16x32_bf16 v[6:9], v[150:153], v[210:213], v[6:9]
	v_mfma_f32_16x16x32_bf16 v[2:5], v[158:161], v[210:213], v[2:5]
	s_setprio 0
	s_barrier
; #define PG8_STAGE(bufoff, gbase, voff) do { _Pragma("unroll") for (int _i = 0; _i < 2; ++_i) \
;         __builtin_amdgcn_global_load_lds((const unsigned*)((const char*)(gbase) + (voff)[_i]), (PG8_LAS unsigned*)(lds + (bufoff) + ldsw + _i * 8192), 16, 0, 0); } while (0)
; #define PG8_LDA(dst, b, h) do { _Pragma("unroll") for (int m = 0; m < 4; ++m) _Pragma("unroll") for (int k = 0; k < 2; ++k) dst[m][k] = *(const PG8_LAS bf16x8*)(lds + PG8_SA(b, h) + aoff + m * 2048 + k * 1024); } while (0)
; #define PG8_LDB(dst, b, h) do { _Pragma("unroll") for (int n = 0; n < 2; ++n) _Pragma("unroll") for (int k = 0; k < 2; ++k) dst[n][k] = *(const PG8_LAS bf16x8*)(lds + PG8_SB(b, h) + boff + n * 2048 + k * 1024); } while (0)
; #define PG8_MMA(ai, bj, At, Bt) do { __builtin_amdgcn_s_setprio(1); _Pragma("unroll") for (int m = 0; m < 4; ++m) _Pragma("unroll") for (int n = 0; n < 2; ++n) _Pragma("unroll") for (int k = 0; k < 2; ++k) \
;         acc[ai][bj][m][n] = __builtin_amdgcn_mfma_f32_16x16x32_bf16(Bt[n][k], At[m][k], acc[ai][bj][m][n], 0, 0, 0); __builtin_amdgcn_s_setprio(0); } while (0)
; #define PG8_WAIT_V(n) asm volatile("s_waitcnt vmcnt(" #n ")" ::: "memory")
; #define PG8_WAIT_L(n) asm volatile("s_waitcnt lgkmcnt(" #n ")" ::: "memory")
; #define PG8_BAR __builtin_amdgcn_s_barrier()
; #define PG8_SCHED __builtin_amdgcn_sched_barrier(0)
; template <class Epi, class Sched, bool ALIGN_EPI = false, bool SP2 = false, bool ABLK = false, bool BBLK = false>
; __device__ __forceinline__ void gemm_phase(PG8_LAS unsigned char* lds, const Gemm g, const Sched& S, const Epi& E) {
;     ...
;             PG8_LDB(B0, 1, 0); PG8_LDB(B1, 1, 1); PG8_SCHED; PG8_LDA(At, 1, 0); PG8_STAGE(PG8_SA(0, 1), a2 + hstepA, voffA);
;             PG8_WAIT_V(8); PG8_WAIT_L(0); PG8_BAR; PG8_MMA(0, 0, At, B0); PG8_MMA(0, 1, At, B1); PG8_BAR; PG8_SCHED;
	s_add_i32 s52, 0, 0x18000
	s_add_i32 s75, 0, 0x1c000
	v_add_u32_e32 v142, s52, v223
	v_add_u32_e32 v158, s75, v223
	ds_read_b128 v[130:133], v142
	ds_read_b128 v[134:137], v142 offset:1024
	ds_read_b128 v[138:141], v142 offset:2048
	ds_read_b128 v[142:145], v142 offset:3072
	ds_read_b128 v[146:149], v158
	ds_read_b128 v[150:153], v158 offset:1024
	ds_read_b128 v[154:157], v158 offset:2048
	ds_read_b128 v[158:161], v158 offset:3072
	s_add_u32 s34, s34, 0x20000
	s_addc_u32 s35, s35, 0
	s_mov_b32 m0, s47
	v_lshl_add_u64 v[192:193], s[34:35], 0, v[186:187]
	ds_read_b128 v[162:165], v225 offset:32768
	ds_read_b128 v[166:169], v225 offset:33792
	ds_read_b128 v[170:173], v225 offset:34816
	ds_read_b128 v[174:177], v225 offset:35840
	ds_read_b128 v[178:181], v225 offset:36864
	ds_read_b128 v[182:185], v225 offset:37888
	ds_read_b128 v[206:209], v225 offset:38912
	ds_read_b128 v[210:213], v225 offset:39936
	global_load_lds_dwordx4 v[192:193], off
	v_lshl_add_u64 v[192:193], s[34:35], 0, v[198:199]
	s_mov_b32 m0, s65
	s_nop 0
	global_load_lds_dwordx4 v[192:193], off
	s_waitcnt vmcnt(8)
	s_waitcnt lgkmcnt(0)
	s_barrier
	s_setprio 1
	s_waitcnt lgkmcnt(0)
	v_mfma_f32_16x16x32_bf16 v[126:129], v[130:133], v[162:165], v[126:129]
	v_mfma_f32_16x16x32_bf16 v[122:125], v[138:141], v[162:165], v[122:125]
	v_mfma_f32_16x16x32_bf16 v[110:113], v[130:133], v[170:173], v[110:113]
	v_mfma_f32_16x16x32_bf16 v[106:109], v[138:141], v[170:173], v[106:109]
	v_mfma_f32_16x16x32_bf16 v[94:97], v[130:133], v[178:181], v[94:97]
	v_mfma_f32_16x16x32_bf16 v[90:93], v[138:141], v[178:181], v[90:93]
	v_mfma_f32_16x16x32_bf16 v[78:81], v[130:133], v[206:209], v[78:81]
	v_mfma_f32_16x16x32_bf16 v[74:77], v[138:141], v[206:209], v[74:77]
	v_mfma_f32_16x16x32_bf16 v[126:129], v[134:137], v[166:169], v[126:129]
	v_mfma_f32_16x16x32_bf16 v[122:125], v[142:145], v[166:169], v[122:125]
	v_mfma_f32_16x16x32_bf16 v[110:113], v[134:137], v[174:177], v[110:113]
	v_mfma_f32_16x16x32_bf16 v[106:109], v[142:145], v[174:177], v[106:109]
	v_mfma_f32_16x16x32_bf16 v[94:97], v[134:137], v[182:185], v[94:97]
	v_mfma_f32_16x16x32_bf16 v[90:93], v[142:145], v[182:185], v[90:93]
	v_mfma_f32_16x16x32_bf16 v[78:81], v[134:137], v[210:213], v[78:81]
	v_mfma_f32_16x16x32_bf16 v[74:77], v[142:145], v[210:213], v[74:77]
	s_setprio 0
	s_setprio 1
	v_mfma_f32_16x16x32_bf16 v[118:121], v[146:149], v[162:165], v[118:121]
	v_mfma_f32_16x16x32_bf16 v[114:117], v[154:157], v[162:165], v[114:117]
	v_mfma_f32_16x16x32_bf16 v[102:105], v[146:149], v[170:173], v[102:105]
	v_mfma_f32_16x16x32_bf16 v[98:101], v[154:157], v[170:173], v[98:101]
	v_mfma_f32_16x16x32_bf16 v[86:89], v[146:149], v[178:181], v[86:89]
	v_mfma_f32_16x16x32_bf16 v[82:85], v[154:157], v[178:181], v[82:85]
	v_mfma_f32_16x16x32_bf16 v[70:73], v[146:149], v[206:209], v[70:73]
	v_mfma_f32_16x16x32_bf16 v[66:69], v[154:157], v[206:209], v[66:69]
	v_mfma_f32_16x16x32_bf16 v[118:121], v[150:153], v[166:169], v[118:121]
	v_mfma_f32_16x16x32_bf16 v[114:117], v[158:161], v[166:169], v[114:117]
	v_mfma_f32_16x16x32_bf16 v[102:105], v[150:153], v[174:177], v[102:105]
	v_mfma_f32_16x16x32_bf16 v[98:101], v[158:161], v[174:177], v[98:101]
	v_mfma_f32_16x16x32_bf16 v[86:89], v[150:153], v[182:185], v[86:89]
	v_mfma_f32_16x16x32_bf16 v[82:85], v[158:161], v[182:185], v[82:85]
	v_mfma_f32_16x16x32_bf16 v[70:73], v[150:153], v[210:213], v[70:73]
	v_mfma_f32_16x16x32_bf16 v[66:69], v[158:161], v[210:213], v[66:69]
	s_setprio 0
	s_barrier
; #define PG8_STAGE(bufoff, gbase, voff) do { _Pragma("unroll") for (int _i = 0; _i < 2; ++_i) \
;         __builtin_amdgcn_global_load_lds((const unsigned*)((const char*)(gbase) + (voff)[_i]), (PG8_LAS unsigned*)(lds + (bufoff) + ldsw + _i * 8192), 16, 0, 0); } while (0)
; #define PG8_LDA(dst, b, h) do { _Pragma("unroll") for (int m = 0; m < 4; ++m) _Pragma("unroll") for (int k = 0; k < 2; ++k) dst[m][k] = *(const PG8_LAS bf16x8*)(lds + PG8_SA(b, h) + aoff + m * 2048 + k * 1024); } while (0)
; #define PG8_MMA(ai, bj, At, Bt) do { __builtin_amdgcn_s_setprio(1); _Pragma("unroll") for (int m = 0; m < 4; ++m) _Pragma("unroll") for (int n = 0; n < 2; ++n) _Pragma("unroll") for (int k = 0; k < 2; ++k) \
;         acc[ai][bj][m][n] = __builtin_amdgcn_mfma_f32_16x16x32_bf16(Bt[n][k], At[m][k], acc[ai][bj][m][n], 0, 0, 0); __builtin_amdgcn_s_setprio(0); } while (0)
; #define PG8_WAIT_V(n) asm volatile("s_waitcnt vmcnt(" #n ")" ::: "memory")
; #define PG8_WAIT_L(n) asm volatile("s_waitcnt lgkmcnt(" #n ")" ::: "memory")
; #define PG8_BAR __builtin_amdgcn_s_barrier()
; #define PG8_SCHED __builtin_amdgcn_sched_barrier(0)
; template <class Epi, class Sched, bool ALIGN_EPI = false, bool SP2 = false, bool ABLK = false, bool BBLK = false>
; __device__ __forceinline__ void gemm_phase(PG8_LAS unsigned char* lds, const Gemm g, const Sched& S, const Epi& E) {
;     ...
;             PG8_LDA(At, 1, 1); PG8_STAGE(PG8_SB(1, 0), b3, voffB); PG8_STAGE(PG8_SB(1, 1), b3 + hstepB, voffB); PG8_STAGE(PG8_SA(1, 0), a3, voffA);
;             PG8_WAIT_V(8); PG8_WAIT_L(0); PG8_BAR; PG8_MMA(1, 0, At, B0); PG8_MMA(1, 1, At, B1); PG8_BAR; PG8_SCHED;
;     ...
;         if constexpr (ALIGN_EPI) { if (wr == 0) PG8_BAR; }
	s_add_u32 s34, s30, 0x8000
	s_addc_u32 s35, s31, 0
	s_add_i32 s52, s52, s45
	v_lshl_add_u64 v[192:193], s[34:35], 0, v[196:197]
	s_mov_b32 m0, s52
	ds_read_b128 v[162:165], v225 offset:49152
	ds_read_b128 v[166:169], v225 offset:50176
	ds_read_b128 v[170:173], v225 offset:51200
	ds_read_b128 v[174:177], v225 offset:52224
	ds_read_b128 v[178:181], v225 offset:53248
	ds_read_b128 v[182:185], v225 offset:54272
	ds_read_b128 v[206:209], v225 offset:55296
	ds_read_b128 v[210:213], v225 offset:56320
	global_load_lds_dwordx4 v[192:193], off
	s_add_i32 m0, s52, 0x2000
	s_add_u32 s30, s30, 0xc000
	v_lshl_add_u64 v[192:193], s[34:35], 0, v[200:201]
	s_addc_u32 s31, s31, 0
	s_add_i32 s34, s75, s45
	global_load_lds_dwordx4 v[192:193], off
	v_lshl_add_u64 v[192:193], s[30:31], 0, v[196:197]
	s_mov_b32 m0, s34
	v_lshl_add_u64 v[188:189], v[188:189], 0, s[62:63]
	global_load_lds_dwordx4 v[192:193], off
	v_lshl_add_u64 v[192:193], s[30:31], 0, v[200:201]
	s_add_i32 m0, s34, 0x2000
	s_nop 0
	global_load_lds_dwordx4 v[192:193], off
	s_mov_b32 m0, s72
	s_nop 0
	global_load_lds_dwordx4 v[188:189], off
	v_lshl_add_u64 v[188:189], v[190:191], 0, s[62:63]
	s_mov_b32 m0, s73
	s_nop 0
	global_load_lds_dwordx4 v[188:189], off
	s_waitcnt vmcnt(8)
	s_waitcnt lgkmcnt(0)
	s_barrier
	s_setprio 1
	s_waitcnt lgkmcnt(0)
	v_mfma_f32_16x16x32_bf16 v[62:65], v[130:133], v[162:165], v[62:65]
	v_mfma_f32_16x16x32_bf16 v[58:61], v[138:141], v[162:165], v[58:61]
	v_mfma_f32_16x16x32_bf16 v[46:49], v[130:133], v[170:173], v[46:49]
	v_mfma_f32_16x16x32_bf16 v[42:45], v[138:141], v[170:173], v[42:45]
	v_mfma_f32_16x16x32_bf16 v[30:33], v[130:133], v[178:181], v[30:33]
	v_mfma_f32_16x16x32_bf16 v[26:29], v[138:141], v[178:181], v[26:29]
	v_mfma_f32_16x16x32_bf16 v[14:17], v[130:133], v[206:209], v[14:17]
	v_mfma_f32_16x16x32_bf16 v[10:13], v[138:141], v[206:209], v[10:13]
	v_mfma_f32_16x16x32_bf16 v[62:65], v[134:137], v[166:169], v[62:65]
	v_mfma_f32_16x16x32_bf16 v[58:61], v[142:145], v[166:169], v[58:61]
	v_mfma_f32_16x16x32_bf16 v[46:49], v[134:137], v[174:177], v[46:49]
	v_mfma_f32_16x16x32_bf16 v[42:45], v[142:145], v[174:177], v[42:45]
	v_mfma_f32_16x16x32_bf16 v[30:33], v[134:137], v[182:185], v[30:33]
	v_mfma_f32_16x16x32_bf16 v[26:29], v[142:145], v[182:185], v[26:29]
	v_mfma_f32_16x16x32_bf16 v[14:17], v[134:137], v[210:213], v[14:17]
	v_mfma_f32_16x16x32_bf16 v[10:13], v[142:145], v[210:213], v[10:13]
	s_setprio 0
	s_setprio 1
	v_mfma_f32_16x16x32_bf16 v[54:57], v[146:149], v[162:165], v[54:57]
	v_mfma_f32_16x16x32_bf16 v[50:53], v[154:157], v[162:165], v[50:53]
	v_mfma_f32_16x16x32_bf16 v[38:41], v[146:149], v[170:173], v[38:41]
	v_mfma_f32_16x16x32_bf16 v[34:37], v[154:157], v[170:173], v[34:37]
	v_mfma_f32_16x16x32_bf16 v[22:25], v[146:149], v[178:181], v[22:25]
	v_mfma_f32_16x16x32_bf16 v[18:21], v[154:157], v[178:181], v[18:21]
	v_mfma_f32_16x16x32_bf16 v[6:9], v[146:149], v[206:209], v[6:9]
	v_mfma_f32_16x16x32_bf16 v[2:5], v[154:157], v[206:209], v[2:5]
	v_mfma_f32_16x16x32_bf16 v[54:57], v[150:153], v[166:169], v[54:57]
	v_mfma_f32_16x16x32_bf16 v[50:53], v[158:161], v[166:169], v[50:53]
	v_mfma_f32_16x16x32_bf16 v[38:41], v[150:153], v[174:177], v[38:41]
	v_mfma_f32_16x16x32_bf16 v[34:37], v[158:161], v[174:177], v[34:37]
	v_mfma_f32_16x16x32_bf16 v[22:25], v[150:153], v[182:185], v[22:25]
	v_mfma_f32_16x16x32_bf16 v[18:21], v[158:161], v[182:185], v[18:21]
	v_mfma_f32_16x16x32_bf16 v[6:9], v[150:153], v[210:213], v[6:9]
	v_mfma_f32_16x16x32_bf16 v[2:5], v[158:161], v[210:213], v[2:5]
	s_setprio 0
	s_barrier
	s_add_i32 s86, s86, 2
	s_add_u32 s83, s83, 0x10000
	s_addc_u32 s84, s84, 0
	s_add_u32 s0, s0, 0x100
	s_addc_u32 s1, s1, 0
	s_cmp_gt_u32 s86, 5
	s_cbranch_scc0 .LBB0_1163
	s_and_b64 vcc, exec, s[12:13]
	s_cbranch_vccz .LBB0_1166
	s_barrier

; #define PG8_STAGE(bufoff, gbase, voff) do { _Pragma("unroll") for (int _i = 0; _i < 2; ++_i) \
;         __builtin_amdgcn_global_load_lds((const unsigned*)((const char*)(gbase) + (voff)[_i]), (PG8_LAS unsigned*)(lds + (bufoff) + ldsw + _i * 8192), 16, 0, 0); } while (0)
; #define PG8_LDA(dst, b, h) do { _Pragma("unroll") for (int m = 0; m < 4; ++m) _Pragma("unroll") for (int k = 0; k < 2; ++k) dst[m][k] = *(const PG8_LAS bf16x8*)(lds + PG8_SA(b, h) + aoff + m * 2048 + k * 1024); } while (0)
; #define PG8_LDB(dst, b, h) do { _Pragma("unroll") for (int n = 0; n < 2; ++n) _Pragma("unroll") for (int k = 0; k < 2; ++k) dst[n][k] = *(const PG8_LAS bf16x8*)(lds + PG8_SB(b, h) + boff + n * 2048 + k * 1024); } while (0)
; #define PG8_BAR __builtin_amdgcn_s_barrier()
; #define PG8_SCHED __builtin_amdgcn_sched_barrier(0)
; template <class Epi, class Sched, bool ALIGN_EPI = false, bool SP2 = false, bool ABLK = false, bool BBLK = false>
; __device__ __forceinline__ void gemm_phase(PG8_LAS unsigned char* lds, const Gemm g, const Sched& S, const Epi& E) {
;     ...
;         const bool has_next = S.next(ui + 1, nxt);
;         const char* nA = has_next ? (const char*)g.A + (size_t)nxt.pm * tstepA : cA; const char* nB = has_next ? (const char*)g.Bt + (size_t)nxt.pn * tstepB : cB;
;         for (int t = 0; t < nt; t += 2) {
;             const bool last = (t == nt - 2);
;             const char* a1 = cA + (size_t)(t + 1) * kstepA;
;             const char* a2 = last ? nA : cA + (size_t)(t + 2) * kstepA; const char* b2 = last ? nB : cB + (size_t)(t + 2) * kstepB;
;             const char* a3 = a2 + kstepA; const char* b3 = b2 + kstepB;
;             if (last && has_next) S.a_ready(nxt);
;             if constexpr (SP2) {
;             PG8_LDB(B0, 0, 0); PG8_LDB(B1, 0, 1); PG8_SCHED; PG8_LDA(At, 0, 0); PG8_STAGE(PG8_SA(1, 1), a1 + hstepA, voffA);
;     ...
; #pragma unroll
;         for (int a = 0; a < 2; ++a)
; #pragma unroll
;             for (int b = 0; b < 2; ++b)
; #pragma unroll
;                 for (int m = 0; m < 4; ++m)
; #pragma unroll
;                     for (int n = 0; n < 2; ++n) acc[a][b][m][n] = (f32x4){0.f, 0.f, 0.f, 0.f};
;         cur = nxt; cA = nA; cB = nB; ++ui;
;         if constexpr (ALIGN_EPI) { if (wr == 1) PG8_BAR; }
.LBB0_1238:
	s_ashr_i32 s27, s26, 31
	s_lshl_b64 s[28:29], s[26:27], 20
	s_add_u32 s28, s50, s28
	s_addc_u32 s29, s51, s29
	s_and_b64 s[30:31], s[6:7], exec
	s_cselect_b32 s27, s29, s9
	s_cselect_b32 s35, s28, s8
	s_ashr_i32 s25, s24, 31
	s_lshl_b64 s[30:31], s[24:25], 20
	s_add_u32 s30, s53, s30
	s_addc_u32 s31, s56, s31
	s_and_b64 s[40:41], s[6:7], exec
	s_cselect_b32 s25, s31, s1
	s_cselect_b32 s37, s30, s0
	s_add_u32 s60, s0, 0x10000
	s_addc_u32 s61, s1, 0
	s_add_u32 s0, s8, 0x80080
	v_mov_b32_e32 v38, 0
	s_addc_u32 s1, s9, 0
	s_mov_b32 s92, -2
	s_add_u32 s8, s0, 0xfff80080
	s_addc_u32 s9, s1, -1
	s_add_i32 s52, 0, 0x10000
	s_cmp_eq_u32 s92, 28
	s_cselect_b32 s41, s27, s9
	s_cselect_b32 s40, s35, s8
	s_cselect_b32 s9, s25, s61
	s_cselect_b32 s8, s37, s60
	s_add_i32 s75, 0, 0x14000
	v_add_u32_e32 v142, s52, v206
	v_add_u32_e32 v158, s75, v206
	ds_read_b128 v[122:125], v142
	v_pk_mov_b32 v[2:3], 0, 0
	v_pk_mov_b32 v[4:5], 0, 0
	v_pk_mov_b32 v[6:7], 0, 0
	v_pk_mov_b32 v[8:9], 0, 0
	ds_read_b128 v[126:129], v142 offset:1024
	v_pk_mov_b32 v[10:11], 0, 0
	v_pk_mov_b32 v[12:13], 0, 0
	v_pk_mov_b32 v[14:15], 0, 0
	v_pk_mov_b32 v[16:17], 0, 0
	ds_read_b128 v[138:141], v142 offset:2048
	v_pk_mov_b32 v[18:19], 0, 0
	v_pk_mov_b32 v[20:21], 0, 0
	v_pk_mov_b32 v[22:23], 0, 0
	v_pk_mov_b32 v[24:25], 0, 0
	ds_read_b128 v[142:145], v142 offset:3072
	v_pk_mov_b32 v[26:27], 0, 0
	v_pk_mov_b32 v[28:29], 0, 0
	v_pk_mov_b32 v[30:31], 0, 0
	v_pk_mov_b32 v[32:33], 0, 0
	ds_read_b128 v[146:149], v158
	v_pk_mov_b32 v[34:35], 0, 0
	v_pk_mov_b32 v[36:37], 0, 0
	v_pk_mov_b32 v[38:39], 0, 0
	v_pk_mov_b32 v[40:41], 0, 0
	ds_read_b128 v[150:153], v158 offset:1024
	v_pk_mov_b32 v[42:43], 0, 0
	v_pk_mov_b32 v[44:45], 0, 0
	v_pk_mov_b32 v[46:47], 0, 0
	v_pk_mov_b32 v[48:49], 0, 0
	ds_read_b128 v[154:157], v158 offset:2048
	v_pk_mov_b32 v[50:51], 0, 0
	v_pk_mov_b32 v[52:53], 0, 0
	v_pk_mov_b32 v[54:55], 0, 0
	v_pk_mov_b32 v[56:57], 0, 0
	ds_read_b128 v[158:161], v158 offset:3072
	v_pk_mov_b32 v[58:59], 0, 0
	v_pk_mov_b32 v[60:61], 0, 0
	v_pk_mov_b32 v[62:63], 0, 0
	v_pk_mov_b32 v[64:65], 0, 0
	v_lshl_add_u64 v[188:189], s[0:1], 0, v[184:185]
	s_add_i32 m0, s47, 0xc000
	ds_read_b128 v[162:165], v207
	v_pk_mov_b32 v[66:67], 0, 0
	v_pk_mov_b32 v[68:69], 0, 0
	v_pk_mov_b32 v[70:71], 0, 0
	v_pk_mov_b32 v[72:73], 0, 0
	ds_read_b128 v[166:169], v207 offset:1024
	v_pk_mov_b32 v[74:75], 0, 0
	v_pk_mov_b32 v[76:77], 0, 0
	v_pk_mov_b32 v[78:79], 0, 0
	v_pk_mov_b32 v[80:81], 0, 0
	ds_read_b128 v[170:173], v207 offset:2048
	v_pk_mov_b32 v[82:83], 0, 0
	v_pk_mov_b32 v[84:85], 0, 0
	v_pk_mov_b32 v[86:87], 0, 0
	v_pk_mov_b32 v[88:89], 0, 0
	ds_read_b128 v[174:177], v207 offset:3072
	v_pk_mov_b32 v[90:91], 0, 0
	v_pk_mov_b32 v[92:93], 0, 0
	v_pk_mov_b32 v[94:95], 0, 0
	v_pk_mov_b32 v[96:97], 0, 0
	ds_read_b128 v[198:201], v207 offset:4096
	v_pk_mov_b32 v[98:99], 0, 0
	v_pk_mov_b32 v[100:101], 0, 0
	v_pk_mov_b32 v[102:103], 0, 0
	v_pk_mov_b32 v[104:105], 0, 0
	ds_read_b128 v[208:211], v207 offset:5120
	v_pk_mov_b32 v[106:107], 0, 0
	v_pk_mov_b32 v[108:109], 0, 0
	v_pk_mov_b32 v[110:111], 0, 0
	v_pk_mov_b32 v[112:113], 0, 0
	ds_read_b128 v[212:215], v207 offset:6144
	v_pk_mov_b32 v[114:115], 0, 0
	v_pk_mov_b32 v[116:117], 0, 0
	v_pk_mov_b32 v[118:119], 0, 0
	v_pk_mov_b32 v[120:121], 0, 0
	ds_read_b128 v[216:219], v207 offset:7168
	v_pk_mov_b32 v[130:131], 0, 0
	v_pk_mov_b32 v[132:133], 0, 0
	v_pk_mov_b32 v[134:135], 0, 0
	v_pk_mov_b32 v[136:137], 0, 0
	global_load_lds_dwordx4 v[188:189], off
	v_lshl_add_u64 v[188:189], s[0:1], 0, v[196:197]
	s_add_i32 m0, s47, 0xe000
	s_nop 0
	global_load_lds_dwordx4 v[188:189], off
	s_waitcnt vmcnt(8)
	s_waitcnt lgkmcnt(0)
	s_barrier
	s_branch .Lpeel_1239

; #define PG8_STAGE(bufoff, gbase, voff) do { _Pragma("unroll") for (int _i = 0; _i < 2; ++_i) \
;         __builtin_amdgcn_global_load_lds((const unsigned*)((const char*)(gbase) + (voff)[_i]), (PG8_LAS unsigned*)(lds + (bufoff) + ldsw + _i * 8192), 16, 0, 0); } while (0)
; #define PG8_LDA(dst, b, h) do { _Pragma("unroll") for (int m = 0; m < 4; ++m) _Pragma("unroll") for (int k = 0; k < 2; ++k) dst[m][k] = *(const PG8_LAS bf16x8*)(lds + PG8_SA(b, h) + aoff + m * 2048 + k * 1024); } while (0)
; #define PG8_MMA(ai, bj, At, Bt) do { __builtin_amdgcn_s_setprio(1); _Pragma("unroll") for (int m = 0; m < 4; ++m) _Pragma("unroll") for (int n = 0; n < 2; ++n) _Pragma("unroll") for (int k = 0; k < 2; ++k) \
;         acc[ai][bj][m][n] = __builtin_amdgcn_mfma_f32_16x16x32_bf16(Bt[n][k], At[m][k], acc[ai][bj][m][n], 0, 0, 0); __builtin_amdgcn_s_setprio(0); } while (0)
; #define PG8_WAIT_V(n) asm volatile("s_waitcnt vmcnt(" #n ")" ::: "memory")
; #define PG8_WAIT_L(n) asm volatile("s_waitcnt lgkmcnt(" #n ")" ::: "memory")
; #define PG8_BAR __builtin_amdgcn_s_barrier()
; #define PG8_SCHED __builtin_amdgcn_sched_barrier(0)
; template <class Epi, class Sched, bool ALIGN_EPI = false, bool SP2 = false, bool ABLK = false, bool BBLK = false>
; __device__ __forceinline__ void gemm_phase(PG8_LAS unsigned char* lds, const Gemm g, const Sched& S, const Epi& E) {
;     ...
;             PG8_WAIT_V(8); PG8_WAIT_L(0); PG8_BAR; PG8_MMA(0, 0, At, B0); PG8_MMA(0, 1, At, B1); PG8_BAR; PG8_SCHED;
;             PG8_LDA(At, 0, 1); PG8_STAGE(PG8_SB(0, 0), b2, voffB); PG8_STAGE(PG8_SB(0, 1), b2 + hstepB, voffB); PG8_STAGE(PG8_SA(0, 0), a2, voffA);
;             PG8_WAIT_V(8); PG8_WAIT_L(0); PG8_BAR; PG8_MMA(1, 0, At, B0); PG8_MMA(1, 1, At, B1); PG8_BAR; PG8_SCHED;
.Lpeel_1239:
	s_setprio 1
	s_waitcnt lgkmcnt(0)
	v_mfma_f32_16x16x32_bf16 v[118:121], v[122:125], v[162:165], v[118:121]
	v_mfma_f32_16x16x32_bf16 v[114:117], v[138:141], v[162:165], v[114:117]
	v_mfma_f32_16x16x32_bf16 v[78:81], v[122:125], v[170:173], v[78:81]
	v_mfma_f32_16x16x32_bf16 v[134:137], v[138:141], v[170:173], v[134:137]
	v_mfma_f32_16x16x32_bf16 v[30:33], v[122:125], v[198:201], v[30:33]
	v_mfma_f32_16x16x32_bf16 v[22:25], v[138:141], v[198:201], v[22:25]
	v_mfma_f32_16x16x32_bf16 v[110:113], v[122:125], v[212:215], v[110:113]
	v_mfma_f32_16x16x32_bf16 v[14:17], v[138:141], v[212:215], v[14:17]
	v_mfma_f32_16x16x32_bf16 v[118:121], v[126:129], v[166:169], v[118:121]
	v_mfma_f32_16x16x32_bf16 v[114:117], v[142:145], v[166:169], v[114:117]
	v_mfma_f32_16x16x32_bf16 v[78:81], v[126:129], v[174:177], v[78:81]
	v_mfma_f32_16x16x32_bf16 v[134:137], v[142:145], v[174:177], v[134:137]
	v_mfma_f32_16x16x32_bf16 v[30:33], v[126:129], v[208:211], v[30:33]
	v_mfma_f32_16x16x32_bf16 v[22:25], v[142:145], v[208:211], v[22:25]
	v_mfma_f32_16x16x32_bf16 v[110:113], v[126:129], v[216:219], v[110:113]
	v_mfma_f32_16x16x32_bf16 v[14:17], v[142:145], v[216:219], v[14:17]
	s_setprio 0
	s_setprio 1
	v_mfma_f32_16x16x32_bf16 v[74:77], v[146:149], v[162:165], v[74:77]
	v_mfma_f32_16x16x32_bf16 v[54:57], v[154:157], v[162:165], v[54:57]
	v_mfma_f32_16x16x32_bf16 v[50:53], v[146:149], v[170:173], v[50:53]
	v_mfma_f32_16x16x32_bf16 v[26:29], v[154:157], v[170:173], v[26:29]
	v_mfma_f32_16x16x32_bf16 v[18:21], v[146:149], v[198:201], v[18:21]
	v_mfma_f32_16x16x32_bf16 v[10:13], v[154:157], v[198:201], v[10:13]
	v_mfma_f32_16x16x32_bf16 v[2:5], v[146:149], v[212:215], v[2:5]
	v_mfma_f32_16x16x32_bf16 v[6:9], v[154:157], v[212:215], v[6:9]
	v_mfma_f32_16x16x32_bf16 v[74:77], v[150:153], v[166:169], v[74:77]
	v_mfma_f32_16x16x32_bf16 v[54:57], v[158:161], v[166:169], v[54:57]
	v_mfma_f32_16x16x32_bf16 v[50:53], v[150:153], v[174:177], v[50:53]
	v_mfma_f32_16x16x32_bf16 v[26:29], v[158:161], v[174:177], v[26:29]
	v_mfma_f32_16x16x32_bf16 v[18:21], v[150:153], v[208:211], v[18:21]
	v_mfma_f32_16x16x32_bf16 v[10:13], v[158:161], v[208:211], v[10:13]
	v_mfma_f32_16x16x32_bf16 v[2:5], v[150:153], v[216:219], v[2:5]
	v_mfma_f32_16x16x32_bf16 v[6:9], v[158:161], v[216:219], v[6:9]
	s_setprio 0
	s_barrier
	s_add_i32 s52, s52, s46
	v_lshl_add_u64 v[188:189], s[8:9], 0, v[178:179]
	s_mov_b32 m0, s52
	ds_read_b128 v[162:165], v207 offset:16384
	ds_read_b128 v[166:169], v207 offset:17408
	ds_read_b128 v[170:173], v207 offset:18432
	ds_read_b128 v[174:177], v207 offset:19456
	ds_read_b128 v[198:201], v207 offset:20480
	ds_read_b128 v[208:211], v207 offset:21504
	ds_read_b128 v[212:215], v207 offset:22528
	ds_read_b128 v[216:219], v207 offset:23552
	global_load_lds_dwordx4 v[188:189], off
	s_add_i32 m0, s52, 0x2000
	s_add_u32 vcc_lo, s8, 0x4000
	v_lshl_add_u64 v[188:189], s[8:9], 0, v[182:183]
	s_addc_u32 vcc_hi, s9, 0
	s_add_i32 s52, s75, s46
	global_load_lds_dwordx4 v[188:189], off
	v_lshl_add_u64 v[188:189], vcc, 0, v[178:179]
	s_mov_b32 m0, s52
	v_lshl_add_u64 v[190:191], s[40:41], 0, v[180:181]
	global_load_lds_dwordx4 v[188:189], off
	v_lshl_add_u64 v[188:189], vcc, 0, v[182:183]
	s_add_i32 m0, s52, 0x2000
	s_nop 0
	global_load_lds_dwordx4 v[188:189], off
	v_lshl_add_u64 v[188:189], s[40:41], 0, v[186:187]
	s_mov_b32 m0, s47
	s_nop 0
	global_load_lds_dwordx4 v[188:189], off
	s_mov_b32 m0, s65
	s_nop 0
	global_load_lds_dwordx4 v[190:191], off
	s_waitcnt vmcnt(8)
	s_waitcnt lgkmcnt(0)
	s_barrier
	s_setprio 1
	s_waitcnt lgkmcnt(0)
	v_mfma_f32_16x16x32_bf16 v[106:109], v[122:125], v[162:165], v[106:109]
	v_mfma_f32_16x16x32_bf16 v[102:105], v[138:141], v[162:165], v[102:105]
	v_mfma_f32_16x16x32_bf16 v[94:97], v[122:125], v[170:173], v[94:97]
	v_mfma_f32_16x16x32_bf16 v[86:89], v[138:141], v[170:173], v[86:89]
	v_mfma_f32_16x16x32_bf16 v[70:73], v[122:125], v[198:201], v[70:73]
	v_mfma_f32_16x16x32_bf16 v[62:65], v[138:141], v[198:201], v[62:65]
	v_mfma_f32_16x16x32_bf16 v[46:49], v[138:141], v[212:215], v[46:49]
	v_mfma_f32_16x16x32_bf16 v[106:109], v[126:129], v[166:169], v[106:109]
	v_mfma_f32_16x16x32_bf16 v[102:105], v[142:145], v[166:169], v[102:105]
	v_mfma_f32_16x16x32_bf16 v[94:97], v[126:129], v[174:177], v[94:97]
	v_mfma_f32_16x16x32_bf16 v[86:89], v[142:145], v[174:177], v[86:89]
	v_mfma_f32_16x16x32_bf16 v[70:73], v[126:129], v[208:211], v[70:73]
	v_mfma_f32_16x16x32_bf16 v[62:65], v[142:145], v[208:211], v[62:65]
	v_mfma_f32_16x16x32_bf16 v[122:125], v[122:125], v[212:215], v[130:133]
	v_mfma_f32_16x16x32_bf16 v[46:49], v[142:145], v[216:219], v[46:49]
	v_mfma_f32_16x16x32_bf16 v[122:125], v[126:129], v[216:219], v[122:125]
	s_setprio 0
	s_setprio 1
	v_mfma_f32_16x16x32_bf16 v[98:101], v[146:149], v[162:165], v[98:101]
	v_mfma_f32_16x16x32_bf16 v[90:93], v[154:157], v[162:165], v[90:93]
	v_mfma_f32_16x16x32_bf16 v[82:85], v[146:149], v[170:173], v[82:85]
	v_mfma_f32_16x16x32_bf16 v[66:69], v[154:157], v[170:173], v[66:69]
	v_mfma_f32_16x16x32_bf16 v[58:61], v[146:149], v[198:201], v[58:61]
	v_mfma_f32_16x16x32_bf16 v[42:45], v[154:157], v[198:201], v[42:45]
	v_mfma_f32_16x16x32_bf16 v[34:37], v[146:149], v[212:215], v[34:37]
	v_mfma_f32_16x16x32_bf16 v[38:41], v[154:157], v[212:215], v[38:41]
	v_mfma_f32_16x16x32_bf16 v[98:101], v[150:153], v[166:169], v[98:101]
	v_mfma_f32_16x16x32_bf16 v[90:93], v[158:161], v[166:169], v[90:93]
	v_mfma_f32_16x16x32_bf16 v[82:85], v[150:153], v[174:177], v[82:85]
	v_mfma_f32_16x16x32_bf16 v[66:69], v[158:161], v[174:177], v[66:69]
	v_mfma_f32_16x16x32_bf16 v[58:61], v[150:153], v[208:211], v[58:61]
	v_mfma_f32_16x16x32_bf16 v[42:45], v[158:161], v[208:211], v[42:45]
	v_mfma_f32_16x16x32_bf16 v[34:37], v[150:153], v[216:219], v[34:37]
	v_mfma_f32_16x16x32_bf16 v[38:41], v[158:161], v[216:219], v[38:41]
	s_setprio 0
	s_barrier
; #define PG8_STAGE(bufoff, gbase, voff) do { _Pragma("unroll") for (int _i = 0; _i < 2; ++_i) \
;         __builtin_amdgcn_global_load_lds((const unsigned*)((const char*)(gbase) + (voff)[_i]), (PG8_LAS unsigned*)(lds + (bufoff) + ldsw + _i * 8192), 16, 0, 0); } while (0)
; #define PG8_LDA(dst, b, h) do { _Pragma("unroll") for (int m = 0; m < 4; ++m) _Pragma("unroll") for (int k = 0; k < 2; ++k) dst[m][k] = *(const PG8_LAS bf16x8*)(lds + PG8_SA(b, h) + aoff + m * 2048 + k * 1024); } while (0)
; #define PG8_LDB(dst, b, h) do { _Pragma("unroll") for (int n = 0; n < 2; ++n) _Pragma("unroll") for (int k = 0; k < 2; ++k) dst[n][k] = *(const PG8_LAS bf16x8*)(lds + PG8_SB(b, h) + boff + n * 2048 + k * 1024); } while (0)
; #define PG8_MMA(ai, bj, At, Bt) do { __builtin_amdgcn_s_setprio(1); _Pragma("unroll") for (int m = 0; m < 4; ++m) _Pragma("unroll") for (int n = 0; n < 2; ++n) _Pragma("unroll") for (int k = 0; k < 2; ++k) \
;         acc[ai][bj][m][n] = __builtin_amdgcn_mfma_f32_16x16x32_bf16(Bt[n][k], At[m][k], acc[ai][bj][m][n], 0, 0, 0); __builtin_amdgcn_s_setprio(0); } while (0)
; #define PG8_WAIT_V(n) asm volatile("s_waitcnt vmcnt(" #n ")" ::: "memory")
; #define PG8_WAIT_L(n) asm volatile("s_waitcnt lgkmcnt(" #n ")" ::: "memory")
; #define PG8_BAR __builtin_amdgcn_s_barrier()
; #define PG8_SCHED __builtin_amdgcn_sched_barrier(0)
; template <class Epi, class Sched, bool ALIGN_EPI = false, bool SP2 = false, bool ABLK = false, bool BBLK = false>
; __device__ __forceinline__ void gemm_phase(PG8_LAS unsigned char* lds, const Gemm g, const Sched& S, const Epi& E) {
;     ...
;             PG8_LDB(B0, 1, 0); PG8_LDB(B1, 1, 1); PG8_SCHED; PG8_LDA(At, 1, 0); PG8_STAGE(PG8_SA(0, 1), a2 + hstepA, voffA);
;             PG8_WAIT_V(8); PG8_WAIT_L(0); PG8_BAR; PG8_MMA(0, 0, At, B0); PG8_MMA(0, 1, At, B1); PG8_BAR; PG8_SCHED;
	s_add_i32 s52, 0, 0x18000
	s_add_i32 s75, 0, 0x1c000
	v_add_u32_e32 v142, s52, v206
	v_add_u32_e32 v158, s75, v206
	ds_read_b128 v[126:129], v142
	ds_read_b128 v[130:133], v142 offset:1024
	ds_read_b128 v[138:141], v142 offset:2048
	ds_read_b128 v[142:145], v142 offset:3072
	ds_read_b128 v[146:149], v158
	ds_read_b128 v[150:153], v158 offset:1024
	ds_read_b128 v[154:157], v158 offset:2048
	ds_read_b128 v[158:161], v158 offset:3072
	s_add_u32 s40, s40, 0x80000
	s_addc_u32 s41, s41, 0
	s_mov_b32 m0, s68
	v_lshl_add_u64 v[192:193], s[40:41], 0, v[186:187]
	ds_read_b128 v[162:165], v207 offset:32768
	ds_read_b128 v[166:169], v207 offset:33792
	ds_read_b128 v[170:173], v207 offset:34816
	ds_read_b128 v[174:177], v207 offset:35840
	ds_read_b128 v[198:201], v207 offset:36864
	ds_read_b128 v[208:211], v207 offset:37888
	ds_read_b128 v[212:215], v207 offset:38912
	ds_read_b128 v[216:219], v207 offset:39936
	global_load_lds_dwordx4 v[192:193], off
	v_lshl_add_u64 v[192:193], s[40:41], 0, v[180:181]
	s_mov_b32 m0, s72
	s_nop 0
	global_load_lds_dwordx4 v[192:193], off
	s_waitcnt vmcnt(8)
	s_waitcnt lgkmcnt(0)
	s_barrier
	s_setprio 1
	s_waitcnt lgkmcnt(0)
	v_mfma_f32_16x16x32_bf16 v[118:121], v[126:129], v[162:165], v[118:121]
	v_mfma_f32_16x16x32_bf16 v[114:117], v[138:141], v[162:165], v[114:117]
	v_mfma_f32_16x16x32_bf16 v[78:81], v[126:129], v[170:173], v[78:81]
	v_mfma_f32_16x16x32_bf16 v[134:137], v[138:141], v[170:173], v[134:137]
	v_mfma_f32_16x16x32_bf16 v[30:33], v[126:129], v[198:201], v[30:33]
	v_mfma_f32_16x16x32_bf16 v[22:25], v[138:141], v[198:201], v[22:25]
	v_mfma_f32_16x16x32_bf16 v[110:113], v[126:129], v[212:215], v[110:113]
	v_mfma_f32_16x16x32_bf16 v[14:17], v[138:141], v[212:215], v[14:17]
	v_mfma_f32_16x16x32_bf16 v[118:121], v[130:133], v[166:169], v[118:121]
	v_mfma_f32_16x16x32_bf16 v[114:117], v[142:145], v[166:169], v[114:117]
	v_mfma_f32_16x16x32_bf16 v[78:81], v[130:133], v[174:177], v[78:81]
	v_mfma_f32_16x16x32_bf16 v[134:137], v[142:145], v[174:177], v[134:137]
	v_mfma_f32_16x16x32_bf16 v[30:33], v[130:133], v[208:211], v[30:33]
	v_mfma_f32_16x16x32_bf16 v[22:25], v[142:145], v[208:211], v[22:25]
	v_mfma_f32_16x16x32_bf16 v[110:113], v[130:133], v[216:219], v[110:113]
	v_mfma_f32_16x16x32_bf16 v[14:17], v[142:145], v[216:219], v[14:17]
	s_setprio 0
	s_setprio 1
	v_mfma_f32_16x16x32_bf16 v[74:77], v[146:149], v[162:165], v[74:77]
	v_mfma_f32_16x16x32_bf16 v[54:57], v[154:157], v[162:165], v[54:57]
	v_mfma_f32_16x16x32_bf16 v[50:53], v[146:149], v[170:173], v[50:53]
	v_mfma_f32_16x16x32_bf16 v[26:29], v[154:157], v[170:173], v[26:29]
	v_mfma_f32_16x16x32_bf16 v[18:21], v[146:149], v[198:201], v[18:21]
	v_mfma_f32_16x16x32_bf16 v[10:13], v[154:157], v[198:201], v[10:13]
	v_mfma_f32_16x16x32_bf16 v[2:5], v[146:149], v[212:215], v[2:5]
	v_mfma_f32_16x16x32_bf16 v[6:9], v[154:157], v[212:215], v[6:9]
	v_mfma_f32_16x16x32_bf16 v[74:77], v[150:153], v[166:169], v[74:77]
	v_mfma_f32_16x16x32_bf16 v[54:57], v[158:161], v[166:169], v[54:57]
	v_mfma_f32_16x16x32_bf16 v[50:53], v[150:153], v[174:177], v[50:53]
	v_mfma_f32_16x16x32_bf16 v[26:29], v[158:161], v[174:177], v[26:29]
	v_mfma_f32_16x16x32_bf16 v[18:21], v[150:153], v[208:211], v[18:21]
	v_mfma_f32_16x16x32_bf16 v[10:13], v[158:161], v[208:211], v[10:13]
	v_mfma_f32_16x16x32_bf16 v[2:5], v[150:153], v[216:219], v[2:5]
	v_mfma_f32_16x16x32_bf16 v[6:9], v[158:161], v[216:219], v[6:9]
	s_setprio 0
	s_barrier
; #define PG8_STAGE(bufoff, gbase, voff) do { _Pragma("unroll") for (int _i = 0; _i < 2; ++_i) \
;         __builtin_amdgcn_global_load_lds((const unsigned*)((const char*)(gbase) + (voff)[_i]), (PG8_LAS unsigned*)(lds + (bufoff) + ldsw + _i * 8192), 16, 0, 0); } while (0)
; #define PG8_LDA(dst, b, h) do { _Pragma("unroll") for (int m = 0; m < 4; ++m) _Pragma("unroll") for (int k = 0; k < 2; ++k) dst[m][k] = *(const PG8_LAS bf16x8*)(lds + PG8_SA(b, h) + aoff + m * 2048 + k * 1024); } while (0)
; #define PG8_MMA(ai, bj, At, Bt) do { __builtin_amdgcn_s_setprio(1); _Pragma("unroll") for (int m = 0; m < 4; ++m) _Pragma("unroll") for (int n = 0; n < 2; ++n) _Pragma("unroll") for (int k = 0; k < 2; ++k) \
;         acc[ai][bj][m][n] = __builtin_amdgcn_mfma_f32_16x16x32_bf16(Bt[n][k], At[m][k], acc[ai][bj][m][n], 0, 0, 0); __builtin_amdgcn_s_setprio(0); } while (0)
; #define PG8_WAIT_V(n) asm volatile("s_waitcnt vmcnt(" #n ")" ::: "memory")
; #define PG8_WAIT_L(n) asm volatile("s_waitcnt lgkmcnt(" #n ")" ::: "memory")
; #define PG8_BAR __builtin_amdgcn_s_barrier()
; #define PG8_SCHED __builtin_amdgcn_sched_barrier(0)
; template <class Epi, class Sched, bool ALIGN_EPI = false, bool SP2 = false, bool ABLK = false, bool BBLK = false>
; __device__ __forceinline__ void gemm_phase(PG8_LAS unsigned char* lds, const Gemm g, const Sched& S, const Epi& E) {
;     ...
;             PG8_LDA(At, 1, 1); PG8_STAGE(PG8_SB(1, 0), b3, voffB); PG8_STAGE(PG8_SB(1, 1), b3 + hstepB, voffB); PG8_STAGE(PG8_SA(1, 0), a3, voffA);
;             PG8_WAIT_V(8); PG8_WAIT_L(0); PG8_BAR; PG8_MMA(1, 0, At, B0); PG8_MMA(1, 1, At, B1); PG8_BAR; PG8_SCHED;
;     ...
;         if constexpr (ALIGN_EPI) { if (wr == 0) PG8_BAR; }
	s_add_u32 s40, s8, 0x8000
	s_addc_u32 s41, s9, 0
	s_add_i32 s52, s52, s46
	v_lshl_add_u64 v[192:193], s[40:41], 0, v[178:179]
	s_mov_b32 m0, s52
	ds_read_b128 v[162:165], v207 offset:49152
	ds_read_b128 v[166:169], v207 offset:50176
	ds_read_b128 v[170:173], v207 offset:51200
	ds_read_b128 v[174:177], v207 offset:52224
	ds_read_b128 v[198:201], v207 offset:53248
	ds_read_b128 v[208:211], v207 offset:54272
	ds_read_b128 v[212:215], v207 offset:55296
	ds_read_b128 v[216:219], v207 offset:56320
	global_load_lds_dwordx4 v[192:193], off
	s_add_i32 m0, s52, 0x2000
	s_add_u32 s8, s8, 0xc000
	v_lshl_add_u64 v[192:193], s[40:41], 0, v[182:183]
	s_addc_u32 s9, s9, 0
	s_add_i32 s40, s75, s46
	global_load_lds_dwordx4 v[192:193], off
	v_lshl_add_u64 v[192:193], s[8:9], 0, v[178:179]
	s_mov_b32 m0, s40
	v_lshl_add_u64 v[188:189], v[188:189], 0, s[62:63]
	global_load_lds_dwordx4 v[192:193], off
	v_lshl_add_u64 v[192:193], s[8:9], 0, v[182:183]
	s_add_i32 m0, s40, 0x2000
	s_nop 0
	global_load_lds_dwordx4 v[192:193], off
	s_mov_b32 m0, s33
	s_nop 0
	global_load_lds_dwordx4 v[188:189], off
	v_lshl_add_u64 v[188:189], v[190:191], 0, s[62:63]
	s_mov_b32 m0, s91
	s_nop 0
	global_load_lds_dwordx4 v[188:189], off
	s_waitcnt vmcnt(8)
	s_waitcnt lgkmcnt(0)
	s_barrier
	s_setprio 1
	s_waitcnt lgkmcnt(0)
	v_mfma_f32_16x16x32_bf16 v[106:109], v[126:129], v[162:165], v[106:109]
	v_mfma_f32_16x16x32_bf16 v[102:105], v[138:141], v[162:165], v[102:105]
	v_mfma_f32_16x16x32_bf16 v[94:97], v[126:129], v[170:173], v[94:97]
	v_mfma_f32_16x16x32_bf16 v[86:89], v[138:141], v[170:173], v[86:89]
	v_mfma_f32_16x16x32_bf16 v[70:73], v[126:129], v[198:201], v[70:73]
	v_mfma_f32_16x16x32_bf16 v[62:65], v[138:141], v[198:201], v[62:65]
	v_mfma_f32_16x16x32_bf16 v[122:125], v[126:129], v[212:215], v[122:125]
	v_mfma_f32_16x16x32_bf16 v[46:49], v[138:141], v[212:215], v[46:49]
	v_mfma_f32_16x16x32_bf16 v[106:109], v[130:133], v[166:169], v[106:109]
	v_mfma_f32_16x16x32_bf16 v[102:105], v[142:145], v[166:169], v[102:105]
	v_mfma_f32_16x16x32_bf16 v[94:97], v[130:133], v[174:177], v[94:97]
	v_mfma_f32_16x16x32_bf16 v[86:89], v[142:145], v[174:177], v[86:89]
	v_mfma_f32_16x16x32_bf16 v[70:73], v[130:133], v[208:211], v[70:73]
	v_mfma_f32_16x16x32_bf16 v[62:65], v[142:145], v[208:211], v[62:65]
	v_mfma_f32_16x16x32_bf16 v[130:133], v[130:133], v[216:219], v[122:125]
	v_mfma_f32_16x16x32_bf16 v[46:49], v[142:145], v[216:219], v[46:49]
	s_setprio 0
	s_setprio 1
	v_mfma_f32_16x16x32_bf16 v[98:101], v[146:149], v[162:165], v[98:101]
	v_mfma_f32_16x16x32_bf16 v[90:93], v[154:157], v[162:165], v[90:93]
	v_mfma_f32_16x16x32_bf16 v[82:85], v[146:149], v[170:173], v[82:85]
	v_mfma_f32_16x16x32_bf16 v[66:69], v[154:157], v[170:173], v[66:69]
	v_mfma_f32_16x16x32_bf16 v[58:61], v[146:149], v[198:201], v[58:61]
	v_mfma_f32_16x16x32_bf16 v[42:45], v[154:157], v[198:201], v[42:45]
	v_mfma_f32_16x16x32_bf16 v[34:37], v[146:149], v[212:215], v[34:37]
	v_mfma_f32_16x16x32_bf16 v[38:41], v[154:157], v[212:215], v[38:41]
	v_mfma_f32_16x16x32_bf16 v[98:101], v[150:153], v[166:169], v[98:101]
	v_mfma_f32_16x16x32_bf16 v[90:93], v[158:161], v[166:169], v[90:93]
	v_mfma_f32_16x16x32_bf16 v[82:85], v[150:153], v[174:177], v[82:85]
	v_mfma_f32_16x16x32_bf16 v[66:69], v[158:161], v[174:177], v[66:69]
	v_mfma_f32_16x16x32_bf16 v[58:61], v[150:153], v[208:211], v[58:61]
	v_mfma_f32_16x16x32_bf16 v[42:45], v[158:161], v[208:211], v[42:45]
	v_mfma_f32_16x16x32_bf16 v[34:37], v[150:153], v[216:219], v[34:37]
	v_mfma_f32_16x16x32_bf16 v[38:41], v[158:161], v[216:219], v[38:41]
	s_setprio 0
	s_barrier
	s_add_i32 s92, s92, 2
	s_add_u32 s60, s60, 0x10000
	s_addc_u32 s61, s61, 0
	s_add_u32 s0, s0, 0x100
	s_addc_u32 s1, s1, 0
	s_cmp_gt_u32 s92, 29
	s_cbranch_scc0 .LBB0_1239
	s_and_b64 vcc, exec, s[18:19]
	s_cbranch_vccz .LBB0_1242
	s_barrier

; #define PG8_STAGE(bufoff, gbase, voff) do { _Pragma("unroll") for (int _i = 0; _i < 2; ++_i) \
;         __builtin_amdgcn_global_load_lds((const unsigned*)((const char*)(gbase) + (voff)[_i]), (PG8_LAS unsigned*)(lds + (bufoff) + ldsw + _i * 8192), 16, 0, 0); } while (0)
; #define PG8_LDA(dst, b, h) do { _Pragma("unroll") for (int m = 0; m < 4; ++m) _Pragma("unroll") for (int k = 0; k < 2; ++k) dst[m][k] = *(const PG8_LAS bf16x8*)(lds + PG8_SA(b, h) + aoff + m * 2048 + k * 1024); } while (0)
; #define PG8_LDB(dst, b, h) do { _Pragma("unroll") for (int n = 0; n < 2; ++n) _Pragma("unroll") for (int k = 0; k < 2; ++k) dst[n][k] = *(const PG8_LAS bf16x8*)(lds + PG8_SB(b, h) + boff + n * 2048 + k * 1024); } while (0)
; #define PG8_BAR __builtin_amdgcn_s_barrier()
; #define PG8_SCHED __builtin_amdgcn_sched_barrier(0)
; template <class Epi, class Sched, bool ALIGN_EPI = false, bool SP2 = false, bool ABLK = false, bool BBLK = false>
; __device__ __forceinline__ void gemm_phase(PG8_LAS unsigned char* lds, const Gemm g, const Sched& S, const Epi& E) {
;     ...
;         const bool has_next = S.next(ui + 1, nxt);
;         const char* nA = has_next ? (const char*)g.A + (size_t)nxt.pm * tstepA : cA; const char* nB = has_next ? (const char*)g.Bt + (size_t)nxt.pn * tstepB : cB;
;         for (int t = 0; t < nt; t += 2) {
;             const bool last = (t == nt - 2);
;             const char* a1 = cA + (size_t)(t + 1) * kstepA;
;             const char* a2 = last ? nA : cA + (size_t)(t + 2) * kstepA; const char* b2 = last ? nB : cB + (size_t)(t + 2) * kstepB;
;             const char* a3 = a2 + kstepA; const char* b3 = b2 + kstepB;
;             if (last && has_next) S.a_ready(nxt);
;             if constexpr (SP2) {
;             PG8_LDB(B0, 0, 0); PG8_LDB(B1, 0, 1); PG8_SCHED; PG8_LDA(At, 0, 0); PG8_STAGE(PG8_SA(1, 1), a1 + hstepA, voffA);
;     ...
; #pragma unroll
;         for (int a = 0; a < 2; ++a)
; #pragma unroll
;             for (int b = 0; b < 2; ++b)
; #pragma unroll
;                 for (int m = 0; m < 4; ++m)
; #pragma unroll
;                     for (int n = 0; n < 2; ++n) acc[a][b][m][n] = (f32x4){0.f, 0.f, 0.f, 0.f};
;         cur = nxt; cA = nA; cB = nB; ++ui;
;         if constexpr (ALIGN_EPI) { if (wr == 1) PG8_BAR; }
.LBB0_1339:
	s_ashr_i32 s19, s18, 31
	s_lshl_b64 s[20:21], s[18:19], 20
	s_add_u32 s20, s40, s20
	s_addc_u32 s21, s41, s21
	s_and_b64 s[22:23], s[6:7], exec
	s_cselect_b32 s1, s21, s27
	s_cselect_b32 s19, s20, s26
	s_ashr_i32 s15, s14, 31
	s_lshl_b64 s[22:23], s[14:15], 20
	s_add_u32 s22, s42, s22
	s_addc_u32 s23, s43, s23
	s_and_b64 s[30:31], s[6:7], exec
	s_cselect_b32 s15, s23, s29
	s_cselect_b32 s72, s22, s28
	s_add_u32 s26, s26, 0xc000
	s_addc_u32 s27, s27, 0
	s_add_u32 s73, s28, 0x10000
	v_mov_b32_e32 v2, 0
	s_addc_u32 s81, s29, 0
	s_mov_b32 s83, -2
	s_add_u32 s28, s26, 0x4000
	s_addc_u32 s29, s27, 0
	s_cmp_eq_u32 s83, 28
	s_cselect_b32 s34, s19, s28
	s_cselect_b32 s35, s1, s29
	s_cselect_b32 s30, s72, s73
	s_cselect_b32 s31, s15, s81
	s_add_u32 s28, s34, 0x8000
	s_addc_u32 s29, s35, 0
	s_add_i32 s52, 0, 0x10000
	v_add_u32_e32 v142, s52, v145
	s_add_i32 s75, 0, 0x14000
	ds_read_b128 v[148:151], v142
	v_pk_mov_b32 v[2:3], 0, 0
	v_pk_mov_b32 v[4:5], 0, 0
	v_pk_mov_b32 v[6:7], 0, 0
	v_pk_mov_b32 v[8:9], 0, 0
	ds_read_b128 v[152:155], v142 offset:1024
	v_pk_mov_b32 v[10:11], 0, 0
	v_pk_mov_b32 v[12:13], 0, 0
	v_pk_mov_b32 v[14:15], 0, 0
	v_pk_mov_b32 v[16:17], 0, 0
	ds_read_b128 v[156:159], v142 offset:2048
	v_pk_mov_b32 v[18:19], 0, 0
	v_pk_mov_b32 v[20:21], 0, 0
	v_pk_mov_b32 v[22:23], 0, 0
	v_pk_mov_b32 v[24:25], 0, 0
	ds_read_b128 v[160:163], v142 offset:3072
	v_pk_mov_b32 v[26:27], 0, 0
	v_pk_mov_b32 v[28:29], 0, 0
	v_pk_mov_b32 v[30:31], 0, 0
	v_pk_mov_b32 v[32:33], 0, 0
	v_add_u32_e32 v142, s75, v145
	ds_read_b128 v[164:167], v142
	v_pk_mov_b32 v[34:35], 0, 0
	v_pk_mov_b32 v[36:37], 0, 0
	v_pk_mov_b32 v[38:39], 0, 0
	v_pk_mov_b32 v[40:41], 0, 0
	ds_read_b128 v[168:171], v142 offset:1024
	v_pk_mov_b32 v[42:43], 0, 0
	v_pk_mov_b32 v[44:45], 0, 0
	v_pk_mov_b32 v[46:47], 0, 0
	v_pk_mov_b32 v[48:49], 0, 0
	ds_read_b128 v[172:175], v142 offset:2048
	v_pk_mov_b32 v[50:51], 0, 0
	v_pk_mov_b32 v[52:53], 0, 0
	v_pk_mov_b32 v[54:55], 0, 0
	v_pk_mov_b32 v[56:57], 0, 0
	ds_read_b128 v[176:179], v142 offset:3072
	v_pk_mov_b32 v[58:59], 0, 0
	v_pk_mov_b32 v[60:61], 0, 0
	v_pk_mov_b32 v[62:63], 0, 0
	v_pk_mov_b32 v[64:65], 0, 0
	v_lshl_add_u64 v[142:143], s[26:27], 0, v[138:139]
	s_add_i32 m0, s25, 0xc000
	ds_read_b128 v[180:183], v146
	v_pk_mov_b32 v[66:67], 0, 0
	v_pk_mov_b32 v[68:69], 0, 0
	v_pk_mov_b32 v[70:71], 0, 0
	v_pk_mov_b32 v[72:73], 0, 0
	ds_read_b128 v[196:199], v146 offset:1024
	v_pk_mov_b32 v[74:75], 0, 0
	v_pk_mov_b32 v[76:77], 0, 0
	v_pk_mov_b32 v[78:79], 0, 0
	v_pk_mov_b32 v[80:81], 0, 0
	ds_read_b128 v[200:203], v146 offset:2048
	v_pk_mov_b32 v[82:83], 0, 0
	v_pk_mov_b32 v[84:85], 0, 0
	v_pk_mov_b32 v[86:87], 0, 0
	v_pk_mov_b32 v[88:89], 0, 0
	ds_read_b128 v[204:207], v146 offset:3072
	v_pk_mov_b32 v[90:91], 0, 0
	v_pk_mov_b32 v[92:93], 0, 0
	v_pk_mov_b32 v[94:95], 0, 0
	v_pk_mov_b32 v[96:97], 0, 0
	ds_read_b128 v[208:211], v146 offset:4096
	v_pk_mov_b32 v[98:99], 0, 0
	v_pk_mov_b32 v[100:101], 0, 0
	v_pk_mov_b32 v[102:103], 0, 0
	v_pk_mov_b32 v[104:105], 0, 0
	ds_read_b128 v[212:215], v146 offset:5120
	v_pk_mov_b32 v[106:107], 0, 0
	v_pk_mov_b32 v[108:109], 0, 0
	v_pk_mov_b32 v[110:111], 0, 0
	v_pk_mov_b32 v[112:113], 0, 0
	ds_read_b128 v[216:219], v146 offset:6144
	v_pk_mov_b32 v[114:115], 0, 0
	v_pk_mov_b32 v[116:117], 0, 0
	v_pk_mov_b32 v[118:119], 0, 0
	v_pk_mov_b32 v[120:121], 0, 0
	ds_read_b128 v[220:223], v146 offset:7168
	v_pk_mov_b32 v[122:123], 0, 0
	v_pk_mov_b32 v[124:125], 0, 0
	v_pk_mov_b32 v[126:127], 0, 0
	v_pk_mov_b32 v[128:129], 0, 0
	global_load_lds_dwordx4 v[142:143], off
	v_lshl_add_u64 v[142:143], s[26:27], 0, v[140:141]
	s_add_i32 m0, s25, 0xe000
	s_nop 0
	global_load_lds_dwordx4 v[142:143], off
	s_waitcnt vmcnt(8)
	s_waitcnt lgkmcnt(0)
	s_barrier
	s_branch .Lpeel_1340

; #define PG8_STAGE(bufoff, gbase, voff) do { _Pragma("unroll") for (int _i = 0; _i < 2; ++_i) \
;         __builtin_amdgcn_global_load_lds((const unsigned*)((const char*)(gbase) + (voff)[_i]), (PG8_LAS unsigned*)(lds + (bufoff) + ldsw + _i * 8192), 16, 0, 0); } while (0)
; #define PG8_LDA(dst, b, h) do { _Pragma("unroll") for (int m = 0; m < 4; ++m) _Pragma("unroll") for (int k = 0; k < 2; ++k) dst[m][k] = *(const PG8_LAS bf16x8*)(lds + PG8_SA(b, h) + aoff + m * 2048 + k * 1024); } while (0)
; #define PG8_MMA(ai, bj, At, Bt) do { __builtin_amdgcn_s_setprio(1); _Pragma("unroll") for (int m = 0; m < 4; ++m) _Pragma("unroll") for (int n = 0; n < 2; ++n) _Pragma("unroll") for (int k = 0; k < 2; ++k) \
;         acc[ai][bj][m][n] = __builtin_amdgcn_mfma_f32_16x16x32_bf16(Bt[n][k], At[m][k], acc[ai][bj][m][n], 0, 0, 0); __builtin_amdgcn_s_setprio(0); } while (0)
; #define PG8_WAIT_V(n) asm volatile("s_waitcnt vmcnt(" #n ")" ::: "memory")
; #define PG8_WAIT_L(n) asm volatile("s_waitcnt lgkmcnt(" #n ")" ::: "memory")
; #define PG8_BAR __builtin_amdgcn_s_barrier()
; #define PG8_SCHED __builtin_amdgcn_sched_barrier(0)
; template <class Epi, class Sched, bool ALIGN_EPI = false, bool SP2 = false, bool ABLK = false, bool BBLK = false>
; __device__ __forceinline__ void gemm_phase(PG8_LAS unsigned char* lds, const Gemm g, const Sched& S, const Epi& E) {
;     ...
;             PG8_WAIT_V(8); PG8_WAIT_L(0); PG8_BAR; PG8_MMA(0, 0, At, B0); PG8_MMA(0, 1, At, B1); PG8_BAR; PG8_SCHED;
;             PG8_LDA(At, 0, 1); PG8_STAGE(PG8_SB(0, 0), b2, voffB); PG8_STAGE(PG8_SB(0, 1), b2 + hstepB, voffB); PG8_STAGE(PG8_SA(0, 0), a2, voffA);
;             PG8_WAIT_V(8); PG8_WAIT_L(0); PG8_BAR; PG8_MMA(1, 0, At, B0); PG8_MMA(1, 1, At, B1); PG8_BAR; PG8_SCHED;
.Lpeel_1340:
	s_setprio 1
	s_waitcnt lgkmcnt(0)
	v_mfma_f32_16x16x32_bf16 v[126:129], v[148:151], v[180:183], v[126:129]
	v_mfma_f32_16x16x32_bf16 v[118:121], v[156:159], v[180:183], v[118:121]
	v_mfma_f32_16x16x32_bf16 v[110:113], v[148:151], v[200:203], v[110:113]
	v_mfma_f32_16x16x32_bf16 v[102:105], v[156:159], v[200:203], v[102:105]
	v_mfma_f32_16x16x32_bf16 v[94:97], v[148:151], v[208:211], v[94:97]
	v_mfma_f32_16x16x32_bf16 v[86:89], v[156:159], v[208:211], v[86:89]
	v_mfma_f32_16x16x32_bf16 v[78:81], v[148:151], v[216:219], v[78:81]
	v_mfma_f32_16x16x32_bf16 v[70:73], v[156:159], v[216:219], v[70:73]
	v_mfma_f32_16x16x32_bf16 v[126:129], v[152:155], v[196:199], v[126:129]
	v_mfma_f32_16x16x32_bf16 v[118:121], v[160:163], v[196:199], v[118:121]
	v_mfma_f32_16x16x32_bf16 v[110:113], v[152:155], v[204:207], v[110:113]
	v_mfma_f32_16x16x32_bf16 v[102:105], v[160:163], v[204:207], v[102:105]
	v_mfma_f32_16x16x32_bf16 v[94:97], v[152:155], v[212:215], v[94:97]
	v_mfma_f32_16x16x32_bf16 v[86:89], v[160:163], v[212:215], v[86:89]
	v_mfma_f32_16x16x32_bf16 v[78:81], v[152:155], v[220:223], v[78:81]
	v_mfma_f32_16x16x32_bf16 v[70:73], v[160:163], v[220:223], v[70:73]
	s_setprio 0
	s_setprio 1
	v_mfma_f32_16x16x32_bf16 v[122:125], v[164:167], v[180:183], v[122:125]
	v_mfma_f32_16x16x32_bf16 v[114:117], v[172:175], v[180:183], v[114:117]
	v_mfma_f32_16x16x32_bf16 v[106:109], v[164:167], v[200:203], v[106:109]
	v_mfma_f32_16x16x32_bf16 v[98:101], v[172:175], v[200:203], v[98:101]
	v_mfma_f32_16x16x32_bf16 v[90:93], v[164:167], v[208:211], v[90:93]
	v_mfma_f32_16x16x32_bf16 v[82:85], v[172:175], v[208:211], v[82:85]
	v_mfma_f32_16x16x32_bf16 v[74:77], v[164:167], v[216:219], v[74:77]
	v_mfma_f32_16x16x32_bf16 v[66:69], v[172:175], v[216:219], v[66:69]
	v_mfma_f32_16x16x32_bf16 v[122:125], v[168:171], v[196:199], v[122:125]
	v_mfma_f32_16x16x32_bf16 v[114:117], v[176:179], v[196:199], v[114:117]
	v_mfma_f32_16x16x32_bf16 v[106:109], v[168:171], v[204:207], v[106:109]
	v_mfma_f32_16x16x32_bf16 v[98:101], v[176:179], v[204:207], v[98:101]
	v_mfma_f32_16x16x32_bf16 v[90:93], v[168:171], v[212:215], v[90:93]
	v_mfma_f32_16x16x32_bf16 v[82:85], v[176:179], v[212:215], v[82:85]
	v_mfma_f32_16x16x32_bf16 v[74:77], v[168:171], v[220:223], v[74:77]
	v_mfma_f32_16x16x32_bf16 v[66:69], v[176:179], v[220:223], v[66:69]
	s_setprio 0
	s_barrier
	s_add_i32 s52, s52, s44
	v_lshl_add_u64 v[142:143], s[30:31], 0, v[134:135]
	s_mov_b32 m0, s52
	ds_read_b128 v[180:183], v146 offset:16384
	ds_read_b128 v[196:199], v146 offset:17408
	ds_read_b128 v[200:203], v146 offset:18432
	ds_read_b128 v[204:207], v146 offset:19456
	ds_read_b128 v[208:211], v146 offset:20480
	ds_read_b128 v[212:215], v146 offset:21504
	ds_read_b128 v[216:219], v146 offset:22528
	ds_read_b128 v[220:223], v146 offset:23552
	global_load_lds_dwordx4 v[142:143], off
	s_add_i32 m0, s52, 0x2000
	s_add_u32 s88, s30, 0x4000
	v_lshl_add_u64 v[142:143], s[30:31], 0, v[130:131]
	s_addc_u32 s89, s31, 0
	s_add_i32 s52, s75, s44
	global_load_lds_dwordx4 v[142:143], off
	v_lshl_add_u64 v[142:143], s[88:89], 0, v[134:135]
	s_mov_b32 m0, s52
	s_nop 0
	global_load_lds_dwordx4 v[142:143], off
	v_lshl_add_u64 v[142:143], s[88:89], 0, v[130:131]
	s_add_i32 m0, s52, 0x2000
	s_nop 0
	global_load_lds_dwordx4 v[142:143], off
	v_lshl_add_u64 v[142:143], s[34:35], 0, v[136:137]
	s_mov_b32 m0, s25
	s_nop 0
	global_load_lds_dwordx4 v[142:143], off
	v_lshl_add_u64 v[142:143], s[34:35], 0, v[132:133]
	s_mov_b32 m0, s46
	s_nop 0
	global_load_lds_dwordx4 v[142:143], off
	s_waitcnt vmcnt(8)
	s_waitcnt lgkmcnt(0)
	s_barrier
	s_setprio 1
	s_waitcnt lgkmcnt(0)
	v_mfma_f32_16x16x32_bf16 v[62:65], v[148:151], v[180:183], v[62:65]
	v_mfma_f32_16x16x32_bf16 v[54:57], v[156:159], v[180:183], v[54:57]
	v_mfma_f32_16x16x32_bf16 v[46:49], v[148:151], v[200:203], v[46:49]
	v_mfma_f32_16x16x32_bf16 v[38:41], v[156:159], v[200:203], v[38:41]
	v_mfma_f32_16x16x32_bf16 v[30:33], v[148:151], v[208:211], v[30:33]
	v_mfma_f32_16x16x32_bf16 v[22:25], v[156:159], v[208:211], v[22:25]
	v_mfma_f32_16x16x32_bf16 v[14:17], v[148:151], v[216:219], v[14:17]
	v_mfma_f32_16x16x32_bf16 v[6:9], v[156:159], v[216:219], v[6:9]
	v_mfma_f32_16x16x32_bf16 v[62:65], v[152:155], v[196:199], v[62:65]
	v_mfma_f32_16x16x32_bf16 v[54:57], v[160:163], v[196:199], v[54:57]
	v_mfma_f32_16x16x32_bf16 v[46:49], v[152:155], v[204:207], v[46:49]
	v_mfma_f32_16x16x32_bf16 v[38:41], v[160:163], v[204:207], v[38:41]
	v_mfma_f32_16x16x32_bf16 v[30:33], v[152:155], v[212:215], v[30:33]
	v_mfma_f32_16x16x32_bf16 v[22:25], v[160:163], v[212:215], v[22:25]
	v_mfma_f32_16x16x32_bf16 v[14:17], v[152:155], v[220:223], v[14:17]
	v_mfma_f32_16x16x32_bf16 v[6:9], v[160:163], v[220:223], v[6:9]
	s_setprio 0
	s_setprio 1
	v_mfma_f32_16x16x32_bf16 v[58:61], v[164:167], v[180:183], v[58:61]
	v_mfma_f32_16x16x32_bf16 v[50:53], v[172:175], v[180:183], v[50:53]
	v_mfma_f32_16x16x32_bf16 v[42:45], v[164:167], v[200:203], v[42:45]
	v_mfma_f32_16x16x32_bf16 v[34:37], v[172:175], v[200:203], v[34:37]
	v_mfma_f32_16x16x32_bf16 v[26:29], v[164:167], v[208:211], v[26:29]
	v_mfma_f32_16x16x32_bf16 v[18:21], v[172:175], v[208:211], v[18:21]
	v_mfma_f32_16x16x32_bf16 v[10:13], v[164:167], v[216:219], v[10:13]
	v_mfma_f32_16x16x32_bf16 v[2:5], v[172:175], v[216:219], v[2:5]
	v_mfma_f32_16x16x32_bf16 v[58:61], v[168:171], v[196:199], v[58:61]
	v_mfma_f32_16x16x32_bf16 v[50:53], v[176:179], v[196:199], v[50:53]
	v_mfma_f32_16x16x32_bf16 v[42:45], v[168:171], v[204:207], v[42:45]
	v_mfma_f32_16x16x32_bf16 v[34:37], v[176:179], v[204:207], v[34:37]
	v_mfma_f32_16x16x32_bf16 v[26:29], v[168:171], v[212:215], v[26:29]
	v_mfma_f32_16x16x32_bf16 v[18:21], v[176:179], v[212:215], v[18:21]
	v_mfma_f32_16x16x32_bf16 v[10:13], v[168:171], v[220:223], v[10:13]
	v_mfma_f32_16x16x32_bf16 v[2:5], v[176:179], v[220:223], v[2:5]
	s_setprio 0
	s_barrier
; #define PG8_STAGE(bufoff, gbase, voff) do { _Pragma("unroll") for (int _i = 0; _i < 2; ++_i) \
;         __builtin_amdgcn_global_load_lds((const unsigned*)((const char*)(gbase) + (voff)[_i]), (PG8_LAS unsigned*)(lds + (bufoff) + ldsw + _i * 8192), 16, 0, 0); } while (0)
; #define PG8_LDA(dst, b, h) do { _Pragma("unroll") for (int m = 0; m < 4; ++m) _Pragma("unroll") for (int k = 0; k < 2; ++k) dst[m][k] = *(const PG8_LAS bf16x8*)(lds + PG8_SA(b, h) + aoff + m * 2048 + k * 1024); } while (0)
; #define PG8_LDB(dst, b, h) do { _Pragma("unroll") for (int n = 0; n < 2; ++n) _Pragma("unroll") for (int k = 0; k < 2; ++k) dst[n][k] = *(const PG8_LAS bf16x8*)(lds + PG8_SB(b, h) + boff + n * 2048 + k * 1024); } while (0)
; #define PG8_MMA(ai, bj, At, Bt) do { __builtin_amdgcn_s_setprio(1); _Pragma("unroll") for (int m = 0; m < 4; ++m) _Pragma("unroll") for (int n = 0; n < 2; ++n) _Pragma("unroll") for (int k = 0; k < 2; ++k) \
;         acc[ai][bj][m][n] = __builtin_amdgcn_mfma_f32_16x16x32_bf16(Bt[n][k], At[m][k], acc[ai][bj][m][n], 0, 0, 0); __builtin_amdgcn_s_setprio(0); } while (0)
; #define PG8_WAIT_V(n) asm volatile("s_waitcnt vmcnt(" #n ")" ::: "memory")
; #define PG8_WAIT_L(n) asm volatile("s_waitcnt lgkmcnt(" #n ")" ::: "memory")
; #define PG8_BAR __builtin_amdgcn_s_barrier()
; #define PG8_SCHED __builtin_amdgcn_sched_barrier(0)
; template <class Epi, class Sched, bool ALIGN_EPI = false, bool SP2 = false, bool ABLK = false, bool BBLK = false>
; __device__ __forceinline__ void gemm_phase(PG8_LAS unsigned char* lds, const Gemm g, const Sched& S, const Epi& E) {
;     ...
;             PG8_LDB(B0, 1, 0); PG8_LDB(B1, 1, 1); PG8_SCHED; PG8_LDA(At, 1, 0); PG8_STAGE(PG8_SA(0, 1), a2 + hstepA, voffA);
;             PG8_WAIT_V(8); PG8_WAIT_L(0); PG8_BAR; PG8_MMA(0, 0, At, B0); PG8_MMA(0, 1, At, B1); PG8_BAR; PG8_SCHED;
	s_add_i32 s52, 0, 0x18000
	v_add_u32_e32 v142, s52, v145
	s_add_i32 s75, 0, 0x1c000
	ds_read_b128 v[148:151], v142
	ds_read_b128 v[152:155], v142 offset:1024
	ds_read_b128 v[156:159], v142 offset:2048
	ds_read_b128 v[160:163], v142 offset:3072
	v_add_u32_e32 v142, s75, v145
	ds_read_b128 v[164:167], v142
	ds_read_b128 v[168:171], v142 offset:1024
	ds_read_b128 v[172:175], v142 offset:2048
	ds_read_b128 v[176:179], v142 offset:3072
	s_add_u32 s34, s34, 0x4000
	s_addc_u32 s35, s35, 0
	s_mov_b32 m0, s47
	v_lshl_add_u64 v[142:143], s[34:35], 0, v[136:137]
	ds_read_b128 v[180:183], v146 offset:32768
	ds_read_b128 v[196:199], v146 offset:33792
	ds_read_b128 v[200:203], v146 offset:34816
	ds_read_b128 v[204:207], v146 offset:35840
	ds_read_b128 v[208:211], v146 offset:36864
	ds_read_b128 v[212:215], v146 offset:37888
	ds_read_b128 v[216:219], v146 offset:38912
	ds_read_b128 v[220:223], v146 offset:39936
	global_load_lds_dwordx4 v[142:143], off
	v_lshl_add_u64 v[142:143], s[34:35], 0, v[132:133]
	s_mov_b32 m0, s50
	s_nop 0
	global_load_lds_dwordx4 v[142:143], off
	s_waitcnt vmcnt(8)
	s_waitcnt lgkmcnt(0)
	s_barrier
	s_setprio 1
	s_waitcnt lgkmcnt(0)
	v_mfma_f32_16x16x32_bf16 v[126:129], v[148:151], v[180:183], v[126:129]
	v_mfma_f32_16x16x32_bf16 v[118:121], v[156:159], v[180:183], v[118:121]
	v_mfma_f32_16x16x32_bf16 v[110:113], v[148:151], v[200:203], v[110:113]
	v_mfma_f32_16x16x32_bf16 v[102:105], v[156:159], v[200:203], v[102:105]
	v_mfma_f32_16x16x32_bf16 v[94:97], v[148:151], v[208:211], v[94:97]
	v_mfma_f32_16x16x32_bf16 v[86:89], v[156:159], v[208:211], v[86:89]
	v_mfma_f32_16x16x32_bf16 v[78:81], v[148:151], v[216:219], v[78:81]
	v_mfma_f32_16x16x32_bf16 v[70:73], v[156:159], v[216:219], v[70:73]
	v_mfma_f32_16x16x32_bf16 v[126:129], v[152:155], v[196:199], v[126:129]
	v_mfma_f32_16x16x32_bf16 v[118:121], v[160:163], v[196:199], v[118:121]
	v_mfma_f32_16x16x32_bf16 v[110:113], v[152:155], v[204:207], v[110:113]
	v_mfma_f32_16x16x32_bf16 v[102:105], v[160:163], v[204:207], v[102:105]
	v_mfma_f32_16x16x32_bf16 v[94:97], v[152:155], v[212:215], v[94:97]
	v_mfma_f32_16x16x32_bf16 v[86:89], v[160:163], v[212:215], v[86:89]
	v_mfma_f32_16x16x32_bf16 v[78:81], v[152:155], v[220:223], v[78:81]
	v_mfma_f32_16x16x32_bf16 v[70:73], v[160:163], v[220:223], v[70:73]
	s_setprio 0
	s_setprio 1
	v_mfma_f32_16x16x32_bf16 v[122:125], v[164:167], v[180:183], v[122:125]
	v_mfma_f32_16x16x32_bf16 v[114:117], v[172:175], v[180:183], v[114:117]
	v_mfma_f32_16x16x32_bf16 v[106:109], v[164:167], v[200:203], v[106:109]
	v_mfma_f32_16x16x32_bf16 v[98:101], v[172:175], v[200:203], v[98:101]
	v_mfma_f32_16x16x32_bf16 v[90:93], v[164:167], v[208:211], v[90:93]
	v_mfma_f32_16x16x32_bf16 v[82:85], v[172:175], v[208:211], v[82:85]
	v_mfma_f32_16x16x32_bf16 v[74:77], v[164:167], v[216:219], v[74:77]
	v_mfma_f32_16x16x32_bf16 v[66:69], v[172:175], v[216:219], v[66:69]
	v_mfma_f32_16x16x32_bf16 v[122:125], v[168:171], v[196:199], v[122:125]
	v_mfma_f32_16x16x32_bf16 v[114:117], v[176:179], v[196:199], v[114:117]
	v_mfma_f32_16x16x32_bf16 v[106:109], v[168:171], v[204:207], v[106:109]
	v_mfma_f32_16x16x32_bf16 v[98:101], v[176:179], v[204:207], v[98:101]
	v_mfma_f32_16x16x32_bf16 v[90:93], v[168:171], v[212:215], v[90:93]
	v_mfma_f32_16x16x32_bf16 v[82:85], v[176:179], v[212:215], v[82:85]
	v_mfma_f32_16x16x32_bf16 v[74:77], v[168:171], v[220:223], v[74:77]
	v_mfma_f32_16x16x32_bf16 v[66:69], v[176:179], v[220:223], v[66:69]
	s_setprio 0
	s_barrier
; #define PG8_STAGE(bufoff, gbase, voff) do { _Pragma("unroll") for (int _i = 0; _i < 2; ++_i) \
;         __builtin_amdgcn_global_load_lds((const unsigned*)((const char*)(gbase) + (voff)[_i]), (PG8_LAS unsigned*)(lds + (bufoff) + ldsw + _i * 8192), 16, 0, 0); } while (0)
; #define PG8_LDA(dst, b, h) do { _Pragma("unroll") for (int m = 0; m < 4; ++m) _Pragma("unroll") for (int k = 0; k < 2; ++k) dst[m][k] = *(const PG8_LAS bf16x8*)(lds + PG8_SA(b, h) + aoff + m * 2048 + k * 1024); } while (0)
; #define PG8_MMA(ai, bj, At, Bt) do { __builtin_amdgcn_s_setprio(1); _Pragma("unroll") for (int m = 0; m < 4; ++m) _Pragma("unroll") for (int n = 0; n < 2; ++n) _Pragma("unroll") for (int k = 0; k < 2; ++k) \
;         acc[ai][bj][m][n] = __builtin_amdgcn_mfma_f32_16x16x32_bf16(Bt[n][k], At[m][k], acc[ai][bj][m][n], 0, 0, 0); __builtin_amdgcn_s_setprio(0); } while (0)
; #define PG8_WAIT_V(n) asm volatile("s_waitcnt vmcnt(" #n ")" ::: "memory")
; #define PG8_WAIT_L(n) asm volatile("s_waitcnt lgkmcnt(" #n ")" ::: "memory")
; #define PG8_BAR __builtin_amdgcn_s_barrier()
; #define PG8_SCHED __builtin_amdgcn_sched_barrier(0)
; template <class Epi, class Sched, bool ALIGN_EPI = false, bool SP2 = false, bool ABLK = false, bool BBLK = false>
; __device__ __forceinline__ void gemm_phase(PG8_LAS unsigned char* lds, const Gemm g, const Sched& S, const Epi& E) {
;     ...
;             PG8_LDA(At, 1, 1); PG8_STAGE(PG8_SB(1, 0), b3, voffB); PG8_STAGE(PG8_SB(1, 1), b3 + hstepB, voffB); PG8_STAGE(PG8_SA(1, 0), a3, voffA);
;             PG8_WAIT_V(8); PG8_WAIT_L(0); PG8_BAR; PG8_MMA(1, 0, At, B0); PG8_MMA(1, 1, At, B1); PG8_BAR; PG8_SCHED;
;     ...
;         if constexpr (ALIGN_EPI) { if (wr == 0) PG8_BAR; }
	s_add_u32 s34, s30, 0x8000
	s_addc_u32 s35, s31, 0
	s_add_i32 s52, s52, s44
	v_lshl_add_u64 v[142:143], s[34:35], 0, v[134:135]
	s_mov_b32 m0, s52
	ds_read_b128 v[180:183], v146 offset:49152
	ds_read_b128 v[196:199], v146 offset:50176
	ds_read_b128 v[200:203], v146 offset:51200
	ds_read_b128 v[204:207], v146 offset:52224
	ds_read_b128 v[208:211], v146 offset:53248
	ds_read_b128 v[212:215], v146 offset:54272
	ds_read_b128 v[216:219], v146 offset:55296
	ds_read_b128 v[220:223], v146 offset:56320
	global_load_lds_dwordx4 v[142:143], off
	s_add_i32 m0, s52, 0x2000
	s_add_u32 s30, s30, 0xc000
	v_lshl_add_u64 v[142:143], s[34:35], 0, v[130:131]
	s_addc_u32 s31, s31, 0
	s_add_i32 s34, s75, s44
	global_load_lds_dwordx4 v[142:143], off
	v_lshl_add_u64 v[142:143], s[30:31], 0, v[134:135]
	s_mov_b32 m0, s34
	s_nop 0
	global_load_lds_dwordx4 v[142:143], off
	v_lshl_add_u64 v[142:143], s[30:31], 0, v[130:131]
	s_add_i32 m0, s34, 0x2000
	s_nop 0
	global_load_lds_dwordx4 v[142:143], off
	v_lshl_add_u64 v[142:143], s[28:29], 0, v[136:137]
	s_mov_b32 m0, s56
	s_nop 0
	global_load_lds_dwordx4 v[142:143], off
	v_lshl_add_u64 v[142:143], s[28:29], 0, v[132:133]
	s_mov_b32 m0, s60
	s_nop 0
	global_load_lds_dwordx4 v[142:143], off
	s_waitcnt vmcnt(8)
	s_waitcnt lgkmcnt(0)
	s_barrier
	s_setprio 1
	s_waitcnt lgkmcnt(0)
	v_mfma_f32_16x16x32_bf16 v[62:65], v[148:151], v[180:183], v[62:65]
	v_mfma_f32_16x16x32_bf16 v[54:57], v[156:159], v[180:183], v[54:57]
	v_mfma_f32_16x16x32_bf16 v[46:49], v[148:151], v[200:203], v[46:49]
	v_mfma_f32_16x16x32_bf16 v[38:41], v[156:159], v[200:203], v[38:41]
	v_mfma_f32_16x16x32_bf16 v[30:33], v[148:151], v[208:211], v[30:33]
	v_mfma_f32_16x16x32_bf16 v[22:25], v[156:159], v[208:211], v[22:25]
	v_mfma_f32_16x16x32_bf16 v[14:17], v[148:151], v[216:219], v[14:17]
	v_mfma_f32_16x16x32_bf16 v[6:9], v[156:159], v[216:219], v[6:9]
	v_mfma_f32_16x16x32_bf16 v[62:65], v[152:155], v[196:199], v[62:65]
	v_mfma_f32_16x16x32_bf16 v[54:57], v[160:163], v[196:199], v[54:57]
	v_mfma_f32_16x16x32_bf16 v[46:49], v[152:155], v[204:207], v[46:49]
	v_mfma_f32_16x16x32_bf16 v[38:41], v[160:163], v[204:207], v[38:41]
	v_mfma_f32_16x16x32_bf16 v[30:33], v[152:155], v[212:215], v[30:33]
	v_mfma_f32_16x16x32_bf16 v[22:25], v[160:163], v[212:215], v[22:25]
	v_mfma_f32_16x16x32_bf16 v[14:17], v[152:155], v[220:223], v[14:17]
	v_mfma_f32_16x16x32_bf16 v[6:9], v[160:163], v[220:223], v[6:9]
	s_setprio 0
	s_setprio 1
	v_mfma_f32_16x16x32_bf16 v[58:61], v[164:167], v[180:183], v[58:61]
	v_mfma_f32_16x16x32_bf16 v[50:53], v[172:175], v[180:183], v[50:53]
	v_mfma_f32_16x16x32_bf16 v[42:45], v[164:167], v[200:203], v[42:45]
	v_mfma_f32_16x16x32_bf16 v[34:37], v[172:175], v[200:203], v[34:37]
	v_mfma_f32_16x16x32_bf16 v[26:29], v[164:167], v[208:211], v[26:29]
	v_mfma_f32_16x16x32_bf16 v[18:21], v[172:175], v[208:211], v[18:21]
	v_mfma_f32_16x16x32_bf16 v[10:13], v[164:167], v[216:219], v[10:13]
	v_mfma_f32_16x16x32_bf16 v[2:5], v[172:175], v[216:219], v[2:5]
	v_mfma_f32_16x16x32_bf16 v[58:61], v[168:171], v[196:199], v[58:61]
	v_mfma_f32_16x16x32_bf16 v[50:53], v[176:179], v[196:199], v[50:53]
	v_mfma_f32_16x16x32_bf16 v[42:45], v[168:171], v[204:207], v[42:45]
	v_mfma_f32_16x16x32_bf16 v[34:37], v[176:179], v[204:207], v[34:37]
	v_mfma_f32_16x16x32_bf16 v[26:29], v[168:171], v[212:215], v[26:29]
	v_mfma_f32_16x16x32_bf16 v[18:21], v[176:179], v[212:215], v[18:21]
	v_mfma_f32_16x16x32_bf16 v[10:13], v[168:171], v[220:223], v[10:13]
	v_mfma_f32_16x16x32_bf16 v[2:5], v[176:179], v[220:223], v[2:5]
	s_setprio 0
	s_barrier
	s_add_i32 s83, s83, 2
	s_add_u32 s26, s26, 0x10000
	s_addc_u32 s27, s27, 0
	s_add_u32 s73, s73, 0x10000
	s_addc_u32 s81, s81, 0
	s_cmp_gt_u32 s83, 29
	s_cbranch_scc0 .LBB0_1340
	s_and_b64 vcc, exec, s[12:13]
	s_cbranch_vccz .LBB0_1343
	s_barrier

; #define PG8_STAGE(bufoff, gbase, voff) do { _Pragma("unroll") for (int _i = 0; _i < 2; ++_i) \
;         __builtin_amdgcn_global_load_lds((const unsigned*)((const char*)(gbase) + (voff)[_i]), (PG8_LAS unsigned*)(lds + (bufoff) + ldsw + _i * 8192), 16, 0, 0); } while (0)
; #define PG8_LDA(dst, b, h) do { _Pragma("unroll") for (int m = 0; m < 4; ++m) _Pragma("unroll") for (int k = 0; k < 2; ++k) dst[m][k] = *(const PG8_LAS bf16x8*)(lds + PG8_SA(b, h) + aoff + m * 2048 + k * 1024); } while (0)
; #define PG8_LDB(dst, b, h) do { _Pragma("unroll") for (int n = 0; n < 2; ++n) _Pragma("unroll") for (int k = 0; k < 2; ++k) dst[n][k] = *(const PG8_LAS bf16x8*)(lds + PG8_SB(b, h) + boff + n * 2048 + k * 1024); } while (0)
; #define PG8_BAR __builtin_amdgcn_s_barrier()
; #define PG8_SCHED __builtin_amdgcn_sched_barrier(0)
; template <class Epi, class Sched, bool ALIGN_EPI = false, bool SP2 = false, bool ABLK = false, bool BBLK = false>
; __device__ __forceinline__ void gemm_phase(PG8_LAS unsigned char* lds, const Gemm g, const Sched& S, const Epi& E) {
;     ...
;         const bool has_next = S.next(ui + 1, nxt);
;         const char* nA = has_next ? (const char*)g.A + (size_t)nxt.pm * tstepA : cA; const char* nB = has_next ? (const char*)g.Bt + (size_t)nxt.pn * tstepB : cB;
;         for (int t = 0; t < nt; t += 2) {
;             const bool last = (t == nt - 2);
;             const char* a1 = cA + (size_t)(t + 1) * kstepA;
;             const char* a2 = last ? nA : cA + (size_t)(t + 2) * kstepA; const char* b2 = last ? nB : cB + (size_t)(t + 2) * kstepB;
;             const char* a3 = a2 + kstepA; const char* b3 = b2 + kstepB;
;             if (last && has_next) S.a_ready(nxt);
;             if constexpr (SP2) {
;             PG8_LDB(B0, 0, 0); PG8_LDB(B1, 0, 1); PG8_SCHED; PG8_LDA(At, 0, 0); PG8_STAGE(PG8_SA(1, 1), a1 + hstepA, voffA);
;     ...
; #pragma unroll
;         for (int a = 0; a < 2; ++a)
; #pragma unroll
;             for (int b = 0; b < 2; ++b)
; #pragma unroll
;                 for (int m = 0; m < 4; ++m)
; #pragma unroll
;                     for (int n = 0; n < 2; ++n) acc[a][b][m][n] = (f32x4){0.f, 0.f, 0.f, 0.f};
;         cur = nxt; cA = nA; cB = nB; ++ui;
;         if constexpr (ALIGN_EPI) { if (wr == 1) PG8_BAR; }
.LBB0_1419:
	s_add_u32 s0, s0, 0xc000
	s_addc_u32 s1, s1, 0
	s_add_u32 s23, s26, 0x10000
	v_mov_b32_e32 v2, 0
	s_addc_u32 s25, s27, 0
	s_mov_b32 s73, -2
	s_add_u32 s8, s0, 0x4000
	s_addc_u32 s9, s1, 0
	s_cmpk_eq_i32 s73, 0x54
	s_cselect_b32 s28, s18, s8
	s_cselect_b32 s29, s19, s9
	s_cselect_b32 s26, s20, s23
	s_cselect_b32 s27, s21, s25
	s_add_u32 s8, s28, 0x8000
	s_addc_u32 s9, s29, 0
	s_add_i32 s52, 0, 0x10000
	s_add_i32 s75, 0, 0x14000
	v_add_u32_e32 v142, s52, v180
	v_add_u32_e32 v168, s75, v180
	ds_read_b128 v[130:133], v142
	v_pk_mov_b32 v[2:3], 0, 0
	v_pk_mov_b32 v[4:5], 0, 0
	v_pk_mov_b32 v[6:7], 0, 0
	v_pk_mov_b32 v[8:9], 0, 0
	ds_read_b128 v[134:137], v142 offset:1024
	v_pk_mov_b32 v[10:11], 0, 0
	v_pk_mov_b32 v[12:13], 0, 0
	v_pk_mov_b32 v[14:15], 0, 0
	v_pk_mov_b32 v[16:17], 0, 0
	ds_read_b128 v[138:141], v142 offset:2048
	v_pk_mov_b32 v[18:19], 0, 0
	v_pk_mov_b32 v[20:21], 0, 0
	v_pk_mov_b32 v[22:23], 0, 0
	v_pk_mov_b32 v[24:25], 0, 0
	ds_read_b128 v[142:145], v142 offset:3072
	v_pk_mov_b32 v[26:27], 0, 0
	v_pk_mov_b32 v[28:29], 0, 0
	v_pk_mov_b32 v[30:31], 0, 0
	v_pk_mov_b32 v[32:33], 0, 0
	ds_read_b128 v[156:159], v168
	v_pk_mov_b32 v[34:35], 0, 0
	v_pk_mov_b32 v[36:37], 0, 0
	v_pk_mov_b32 v[38:39], 0, 0
	v_pk_mov_b32 v[40:41], 0, 0
	ds_read_b128 v[160:163], v168 offset:1024
	v_pk_mov_b32 v[42:43], 0, 0
	v_pk_mov_b32 v[44:45], 0, 0
	v_pk_mov_b32 v[46:47], 0, 0
	v_pk_mov_b32 v[48:49], 0, 0
	ds_read_b128 v[164:167], v168 offset:2048
	v_pk_mov_b32 v[50:51], 0, 0
	v_pk_mov_b32 v[52:53], 0, 0
	v_pk_mov_b32 v[54:55], 0, 0
	v_pk_mov_b32 v[56:57], 0, 0
	ds_read_b128 v[168:171], v168 offset:3072
	v_pk_mov_b32 v[58:59], 0, 0
	v_pk_mov_b32 v[60:61], 0, 0
	v_pk_mov_b32 v[62:63], 0, 0
	v_pk_mov_b32 v[64:65], 0, 0
	v_lshl_add_u64 v[176:177], s[0:1], 0, v[152:153]
	s_add_i32 m0, s3, 0xc000
	ds_read_b128 v[172:175], v181
	v_pk_mov_b32 v[66:67], 0, 0
	v_pk_mov_b32 v[68:69], 0, 0
	v_pk_mov_b32 v[70:71], 0, 0
	v_pk_mov_b32 v[72:73], 0, 0
	ds_read_b128 v[182:185], v181 offset:1024
	v_pk_mov_b32 v[74:75], 0, 0
	v_pk_mov_b32 v[76:77], 0, 0
	v_pk_mov_b32 v[78:79], 0, 0
	v_pk_mov_b32 v[80:81], 0, 0
	ds_read_b128 v[196:199], v181 offset:2048
	v_pk_mov_b32 v[82:83], 0, 0
	v_pk_mov_b32 v[84:85], 0, 0
	v_pk_mov_b32 v[86:87], 0, 0
	v_pk_mov_b32 v[88:89], 0, 0
	ds_read_b128 v[200:203], v181 offset:3072
	v_pk_mov_b32 v[90:91], 0, 0
	v_pk_mov_b32 v[92:93], 0, 0
	v_pk_mov_b32 v[94:95], 0, 0
	v_pk_mov_b32 v[96:97], 0, 0
	ds_read_b128 v[204:207], v181 offset:4096
	v_pk_mov_b32 v[98:99], 0, 0
	v_pk_mov_b32 v[100:101], 0, 0
	v_pk_mov_b32 v[102:103], 0, 0
	v_pk_mov_b32 v[104:105], 0, 0
	ds_read_b128 v[208:211], v181 offset:5120
	v_pk_mov_b32 v[106:107], 0, 0
	v_pk_mov_b32 v[108:109], 0, 0
	v_pk_mov_b32 v[110:111], 0, 0
	v_pk_mov_b32 v[112:113], 0, 0
	ds_read_b128 v[212:215], v181 offset:6144
	v_pk_mov_b32 v[114:115], 0, 0
	v_pk_mov_b32 v[116:117], 0, 0
	v_pk_mov_b32 v[118:119], 0, 0
	v_pk_mov_b32 v[120:121], 0, 0
	ds_read_b128 v[216:219], v181 offset:7168
	v_pk_mov_b32 v[122:123], 0, 0
	v_pk_mov_b32 v[124:125], 0, 0
	v_pk_mov_b32 v[126:127], 0, 0
	v_pk_mov_b32 v[128:129], 0, 0
	global_load_lds_dwordx4 v[176:177], off
	v_lshl_add_u64 v[176:177], s[0:1], 0, v[154:155]
	s_add_i32 m0, s3, 0xe000
	s_nop 0
	global_load_lds_dwordx4 v[176:177], off
	s_waitcnt vmcnt(8)
	s_waitcnt lgkmcnt(0)
	s_barrier
	s_branch .Lpeel_1420

; #define PG8_STAGE(bufoff, gbase, voff) do { _Pragma("unroll") for (int _i = 0; _i < 2; ++_i) \
;         __builtin_amdgcn_global_load_lds((const unsigned*)((const char*)(gbase) + (voff)[_i]), (PG8_LAS unsigned*)(lds + (bufoff) + ldsw + _i * 8192), 16, 0, 0); } while (0)
; #define PG8_LDA(dst, b, h) do { _Pragma("unroll") for (int m = 0; m < 4; ++m) _Pragma("unroll") for (int k = 0; k < 2; ++k) dst[m][k] = *(const PG8_LAS bf16x8*)(lds + PG8_SA(b, h) + aoff + m * 2048 + k * 1024); } while (0)
; #define PG8_MMA(ai, bj, At, Bt) do { __builtin_amdgcn_s_setprio(1); _Pragma("unroll") for (int m = 0; m < 4; ++m) _Pragma("unroll") for (int n = 0; n < 2; ++n) _Pragma("unroll") for (int k = 0; k < 2; ++k) \
;         acc[ai][bj][m][n] = __builtin_amdgcn_mfma_f32_16x16x32_bf16(Bt[n][k], At[m][k], acc[ai][bj][m][n], 0, 0, 0); __builtin_amdgcn_s_setprio(0); } while (0)
; #define PG8_WAIT_V(n) asm volatile("s_waitcnt vmcnt(" #n ")" ::: "memory")
; #define PG8_WAIT_L(n) asm volatile("s_waitcnt lgkmcnt(" #n ")" ::: "memory")
; #define PG8_BAR __builtin_amdgcn_s_barrier()
; #define PG8_SCHED __builtin_amdgcn_sched_barrier(0)
; template <class Epi, class Sched, bool ALIGN_EPI = false, bool SP2 = false, bool ABLK = false, bool BBLK = false>
; __device__ __forceinline__ void gemm_phase(PG8_LAS unsigned char* lds, const Gemm g, const Sched& S, const Epi& E) {
;     ...
;             PG8_WAIT_V(8); PG8_WAIT_L(0); PG8_BAR; PG8_MMA(0, 0, At, B0); PG8_MMA(0, 1, At, B1); PG8_BAR; PG8_SCHED;
;             PG8_LDA(At, 0, 1); PG8_STAGE(PG8_SB(0, 0), b2, voffB); PG8_STAGE(PG8_SB(0, 1), b2 + hstepB, voffB); PG8_STAGE(PG8_SA(0, 0), a2, voffA);
;             PG8_WAIT_V(8); PG8_WAIT_L(0); PG8_BAR; PG8_MMA(1, 0, At, B0); PG8_MMA(1, 1, At, B1); PG8_BAR; PG8_SCHED;
.Lpeel_1420:
	s_setprio 1
	s_waitcnt lgkmcnt(0)
	v_mfma_f32_16x16x32_bf16 v[58:61], v[130:133], v[172:175], v[58:61]
	v_mfma_f32_16x16x32_bf16 v[50:53], v[138:141], v[172:175], v[50:53]
	v_mfma_f32_16x16x32_bf16 v[78:81], v[130:133], v[196:199], v[78:81]
	v_mfma_f32_16x16x32_bf16 v[70:73], v[138:141], v[196:199], v[70:73]
	v_mfma_f32_16x16x32_bf16 v[98:101], v[130:133], v[204:207], v[98:101]
	v_mfma_f32_16x16x32_bf16 v[102:105], v[138:141], v[204:207], v[102:105]
	v_mfma_f32_16x16x32_bf16 v[114:117], v[130:133], v[212:215], v[114:117]
	v_mfma_f32_16x16x32_bf16 v[118:121], v[138:141], v[212:215], v[118:121]
	v_mfma_f32_16x16x32_bf16 v[58:61], v[134:137], v[182:185], v[58:61]
	v_mfma_f32_16x16x32_bf16 v[50:53], v[142:145], v[182:185], v[50:53]
	v_mfma_f32_16x16x32_bf16 v[78:81], v[134:137], v[200:203], v[78:81]
	v_mfma_f32_16x16x32_bf16 v[70:73], v[142:145], v[200:203], v[70:73]
	v_mfma_f32_16x16x32_bf16 v[98:101], v[134:137], v[208:211], v[98:101]
	v_mfma_f32_16x16x32_bf16 v[102:105], v[142:145], v[208:211], v[102:105]
	v_mfma_f32_16x16x32_bf16 v[114:117], v[134:137], v[216:219], v[114:117]
	v_mfma_f32_16x16x32_bf16 v[118:121], v[142:145], v[216:219], v[118:121]
	s_setprio 0
	s_setprio 1
	v_mfma_f32_16x16x32_bf16 v[66:69], v[156:159], v[172:175], v[66:69]
	v_mfma_f32_16x16x32_bf16 v[54:57], v[164:167], v[172:175], v[54:57]
	v_mfma_f32_16x16x32_bf16 v[86:89], v[156:159], v[196:199], v[86:89]
	v_mfma_f32_16x16x32_bf16 v[94:97], v[164:167], v[196:199], v[94:97]
	v_mfma_f32_16x16x32_bf16 v[106:109], v[156:159], v[204:207], v[106:109]
	v_mfma_f32_16x16x32_bf16 v[110:113], v[164:167], v[204:207], v[110:113]
	v_mfma_f32_16x16x32_bf16 v[122:125], v[156:159], v[212:215], v[122:125]
	v_mfma_f32_16x16x32_bf16 v[126:129], v[164:167], v[212:215], v[126:129]
	v_mfma_f32_16x16x32_bf16 v[66:69], v[160:163], v[182:185], v[66:69]
	v_mfma_f32_16x16x32_bf16 v[54:57], v[168:171], v[182:185], v[54:57]
	v_mfma_f32_16x16x32_bf16 v[86:89], v[160:163], v[200:203], v[86:89]
	v_mfma_f32_16x16x32_bf16 v[94:97], v[168:171], v[200:203], v[94:97]
	v_mfma_f32_16x16x32_bf16 v[106:109], v[160:163], v[208:211], v[106:109]
	v_mfma_f32_16x16x32_bf16 v[110:113], v[168:171], v[208:211], v[110:113]
	v_mfma_f32_16x16x32_bf16 v[122:125], v[160:163], v[216:219], v[122:125]
	v_mfma_f32_16x16x32_bf16 v[126:129], v[168:171], v[216:219], v[126:129]
	s_setprio 0
	s_barrier
	s_add_i32 s52, s52, s2
	v_lshl_add_u64 v[176:177], s[26:27], 0, v[186:187]
	s_mov_b32 m0, s52
	ds_read_b128 v[172:175], v181 offset:16384
	ds_read_b128 v[182:185], v181 offset:17408
	ds_read_b128 v[196:199], v181 offset:18432
	ds_read_b128 v[200:203], v181 offset:19456
	ds_read_b128 v[204:207], v181 offset:20480
	ds_read_b128 v[208:211], v181 offset:21504
	ds_read_b128 v[212:215], v181 offset:22528
	ds_read_b128 v[216:219], v181 offset:23552
	global_load_lds_dwordx4 v[176:177], off
	s_add_i32 m0, s52, 0x2000
	s_add_u32 s80, s26, 0x4000
	v_lshl_add_u64 v[176:177], s[26:27], 0, v[150:151]
	s_addc_u32 s81, s27, 0
	s_add_i32 s52, s75, s2
	global_load_lds_dwordx4 v[176:177], off
	v_lshl_add_u64 v[176:177], s[80:81], 0, v[186:187]
	s_mov_b32 m0, s52
	s_nop 0
	global_load_lds_dwordx4 v[176:177], off
	v_lshl_add_u64 v[176:177], s[80:81], 0, v[150:151]
	s_add_i32 m0, s52, 0x2000
	s_nop 0
	global_load_lds_dwordx4 v[176:177], off
	v_lshl_add_u64 v[176:177], s[28:29], 0, v[146:147]
	s_mov_b32 m0, s3
	s_nop 0
	global_load_lds_dwordx4 v[176:177], off
	v_lshl_add_u64 v[176:177], s[28:29], 0, v[148:149]
	s_mov_b32 m0, s16
	s_nop 0
	global_load_lds_dwordx4 v[176:177], off
	s_waitcnt vmcnt(8)
	s_waitcnt lgkmcnt(0)
	s_barrier
	s_setprio 1
	s_waitcnt lgkmcnt(0)
	v_mfma_f32_16x16x32_bf16 v[90:93], v[130:133], v[172:175], v[90:93]
	v_mfma_f32_16x16x32_bf16 v[82:85], v[138:141], v[172:175], v[82:85]
	v_mfma_f32_16x16x32_bf16 v[46:49], v[130:133], v[196:199], v[46:49]
	v_mfma_f32_16x16x32_bf16 v[42:45], v[138:141], v[196:199], v[42:45]
	v_mfma_f32_16x16x32_bf16 v[30:33], v[130:133], v[204:207], v[30:33]
	v_mfma_f32_16x16x32_bf16 v[26:29], v[138:141], v[204:207], v[26:29]
	v_mfma_f32_16x16x32_bf16 v[14:17], v[130:133], v[212:215], v[14:17]
	v_mfma_f32_16x16x32_bf16 v[10:13], v[138:141], v[212:215], v[10:13]
	v_mfma_f32_16x16x32_bf16 v[90:93], v[134:137], v[182:185], v[90:93]
	v_mfma_f32_16x16x32_bf16 v[82:85], v[142:145], v[182:185], v[82:85]
	v_mfma_f32_16x16x32_bf16 v[46:49], v[134:137], v[200:203], v[46:49]
	v_mfma_f32_16x16x32_bf16 v[42:45], v[142:145], v[200:203], v[42:45]
	v_mfma_f32_16x16x32_bf16 v[30:33], v[134:137], v[208:211], v[30:33]
	v_mfma_f32_16x16x32_bf16 v[26:29], v[142:145], v[208:211], v[26:29]
	v_mfma_f32_16x16x32_bf16 v[14:17], v[134:137], v[216:219], v[14:17]
	v_mfma_f32_16x16x32_bf16 v[10:13], v[142:145], v[216:219], v[10:13]
	s_setprio 0
	s_setprio 1
	v_mfma_f32_16x16x32_bf16 v[74:77], v[156:159], v[172:175], v[74:77]
	v_mfma_f32_16x16x32_bf16 v[62:65], v[164:167], v[172:175], v[62:65]
	v_mfma_f32_16x16x32_bf16 v[38:41], v[156:159], v[196:199], v[38:41]
	v_mfma_f32_16x16x32_bf16 v[34:37], v[164:167], v[196:199], v[34:37]
	v_mfma_f32_16x16x32_bf16 v[22:25], v[156:159], v[204:207], v[22:25]
	v_mfma_f32_16x16x32_bf16 v[18:21], v[164:167], v[204:207], v[18:21]
	v_mfma_f32_16x16x32_bf16 v[6:9], v[156:159], v[212:215], v[6:9]
	v_mfma_f32_16x16x32_bf16 v[2:5], v[164:167], v[212:215], v[2:5]
	v_mfma_f32_16x16x32_bf16 v[74:77], v[160:163], v[182:185], v[74:77]
	v_mfma_f32_16x16x32_bf16 v[62:65], v[168:171], v[182:185], v[62:65]
	v_mfma_f32_16x16x32_bf16 v[38:41], v[160:163], v[200:203], v[38:41]
	v_mfma_f32_16x16x32_bf16 v[34:37], v[168:171], v[200:203], v[34:37]
	v_mfma_f32_16x16x32_bf16 v[22:25], v[160:163], v[208:211], v[22:25]
	v_mfma_f32_16x16x32_bf16 v[18:21], v[168:171], v[208:211], v[18:21]
	v_mfma_f32_16x16x32_bf16 v[6:9], v[160:163], v[216:219], v[6:9]
	v_mfma_f32_16x16x32_bf16 v[2:5], v[168:171], v[216:219], v[2:5]
	s_setprio 0
	s_barrier
; #define PG8_STAGE(bufoff, gbase, voff) do { _Pragma("unroll") for (int _i = 0; _i < 2; ++_i) \
;         __builtin_amdgcn_global_load_lds((const unsigned*)((const char*)(gbase) + (voff)[_i]), (PG8_LAS unsigned*)(lds + (bufoff) + ldsw + _i * 8192), 16, 0, 0); } while (0)
; #define PG8_LDA(dst, b, h) do { _Pragma("unroll") for (int m = 0; m < 4; ++m) _Pragma("unroll") for (int k = 0; k < 2; ++k) dst[m][k] = *(const PG8_LAS bf16x8*)(lds + PG8_SA(b, h) + aoff + m * 2048 + k * 1024); } while (0)
; #define PG8_LDB(dst, b, h) do { _Pragma("unroll") for (int n = 0; n < 2; ++n) _Pragma("unroll") for (int k = 0; k < 2; ++k) dst[n][k] = *(const PG8_LAS bf16x8*)(lds + PG8_SB(b, h) + boff + n * 2048 + k * 1024); } while (0)
; #define PG8_MMA(ai, bj, At, Bt) do { __builtin_amdgcn_s_setprio(1); _Pragma("unroll") for (int m = 0; m < 4; ++m) _Pragma("unroll") for (int n = 0; n < 2; ++n) _Pragma("unroll") for (int k = 0; k < 2; ++k) \
;         acc[ai][bj][m][n] = __builtin_amdgcn_mfma_f32_16x16x32_bf16(Bt[n][k], At[m][k], acc[ai][bj][m][n], 0, 0, 0); __builtin_amdgcn_s_setprio(0); } while (0)
; #define PG8_WAIT_V(n) asm volatile("s_waitcnt vmcnt(" #n ")" ::: "memory")
; #define PG8_WAIT_L(n) asm volatile("s_waitcnt lgkmcnt(" #n ")" ::: "memory")
; #define PG8_BAR __builtin_amdgcn_s_barrier()
; #define PG8_SCHED __builtin_amdgcn_sched_barrier(0)
; template <class Epi, class Sched, bool ALIGN_EPI = false, bool SP2 = false, bool ABLK = false, bool BBLK = false>
; __device__ __forceinline__ void gemm_phase(PG8_LAS unsigned char* lds, const Gemm g, const Sched& S, const Epi& E) {
;     ...
;             PG8_LDB(B0, 1, 0); PG8_LDB(B1, 1, 1); PG8_SCHED; PG8_LDA(At, 1, 0); PG8_STAGE(PG8_SA(0, 1), a2 + hstepA, voffA);
;             PG8_WAIT_V(8); PG8_WAIT_L(0); PG8_BAR; PG8_MMA(0, 0, At, B0); PG8_MMA(0, 1, At, B1); PG8_BAR; PG8_SCHED;
	s_add_i32 s52, 0, 0x18000
	s_add_i32 s75, 0, 0x1c000
	v_add_u32_e32 v142, s52, v180
	v_add_u32_e32 v168, s75, v180
	ds_read_b128 v[130:133], v142
	ds_read_b128 v[134:137], v142 offset:1024
	ds_read_b128 v[138:141], v142 offset:2048
	ds_read_b128 v[142:145], v142 offset:3072
	ds_read_b128 v[156:159], v168
	ds_read_b128 v[160:163], v168 offset:1024
	ds_read_b128 v[164:167], v168 offset:2048
	ds_read_b128 v[168:171], v168 offset:3072
	s_add_u32 s28, s28, 0x4000
	s_addc_u32 s29, s29, 0
	s_mov_b32 m0, s30
	v_lshl_add_u64 v[176:177], s[28:29], 0, v[146:147]
	ds_read_b128 v[172:175], v181 offset:32768
	ds_read_b128 v[182:185], v181 offset:33792
	ds_read_b128 v[196:199], v181 offset:34816
	ds_read_b128 v[200:203], v181 offset:35840
	ds_read_b128 v[204:207], v181 offset:36864
	ds_read_b128 v[208:211], v181 offset:37888
	ds_read_b128 v[212:215], v181 offset:38912
	ds_read_b128 v[216:219], v181 offset:39936
	global_load_lds_dwordx4 v[176:177], off
	v_lshl_add_u64 v[176:177], s[28:29], 0, v[148:149]
	s_mov_b32 m0, s31
	s_nop 0
	global_load_lds_dwordx4 v[176:177], off
	s_waitcnt vmcnt(8)
	s_waitcnt lgkmcnt(0)
	s_barrier
	s_setprio 1
	s_waitcnt lgkmcnt(0)
	v_mfma_f32_16x16x32_bf16 v[58:61], v[130:133], v[172:175], v[58:61]
	v_mfma_f32_16x16x32_bf16 v[50:53], v[138:141], v[172:175], v[50:53]
	v_mfma_f32_16x16x32_bf16 v[78:81], v[130:133], v[196:199], v[78:81]
	v_mfma_f32_16x16x32_bf16 v[70:73], v[138:141], v[196:199], v[70:73]
	v_mfma_f32_16x16x32_bf16 v[98:101], v[130:133], v[204:207], v[98:101]
	v_mfma_f32_16x16x32_bf16 v[102:105], v[138:141], v[204:207], v[102:105]
	v_mfma_f32_16x16x32_bf16 v[114:117], v[130:133], v[212:215], v[114:117]
	v_mfma_f32_16x16x32_bf16 v[118:121], v[138:141], v[212:215], v[118:121]
	v_mfma_f32_16x16x32_bf16 v[58:61], v[134:137], v[182:185], v[58:61]
	v_mfma_f32_16x16x32_bf16 v[50:53], v[142:145], v[182:185], v[50:53]
	v_mfma_f32_16x16x32_bf16 v[78:81], v[134:137], v[200:203], v[78:81]
	v_mfma_f32_16x16x32_bf16 v[70:73], v[142:145], v[200:203], v[70:73]
	v_mfma_f32_16x16x32_bf16 v[98:101], v[134:137], v[208:211], v[98:101]
	v_mfma_f32_16x16x32_bf16 v[102:105], v[142:145], v[208:211], v[102:105]
	v_mfma_f32_16x16x32_bf16 v[114:117], v[134:137], v[216:219], v[114:117]
	v_mfma_f32_16x16x32_bf16 v[118:121], v[142:145], v[216:219], v[118:121]
	s_setprio 0
	s_setprio 1
	v_mfma_f32_16x16x32_bf16 v[66:69], v[156:159], v[172:175], v[66:69]
	v_mfma_f32_16x16x32_bf16 v[54:57], v[164:167], v[172:175], v[54:57]
	v_mfma_f32_16x16x32_bf16 v[86:89], v[156:159], v[196:199], v[86:89]
	v_mfma_f32_16x16x32_bf16 v[94:97], v[164:167], v[196:199], v[94:97]
	v_mfma_f32_16x16x32_bf16 v[106:109], v[156:159], v[204:207], v[106:109]
	v_mfma_f32_16x16x32_bf16 v[110:113], v[164:167], v[204:207], v[110:113]
	v_mfma_f32_16x16x32_bf16 v[122:125], v[156:159], v[212:215], v[122:125]
	v_mfma_f32_16x16x32_bf16 v[126:129], v[164:167], v[212:215], v[126:129]
	v_mfma_f32_16x16x32_bf16 v[66:69], v[160:163], v[182:185], v[66:69]
	v_mfma_f32_16x16x32_bf16 v[54:57], v[168:171], v[182:185], v[54:57]
	v_mfma_f32_16x16x32_bf16 v[86:89], v[160:163], v[200:203], v[86:89]
	v_mfma_f32_16x16x32_bf16 v[94:97], v[168:171], v[200:203], v[94:97]
	v_mfma_f32_16x16x32_bf16 v[106:109], v[160:163], v[208:211], v[106:109]
	v_mfma_f32_16x16x32_bf16 v[110:113], v[168:171], v[208:211], v[110:113]
	v_mfma_f32_16x16x32_bf16 v[122:125], v[160:163], v[216:219], v[122:125]
	v_mfma_f32_16x16x32_bf16 v[126:129], v[168:171], v[216:219], v[126:129]
	s_setprio 0
	s_barrier
; #define PG8_STAGE(bufoff, gbase, voff) do { _Pragma("unroll") for (int _i = 0; _i < 2; ++_i) \
;         __builtin_amdgcn_global_load_lds((const unsigned*)((const char*)(gbase) + (voff)[_i]), (PG8_LAS unsigned*)(lds + (bufoff) + ldsw + _i * 8192), 16, 0, 0); } while (0)
; #define PG8_LDA(dst, b, h) do { _Pragma("unroll") for (int m = 0; m < 4; ++m) _Pragma("unroll") for (int k = 0; k < 2; ++k) dst[m][k] = *(const PG8_LAS bf16x8*)(lds + PG8_SA(b, h) + aoff + m * 2048 + k * 1024); } while (0)
; #define PG8_MMA(ai, bj, At, Bt) do { __builtin_amdgcn_s_setprio(1); _Pragma("unroll") for (int m = 0; m < 4; ++m) _Pragma("unroll") for (int n = 0; n < 2; ++n) _Pragma("unroll") for (int k = 0; k < 2; ++k) \
;         acc[ai][bj][m][n] = __builtin_amdgcn_mfma_f32_16x16x32_bf16(Bt[n][k], At[m][k], acc[ai][bj][m][n], 0, 0, 0); __builtin_amdgcn_s_setprio(0); } while (0)
; #define PG8_WAIT_V(n) asm volatile("s_waitcnt vmcnt(" #n ")" ::: "memory")
; #define PG8_WAIT_L(n) asm volatile("s_waitcnt lgkmcnt(" #n ")" ::: "memory")
; #define PG8_BAR __builtin_amdgcn_s_barrier()
; #define PG8_SCHED __builtin_amdgcn_sched_barrier(0)
; template <class Epi, class Sched, bool ALIGN_EPI = false, bool SP2 = false, bool ABLK = false, bool BBLK = false>
; __device__ __forceinline__ void gemm_phase(PG8_LAS unsigned char* lds, const Gemm g, const Sched& S, const Epi& E) {
;     ...
;             PG8_LDA(At, 1, 1); PG8_STAGE(PG8_SB(1, 0), b3, voffB); PG8_STAGE(PG8_SB(1, 1), b3 + hstepB, voffB); PG8_STAGE(PG8_SA(1, 0), a3, voffA);
;             PG8_WAIT_V(8); PG8_WAIT_L(0); PG8_BAR; PG8_MMA(1, 0, At, B0); PG8_MMA(1, 1, At, B1); PG8_BAR; PG8_SCHED;
;     ...
;         if constexpr (ALIGN_EPI) { if (wr == 0) PG8_BAR; }
	s_add_u32 s28, s26, 0x8000
	s_addc_u32 s29, s27, 0
	s_add_i32 s52, s52, s2
	v_lshl_add_u64 v[176:177], s[28:29], 0, v[186:187]
	s_mov_b32 m0, s52
	ds_read_b128 v[172:175], v181 offset:49152
	ds_read_b128 v[182:185], v181 offset:50176
	ds_read_b128 v[196:199], v181 offset:51200
	ds_read_b128 v[200:203], v181 offset:52224
	ds_read_b128 v[204:207], v181 offset:53248
	ds_read_b128 v[208:211], v181 offset:54272
	ds_read_b128 v[212:215], v181 offset:55296
	ds_read_b128 v[216:219], v181 offset:56320
	global_load_lds_dwordx4 v[176:177], off
	s_add_i32 m0, s52, 0x2000
	s_add_u32 s26, s26, 0xc000
	v_lshl_add_u64 v[176:177], s[28:29], 0, v[150:151]
	s_addc_u32 s27, s27, 0
	s_add_i32 s28, s75, s2
	global_load_lds_dwordx4 v[176:177], off
	v_lshl_add_u64 v[176:177], s[26:27], 0, v[186:187]
	s_mov_b32 m0, s28
	s_nop 0
	global_load_lds_dwordx4 v[176:177], off
	v_lshl_add_u64 v[176:177], s[26:27], 0, v[150:151]
	s_add_i32 m0, s28, 0x2000
	s_nop 0
	global_load_lds_dwordx4 v[176:177], off
	v_lshl_add_u64 v[176:177], s[8:9], 0, v[146:147]
	s_mov_b32 m0, s45
	s_nop 0
	global_load_lds_dwordx4 v[176:177], off
	v_lshl_add_u64 v[176:177], s[8:9], 0, v[148:149]
	s_mov_b32 m0, s46
	s_nop 0
	global_load_lds_dwordx4 v[176:177], off
	s_waitcnt vmcnt(8)
	s_waitcnt lgkmcnt(0)
	s_barrier
	s_setprio 1
	s_waitcnt lgkmcnt(0)
	v_mfma_f32_16x16x32_bf16 v[90:93], v[130:133], v[172:175], v[90:93]
	v_mfma_f32_16x16x32_bf16 v[82:85], v[138:141], v[172:175], v[82:85]
	v_mfma_f32_16x16x32_bf16 v[46:49], v[130:133], v[196:199], v[46:49]
	v_mfma_f32_16x16x32_bf16 v[42:45], v[138:141], v[196:199], v[42:45]
	v_mfma_f32_16x16x32_bf16 v[30:33], v[130:133], v[204:207], v[30:33]
	v_mfma_f32_16x16x32_bf16 v[26:29], v[138:141], v[204:207], v[26:29]
	v_mfma_f32_16x16x32_bf16 v[14:17], v[130:133], v[212:215], v[14:17]
	v_mfma_f32_16x16x32_bf16 v[10:13], v[138:141], v[212:215], v[10:13]
	v_mfma_f32_16x16x32_bf16 v[90:93], v[134:137], v[182:185], v[90:93]
	v_mfma_f32_16x16x32_bf16 v[82:85], v[142:145], v[182:185], v[82:85]
	v_mfma_f32_16x16x32_bf16 v[46:49], v[134:137], v[200:203], v[46:49]
	v_mfma_f32_16x16x32_bf16 v[42:45], v[142:145], v[200:203], v[42:45]
	v_mfma_f32_16x16x32_bf16 v[30:33], v[134:137], v[208:211], v[30:33]
	v_mfma_f32_16x16x32_bf16 v[26:29], v[142:145], v[208:211], v[26:29]
	v_mfma_f32_16x16x32_bf16 v[14:17], v[134:137], v[216:219], v[14:17]
	v_mfma_f32_16x16x32_bf16 v[10:13], v[142:145], v[216:219], v[10:13]
	s_setprio 0
	s_setprio 1
	v_mfma_f32_16x16x32_bf16 v[74:77], v[156:159], v[172:175], v[74:77]
	v_mfma_f32_16x16x32_bf16 v[62:65], v[164:167], v[172:175], v[62:65]
	v_mfma_f32_16x16x32_bf16 v[38:41], v[156:159], v[196:199], v[38:41]
	v_mfma_f32_16x16x32_bf16 v[34:37], v[164:167], v[196:199], v[34:37]
	v_mfma_f32_16x16x32_bf16 v[22:25], v[156:159], v[204:207], v[22:25]
	v_mfma_f32_16x16x32_bf16 v[18:21], v[164:167], v[204:207], v[18:21]
	v_mfma_f32_16x16x32_bf16 v[6:9], v[156:159], v[212:215], v[6:9]
	v_mfma_f32_16x16x32_bf16 v[2:5], v[164:167], v[212:215], v[2:5]
	v_mfma_f32_16x16x32_bf16 v[74:77], v[160:163], v[182:185], v[74:77]
	v_mfma_f32_16x16x32_bf16 v[62:65], v[168:171], v[182:185], v[62:65]
	v_mfma_f32_16x16x32_bf16 v[38:41], v[160:163], v[200:203], v[38:41]
	v_mfma_f32_16x16x32_bf16 v[34:37], v[168:171], v[200:203], v[34:37]
	v_mfma_f32_16x16x32_bf16 v[22:25], v[160:163], v[208:211], v[22:25]
	v_mfma_f32_16x16x32_bf16 v[18:21], v[168:171], v[208:211], v[18:21]
	v_mfma_f32_16x16x32_bf16 v[6:9], v[160:163], v[216:219], v[6:9]
	v_mfma_f32_16x16x32_bf16 v[2:5], v[168:171], v[216:219], v[2:5]
	s_setprio 0
	s_barrier
	s_add_i32 s73, s73, 2
	s_add_u32 s0, s0, 0x10000
	s_addc_u32 s1, s1, 0
	s_add_u32 s23, s23, 0x10000
	s_addc_u32 s25, s25, 0
	s_cmpk_gt_u32 s73, 0x55
	s_cbranch_scc0 .LBB0_1420
	s_and_b64 vcc, exec, s[14:15]
	s_cbranch_vccz .LBB0_1423
	s_barrier

; #define PG8_STAGE(bufoff, gbase, voff) do { _Pragma("unroll") for (int _i = 0; _i < 2; ++_i) \
;         __builtin_amdgcn_global_load_lds((const unsigned*)((const char*)(gbase) + (voff)[_i]), (PG8_LAS unsigned*)(lds + (bufoff) + ldsw + _i * 8192), 16, 0, 0); } while (0)
; #define PG8_LDA(dst, b, h) do { _Pragma("unroll") for (int m = 0; m < 4; ++m) _Pragma("unroll") for (int k = 0; k < 2; ++k) dst[m][k] = *(const PG8_LAS bf16x8*)(lds + PG8_SA(b, h) + aoff + m * 2048 + k * 1024); } while (0)
; #define PG8_LDB(dst, b, h) do { _Pragma("unroll") for (int n = 0; n < 2; ++n) _Pragma("unroll") for (int k = 0; k < 2; ++k) dst[n][k] = *(const PG8_LAS bf16x8*)(lds + PG8_SB(b, h) + boff + n * 2048 + k * 1024); } while (0)
; #define PG8_BAR __builtin_amdgcn_s_barrier()
; #define PG8_SCHED __builtin_amdgcn_sched_barrier(0)
; template <class Epi, class Sched, bool ALIGN_EPI = false, bool SP2 = false, bool ABLK = false, bool BBLK = false>
; __device__ __forceinline__ void gemm_phase(PG8_LAS unsigned char* lds, const Gemm g, const Sched& S, const Epi& E) {
;     ...
;         const bool has_next = S.next(ui + 1, nxt);
;         const char* nA = has_next ? (const char*)g.A + (size_t)nxt.pm * tstepA : cA; const char* nB = has_next ? (const char*)g.Bt + (size_t)nxt.pn * tstepB : cB;
;         for (int t = 0; t < nt; t += 2) {
;             const bool last = (t == nt - 2);
;             const char* a1 = cA + (size_t)(t + 1) * kstepA;
;             const char* a2 = last ? nA : cA + (size_t)(t + 2) * kstepA; const char* b2 = last ? nB : cB + (size_t)(t + 2) * kstepB;
;             const char* a3 = a2 + kstepA; const char* b3 = b2 + kstepB;
;             if (last && has_next) S.a_ready(nxt);
;             if constexpr (SP2) {
;             PG8_LDB(B0, 0, 0); PG8_LDB(B1, 0, 1); PG8_SCHED; PG8_LDA(At, 0, 0); PG8_STAGE(PG8_SA(1, 1), a1 + hstepA, voffA);
;     ...
; #pragma unroll
;         for (int a = 0; a < 2; ++a)
; #pragma unroll
;             for (int b = 0; b < 2; ++b)
; #pragma unroll
;                 for (int m = 0; m < 4; ++m)
; #pragma unroll
;                     for (int n = 0; n < 2; ++n) acc[a][b][m][n] = (f32x4){0.f, 0.f, 0.f, 0.f};
;         cur = nxt; cA = nA; cB = nB; ++ui;
;         if constexpr (ALIGN_EPI) { if (wr == 1) PG8_BAR; }
.LBB0_1482:
	s_add_u32 s0, s0, 0xc000
	s_addc_u32 s1, s1, 0
	s_add_u32 s31, s36, 0x10000
	v_mov_b32_e32 v2, 0
	s_addc_u32 s33, s37, 0
	s_mov_b32 s35, -2
	s_add_u32 s8, s0, 0x4000
	s_addc_u32 s9, s1, 0
	s_cmpk_eq_i32 s35, 0x54
	s_cselect_b32 s40, s26, s8
	s_cselect_b32 s41, s27, s9
	s_cselect_b32 s36, s28, s31
	s_cselect_b32 s37, s29, s33
	s_add_u32 s8, s40, 0x8000
	s_addc_u32 s9, s41, 0
	s_add_i32 s44, 0, 0x10000
	s_add_i32 s52, 0, 0x14000
	v_add_u32_e32 v142, s44, v206
	v_add_u32_e32 v158, s52, v206
	ds_read_b128 v[130:133], v142
	v_pk_mov_b32 v[2:3], 0, 0
	v_pk_mov_b32 v[4:5], 0, 0
	v_pk_mov_b32 v[6:7], 0, 0
	v_pk_mov_b32 v[8:9], 0, 0
	ds_read_b128 v[134:137], v142 offset:1024
	v_pk_mov_b32 v[10:11], 0, 0
	v_pk_mov_b32 v[12:13], 0, 0
	v_pk_mov_b32 v[14:15], 0, 0
	v_pk_mov_b32 v[16:17], 0, 0
	ds_read_b128 v[138:141], v142 offset:2048
	v_pk_mov_b32 v[18:19], 0, 0
	v_pk_mov_b32 v[20:21], 0, 0
	v_pk_mov_b32 v[22:23], 0, 0
	v_pk_mov_b32 v[24:25], 0, 0
	ds_read_b128 v[142:145], v142 offset:3072
	v_pk_mov_b32 v[26:27], 0, 0
	v_pk_mov_b32 v[28:29], 0, 0
	v_pk_mov_b32 v[30:31], 0, 0
	v_pk_mov_b32 v[32:33], 0, 0
	ds_read_b128 v[146:149], v158
	v_pk_mov_b32 v[34:35], 0, 0
	v_pk_mov_b32 v[36:37], 0, 0
	v_pk_mov_b32 v[38:39], 0, 0
	v_pk_mov_b32 v[40:41], 0, 0
	ds_read_b128 v[150:153], v158 offset:1024
	v_pk_mov_b32 v[42:43], 0, 0
	v_pk_mov_b32 v[44:45], 0, 0
	v_pk_mov_b32 v[46:47], 0, 0
	v_pk_mov_b32 v[48:49], 0, 0
	ds_read_b128 v[154:157], v158 offset:2048
	v_pk_mov_b32 v[50:51], 0, 0
	v_pk_mov_b32 v[52:53], 0, 0
	v_pk_mov_b32 v[54:55], 0, 0
	v_pk_mov_b32 v[56:57], 0, 0
	ds_read_b128 v[158:161], v158 offset:3072
	v_pk_mov_b32 v[58:59], 0, 0
	v_pk_mov_b32 v[60:61], 0, 0
	v_pk_mov_b32 v[62:63], 0, 0
	v_pk_mov_b32 v[64:65], 0, 0
	v_lshl_add_u64 v[188:189], s[0:1], 0, v[184:185]
	s_add_i32 m0, s68, 0xc000
	ds_read_b128 v[162:165], v207
	v_pk_mov_b32 v[66:67], 0, 0
	v_pk_mov_b32 v[68:69], 0, 0
	v_pk_mov_b32 v[70:71], 0, 0
	v_pk_mov_b32 v[72:73], 0, 0
	ds_read_b128 v[166:169], v207 offset:1024
	v_pk_mov_b32 v[74:75], 0, 0
	v_pk_mov_b32 v[76:77], 0, 0
	v_pk_mov_b32 v[78:79], 0, 0
	v_pk_mov_b32 v[80:81], 0, 0
	ds_read_b128 v[170:173], v207 offset:2048
	v_pk_mov_b32 v[82:83], 0, 0
	v_pk_mov_b32 v[84:85], 0, 0
	v_pk_mov_b32 v[86:87], 0, 0
	v_pk_mov_b32 v[88:89], 0, 0
	ds_read_b128 v[174:177], v207 offset:3072
	v_pk_mov_b32 v[90:91], 0, 0
	v_pk_mov_b32 v[92:93], 0, 0
	v_pk_mov_b32 v[94:95], 0, 0
	v_pk_mov_b32 v[96:97], 0, 0
	ds_read_b128 v[198:201], v207 offset:4096
	v_pk_mov_b32 v[98:99], 0, 0
	v_pk_mov_b32 v[100:101], 0, 0
	v_pk_mov_b32 v[102:103], 0, 0
	v_pk_mov_b32 v[104:105], 0, 0
	ds_read_b128 v[208:211], v207 offset:5120
	v_pk_mov_b32 v[106:107], 0, 0
	v_pk_mov_b32 v[108:109], 0, 0
	v_pk_mov_b32 v[110:111], 0, 0
	v_pk_mov_b32 v[112:113], 0, 0
	ds_read_b128 v[212:215], v207 offset:6144
	v_pk_mov_b32 v[114:115], 0, 0
	v_pk_mov_b32 v[116:117], 0, 0
	v_pk_mov_b32 v[118:119], 0, 0
	v_pk_mov_b32 v[120:121], 0, 0
	ds_read_b128 v[216:219], v207 offset:7168
	v_pk_mov_b32 v[122:123], 0, 0
	v_pk_mov_b32 v[124:125], 0, 0
	v_pk_mov_b32 v[126:127], 0, 0
	v_pk_mov_b32 v[128:129], 0, 0
	global_load_lds_dwordx4 v[188:189], off
	v_lshl_add_u64 v[188:189], s[0:1], 0, v[196:197]
	s_add_i32 m0, s68, 0xe000
	s_nop 0
	global_load_lds_dwordx4 v[188:189], off
	s_waitcnt vmcnt(8)
	s_waitcnt lgkmcnt(0)
	s_barrier
	s_branch .Lpeel_1483

; #define PG8_STAGE(bufoff, gbase, voff) do { _Pragma("unroll") for (int _i = 0; _i < 2; ++_i) \
;         __builtin_amdgcn_global_load_lds((const unsigned*)((const char*)(gbase) + (voff)[_i]), (PG8_LAS unsigned*)(lds + (bufoff) + ldsw + _i * 8192), 16, 0, 0); } while (0)
; #define PG8_LDA(dst, b, h) do { _Pragma("unroll") for (int m = 0; m < 4; ++m) _Pragma("unroll") for (int k = 0; k < 2; ++k) dst[m][k] = *(const PG8_LAS bf16x8*)(lds + PG8_SA(b, h) + aoff + m * 2048 + k * 1024); } while (0)
; #define PG8_MMA(ai, bj, At, Bt) do { __builtin_amdgcn_s_setprio(1); _Pragma("unroll") for (int m = 0; m < 4; ++m) _Pragma("unroll") for (int n = 0; n < 2; ++n) _Pragma("unroll") for (int k = 0; k < 2; ++k) \
;         acc[ai][bj][m][n] = __builtin_amdgcn_mfma_f32_16x16x32_bf16(Bt[n][k], At[m][k], acc[ai][bj][m][n], 0, 0, 0); __builtin_amdgcn_s_setprio(0); } while (0)
; #define PG8_WAIT_V(n) asm volatile("s_waitcnt vmcnt(" #n ")" ::: "memory")
; #define PG8_WAIT_L(n) asm volatile("s_waitcnt lgkmcnt(" #n ")" ::: "memory")
; #define PG8_BAR __builtin_amdgcn_s_barrier()
; #define PG8_SCHED __builtin_amdgcn_sched_barrier(0)
; template <class Epi, class Sched, bool ALIGN_EPI = false, bool SP2 = false, bool ABLK = false, bool BBLK = false>
; __device__ __forceinline__ void gemm_phase(PG8_LAS unsigned char* lds, const Gemm g, const Sched& S, const Epi& E) {
;     ...
;             PG8_WAIT_V(8); PG8_WAIT_L(0); PG8_BAR; PG8_MMA(0, 0, At, B0); PG8_MMA(0, 1, At, B1); PG8_BAR; PG8_SCHED;
;             PG8_LDA(At, 0, 1); PG8_STAGE(PG8_SB(0, 0), b2, voffB); PG8_STAGE(PG8_SB(0, 1), b2 + hstepB, voffB); PG8_STAGE(PG8_SA(0, 0), a2, voffA);
;             PG8_WAIT_V(8); PG8_WAIT_L(0); PG8_BAR; PG8_MMA(1, 0, At, B0); PG8_MMA(1, 1, At, B1); PG8_BAR; PG8_SCHED;
.Lpeel_1483:
	s_setprio 1
	s_waitcnt lgkmcnt(0)
	v_mfma_f32_16x16x32_bf16 v[30:33], v[130:133], v[162:165], v[30:33]
	v_mfma_f32_16x16x32_bf16 v[22:25], v[138:141], v[162:165], v[22:25]
	v_mfma_f32_16x16x32_bf16 v[18:21], v[130:133], v[170:173], v[18:21]
	v_mfma_f32_16x16x32_bf16 v[10:13], v[138:141], v[170:173], v[10:13]
	v_mfma_f32_16x16x32_bf16 v[50:53], v[130:133], v[198:201], v[50:53]
	v_mfma_f32_16x16x32_bf16 v[54:57], v[138:141], v[198:201], v[54:57]
	v_mfma_f32_16x16x32_bf16 v[74:77], v[130:133], v[212:215], v[74:77]
	v_mfma_f32_16x16x32_bf16 v[78:81], v[138:141], v[212:215], v[78:81]
	v_mfma_f32_16x16x32_bf16 v[30:33], v[134:137], v[166:169], v[30:33]
	v_mfma_f32_16x16x32_bf16 v[22:25], v[142:145], v[166:169], v[22:25]
	v_mfma_f32_16x16x32_bf16 v[18:21], v[134:137], v[174:177], v[18:21]
	v_mfma_f32_16x16x32_bf16 v[10:13], v[142:145], v[174:177], v[10:13]
	v_mfma_f32_16x16x32_bf16 v[50:53], v[134:137], v[208:211], v[50:53]
	v_mfma_f32_16x16x32_bf16 v[54:57], v[142:145], v[208:211], v[54:57]
	v_mfma_f32_16x16x32_bf16 v[74:77], v[134:137], v[216:219], v[74:77]
	v_mfma_f32_16x16x32_bf16 v[78:81], v[142:145], v[216:219], v[78:81]
	s_setprio 0
	s_setprio 1
	v_mfma_f32_16x16x32_bf16 v[26:29], v[146:149], v[162:165], v[26:29]
	v_mfma_f32_16x16x32_bf16 v[14:17], v[154:157], v[162:165], v[14:17]
	v_mfma_f32_16x16x32_bf16 v[42:45], v[146:149], v[170:173], v[42:45]
	v_mfma_f32_16x16x32_bf16 v[46:49], v[154:157], v[170:173], v[46:49]
	v_mfma_f32_16x16x32_bf16 v[66:69], v[146:149], v[198:201], v[66:69]
	v_mfma_f32_16x16x32_bf16 v[70:73], v[154:157], v[198:201], v[70:73]
	v_mfma_f32_16x16x32_bf16 v[82:85], v[146:149], v[212:215], v[82:85]
	v_mfma_f32_16x16x32_bf16 v[86:89], v[154:157], v[212:215], v[86:89]
	v_mfma_f32_16x16x32_bf16 v[26:29], v[150:153], v[166:169], v[26:29]
	v_mfma_f32_16x16x32_bf16 v[14:17], v[158:161], v[166:169], v[14:17]
	v_mfma_f32_16x16x32_bf16 v[42:45], v[150:153], v[174:177], v[42:45]
	v_mfma_f32_16x16x32_bf16 v[46:49], v[158:161], v[174:177], v[46:49]
	v_mfma_f32_16x16x32_bf16 v[66:69], v[150:153], v[208:211], v[66:69]
	v_mfma_f32_16x16x32_bf16 v[70:73], v[158:161], v[208:211], v[70:73]
	v_mfma_f32_16x16x32_bf16 v[82:85], v[150:153], v[216:219], v[82:85]
	v_mfma_f32_16x16x32_bf16 v[86:89], v[158:161], v[216:219], v[86:89]
	s_setprio 0
	s_barrier
	s_add_i32 s44, s44, s65
	v_lshl_add_u64 v[188:189], s[36:37], 0, v[186:187]
	s_mov_b32 m0, s44
	ds_read_b128 v[162:165], v207 offset:16384
	ds_read_b128 v[166:169], v207 offset:17408
	ds_read_b128 v[170:173], v207 offset:18432
	ds_read_b128 v[174:177], v207 offset:19456
	ds_read_b128 v[198:201], v207 offset:20480
	ds_read_b128 v[208:211], v207 offset:21504
	ds_read_b128 v[212:215], v207 offset:22528
	ds_read_b128 v[216:219], v207 offset:23552
	global_load_lds_dwordx4 v[188:189], off
	s_add_i32 m0, s44, 0x2000
	s_add_u32 s44, s36, 0x4000
	v_lshl_add_u64 v[188:189], s[36:37], 0, v[182:183]
	s_addc_u32 s45, s37, 0
	s_add_i32 s52, s52, s65
	global_load_lds_dwordx4 v[188:189], off
	v_lshl_add_u64 v[188:189], s[44:45], 0, v[186:187]
	s_mov_b32 m0, s52
	s_nop 0
	global_load_lds_dwordx4 v[188:189], off
	v_lshl_add_u64 v[188:189], s[44:45], 0, v[182:183]
	s_add_i32 m0, s52, 0x2000
	s_nop 0
	global_load_lds_dwordx4 v[188:189], off
	v_lshl_add_u64 v[188:189], s[40:41], 0, v[178:179]
	s_mov_b32 m0, s68
	s_nop 0
	global_load_lds_dwordx4 v[188:189], off
	v_lshl_add_u64 v[188:189], s[40:41], 0, v[180:181]
	s_mov_b32 m0, s72
	s_nop 0
	global_load_lds_dwordx4 v[188:189], off
	s_waitcnt vmcnt(8)
	s_waitcnt lgkmcnt(0)
	s_barrier
	s_setprio 1
	s_waitcnt lgkmcnt(0)
	v_mfma_f32_16x16x32_bf16 v[106:109], v[130:133], v[162:165], v[106:109]
	v_mfma_f32_16x16x32_bf16 v[110:113], v[138:141], v[162:165], v[110:113]
	v_mfma_f32_16x16x32_bf16 v[122:125], v[130:133], v[170:173], v[122:125]
	v_mfma_f32_16x16x32_bf16 v[126:129], v[138:141], v[170:173], v[126:129]
	v_mfma_f32_16x16x32_bf16 v[94:97], v[130:133], v[198:201], v[94:97]
	v_mfma_f32_16x16x32_bf16 v[90:93], v[138:141], v[198:201], v[90:93]
	v_mfma_f32_16x16x32_bf16 v[38:41], v[130:133], v[212:215], v[38:41]
	v_mfma_f32_16x16x32_bf16 v[34:37], v[138:141], v[212:215], v[34:37]
	v_mfma_f32_16x16x32_bf16 v[106:109], v[134:137], v[166:169], v[106:109]
	v_mfma_f32_16x16x32_bf16 v[110:113], v[142:145], v[166:169], v[110:113]
	v_mfma_f32_16x16x32_bf16 v[122:125], v[134:137], v[174:177], v[122:125]
	v_mfma_f32_16x16x32_bf16 v[126:129], v[142:145], v[174:177], v[126:129]
	v_mfma_f32_16x16x32_bf16 v[94:97], v[134:137], v[208:211], v[94:97]
	v_mfma_f32_16x16x32_bf16 v[90:93], v[142:145], v[208:211], v[90:93]
	v_mfma_f32_16x16x32_bf16 v[38:41], v[134:137], v[216:219], v[38:41]
	v_mfma_f32_16x16x32_bf16 v[34:37], v[142:145], v[216:219], v[34:37]
	s_setprio 0
	s_setprio 1
	v_mfma_f32_16x16x32_bf16 v[114:117], v[146:149], v[162:165], v[114:117]
	v_mfma_f32_16x16x32_bf16 v[118:121], v[154:157], v[162:165], v[118:121]
	v_mfma_f32_16x16x32_bf16 v[102:105], v[146:149], v[170:173], v[102:105]
	v_mfma_f32_16x16x32_bf16 v[98:101], v[154:157], v[170:173], v[98:101]
	v_mfma_f32_16x16x32_bf16 v[62:65], v[146:149], v[198:201], v[62:65]
	v_mfma_f32_16x16x32_bf16 v[58:61], v[154:157], v[198:201], v[58:61]
	v_mfma_f32_16x16x32_bf16 v[6:9], v[146:149], v[212:215], v[6:9]
	v_mfma_f32_16x16x32_bf16 v[2:5], v[154:157], v[212:215], v[2:5]
	v_mfma_f32_16x16x32_bf16 v[114:117], v[150:153], v[166:169], v[114:117]
	v_mfma_f32_16x16x32_bf16 v[118:121], v[158:161], v[166:169], v[118:121]
	v_mfma_f32_16x16x32_bf16 v[102:105], v[150:153], v[174:177], v[102:105]
	v_mfma_f32_16x16x32_bf16 v[98:101], v[158:161], v[174:177], v[98:101]
	v_mfma_f32_16x16x32_bf16 v[62:65], v[150:153], v[208:211], v[62:65]
	v_mfma_f32_16x16x32_bf16 v[58:61], v[158:161], v[208:211], v[58:61]
	v_mfma_f32_16x16x32_bf16 v[6:9], v[150:153], v[216:219], v[6:9]
	v_mfma_f32_16x16x32_bf16 v[2:5], v[158:161], v[216:219], v[2:5]
	s_setprio 0
	s_barrier
; #define PG8_STAGE(bufoff, gbase, voff) do { _Pragma("unroll") for (int _i = 0; _i < 2; ++_i) \
;         __builtin_amdgcn_global_load_lds((const unsigned*)((const char*)(gbase) + (voff)[_i]), (PG8_LAS unsigned*)(lds + (bufoff) + ldsw + _i * 8192), 16, 0, 0); } while (0)
; #define PG8_LDA(dst, b, h) do { _Pragma("unroll") for (int m = 0; m < 4; ++m) _Pragma("unroll") for (int k = 0; k < 2; ++k) dst[m][k] = *(const PG8_LAS bf16x8*)(lds + PG8_SA(b, h) + aoff + m * 2048 + k * 1024); } while (0)
; #define PG8_LDB(dst, b, h) do { _Pragma("unroll") for (int n = 0; n < 2; ++n) _Pragma("unroll") for (int k = 0; k < 2; ++k) dst[n][k] = *(const PG8_LAS bf16x8*)(lds + PG8_SB(b, h) + boff + n * 2048 + k * 1024); } while (0)
; #define PG8_MMA(ai, bj, At, Bt) do { __builtin_amdgcn_s_setprio(1); _Pragma("unroll") for (int m = 0; m < 4; ++m) _Pragma("unroll") for (int n = 0; n < 2; ++n) _Pragma("unroll") for (int k = 0; k < 2; ++k) \
;         acc[ai][bj][m][n] = __builtin_amdgcn_mfma_f32_16x16x32_bf16(Bt[n][k], At[m][k], acc[ai][bj][m][n], 0, 0, 0); __builtin_amdgcn_s_setprio(0); } while (0)
; #define PG8_WAIT_V(n) asm volatile("s_waitcnt vmcnt(" #n ")" ::: "memory")
; #define PG8_WAIT_L(n) asm volatile("s_waitcnt lgkmcnt(" #n ")" ::: "memory")
; #define PG8_BAR __builtin_amdgcn_s_barrier()
; #define PG8_SCHED __builtin_amdgcn_sched_barrier(0)
; template <class Epi, class Sched, bool ALIGN_EPI = false, bool SP2 = false, bool ABLK = false, bool BBLK = false>
; __device__ __forceinline__ void gemm_phase(PG8_LAS unsigned char* lds, const Gemm g, const Sched& S, const Epi& E) {
;     ...
;             PG8_LDB(B0, 1, 0); PG8_LDB(B1, 1, 1); PG8_SCHED; PG8_LDA(At, 1, 0); PG8_STAGE(PG8_SA(0, 1), a2 + hstepA, voffA);
;             PG8_WAIT_V(8); PG8_WAIT_L(0); PG8_BAR; PG8_MMA(0, 0, At, B0); PG8_MMA(0, 1, At, B1); PG8_BAR; PG8_SCHED;
	s_add_i32 s44, 0, 0x18000
	s_add_i32 s45, 0, 0x1c000
	v_add_u32_e32 v142, s44, v206
	v_add_u32_e32 v158, s45, v206
	ds_read_b128 v[130:133], v142
	ds_read_b128 v[134:137], v142 offset:1024
	ds_read_b128 v[138:141], v142 offset:2048
	ds_read_b128 v[142:145], v142 offset:3072
	ds_read_b128 v[146:149], v158
	ds_read_b128 v[150:153], v158 offset:1024
	ds_read_b128 v[154:157], v158 offset:2048
	ds_read_b128 v[158:161], v158 offset:3072
	s_add_u32 s40, s40, 0x4000
	s_addc_u32 s41, s41, 0
	s_mov_b32 m0, s73
	v_lshl_add_u64 v[188:189], s[40:41], 0, v[178:179]
	ds_read_b128 v[162:165], v207 offset:32768
	ds_read_b128 v[166:169], v207 offset:33792
	ds_read_b128 v[170:173], v207 offset:34816
	ds_read_b128 v[174:177], v207 offset:35840
	ds_read_b128 v[198:201], v207 offset:36864
	ds_read_b128 v[208:211], v207 offset:37888
	ds_read_b128 v[212:215], v207 offset:38912
	ds_read_b128 v[216:219], v207 offset:39936
	global_load_lds_dwordx4 v[188:189], off
	v_lshl_add_u64 v[188:189], s[40:41], 0, v[180:181]
	s_mov_b32 m0, s84
	s_nop 0
	global_load_lds_dwordx4 v[188:189], off
	s_waitcnt vmcnt(8)
	s_waitcnt lgkmcnt(0)
	s_barrier
	s_setprio 1
	s_waitcnt lgkmcnt(0)
	v_mfma_f32_16x16x32_bf16 v[30:33], v[130:133], v[162:165], v[30:33]
	v_mfma_f32_16x16x32_bf16 v[22:25], v[138:141], v[162:165], v[22:25]
	v_mfma_f32_16x16x32_bf16 v[18:21], v[130:133], v[170:173], v[18:21]
	v_mfma_f32_16x16x32_bf16 v[10:13], v[138:141], v[170:173], v[10:13]
	v_mfma_f32_16x16x32_bf16 v[50:53], v[130:133], v[198:201], v[50:53]
	v_mfma_f32_16x16x32_bf16 v[54:57], v[138:141], v[198:201], v[54:57]
	v_mfma_f32_16x16x32_bf16 v[74:77], v[130:133], v[212:215], v[74:77]
	v_mfma_f32_16x16x32_bf16 v[78:81], v[138:141], v[212:215], v[78:81]
	v_mfma_f32_16x16x32_bf16 v[30:33], v[134:137], v[166:169], v[30:33]
	v_mfma_f32_16x16x32_bf16 v[22:25], v[142:145], v[166:169], v[22:25]
	v_mfma_f32_16x16x32_bf16 v[18:21], v[134:137], v[174:177], v[18:21]
	v_mfma_f32_16x16x32_bf16 v[10:13], v[142:145], v[174:177], v[10:13]
	v_mfma_f32_16x16x32_bf16 v[50:53], v[134:137], v[208:211], v[50:53]
	v_mfma_f32_16x16x32_bf16 v[54:57], v[142:145], v[208:211], v[54:57]
	v_mfma_f32_16x16x32_bf16 v[74:77], v[134:137], v[216:219], v[74:77]
	v_mfma_f32_16x16x32_bf16 v[78:81], v[142:145], v[216:219], v[78:81]
	s_setprio 0
	s_setprio 1
	v_mfma_f32_16x16x32_bf16 v[26:29], v[146:149], v[162:165], v[26:29]
	v_mfma_f32_16x16x32_bf16 v[14:17], v[154:157], v[162:165], v[14:17]
	v_mfma_f32_16x16x32_bf16 v[42:45], v[146:149], v[170:173], v[42:45]
	v_mfma_f32_16x16x32_bf16 v[46:49], v[154:157], v[170:173], v[46:49]
	v_mfma_f32_16x16x32_bf16 v[66:69], v[146:149], v[198:201], v[66:69]
	v_mfma_f32_16x16x32_bf16 v[70:73], v[154:157], v[198:201], v[70:73]
	v_mfma_f32_16x16x32_bf16 v[82:85], v[146:149], v[212:215], v[82:85]
	v_mfma_f32_16x16x32_bf16 v[86:89], v[154:157], v[212:215], v[86:89]
	v_mfma_f32_16x16x32_bf16 v[26:29], v[150:153], v[166:169], v[26:29]
	v_mfma_f32_16x16x32_bf16 v[14:17], v[158:161], v[166:169], v[14:17]
	v_mfma_f32_16x16x32_bf16 v[42:45], v[150:153], v[174:177], v[42:45]
	v_mfma_f32_16x16x32_bf16 v[46:49], v[158:161], v[174:177], v[46:49]
	v_mfma_f32_16x16x32_bf16 v[66:69], v[150:153], v[208:211], v[66:69]
	v_mfma_f32_16x16x32_bf16 v[70:73], v[158:161], v[208:211], v[70:73]
	v_mfma_f32_16x16x32_bf16 v[82:85], v[150:153], v[216:219], v[82:85]
	v_mfma_f32_16x16x32_bf16 v[86:89], v[158:161], v[216:219], v[86:89]
	s_setprio 0
	s_barrier
; #define PG8_STAGE(bufoff, gbase, voff) do { _Pragma("unroll") for (int _i = 0; _i < 2; ++_i) \
;         __builtin_amdgcn_global_load_lds((const unsigned*)((const char*)(gbase) + (voff)[_i]), (PG8_LAS unsigned*)(lds + (bufoff) + ldsw + _i * 8192), 16, 0, 0); } while (0)
; #define PG8_LDA(dst, b, h) do { _Pragma("unroll") for (int m = 0; m < 4; ++m) _Pragma("unroll") for (int k = 0; k < 2; ++k) dst[m][k] = *(const PG8_LAS bf16x8*)(lds + PG8_SA(b, h) + aoff + m * 2048 + k * 1024); } while (0)
; #define PG8_MMA(ai, bj, At, Bt) do { __builtin_amdgcn_s_setprio(1); _Pragma("unroll") for (int m = 0; m < 4; ++m) _Pragma("unroll") for (int n = 0; n < 2; ++n) _Pragma("unroll") for (int k = 0; k < 2; ++k) \
;         acc[ai][bj][m][n] = __builtin_amdgcn_mfma_f32_16x16x32_bf16(Bt[n][k], At[m][k], acc[ai][bj][m][n], 0, 0, 0); __builtin_amdgcn_s_setprio(0); } while (0)
; #define PG8_WAIT_V(n) asm volatile("s_waitcnt vmcnt(" #n ")" ::: "memory")
; #define PG8_WAIT_L(n) asm volatile("s_waitcnt lgkmcnt(" #n ")" ::: "memory")
; #define PG8_BAR __builtin_amdgcn_s_barrier()
; #define PG8_SCHED __builtin_amdgcn_sched_barrier(0)
; template <class Epi, class Sched, bool ALIGN_EPI = false, bool SP2 = false, bool ABLK = false, bool BBLK = false>
; __device__ __forceinline__ void gemm_phase(PG8_LAS unsigned char* lds, const Gemm g, const Sched& S, const Epi& E) {
;     ...
;             PG8_LDA(At, 1, 1); PG8_STAGE(PG8_SB(1, 0), b3, voffB); PG8_STAGE(PG8_SB(1, 1), b3 + hstepB, voffB); PG8_STAGE(PG8_SA(1, 0), a3, voffA);
;             PG8_WAIT_V(8); PG8_WAIT_L(0); PG8_BAR; PG8_MMA(1, 0, At, B0); PG8_MMA(1, 1, At, B1); PG8_BAR; PG8_SCHED;
;     ...
;         if constexpr (ALIGN_EPI) { if (wr == 0) PG8_BAR; }
	s_add_u32 s40, s36, 0x8000
	s_addc_u32 s41, s37, 0
	s_add_i32 s44, s44, s65
	v_lshl_add_u64 v[188:189], s[40:41], 0, v[186:187]
	s_mov_b32 m0, s44
	ds_read_b128 v[162:165], v207 offset:49152
	ds_read_b128 v[166:169], v207 offset:50176
	ds_read_b128 v[170:173], v207 offset:51200
	ds_read_b128 v[174:177], v207 offset:52224
	ds_read_b128 v[198:201], v207 offset:53248
	ds_read_b128 v[208:211], v207 offset:54272
	ds_read_b128 v[212:215], v207 offset:55296
	ds_read_b128 v[216:219], v207 offset:56320
	global_load_lds_dwordx4 v[188:189], off
	s_add_i32 m0, s44, 0x2000
	s_add_u32 s36, s36, 0xc000
	v_lshl_add_u64 v[188:189], s[40:41], 0, v[182:183]
	s_addc_u32 s37, s37, 0
	s_add_i32 s40, s45, s65
	global_load_lds_dwordx4 v[188:189], off
	v_lshl_add_u64 v[188:189], s[36:37], 0, v[186:187]
	s_mov_b32 m0, s40
	s_nop 0
	global_load_lds_dwordx4 v[188:189], off
	v_lshl_add_u64 v[188:189], s[36:37], 0, v[182:183]
	s_add_i32 m0, s40, 0x2000
	s_nop 0
	global_load_lds_dwordx4 v[188:189], off
	v_lshl_add_u64 v[188:189], s[8:9], 0, v[178:179]
	s_mov_b32 m0, s24
	s_nop 0
	global_load_lds_dwordx4 v[188:189], off
	v_lshl_add_u64 v[188:189], s[8:9], 0, v[180:181]
	s_mov_b32 m0, s25
	s_nop 0
	global_load_lds_dwordx4 v[188:189], off
	s_waitcnt vmcnt(8)
	s_waitcnt lgkmcnt(0)
	s_barrier
	s_setprio 1
	s_waitcnt lgkmcnt(0)
	v_mfma_f32_16x16x32_bf16 v[106:109], v[130:133], v[162:165], v[106:109]
	v_mfma_f32_16x16x32_bf16 v[110:113], v[138:141], v[162:165], v[110:113]
	v_mfma_f32_16x16x32_bf16 v[122:125], v[130:133], v[170:173], v[122:125]
	v_mfma_f32_16x16x32_bf16 v[126:129], v[138:141], v[170:173], v[126:129]
	v_mfma_f32_16x16x32_bf16 v[94:97], v[130:133], v[198:201], v[94:97]
	v_mfma_f32_16x16x32_bf16 v[90:93], v[138:141], v[198:201], v[90:93]
	v_mfma_f32_16x16x32_bf16 v[38:41], v[130:133], v[212:215], v[38:41]
	v_mfma_f32_16x16x32_bf16 v[34:37], v[138:141], v[212:215], v[34:37]
	v_mfma_f32_16x16x32_bf16 v[106:109], v[134:137], v[166:169], v[106:109]
	v_mfma_f32_16x16x32_bf16 v[110:113], v[142:145], v[166:169], v[110:113]
	v_mfma_f32_16x16x32_bf16 v[122:125], v[134:137], v[174:177], v[122:125]
	v_mfma_f32_16x16x32_bf16 v[126:129], v[142:145], v[174:177], v[126:129]
	v_mfma_f32_16x16x32_bf16 v[94:97], v[134:137], v[208:211], v[94:97]
	v_mfma_f32_16x16x32_bf16 v[90:93], v[142:145], v[208:211], v[90:93]
	v_mfma_f32_16x16x32_bf16 v[38:41], v[134:137], v[216:219], v[38:41]
	v_mfma_f32_16x16x32_bf16 v[34:37], v[142:145], v[216:219], v[34:37]
	s_setprio 0
	s_setprio 1
	v_mfma_f32_16x16x32_bf16 v[114:117], v[146:149], v[162:165], v[114:117]
	v_mfma_f32_16x16x32_bf16 v[118:121], v[154:157], v[162:165], v[118:121]
	v_mfma_f32_16x16x32_bf16 v[102:105], v[146:149], v[170:173], v[102:105]
	v_mfma_f32_16x16x32_bf16 v[98:101], v[154:157], v[170:173], v[98:101]
	v_mfma_f32_16x16x32_bf16 v[62:65], v[146:149], v[198:201], v[62:65]
	v_mfma_f32_16x16x32_bf16 v[58:61], v[154:157], v[198:201], v[58:61]
	v_mfma_f32_16x16x32_bf16 v[6:9], v[146:149], v[212:215], v[6:9]
	v_mfma_f32_16x16x32_bf16 v[2:5], v[154:157], v[212:215], v[2:5]
	v_mfma_f32_16x16x32_bf16 v[114:117], v[150:153], v[166:169], v[114:117]
	v_mfma_f32_16x16x32_bf16 v[118:121], v[158:161], v[166:169], v[118:121]
	v_mfma_f32_16x16x32_bf16 v[102:105], v[150:153], v[174:177], v[102:105]
	v_mfma_f32_16x16x32_bf16 v[98:101], v[158:161], v[174:177], v[98:101]
	v_mfma_f32_16x16x32_bf16 v[62:65], v[150:153], v[208:211], v[62:65]
	v_mfma_f32_16x16x32_bf16 v[58:61], v[158:161], v[208:211], v[58:61]
	v_mfma_f32_16x16x32_bf16 v[6:9], v[150:153], v[216:219], v[6:9]
	v_mfma_f32_16x16x32_bf16 v[2:5], v[158:161], v[216:219], v[2:5]
	s_setprio 0
	s_barrier
	s_add_i32 s35, s35, 2
	s_add_u32 s0, s0, 0x10000
	s_addc_u32 s1, s1, 0
	s_add_u32 s31, s31, 0x10000
	s_addc_u32 s33, s33, 0
	s_cmpk_gt_u32 s35, 0x55
	s_cbranch_scc0 .LBB0_1483
	s_and_b64 vcc, exec, s[20:21]
	s_cbranch_vccz .LBB0_1486
	s_barrier
